# v062 plus conservative s_nop 0 between the inline v_max3 pairs removed (46) and fused residual epilogues: 1/sqrt(mean square + eps) via v_rsq_f32 + one Newton step (f32, as the SwiGLU epilogue already
# baseline (speedup 1.0000x reference)
; DI unsigned pk_bf16(float lo, float hi) { f32x2 v = {lo, hi}; bf16x2_t b = __builtin_convertvector(v, bf16x2_t); return __builtin_bit_cast(unsigned, b); }
; DI float bflo(unsigned w) { return __uint_as_float(w << 16); }
; DI float bfhi(unsigned w) { return __uint_as_float(w & 0xffff0000u); }
;     __device__ __forceinline__ void fused(f32x4 (&acc)[2][2][4][2], const pg8::Unit& u, int wr, int wc, int fr, int fq, PG8_LAS unsigned char* lds, int wid, int lane) const {
;     ...
;         const int colb = u.pn * 256 + wc * 32 + 8 * fq;
;         f32x4 gv[2][2];
; #pragma unroll
;         for (int bj = 0; bj < 2; ++bj)
; #pragma unroll
;             for (int n = 0; n < 2; ++n) gv[bj][n] = *(const f32x4*)(gA + colb + bj * 128 + 4 * n);
; #pragma unroll
;         for (int ai = 0; ai < 2; ++ai)
; #pragma unroll
;             for (int m = 0; m < 4; ++m) {
;                 const int rl = ai * 128 + wr * 64 + m * 16 + fr; const size_t row = (size_t)u.pm * 256 + rl;
;                 const float rm = 1.f / sqrtf(__hip_atomic_load(ssqm + row, __ATOMIC_RELAXED, __HIP_MEMORY_SCOPE_AGENT) * (1.f / DM) + RMS_EPS);
;                 float sh = 0.f;
; #pragma unroll
;                 for (int bj = 0; bj < 2; ++bj) {
;                     const size_t off = row * DM + colb + bj * 128;
;                     f32x4 h0, h1;
;                     if (IN16) { const u32x4 hw = *(const u32x4*)((const bf16_t*)hin + off); h0 = (f32x4){bflo(hw.x), bfhi(hw.x), bflo(hw.y), bfhi(hw.y)}; h1 = (f32x4){bflo(hw.z), bfhi(hw.z), bflo(hw.w), bfhi(hw.w)}; }
;                     else { h0 = *(const f32x4*)((const float*)hin + off); h1 = *(const f32x4*)((const float*)hin + off + 4); }
;                     h0 = h0 + acc[ai][bj][m][0] * rm * gv[bj][0]; h1 = h1 + acc[ai][bj][m][1] * rm * gv[bj][1];
;                     sh += ((h0[0] * h0[0] + h0[1] * h0[1]) + (h0[2] * h0[2] + h0[3] * h0[3])) + ((h1[0] * h1[0] + h1[1] * h1[1]) + (h1[2] * h1[2] + h1[3] * h1[3]));
;                     if (OUT16) { u32x4 w; w.x = pk_bf16(h0[0], h0[1]); w.y = pk_bf16(h0[2], h0[3]); w.z = pk_bf16(h1[0], h1[1]); w.w = pk_bf16(h1[2], h1[3]); *(u32x4*)((bf16_t*)hout + off) = w; }
;                     else { *(f32x4*)((float*)hout + off) = h0; *(f32x4*)((float*)hout + off + 4) = h1; }
;                 }
;                 if (ssqh) { sh += __shfl_xor(sh, 16); sh += __shfl_xor(sh, 32); if (fq == 0) red[rl * 4 + wc] = sh; }
.LBB0_911:
	s_or_b64 exec, exec, s[0:1]
	s_lshl_b32 s0, s41, 5
	s_lshl_b32 s1, s33, 8
	s_or_b32 s0, s1, s0
	v_mov_b32_e32 v159, 0
	v_or_b32_e32 v156, s0, v160
	s_lshl_b64 s[18:19], s[16:17], 8
	v_mov_b32_e32 v153, v159
	v_ashrrev_i32_e32 v157, 31, v156
	v_lshl_add_u64 v[168:169], s[18:19], 0, v[152:153]
	v_lshl_add_u64 v[100:101], v[156:157], 2, s[14:15]
	v_lshl_add_u64 v[170:171], v[168:169], 2, s[12:13]
	s_barrier
	global_load_dwordx4 v[104:107], v[100:101], off offset:16
	global_load_dwordx4 v[108:111], v[100:101], off
	global_load_dwordx4 v[96:99], v[100:101], off offset:528
	s_nop 0
	global_load_dwordx4 v[100:103], v[100:101], off offset:512
	v_lshlrev_b64 v[168:169], 10, v[168:169]
	global_load_dword v151, v[170:171], off sc1
	v_lshl_add_u64 v[176:177], v[168:169], 0, v[156:157]
	v_lshl_add_u64 v[178:179], v[176:177], 2, s[36:37]
	global_load_dwordx4 v[168:171], v[178:179], off
	global_load_dwordx4 v[172:175], v[178:179], off offset:16
	v_mov_b32_e32 v153, 0x358637bd
	s_mov_b32 s2, 0xf800000
	v_lshlrev_b64 v[176:177], 1, v[176:177]
	s_waitcnt vmcnt(2)
	v_fmamk_f32 v151, v151, 0x3a800000, v153
	v_rsq_f32_e32 v252, v151
	s_nop 0
	v_mul_f32_e32 v253, v151, v252
	v_mul_f32_e32 v253, v253, v252
	v_fmaak_f32 v253, -0.5, v253, 0x3fc00000
	v_mul_f32_e32 v252, v252, v253
	s_nop 1
	v_mov_b32_e32 v151, 0x260
	s_nop 1
	s_nop 1
	s_nop 1
	v_lshl_add_u64 v[180:181], s[10:11], 0, v[176:177]
	v_mov_b32_e32 v158, v252
	v_pk_mul_f32 v[140:141], v[140:141], v[158:159] op_sel_hi:[1,0]
	v_pk_mul_f32 v[142:143], v[142:143], v[158:159] op_sel_hi:[1,0]
	v_pk_mul_f32 v[136:137], v[136:137], v[158:159] op_sel_hi:[1,0]
	v_pk_mul_f32 v[138:139], v[138:139], v[158:159] op_sel_hi:[1,0]
	s_waitcnt vmcnt(1)
	v_pk_fma_f32 v[170:171], v[110:111], v[142:143], v[170:171]
	v_pk_fma_f32 v[168:169], v[108:109], v[140:141], v[168:169]
	s_waitcnt vmcnt(0)
	v_pk_fma_f32 v[174:175], v[106:107], v[138:139], v[174:175]
	v_pk_fma_f32 v[172:173], v[104:105], v[136:137], v[172:173]
	v_cvt_pk_bf16_f32 v136, v168, v169
	v_cvt_pk_bf16_f32 v137, v170, v171
	v_cvt_pk_bf16_f32 v138, v172, v173
	v_cvt_pk_bf16_f32 v139, v174, v175
	global_store_dwordx4 v[180:181], v[136:139], off
	global_load_dwordx4 v[136:139], v[178:179], off offset:512
	s_nop 0
	global_load_dwordx4 v[140:143], v[178:179], off offset:528
	v_pk_mul_f32 v[132:133], v[132:133], v[158:159] op_sel_hi:[1,0]
	v_pk_mul_f32 v[134:135], v[134:135], v[158:159] op_sel_hi:[1,0]
	v_pk_mul_f32 v[128:129], v[128:129], v[158:159] op_sel_hi:[1,0]
	v_pk_mul_f32 v[130:131], v[130:131], v[158:159] op_sel_hi:[1,0]
	v_mul_f32_e32 v158, v169, v169
	v_mul_f32_e32 v169, v171, v171
	v_mul_f32_e32 v171, v173, v173
	v_mul_f32_e32 v173, v175, v175
	v_fmac_f32_e32 v158, v168, v168
	v_fmac_f32_e32 v169, v170, v170
	v_fmac_f32_e32 v171, v172, v172
	v_fmac_f32_e32 v173, v174, v174
	v_add_f32_e32 v158, v158, v169
	v_add_f32_e32 v168, v171, v173
	v_add_f32_e32 v158, v158, v168
	v_or_b32_e32 v176, 0x100, v176
	s_waitcnt vmcnt(1)
	v_pk_fma_f32 v[134:135], v[102:103], v[134:135], v[138:139]
	v_pk_fma_f32 v[132:133], v[100:101], v[132:133], v[136:137]
	s_waitcnt vmcnt(0)
	v_pk_fma_f32 v[136:137], v[98:99], v[130:131], v[142:143]
	v_pk_fma_f32 v[128:129], v[96:97], v[128:129], v[140:141]
	v_mul_f32_e32 v130, v133, v133
	v_mul_f32_e32 v131, v135, v135
	v_mul_f32_e32 v138, v129, v129
	v_mul_f32_e32 v139, v137, v137
	v_fmac_f32_e32 v130, v132, v132
	v_fmac_f32_e32 v131, v134, v134
	v_fmac_f32_e32 v138, v128, v128
	v_fmac_f32_e32 v139, v136, v136
	v_add_f32_e32 v130, v130, v131
	v_add_f32_e32 v131, v138, v139
	v_add_f32_e32 v130, v130, v131
	v_add_f32_e32 v138, v158, v130
	ds_bpermute_b32 v139, v145, v138
	v_cvt_pk_bf16_f32 v130, v132, v133
	v_cvt_pk_bf16_f32 v132, v128, v129
	v_cvt_pk_bf16_f32 v131, v134, v135
	v_cvt_pk_bf16_f32 v133, v136, v137
	s_waitcnt lgkmcnt(0)
	v_add_f32_e32 v128, v138, v139
	ds_bpermute_b32 v129, v147, v128
	v_lshl_add_u64 v[134:135], s[10:11], 0, v[176:177]
	global_store_dwordx4 v[134:135], v[130:133], off
	s_and_saveexec_b64 s[0:1], s[4:5]
	s_cbranch_execz .LBB0_913
	v_lshl_add_u32 v130, v152, 4, s22
	s_waitcnt lgkmcnt(0)
	v_add_f32_e32 v128, v128, v129
	ds_write_b32 v130, v128
.LBB0_913:
	s_or_b64 exec, exec, s[0:1]
	v_or_b32_e32 v158, 16, v152
	s_waitcnt lgkmcnt(0)
	v_lshl_add_u64 v[128:129], s[18:19], 0, v[158:159]
	v_lshl_add_u64 v[130:131], v[128:129], 2, s[12:13]
	global_load_dword v140, v[130:131], off sc1
	v_lshlrev_b64 v[128:129], 10, v[128:129]
	v_lshl_add_u64 v[136:137], v[128:129], 0, v[156:157]
	v_lshl_add_u64 v[138:139], v[136:137], 2, s[36:37]
	global_load_dwordx4 v[128:131], v[138:139], off
	global_load_dwordx4 v[132:135], v[138:139], off offset:16
	v_lshlrev_b64 v[136:137], 1, v[136:137]
	s_waitcnt vmcnt(2)
	v_fmac_f32_e32 v153, 0x3a800000, v140
	v_rsq_f32_e32 v252, v153
	s_nop 0
	v_mul_f32_e32 v253, v153, v252
	v_mul_f32_e32 v253, v253, v252
	v_fmaak_f32 v253, -0.5, v253, 0x3fc00000
	v_mul_f32_e32 v252, v252, v253
	s_nop 1
	s_nop 0
	s_nop 1
	s_nop 1
	s_nop 1
	v_lshl_add_u64 v[140:141], s[10:11], 0, v[136:137]
	v_mov_b32_e32 v142, v252
	v_pk_mul_f32 v[124:125], v[124:125], v[142:143] op_sel_hi:[1,0]
	v_pk_mul_f32 v[126:127], v[126:127], v[142:143] op_sel_hi:[1,0]
	v_pk_mul_f32 v[120:121], v[120:121], v[142:143] op_sel_hi:[1,0]
	v_pk_mul_f32 v[122:123], v[122:123], v[142:143] op_sel_hi:[1,0]
	s_waitcnt vmcnt(1)
	v_pk_fma_f32 v[130:131], v[110:111], v[126:127], v[130:131]
	v_pk_fma_f32 v[128:129], v[108:109], v[124:125], v[128:129]
	s_waitcnt vmcnt(0)
; DI unsigned pk_bf16(float lo, float hi) { f32x2 v = {lo, hi}; bf16x2_t b = __builtin_convertvector(v, bf16x2_t); return __builtin_bit_cast(unsigned, b); }
; DI float bflo(unsigned w) { return __uint_as_float(w << 16); }
; DI float bfhi(unsigned w) { return __uint_as_float(w & 0xffff0000u); }
;     __device__ __forceinline__ void fused(f32x4 (&acc)[2][2][4][2], const pg8::Unit& u, int wr, int wc, int fr, int fq, PG8_LAS unsigned char* lds, int wid, int lane) const {
;     ...
;             for (int m = 0; m < 4; ++m) {
;                 const int rl = ai * 128 + wr * 64 + m * 16 + fr; const size_t row = (size_t)u.pm * 256 + rl;
;                 const float rm = 1.f / sqrtf(__hip_atomic_load(ssqm + row, __ATOMIC_RELAXED, __HIP_MEMORY_SCOPE_AGENT) * (1.f / DM) + RMS_EPS);
;                 float sh = 0.f;
; #pragma unroll
;                 for (int bj = 0; bj < 2; ++bj) {
;                     const size_t off = row * DM + colb + bj * 128;
;                     f32x4 h0, h1;
;                     if (IN16) { const u32x4 hw = *(const u32x4*)((const bf16_t*)hin + off); h0 = (f32x4){bflo(hw.x), bfhi(hw.x), bflo(hw.y), bfhi(hw.y)}; h1 = (f32x4){bflo(hw.z), bfhi(hw.z), bflo(hw.w), bfhi(hw.w)}; }
;                     else { h0 = *(const f32x4*)((const float*)hin + off); h1 = *(const f32x4*)((const float*)hin + off + 4); }
;                     h0 = h0 + acc[ai][bj][m][0] * rm * gv[bj][0]; h1 = h1 + acc[ai][bj][m][1] * rm * gv[bj][1];
;                     sh += ((h0[0] * h0[0] + h0[1] * h0[1]) + (h0[2] * h0[2] + h0[3] * h0[3])) + ((h1[0] * h1[0] + h1[1] * h1[1]) + (h1[2] * h1[2] + h1[3] * h1[3]));
;                     if (OUT16) { u32x4 w; w.x = pk_bf16(h0[0], h0[1]); w.y = pk_bf16(h0[2], h0[3]); w.z = pk_bf16(h1[0], h1[1]); w.w = pk_bf16(h1[2], h1[3]); *(u32x4*)((bf16_t*)hout + off) = w; }
;                     else { *(f32x4*)((float*)hout + off) = h0; *(f32x4*)((float*)hout + off + 4) = h1; }
;                 }
;                 if (ssqh) { sh += __shfl_xor(sh, 16); sh += __shfl_xor(sh, 32); if (fq == 0) red[rl * 4 + wc] = sh; }
	v_pk_fma_f32 v[134:135], v[106:107], v[122:123], v[134:135]
	v_pk_fma_f32 v[132:133], v[104:105], v[120:121], v[132:133]
	v_cvt_pk_bf16_f32 v120, v128, v129
	v_cvt_pk_bf16_f32 v121, v130, v131
	v_cvt_pk_bf16_f32 v122, v132, v133
	v_cvt_pk_bf16_f32 v123, v134, v135
	global_store_dwordx4 v[140:141], v[120:123], off
	global_load_dwordx4 v[120:123], v[138:139], off offset:512
	s_nop 0
	global_load_dwordx4 v[124:127], v[138:139], off offset:528
	v_pk_mul_f32 v[116:117], v[116:117], v[142:143] op_sel_hi:[1,0]
	v_pk_mul_f32 v[118:119], v[118:119], v[142:143] op_sel_hi:[1,0]
	v_pk_mul_f32 v[112:113], v[112:113], v[142:143] op_sel_hi:[1,0]
	v_pk_mul_f32 v[114:115], v[114:115], v[142:143] op_sel_hi:[1,0]
	v_mul_f32_e32 v129, v129, v129
	v_mul_f32_e32 v131, v131, v131
	v_mul_f32_e32 v133, v133, v133
	v_mul_f32_e32 v135, v135, v135
	v_fmac_f32_e32 v129, v128, v128
	v_fmac_f32_e32 v131, v130, v130
	v_fmac_f32_e32 v133, v132, v132
	v_fmac_f32_e32 v135, v134, v134
	v_add_f32_e32 v128, v129, v131
	v_add_f32_e32 v129, v133, v135
	v_add_f32_e32 v128, v128, v129
	v_or_b32_e32 v136, 0x100, v136
	s_waitcnt vmcnt(1)
	v_pk_fma_f32 v[118:119], v[102:103], v[118:119], v[122:123]
	v_pk_fma_f32 v[116:117], v[100:101], v[116:117], v[120:121]
	s_waitcnt vmcnt(0)
	v_pk_fma_f32 v[120:121], v[98:99], v[114:115], v[126:127]
	v_pk_fma_f32 v[112:113], v[96:97], v[112:113], v[124:125]
	v_mul_f32_e32 v114, v117, v117
	v_mul_f32_e32 v115, v119, v119
	v_mul_f32_e32 v122, v113, v113
	v_mul_f32_e32 v123, v121, v121
	v_fmac_f32_e32 v114, v116, v116
	v_fmac_f32_e32 v115, v118, v118
	v_fmac_f32_e32 v122, v112, v112
	v_fmac_f32_e32 v123, v120, v120
	v_add_f32_e32 v114, v114, v115
	v_add_f32_e32 v115, v122, v123
	v_add_f32_e32 v114, v114, v115
	v_add_f32_e32 v122, v128, v114
	ds_bpermute_b32 v123, v145, v122
	v_cvt_pk_bf16_f32 v114, v116, v117
	v_cvt_pk_bf16_f32 v116, v112, v113
	v_cvt_pk_bf16_f32 v115, v118, v119
	v_cvt_pk_bf16_f32 v117, v120, v121
	s_waitcnt lgkmcnt(0)
	v_add_f32_e32 v112, v122, v123
	ds_bpermute_b32 v113, v147, v112
	v_lshl_add_u64 v[118:119], s[10:11], 0, v[136:137]
	global_store_dwordx4 v[118:119], v[114:117], off
	s_and_saveexec_b64 s[0:1], s[4:5]
	s_cbranch_execz .LBB0_915
	v_lshl_add_u32 v114, v158, 4, s22
	s_waitcnt lgkmcnt(0)
	v_add_f32_e32 v112, v112, v113
	ds_write_b32 v114, v112
.LBB0_915:
	s_or_b64 exec, exec, s[0:1]
	v_or_b32_e32 v112, 32, v152
	s_waitcnt lgkmcnt(0)
	v_mov_b32_e32 v113, 0
	v_lshl_add_u64 v[114:115], s[18:19], 0, v[112:113]
	v_lshl_add_u64 v[116:117], v[114:115], 2, s[12:13]
	global_load_dword v128, v[116:117], off sc1
	v_lshlrev_b64 v[114:115], 10, v[114:115]
	v_lshl_add_u64 v[124:125], v[114:115], 0, v[156:157]
	v_lshl_add_u64 v[126:127], v[124:125], 2, s[36:37]
	global_load_dwordx4 v[116:119], v[126:127], off
	global_load_dwordx4 v[120:123], v[126:127], off offset:16
	v_mov_b32_e32 v115, 0x358637bd
	v_lshlrev_b64 v[124:125], 1, v[124:125]
	s_waitcnt vmcnt(2)
	v_fmamk_f32 v114, v128, 0x3a800000, v115
	v_rsq_f32_e32 v252, v114
	s_nop 0
	v_mul_f32_e32 v253, v114, v252
	v_mul_f32_e32 v253, v253, v252
	v_fmaak_f32 v253, -0.5, v253, 0x3fc00000
	v_mul_f32_e32 v252, v252, v253
	s_nop 1
	v_mov_b32_e32 v114, 0x260
	s_nop 1
	s_nop 1
	s_nop 1
	v_lshl_add_u64 v[128:129], s[10:11], 0, v[124:125]
	v_mov_b32_e32 v130, v252
	v_pk_mul_f32 v[92:93], v[92:93], v[130:131] op_sel_hi:[1,0]
	v_pk_mul_f32 v[94:95], v[94:95], v[130:131] op_sel_hi:[1,0]
	v_pk_mul_f32 v[88:89], v[88:89], v[130:131] op_sel_hi:[1,0]
	v_pk_mul_f32 v[90:91], v[90:91], v[130:131] op_sel_hi:[1,0]
	s_waitcnt vmcnt(1)
	v_pk_fma_f32 v[118:119], v[110:111], v[94:95], v[118:119]
	v_pk_fma_f32 v[116:117], v[108:109], v[92:93], v[116:117]
	s_waitcnt vmcnt(0)
	v_pk_fma_f32 v[122:123], v[106:107], v[90:91], v[122:123]
	v_pk_fma_f32 v[120:121], v[104:105], v[88:89], v[120:121]
	v_cvt_pk_bf16_f32 v88, v116, v117
	v_cvt_pk_bf16_f32 v89, v118, v119
	v_cvt_pk_bf16_f32 v90, v120, v121
	v_cvt_pk_bf16_f32 v91, v122, v123
	global_store_dwordx4 v[128:129], v[88:91], off
	global_load_dwordx4 v[88:91], v[126:127], off offset:512
	s_nop 0
	global_load_dwordx4 v[92:95], v[126:127], off offset:528
	v_pk_mul_f32 v[84:85], v[84:85], v[130:131] op_sel_hi:[1,0]
	v_pk_mul_f32 v[86:87], v[86:87], v[130:131] op_sel_hi:[1,0]
	v_pk_mul_f32 v[80:81], v[80:81], v[130:131] op_sel_hi:[1,0]
	v_pk_mul_f32 v[82:83], v[82:83], v[130:131] op_sel_hi:[1,0]
	v_mul_f32_e32 v117, v117, v117
	v_mul_f32_e32 v119, v119, v119
	v_mul_f32_e32 v121, v121, v121
	v_mul_f32_e32 v123, v123, v123
	v_fmac_f32_e32 v117, v116, v116
	v_fmac_f32_e32 v119, v118, v118
	v_fmac_f32_e32 v121, v120, v120
	v_fmac_f32_e32 v123, v122, v122
	v_add_f32_e32 v116, v117, v119
	v_add_f32_e32 v117, v121, v123
	v_add_f32_e32 v116, v116, v117
	v_or_b32_e32 v124, 0x100, v124
	s_waitcnt vmcnt(1)
	v_pk_fma_f32 v[86:87], v[102:103], v[86:87], v[90:91]
	v_pk_fma_f32 v[84:85], v[100:101], v[84:85], v[88:89]
	s_waitcnt vmcnt(0)
	v_pk_fma_f32 v[88:89], v[98:99], v[82:83], v[94:95]
	v_pk_fma_f32 v[80:81], v[96:97], v[80:81], v[92:93]
	v_mul_f32_e32 v82, v85, v85
	v_mul_f32_e32 v83, v87, v87
	v_mul_f32_e32 v90, v81, v81
	v_mul_f32_e32 v91, v89, v89
	v_fmac_f32_e32 v82, v84, v84
	v_fmac_f32_e32 v83, v86, v86
	v_fmac_f32_e32 v90, v80, v80
	v_fmac_f32_e32 v91, v88, v88
	v_add_f32_e32 v82, v82, v83
	v_add_f32_e32 v83, v90, v91
	v_add_f32_e32 v82, v82, v83
	v_add_f32_e32 v90, v116, v82
	ds_bpermute_b32 v91, v145, v90
	v_cvt_pk_bf16_f32 v82, v84, v85
	v_cvt_pk_bf16_f32 v84, v80, v81
	v_cvt_pk_bf16_f32 v83, v86, v87
	v_cvt_pk_bf16_f32 v85, v88, v89
	s_waitcnt lgkmcnt(0)
	v_add_f32_e32 v80, v90, v91
	ds_bpermute_b32 v81, v147, v80
	v_lshl_add_u64 v[86:87], s[10:11], 0, v[124:125]
	global_store_dwordx4 v[86:87], v[82:85], off
	s_and_saveexec_b64 s[0:1], s[4:5]
	s_cbranch_execz .LBB0_917
	v_lshl_add_u32 v82, v112, 4, s22
	s_waitcnt lgkmcnt(0)
	v_add_f32_e32 v80, v80, v81
	ds_write_b32 v82, v80
; DI unsigned pk_bf16(float lo, float hi) { f32x2 v = {lo, hi}; bf16x2_t b = __builtin_convertvector(v, bf16x2_t); return __builtin_bit_cast(unsigned, b); }
; DI float bflo(unsigned w) { return __uint_as_float(w << 16); }
; DI float bfhi(unsigned w) { return __uint_as_float(w & 0xffff0000u); }
;     __device__ __forceinline__ void fused(f32x4 (&acc)[2][2][4][2], const pg8::Unit& u, int wr, int wc, int fr, int fq, PG8_LAS unsigned char* lds, int wid, int lane) const {
;     ...
;             for (int m = 0; m < 4; ++m) {
;                 const int rl = ai * 128 + wr * 64 + m * 16 + fr; const size_t row = (size_t)u.pm * 256 + rl;
;                 const float rm = 1.f / sqrtf(__hip_atomic_load(ssqm + row, __ATOMIC_RELAXED, __HIP_MEMORY_SCOPE_AGENT) * (1.f / DM) + RMS_EPS);
;                 float sh = 0.f;
; #pragma unroll
;                 for (int bj = 0; bj < 2; ++bj) {
;                     const size_t off = row * DM + colb + bj * 128;
;                     f32x4 h0, h1;
;                     if (IN16) { const u32x4 hw = *(const u32x4*)((const bf16_t*)hin + off); h0 = (f32x4){bflo(hw.x), bfhi(hw.x), bflo(hw.y), bfhi(hw.y)}; h1 = (f32x4){bflo(hw.z), bfhi(hw.z), bflo(hw.w), bfhi(hw.w)}; }
;                     else { h0 = *(const f32x4*)((const float*)hin + off); h1 = *(const f32x4*)((const float*)hin + off + 4); }
;                     h0 = h0 + acc[ai][bj][m][0] * rm * gv[bj][0]; h1 = h1 + acc[ai][bj][m][1] * rm * gv[bj][1];
;                     sh += ((h0[0] * h0[0] + h0[1] * h0[1]) + (h0[2] * h0[2] + h0[3] * h0[3])) + ((h1[0] * h1[0] + h1[1] * h1[1]) + (h1[2] * h1[2] + h1[3] * h1[3]));
;                     if (OUT16) { u32x4 w; w.x = pk_bf16(h0[0], h0[1]); w.y = pk_bf16(h0[2], h0[3]); w.z = pk_bf16(h1[0], h1[1]); w.w = pk_bf16(h1[2], h1[3]); *(u32x4*)((bf16_t*)hout + off) = w; }
;                     else { *(f32x4*)((float*)hout + off) = h0; *(f32x4*)((float*)hout + off + 4) = h1; }
;                 }
;                 if (ssqh) { sh += __shfl_xor(sh, 16); sh += __shfl_xor(sh, 32); if (fq == 0) red[rl * 4 + wc] = sh; }
.LBB0_917:
	s_or_b64 exec, exec, s[0:1]
	v_or_b32_e32 v112, 48, v152
	s_waitcnt lgkmcnt(0)
	v_lshl_add_u64 v[80:81], s[18:19], 0, v[112:113]
	v_lshl_add_u64 v[82:83], v[80:81], 2, s[12:13]
	global_load_dword v92, v[82:83], off sc1
	v_lshlrev_b64 v[80:81], 10, v[80:81]
	v_lshl_add_u64 v[88:89], v[80:81], 0, v[156:157]
	v_lshl_add_u64 v[90:91], v[88:89], 2, s[36:37]
	global_load_dwordx4 v[80:83], v[90:91], off
	global_load_dwordx4 v[84:87], v[90:91], off offset:16
	v_lshlrev_b64 v[88:89], 1, v[88:89]
	s_waitcnt vmcnt(2)
	v_fmac_f32_e32 v115, 0x3a800000, v92
	v_rsq_f32_e32 v252, v115
	s_nop 0
	v_mul_f32_e32 v253, v115, v252
	v_mul_f32_e32 v253, v253, v252
	v_fmaak_f32 v253, -0.5, v253, 0x3fc00000
	v_mul_f32_e32 v252, v252, v253
	s_nop 1
	s_nop 0
	s_nop 1
	s_nop 1
	s_nop 1
	v_lshl_add_u64 v[92:93], s[10:11], 0, v[88:89]
	v_mov_b32_e32 v94, v252
	v_pk_mul_f32 v[76:77], v[76:77], v[94:95] op_sel_hi:[1,0]
	v_pk_mul_f32 v[78:79], v[78:79], v[94:95] op_sel_hi:[1,0]
	v_pk_mul_f32 v[72:73], v[72:73], v[94:95] op_sel_hi:[1,0]
	v_pk_mul_f32 v[74:75], v[74:75], v[94:95] op_sel_hi:[1,0]
	s_waitcnt vmcnt(1)
	v_pk_fma_f32 v[82:83], v[110:111], v[78:79], v[82:83]
	v_pk_fma_f32 v[80:81], v[108:109], v[76:77], v[80:81]
	s_waitcnt vmcnt(0)
	v_pk_fma_f32 v[86:87], v[106:107], v[74:75], v[86:87]
	v_pk_fma_f32 v[84:85], v[104:105], v[72:73], v[84:85]
	v_cvt_pk_bf16_f32 v72, v80, v81
	v_cvt_pk_bf16_f32 v73, v82, v83
	v_cvt_pk_bf16_f32 v74, v84, v85
	v_cvt_pk_bf16_f32 v75, v86, v87
	global_store_dwordx4 v[92:93], v[72:75], off
	global_load_dwordx4 v[72:75], v[90:91], off offset:512
	s_nop 0
	global_load_dwordx4 v[76:79], v[90:91], off offset:528
	v_pk_mul_f32 v[68:69], v[68:69], v[94:95] op_sel_hi:[1,0]
	v_pk_mul_f32 v[70:71], v[70:71], v[94:95] op_sel_hi:[1,0]
	v_pk_mul_f32 v[64:65], v[64:65], v[94:95] op_sel_hi:[1,0]
	v_pk_mul_f32 v[66:67], v[66:67], v[94:95] op_sel_hi:[1,0]
	v_mul_f32_e32 v81, v81, v81
	v_mul_f32_e32 v83, v83, v83
	v_mul_f32_e32 v85, v85, v85
	v_mul_f32_e32 v87, v87, v87
	v_fmac_f32_e32 v81, v80, v80
	v_fmac_f32_e32 v83, v82, v82
	v_fmac_f32_e32 v85, v84, v84
	v_fmac_f32_e32 v87, v86, v86
	v_add_f32_e32 v80, v81, v83
	v_add_f32_e32 v81, v85, v87
	v_add_f32_e32 v80, v80, v81
	v_or_b32_e32 v88, 0x100, v88
	s_waitcnt vmcnt(1)
	v_pk_fma_f32 v[70:71], v[102:103], v[70:71], v[74:75]
	v_pk_fma_f32 v[68:69], v[100:101], v[68:69], v[72:73]
	s_waitcnt vmcnt(0)
	v_pk_fma_f32 v[72:73], v[98:99], v[66:67], v[78:79]
	v_pk_fma_f32 v[64:65], v[96:97], v[64:65], v[76:77]
	v_mul_f32_e32 v66, v69, v69
	v_mul_f32_e32 v67, v71, v71
	v_mul_f32_e32 v74, v65, v65
	v_mul_f32_e32 v75, v73, v73
	v_fmac_f32_e32 v66, v68, v68
	v_fmac_f32_e32 v67, v70, v70
	v_fmac_f32_e32 v74, v64, v64
	v_fmac_f32_e32 v75, v72, v72
	v_add_f32_e32 v66, v66, v67
	v_add_f32_e32 v67, v74, v75
	v_add_f32_e32 v66, v66, v67
	v_add_f32_e32 v74, v80, v66
	ds_bpermute_b32 v75, v145, v74
	v_cvt_pk_bf16_f32 v66, v68, v69
	v_cvt_pk_bf16_f32 v68, v64, v65
	v_cvt_pk_bf16_f32 v67, v70, v71
	v_cvt_pk_bf16_f32 v69, v72, v73
	s_waitcnt lgkmcnt(0)
	v_add_f32_e32 v64, v74, v75
	ds_bpermute_b32 v65, v147, v64
	v_lshl_add_u64 v[70:71], s[10:11], 0, v[88:89]
	global_store_dwordx4 v[70:71], v[66:69], off
	s_and_saveexec_b64 s[0:1], s[4:5]
	s_cbranch_execz .LBB0_919
	v_lshl_add_u32 v66, v112, 4, s22
	s_waitcnt lgkmcnt(0)
	v_add_f32_e32 v64, v64, v65
	ds_write_b32 v66, v64
.LBB0_919:
	s_or_b64 exec, exec, s[0:1]
	v_add_u32_e32 v64, 0x80, v152
	s_waitcnt lgkmcnt(0)
	v_mov_b32_e32 v65, 0
	v_lshl_add_u64 v[66:67], s[18:19], 0, v[64:65]
	v_lshl_add_u64 v[68:69], v[66:67], 2, s[12:13]
	global_load_dword v80, v[68:69], off sc1
	v_lshlrev_b64 v[66:67], 10, v[66:67]
	v_lshl_add_u64 v[76:77], v[66:67], 0, v[156:157]
	v_lshl_add_u64 v[78:79], v[76:77], 2, s[36:37]
	global_load_dwordx4 v[68:71], v[78:79], off
	global_load_dwordx4 v[72:75], v[78:79], off offset:16
	v_mov_b32_e32 v67, 0x358637bd
	v_lshlrev_b64 v[76:77], 1, v[76:77]
	s_waitcnt vmcnt(2)
	v_fmamk_f32 v66, v80, 0x3a800000, v67
	v_rsq_f32_e32 v252, v66
	s_nop 0
	v_mul_f32_e32 v253, v66, v252
	v_mul_f32_e32 v253, v253, v252
	v_fmaak_f32 v253, -0.5, v253, 0x3fc00000
	v_mul_f32_e32 v252, v252, v253
	s_nop 1
	v_mov_b32_e32 v66, 0x260
	s_nop 1
	s_nop 1
	s_nop 1
	v_lshl_add_u64 v[80:81], s[10:11], 0, v[76:77]
	v_mov_b32_e32 v82, v252
	v_pk_mul_f32 v[60:61], v[60:61], v[82:83] op_sel_hi:[1,0]
	v_pk_mul_f32 v[62:63], v[62:63], v[82:83] op_sel_hi:[1,0]
	v_pk_mul_f32 v[56:57], v[56:57], v[82:83] op_sel_hi:[1,0]
	v_pk_mul_f32 v[58:59], v[58:59], v[82:83] op_sel_hi:[1,0]
	s_waitcnt vmcnt(1)
	v_pk_fma_f32 v[70:71], v[110:111], v[62:63], v[70:71]
	v_pk_fma_f32 v[68:69], v[108:109], v[60:61], v[68:69]
	s_waitcnt vmcnt(0)
	v_pk_fma_f32 v[74:75], v[106:107], v[58:59], v[74:75]
	v_pk_fma_f32 v[72:73], v[104:105], v[56:57], v[72:73]
	v_cvt_pk_bf16_f32 v56, v68, v69
	v_cvt_pk_bf16_f32 v57, v70, v71
	v_cvt_pk_bf16_f32 v58, v72, v73
	v_cvt_pk_bf16_f32 v59, v74, v75
	global_store_dwordx4 v[80:81], v[56:59], off
	global_load_dwordx4 v[56:59], v[78:79], off offset:512
	s_nop 0
	global_load_dwordx4 v[60:63], v[78:79], off offset:528
	v_pk_mul_f32 v[52:53], v[52:53], v[82:83] op_sel_hi:[1,0]
	v_pk_mul_f32 v[54:55], v[54:55], v[82:83] op_sel_hi:[1,0]
	v_pk_mul_f32 v[48:49], v[48:49], v[82:83] op_sel_hi:[1,0]
	v_pk_mul_f32 v[50:51], v[50:51], v[82:83] op_sel_hi:[1,0]
	v_mul_f32_e32 v69, v69, v69
	v_mul_f32_e32 v71, v71, v71
	v_mul_f32_e32 v73, v73, v73
	v_mul_f32_e32 v75, v75, v75
	v_fmac_f32_e32 v69, v68, v68
	v_fmac_f32_e32 v71, v70, v70
	v_fmac_f32_e32 v73, v72, v72
	v_fmac_f32_e32 v75, v74, v74
	v_add_f32_e32 v68, v69, v71
	v_add_f32_e32 v69, v73, v75
	v_add_f32_e32 v68, v68, v69
	v_or_b32_e32 v76, 0x100, v76
	s_waitcnt vmcnt(1)
	v_pk_fma_f32 v[54:55], v[102:103], v[54:55], v[58:59]
	v_pk_fma_f32 v[52:53], v[100:101], v[52:53], v[56:57]
	s_waitcnt vmcnt(0)
	v_pk_fma_f32 v[56:57], v[98:99], v[50:51], v[62:63]
	v_pk_fma_f32 v[48:49], v[96:97], v[48:49], v[60:61]
	v_mul_f32_e32 v50, v53, v53
	v_mul_f32_e32 v51, v55, v55
	v_mul_f32_e32 v58, v49, v49
	v_mul_f32_e32 v59, v57, v57
	v_fmac_f32_e32 v50, v52, v52
	v_fmac_f32_e32 v51, v54, v54
	v_fmac_f32_e32 v58, v48, v48
	v_fmac_f32_e32 v59, v56, v56
	v_add_f32_e32 v50, v50, v51
	v_add_f32_e32 v51, v58, v59
	v_add_f32_e32 v50, v50, v51
	v_add_f32_e32 v58, v68, v50
	ds_bpermute_b32 v59, v145, v58
	v_cvt_pk_bf16_f32 v50, v52, v53
	v_cvt_pk_bf16_f32 v52, v48, v49
	v_cvt_pk_bf16_f32 v51, v54, v55
	v_cvt_pk_bf16_f32 v53, v56, v57
	s_waitcnt lgkmcnt(0)
	v_add_f32_e32 v48, v58, v59
	ds_bpermute_b32 v49, v147, v48
	v_lshl_add_u64 v[54:55], s[10:11], 0, v[76:77]
	global_store_dwordx4 v[54:55], v[50:53], off
	s_and_saveexec_b64 s[0:1], s[4:5]
	s_cbranch_execz .LBB0_921
	v_lshl_add_u32 v50, v64, 4, s22
	s_waitcnt lgkmcnt(0)
	v_add_f32_e32 v48, v48, v49
	ds_write_b32 v50, v48
; DI unsigned pk_bf16(float lo, float hi) { f32x2 v = {lo, hi}; bf16x2_t b = __builtin_convertvector(v, bf16x2_t); return __builtin_bit_cast(unsigned, b); }
; DI float bflo(unsigned w) { return __uint_as_float(w << 16); }
; DI float bfhi(unsigned w) { return __uint_as_float(w & 0xffff0000u); }
;     __device__ __forceinline__ void fused(f32x4 (&acc)[2][2][4][2], const pg8::Unit& u, int wr, int wc, int fr, int fq, PG8_LAS unsigned char* lds, int wid, int lane) const {
;     ...
;             for (int m = 0; m < 4; ++m) {
;                 const int rl = ai * 128 + wr * 64 + m * 16 + fr; const size_t row = (size_t)u.pm * 256 + rl;
;                 const float rm = 1.f / sqrtf(__hip_atomic_load(ssqm + row, __ATOMIC_RELAXED, __HIP_MEMORY_SCOPE_AGENT) * (1.f / DM) + RMS_EPS);
;                 float sh = 0.f;
; #pragma unroll
;                 for (int bj = 0; bj < 2; ++bj) {
;                     const size_t off = row * DM + colb + bj * 128;
;                     f32x4 h0, h1;
;                     if (IN16) { const u32x4 hw = *(const u32x4*)((const bf16_t*)hin + off); h0 = (f32x4){bflo(hw.x), bfhi(hw.x), bflo(hw.y), bfhi(hw.y)}; h1 = (f32x4){bflo(hw.z), bfhi(hw.z), bflo(hw.w), bfhi(hw.w)}; }
;                     else { h0 = *(const f32x4*)((const float*)hin + off); h1 = *(const f32x4*)((const float*)hin + off + 4); }
;                     h0 = h0 + acc[ai][bj][m][0] * rm * gv[bj][0]; h1 = h1 + acc[ai][bj][m][1] * rm * gv[bj][1];
;                     sh += ((h0[0] * h0[0] + h0[1] * h0[1]) + (h0[2] * h0[2] + h0[3] * h0[3])) + ((h1[0] * h1[0] + h1[1] * h1[1]) + (h1[2] * h1[2] + h1[3] * h1[3]));
;                     if (OUT16) { u32x4 w; w.x = pk_bf16(h0[0], h0[1]); w.y = pk_bf16(h0[2], h0[3]); w.z = pk_bf16(h1[0], h1[1]); w.w = pk_bf16(h1[2], h1[3]); *(u32x4*)((bf16_t*)hout + off) = w; }
;                     else { *(f32x4*)((float*)hout + off) = h0; *(f32x4*)((float*)hout + off + 4) = h1; }
;                 }
;                 if (ssqh) { sh += __shfl_xor(sh, 16); sh += __shfl_xor(sh, 32); if (fq == 0) red[rl * 4 + wc] = sh; }
.LBB0_921:
	s_or_b64 exec, exec, s[0:1]
	v_add_u32_e32 v64, 0x90, v152
	s_waitcnt lgkmcnt(0)
	v_lshl_add_u64 v[48:49], s[18:19], 0, v[64:65]
	v_lshl_add_u64 v[50:51], v[48:49], 2, s[12:13]
	global_load_dword v60, v[50:51], off sc1
	v_lshlrev_b64 v[48:49], 10, v[48:49]
	v_lshl_add_u64 v[56:57], v[48:49], 0, v[156:157]
	v_lshl_add_u64 v[58:59], v[56:57], 2, s[36:37]
	global_load_dwordx4 v[48:51], v[58:59], off
	global_load_dwordx4 v[52:55], v[58:59], off offset:16
	v_lshlrev_b64 v[56:57], 1, v[56:57]
	s_waitcnt vmcnt(2)
	v_fmac_f32_e32 v67, 0x3a800000, v60
	v_rsq_f32_e32 v252, v67
	s_nop 0
	v_mul_f32_e32 v253, v67, v252
	v_mul_f32_e32 v253, v253, v252
	v_fmaak_f32 v253, -0.5, v253, 0x3fc00000
	v_mul_f32_e32 v252, v252, v253
	s_nop 1
	s_nop 0
	s_nop 1
	s_nop 1
	s_nop 1
	v_lshl_add_u64 v[60:61], s[10:11], 0, v[56:57]
	v_mov_b32_e32 v62, v252
	v_pk_mul_f32 v[44:45], v[44:45], v[62:63] op_sel_hi:[1,0]
	v_pk_mul_f32 v[46:47], v[46:47], v[62:63] op_sel_hi:[1,0]
	v_pk_mul_f32 v[40:41], v[40:41], v[62:63] op_sel_hi:[1,0]
	v_pk_mul_f32 v[42:43], v[42:43], v[62:63] op_sel_hi:[1,0]
	s_waitcnt vmcnt(1)
	v_pk_fma_f32 v[50:51], v[110:111], v[46:47], v[50:51]
	v_pk_fma_f32 v[48:49], v[108:109], v[44:45], v[48:49]
	s_waitcnt vmcnt(0)
	v_pk_fma_f32 v[54:55], v[106:107], v[42:43], v[54:55]
	v_pk_fma_f32 v[52:53], v[104:105], v[40:41], v[52:53]
	v_cvt_pk_bf16_f32 v40, v48, v49
	v_cvt_pk_bf16_f32 v41, v50, v51
	v_cvt_pk_bf16_f32 v42, v52, v53
	v_cvt_pk_bf16_f32 v43, v54, v55
	global_store_dwordx4 v[60:61], v[40:43], off
	global_load_dwordx4 v[40:43], v[58:59], off offset:512
	s_nop 0
	global_load_dwordx4 v[44:47], v[58:59], off offset:528
	v_pk_mul_f32 v[36:37], v[36:37], v[62:63] op_sel_hi:[1,0]
	v_pk_mul_f32 v[38:39], v[38:39], v[62:63] op_sel_hi:[1,0]
	v_pk_mul_f32 v[32:33], v[32:33], v[62:63] op_sel_hi:[1,0]
	v_pk_mul_f32 v[34:35], v[34:35], v[62:63] op_sel_hi:[1,0]
	v_mul_f32_e32 v49, v49, v49
	v_mul_f32_e32 v51, v51, v51
	v_mul_f32_e32 v53, v53, v53
	v_mul_f32_e32 v55, v55, v55
	v_fmac_f32_e32 v49, v48, v48
	v_fmac_f32_e32 v51, v50, v50
	v_fmac_f32_e32 v53, v52, v52
	v_fmac_f32_e32 v55, v54, v54
	v_add_f32_e32 v48, v49, v51
	v_add_f32_e32 v49, v53, v55
	v_add_f32_e32 v48, v48, v49
	v_or_b32_e32 v56, 0x100, v56
	s_waitcnt vmcnt(1)
	v_pk_fma_f32 v[38:39], v[102:103], v[38:39], v[42:43]
	v_pk_fma_f32 v[36:37], v[100:101], v[36:37], v[40:41]
	s_waitcnt vmcnt(0)
	v_pk_fma_f32 v[40:41], v[98:99], v[34:35], v[46:47]
	v_pk_fma_f32 v[32:33], v[96:97], v[32:33], v[44:45]
	v_mul_f32_e32 v34, v37, v37
	v_mul_f32_e32 v35, v39, v39
	v_mul_f32_e32 v42, v33, v33
	v_mul_f32_e32 v43, v41, v41
	v_fmac_f32_e32 v34, v36, v36
	v_fmac_f32_e32 v35, v38, v38
	v_fmac_f32_e32 v42, v32, v32
	v_fmac_f32_e32 v43, v40, v40
	v_add_f32_e32 v34, v34, v35
	v_add_f32_e32 v35, v42, v43
	v_add_f32_e32 v34, v34, v35
	v_add_f32_e32 v42, v48, v34
	ds_bpermute_b32 v43, v145, v42
	v_cvt_pk_bf16_f32 v34, v36, v37
	v_cvt_pk_bf16_f32 v36, v32, v33
	v_cvt_pk_bf16_f32 v35, v38, v39
	v_cvt_pk_bf16_f32 v37, v40, v41
	s_waitcnt lgkmcnt(0)
	v_add_f32_e32 v32, v42, v43
	ds_bpermute_b32 v33, v147, v32
	v_lshl_add_u64 v[38:39], s[10:11], 0, v[56:57]
	global_store_dwordx4 v[38:39], v[34:37], off
	s_and_saveexec_b64 s[0:1], s[4:5]
	s_cbranch_execz .LBB0_923
	v_lshl_add_u32 v34, v64, 4, s22
	s_waitcnt lgkmcnt(0)
	v_add_f32_e32 v32, v32, v33
	ds_write_b32 v34, v32
; DI unsigned pk_bf16(float lo, float hi) { f32x2 v = {lo, hi}; bf16x2_t b = __builtin_convertvector(v, bf16x2_t); return __builtin_bit_cast(unsigned, b); }
; DI float bflo(unsigned w) { return __uint_as_float(w << 16); }
; DI float bfhi(unsigned w) { return __uint_as_float(w & 0xffff0000u); }
;     __device__ __forceinline__ void fused(f32x4 (&acc)[2][2][4][2], const pg8::Unit& u, int wr, int wc, int fr, int fq, PG8_LAS unsigned char* lds, int wid, int lane) const {
;     ...
;                 const int rl = ai * 128 + wr * 64 + m * 16 + fr; const size_t row = (size_t)u.pm * 256 + rl;
;                 const float rm = 1.f / sqrtf(__hip_atomic_load(ssqm + row, __ATOMIC_RELAXED, __HIP_MEMORY_SCOPE_AGENT) * (1.f / DM) + RMS_EPS);
;                 float sh = 0.f;
; #pragma unroll
;                 for (int bj = 0; bj < 2; ++bj) {
;                     const size_t off = row * DM + colb + bj * 128;
;                     f32x4 h0, h1;
;                     if (IN16) { const u32x4 hw = *(const u32x4*)((const bf16_t*)hin + off); h0 = (f32x4){bflo(hw.x), bfhi(hw.x), bflo(hw.y), bfhi(hw.y)}; h1 = (f32x4){bflo(hw.z), bfhi(hw.z), bflo(hw.w), bfhi(hw.w)}; }
;                     else { h0 = *(const f32x4*)((const float*)hin + off); h1 = *(const f32x4*)((const float*)hin + off + 4); }
;                     h0 = h0 + acc[ai][bj][m][0] * rm * gv[bj][0]; h1 = h1 + acc[ai][bj][m][1] * rm * gv[bj][1];
;                     sh += ((h0[0] * h0[0] + h0[1] * h0[1]) + (h0[2] * h0[2] + h0[3] * h0[3])) + ((h1[0] * h1[0] + h1[1] * h1[1]) + (h1[2] * h1[2] + h1[3] * h1[3]));
;                     if (OUT16) { u32x4 w; w.x = pk_bf16(h0[0], h0[1]); w.y = pk_bf16(h0[2], h0[3]); w.z = pk_bf16(h1[0], h1[1]); w.w = pk_bf16(h1[2], h1[3]); *(u32x4*)((bf16_t*)hout + off) = w; }
;                     else { *(f32x4*)((float*)hout + off) = h0; *(f32x4*)((float*)hout + off + 4) = h1; }
;                 }
;                 if (ssqh) { sh += __shfl_xor(sh, 16); sh += __shfl_xor(sh, 32); if (fq == 0) red[rl * 4 + wc] = sh; }
.LBB0_923:
	s_or_b64 exec, exec, s[0:1]
	v_add_u32_e32 v32, 0xa0, v152
	s_waitcnt lgkmcnt(0)
	v_mov_b32_e32 v33, 0
	v_lshl_add_u64 v[34:35], s[18:19], 0, v[32:33]
	v_lshl_add_u64 v[36:37], v[34:35], 2, s[12:13]
	global_load_dword v48, v[36:37], off sc1
	v_lshlrev_b64 v[34:35], 10, v[34:35]
	v_lshl_add_u64 v[44:45], v[34:35], 0, v[156:157]
	v_lshl_add_u64 v[46:47], v[44:45], 2, s[36:37]
	global_load_dwordx4 v[36:39], v[46:47], off
	global_load_dwordx4 v[40:43], v[46:47], off offset:16
	v_mov_b32_e32 v35, 0x358637bd
	v_lshlrev_b64 v[44:45], 1, v[44:45]
	s_waitcnt vmcnt(2)
	v_fmamk_f32 v34, v48, 0x3a800000, v35
	v_rsq_f32_e32 v252, v34
	s_nop 0
	v_mul_f32_e32 v253, v34, v252
	v_mul_f32_e32 v253, v253, v252
	v_fmaak_f32 v253, -0.5, v253, 0x3fc00000
	v_mul_f32_e32 v252, v252, v253
	s_nop 1
	v_mov_b32_e32 v34, 0x260
	s_nop 1
	s_nop 1
	s_nop 1
	v_lshl_add_u64 v[48:49], s[10:11], 0, v[44:45]
	v_mov_b32_e32 v50, v252
	v_pk_mul_f32 v[28:29], v[28:29], v[50:51] op_sel_hi:[1,0]
	v_pk_mul_f32 v[30:31], v[30:31], v[50:51] op_sel_hi:[1,0]
	v_pk_mul_f32 v[24:25], v[24:25], v[50:51] op_sel_hi:[1,0]
	v_pk_mul_f32 v[26:27], v[26:27], v[50:51] op_sel_hi:[1,0]
	s_waitcnt vmcnt(1)
	v_pk_fma_f32 v[38:39], v[110:111], v[30:31], v[38:39]
	v_pk_fma_f32 v[36:37], v[108:109], v[28:29], v[36:37]
	s_waitcnt vmcnt(0)
	v_pk_fma_f32 v[42:43], v[106:107], v[26:27], v[42:43]
	v_pk_fma_f32 v[40:41], v[104:105], v[24:25], v[40:41]
	v_cvt_pk_bf16_f32 v24, v36, v37
	v_cvt_pk_bf16_f32 v25, v38, v39
	v_cvt_pk_bf16_f32 v26, v40, v41
	v_cvt_pk_bf16_f32 v27, v42, v43
	global_store_dwordx4 v[48:49], v[24:27], off
	global_load_dwordx4 v[24:27], v[46:47], off offset:512
	s_nop 0
	global_load_dwordx4 v[28:31], v[46:47], off offset:528
	v_pk_mul_f32 v[20:21], v[20:21], v[50:51] op_sel_hi:[1,0]
	v_pk_mul_f32 v[22:23], v[22:23], v[50:51] op_sel_hi:[1,0]
	v_pk_mul_f32 v[16:17], v[16:17], v[50:51] op_sel_hi:[1,0]
	v_pk_mul_f32 v[18:19], v[18:19], v[50:51] op_sel_hi:[1,0]
	v_mul_f32_e32 v37, v37, v37
	v_mul_f32_e32 v39, v39, v39
	v_mul_f32_e32 v41, v41, v41
	v_mul_f32_e32 v43, v43, v43
	v_fmac_f32_e32 v37, v36, v36
	v_fmac_f32_e32 v39, v38, v38
	v_fmac_f32_e32 v41, v40, v40
	v_fmac_f32_e32 v43, v42, v42
	v_add_f32_e32 v36, v37, v39
	v_add_f32_e32 v37, v41, v43
	v_add_f32_e32 v36, v36, v37
	v_or_b32_e32 v44, 0x100, v44
	s_waitcnt vmcnt(1)
	v_pk_fma_f32 v[22:23], v[102:103], v[22:23], v[26:27]
	v_pk_fma_f32 v[20:21], v[100:101], v[20:21], v[24:25]
	s_waitcnt vmcnt(0)
	v_pk_fma_f32 v[24:25], v[98:99], v[18:19], v[30:31]
	v_pk_fma_f32 v[16:17], v[96:97], v[16:17], v[28:29]
	v_mul_f32_e32 v18, v21, v21
	v_mul_f32_e32 v19, v23, v23
	v_mul_f32_e32 v26, v17, v17
	v_mul_f32_e32 v27, v25, v25
	v_fmac_f32_e32 v18, v20, v20
	v_fmac_f32_e32 v19, v22, v22
	v_fmac_f32_e32 v26, v16, v16
	v_fmac_f32_e32 v27, v24, v24
	v_add_f32_e32 v18, v18, v19
	v_add_f32_e32 v19, v26, v27
	v_add_f32_e32 v18, v18, v19
	v_add_f32_e32 v26, v36, v18
	ds_bpermute_b32 v27, v145, v26
	v_cvt_pk_bf16_f32 v18, v20, v21
	v_cvt_pk_bf16_f32 v20, v16, v17
	v_cvt_pk_bf16_f32 v19, v22, v23
	v_cvt_pk_bf16_f32 v21, v24, v25
	s_waitcnt lgkmcnt(0)
	v_add_f32_e32 v16, v26, v27
	ds_bpermute_b32 v17, v147, v16
	v_lshl_add_u64 v[22:23], s[10:11], 0, v[44:45]
	global_store_dwordx4 v[22:23], v[18:21], off
	s_and_saveexec_b64 s[0:1], s[4:5]
	s_cbranch_execz .LBB0_925
	v_lshl_add_u32 v18, v32, 4, s22
	s_waitcnt lgkmcnt(0)
	v_add_f32_e32 v16, v16, v17
	ds_write_b32 v18, v16
.LBB0_925:
	s_or_b64 exec, exec, s[0:1]
	v_add_u32_e32 v32, 0xb0, v152
	s_waitcnt lgkmcnt(0)
	v_lshl_add_u64 v[16:17], s[18:19], 0, v[32:33]
	v_lshl_add_u64 v[18:19], v[16:17], 2, s[12:13]
	global_load_dword v28, v[18:19], off sc1
	v_lshlrev_b64 v[16:17], 10, v[16:17]
	v_lshl_add_u64 v[24:25], v[16:17], 0, v[156:157]
	v_lshl_add_u64 v[26:27], v[24:25], 2, s[36:37]
	global_load_dwordx4 v[16:19], v[26:27], off
	global_load_dwordx4 v[20:23], v[26:27], off offset:16
	v_lshlrev_b64 v[24:25], 1, v[24:25]
	s_waitcnt vmcnt(2)
	v_fmac_f32_e32 v35, 0x3a800000, v28
	v_rsq_f32_e32 v252, v35
	s_nop 0
	v_mul_f32_e32 v253, v35, v252
	v_mul_f32_e32 v253, v253, v252
	v_fmaak_f32 v253, -0.5, v253, 0x3fc00000
	v_mul_f32_e32 v252, v252, v253
	s_nop 1
	s_nop 0
	s_nop 1
	s_nop 1
	s_nop 1
	v_lshl_add_u64 v[28:29], s[10:11], 0, v[24:25]
	v_mov_b32_e32 v30, v252
	v_pk_mul_f32 v[12:13], v[12:13], v[30:31] op_sel_hi:[1,0]
	v_pk_mul_f32 v[14:15], v[14:15], v[30:31] op_sel_hi:[1,0]
	v_pk_mul_f32 v[8:9], v[8:9], v[30:31] op_sel_hi:[1,0]
	v_pk_mul_f32 v[10:11], v[10:11], v[30:31] op_sel_hi:[1,0]
	s_waitcnt vmcnt(1)
	v_pk_fma_f32 v[18:19], v[110:111], v[14:15], v[18:19]
	v_pk_fma_f32 v[16:17], v[108:109], v[12:13], v[16:17]
	s_waitcnt vmcnt(0)
	v_pk_fma_f32 v[22:23], v[106:107], v[10:11], v[22:23]
	v_pk_fma_f32 v[20:21], v[104:105], v[8:9], v[20:21]
	v_cvt_pk_bf16_f32 v8, v16, v17
	v_cvt_pk_bf16_f32 v9, v18, v19
	v_cvt_pk_bf16_f32 v10, v20, v21
	v_cvt_pk_bf16_f32 v11, v22, v23
	global_store_dwordx4 v[28:29], v[8:11], off
	global_load_dwordx4 v[8:11], v[26:27], off offset:512
	s_nop 0
	global_load_dwordx4 v[12:15], v[26:27], off offset:528
	v_pk_mul_f32 v[4:5], v[4:5], v[30:31] op_sel_hi:[1,0]
	v_pk_mul_f32 v[6:7], v[6:7], v[30:31] op_sel_hi:[1,0]
	v_pk_mul_f32 v[0:1], v[0:1], v[30:31] op_sel_hi:[1,0]
	v_pk_mul_f32 v[2:3], v[2:3], v[30:31] op_sel_hi:[1,0]
	v_mul_f32_e32 v17, v17, v17
	v_mul_f32_e32 v19, v19, v19
	v_mul_f32_e32 v21, v21, v21
	v_mul_f32_e32 v23, v23, v23
	v_fmac_f32_e32 v17, v16, v16
	v_fmac_f32_e32 v19, v18, v18
	v_fmac_f32_e32 v21, v20, v20
	v_fmac_f32_e32 v23, v22, v22
	v_add_f32_e32 v16, v17, v19
	v_add_f32_e32 v17, v21, v23
	v_add_f32_e32 v16, v16, v17
	v_or_b32_e32 v24, 0x100, v24
	s_waitcnt vmcnt(1)
	v_pk_fma_f32 v[6:7], v[102:103], v[6:7], v[10:11]
	v_pk_fma_f32 v[4:5], v[100:101], v[4:5], v[8:9]
	s_waitcnt vmcnt(0)
	v_pk_fma_f32 v[8:9], v[98:99], v[2:3], v[14:15]
	v_pk_fma_f32 v[0:1], v[96:97], v[0:1], v[12:13]
	v_mul_f32_e32 v2, v5, v5
	v_mul_f32_e32 v3, v7, v7
	v_mul_f32_e32 v10, v1, v1
	v_mul_f32_e32 v11, v9, v9
	v_fmac_f32_e32 v2, v4, v4
	v_fmac_f32_e32 v3, v6, v6
	v_fmac_f32_e32 v10, v0, v0
	v_fmac_f32_e32 v11, v8, v8
	v_add_f32_e32 v2, v2, v3
	v_add_f32_e32 v3, v10, v11
	v_add_f32_e32 v2, v2, v3
	v_add_f32_e32 v10, v16, v2
	ds_bpermute_b32 v11, v145, v10
	v_cvt_pk_bf16_f32 v2, v4, v5
	v_cvt_pk_bf16_f32 v4, v0, v1
	v_cvt_pk_bf16_f32 v3, v6, v7
	v_cvt_pk_bf16_f32 v5, v8, v9
	s_waitcnt lgkmcnt(0)
	v_add_f32_e32 v0, v10, v11
	ds_bpermute_b32 v1, v147, v0
	v_lshl_add_u64 v[6:7], s[10:11], 0, v[24:25]
	global_store_dwordx4 v[6:7], v[2:5], off
	s_and_saveexec_b64 s[0:1], s[4:5]
	s_cbranch_execz .LBB0_927
	v_lshl_add_u32 v2, v32, 4, s22
	s_waitcnt lgkmcnt(0)
	v_add_f32_e32 v0, v0, v1
	ds_write_b32 v2, v0

; DI unsigned pk_bf16(float lo, float hi) { f32x2 v = {lo, hi}; bf16x2_t b = __builtin_convertvector(v, bf16x2_t); return __builtin_bit_cast(unsigned, b); }
; DI float bflo(unsigned w) { return __uint_as_float(w << 16); }
; DI float bfhi(unsigned w) { return __uint_as_float(w & 0xffff0000u); }
;     __device__ __forceinline__ void fused(f32x4 (&acc)[2][2][4][2], const pg8::Unit& u, int wr, int wc, int fr, int fq, PG8_LAS unsigned char* lds, int wid, int lane) const {
;     ...
;         const int colb = u.pn * 256 + wc * 32 + 8 * fq;
;         f32x4 gv[2][2];
; #pragma unroll
;         for (int bj = 0; bj < 2; ++bj)
; #pragma unroll
;             for (int n = 0; n < 2; ++n) gv[bj][n] = *(const f32x4*)(gA + colb + bj * 128 + 4 * n);
; #pragma unroll
;         for (int ai = 0; ai < 2; ++ai)
; #pragma unroll
;             for (int m = 0; m < 4; ++m) {
;                 const int rl = ai * 128 + wr * 64 + m * 16 + fr; const size_t row = (size_t)u.pm * 256 + rl;
;                 const float rm = 1.f / sqrtf(__hip_atomic_load(ssqm + row, __ATOMIC_RELAXED, __HIP_MEMORY_SCOPE_AGENT) * (1.f / DM) + RMS_EPS);
;                 float sh = 0.f;
; #pragma unroll
;                 for (int bj = 0; bj < 2; ++bj) {
;                     const size_t off = row * DM + colb + bj * 128;
;                     f32x4 h0, h1;
;                     if (IN16) { const u32x4 hw = *(const u32x4*)((const bf16_t*)hin + off); h0 = (f32x4){bflo(hw.x), bfhi(hw.x), bflo(hw.y), bfhi(hw.y)}; h1 = (f32x4){bflo(hw.z), bfhi(hw.z), bflo(hw.w), bfhi(hw.w)}; }
;                     else { h0 = *(const f32x4*)((const float*)hin + off); h1 = *(const f32x4*)((const float*)hin + off + 4); }
;                     h0 = h0 + acc[ai][bj][m][0] * rm * gv[bj][0]; h1 = h1 + acc[ai][bj][m][1] * rm * gv[bj][1];
;                     sh += ((h0[0] * h0[0] + h0[1] * h0[1]) + (h0[2] * h0[2] + h0[3] * h0[3])) + ((h1[0] * h1[0] + h1[1] * h1[1]) + (h1[2] * h1[2] + h1[3] * h1[3]));
;                     if (OUT16) { u32x4 w; w.x = pk_bf16(h0[0], h0[1]); w.y = pk_bf16(h0[2], h0[3]); w.z = pk_bf16(h1[0], h1[1]); w.w = pk_bf16(h1[2], h1[3]); *(u32x4*)((bf16_t*)hout + off) = w; }
;                     else { *(f32x4*)((float*)hout + off) = h0; *(f32x4*)((float*)hout + off + 4) = h1; }
;                 }
;                 if (ssqh) { sh += __shfl_xor(sh, 16); sh += __shfl_xor(sh, 32); if (fq == 0) red[rl * 4 + wc] = sh; }
.LBB0_966:
	s_or_b64 exec, exec, s[0:1]
	s_lshl_b32 s0, s30, 5
	s_lshl_b32 s1, s33, 8
	s_or_b32 s0, s1, s0
	v_or_b32_e32 v146, s0, v160
	v_ashrrev_i32_e32 v147, 31, v146
	v_mov_b32_e32 v149, 0
	v_lshl_add_u64 v[100:101], v[146:147], 2, s[14:15]
	s_lshl_b64 s[14:15], s[16:17], 8
	v_mov_b32_e32 v153, v149
	v_lshl_add_u64 v[156:157], s[14:15], 0, v[152:153]
	v_lshl_add_u64 v[158:159], v[156:157], 2, s[12:13]
	s_barrier
	global_load_dwordx4 v[104:107], v[100:101], off offset:16
	global_load_dwordx4 v[108:111], v[100:101], off
	global_load_dwordx4 v[96:99], v[100:101], off offset:528
	s_nop 0
	global_load_dwordx4 v[100:103], v[100:101], off offset:512
	v_lshlrev_b64 v[156:157], 10, v[156:157]
	global_load_dword v148, v[158:159], off sc1
	v_lshl_add_u64 v[164:165], v[156:157], 0, v[146:147]
	v_lshl_add_u64 v[166:167], v[164:165], 2, s[36:37]
	global_load_dwordx4 v[156:159], v[166:167], off
	global_load_dwordx4 v[160:163], v[166:167], off offset:16
	v_mov_b32_e32 v155, 0x358637bd
	s_mov_b32 s2, 0xf800000
	v_lshlrev_b64 v[164:165], 1, v[164:165]
	s_waitcnt vmcnt(2)
	v_fmamk_f32 v148, v148, 0x3a800000, v155
	v_rsq_f32_e32 v252, v148
	s_nop 0
	v_mul_f32_e32 v253, v148, v252
	v_mul_f32_e32 v253, v253, v252
	v_fmaak_f32 v253, -0.5, v253, 0x3fc00000
	v_mul_f32_e32 v252, v252, v253
	s_nop 1
	v_mov_b32_e32 v153, 0x260
	s_nop 1
	s_nop 1
	s_nop 1
	v_lshl_add_u64 v[168:169], s[10:11], 0, v[164:165]
	v_mov_b32_e32 v148, v252
	v_pk_mul_f32 v[140:141], v[140:141], v[148:149] op_sel_hi:[1,0]
	v_pk_mul_f32 v[142:143], v[142:143], v[148:149] op_sel_hi:[1,0]
	v_pk_mul_f32 v[136:137], v[136:137], v[148:149] op_sel_hi:[1,0]
	v_pk_mul_f32 v[138:139], v[138:139], v[148:149] op_sel_hi:[1,0]
	s_waitcnt vmcnt(1)
	v_pk_fma_f32 v[158:159], v[110:111], v[142:143], v[158:159]
	v_pk_fma_f32 v[156:157], v[108:109], v[140:141], v[156:157]
	s_waitcnt vmcnt(0)
	v_pk_fma_f32 v[162:163], v[106:107], v[138:139], v[162:163]
	v_pk_fma_f32 v[160:161], v[104:105], v[136:137], v[160:161]
	v_cvt_pk_bf16_f32 v136, v156, v157
	v_cvt_pk_bf16_f32 v137, v158, v159
	v_cvt_pk_bf16_f32 v138, v160, v161
	v_cvt_pk_bf16_f32 v139, v162, v163
	global_store_dwordx4 v[168:169], v[136:139], off
	global_load_dwordx4 v[136:139], v[166:167], off offset:512
	s_nop 0
	global_load_dwordx4 v[140:143], v[166:167], off offset:528
	v_pk_mul_f32 v[132:133], v[132:133], v[148:149] op_sel_hi:[1,0]
	v_pk_mul_f32 v[134:135], v[134:135], v[148:149] op_sel_hi:[1,0]
	v_pk_mul_f32 v[128:129], v[128:129], v[148:149] op_sel_hi:[1,0]
	v_pk_mul_f32 v[130:131], v[130:131], v[148:149] op_sel_hi:[1,0]
	v_mul_f32_e32 v148, v157, v157
	v_mul_f32_e32 v157, v159, v159
	v_mul_f32_e32 v159, v161, v161
	v_mul_f32_e32 v161, v163, v163
	v_fmac_f32_e32 v148, v156, v156
	v_fmac_f32_e32 v157, v158, v158
	v_fmac_f32_e32 v159, v160, v160
	v_fmac_f32_e32 v161, v162, v162
	v_add_f32_e32 v148, v148, v157
	v_add_f32_e32 v156, v159, v161
	v_add_f32_e32 v148, v148, v156
	v_or_b32_e32 v164, 0x100, v164
	s_waitcnt vmcnt(1)
	v_pk_fma_f32 v[134:135], v[102:103], v[134:135], v[138:139]
	v_pk_fma_f32 v[132:133], v[100:101], v[132:133], v[136:137]
	s_waitcnt vmcnt(0)
	v_pk_fma_f32 v[136:137], v[98:99], v[130:131], v[142:143]
	v_pk_fma_f32 v[128:129], v[96:97], v[128:129], v[140:141]
	v_mul_f32_e32 v130, v133, v133
	v_mul_f32_e32 v131, v135, v135
	v_mul_f32_e32 v138, v129, v129
	v_mul_f32_e32 v139, v137, v137
	v_fmac_f32_e32 v130, v132, v132
	v_fmac_f32_e32 v131, v134, v134
	v_fmac_f32_e32 v138, v128, v128
	v_fmac_f32_e32 v139, v136, v136
	v_add_f32_e32 v130, v130, v131
	v_add_f32_e32 v131, v138, v139
	v_add_f32_e32 v130, v130, v131
	v_add_f32_e32 v138, v148, v130
	ds_bpermute_b32 v139, v150, v138
	v_cvt_pk_bf16_f32 v130, v132, v133
	v_cvt_pk_bf16_f32 v132, v128, v129
	v_cvt_pk_bf16_f32 v131, v134, v135
	v_cvt_pk_bf16_f32 v133, v136, v137
	s_waitcnt lgkmcnt(0)
	v_add_f32_e32 v128, v138, v139
	ds_bpermute_b32 v129, v151, v128
	v_lshl_add_u64 v[134:135], s[10:11], 0, v[164:165]
	global_store_dwordx4 v[134:135], v[130:133], off
	s_and_saveexec_b64 s[0:1], s[4:5]
	s_cbranch_execz .LBB0_968
	v_lshl_add_u32 v130, v152, 4, s22
	s_waitcnt lgkmcnt(0)
	v_add_f32_e32 v128, v128, v129
	ds_write_b32 v130, v128
.LBB0_968:
	s_or_b64 exec, exec, s[0:1]
	v_or_b32_e32 v148, 16, v152
	s_waitcnt lgkmcnt(0)
	v_lshl_add_u64 v[128:129], s[14:15], 0, v[148:149]
	v_lshl_add_u64 v[130:131], v[128:129], 2, s[12:13]
	global_load_dword v140, v[130:131], off sc1
	v_lshlrev_b64 v[128:129], 10, v[128:129]
	v_lshl_add_u64 v[136:137], v[128:129], 0, v[146:147]
	v_lshl_add_u64 v[138:139], v[136:137], 2, s[36:37]
	global_load_dwordx4 v[128:131], v[138:139], off
	global_load_dwordx4 v[132:135], v[138:139], off offset:16
	v_lshlrev_b64 v[136:137], 1, v[136:137]
	s_waitcnt vmcnt(2)
	v_fmac_f32_e32 v155, 0x3a800000, v140
	v_rsq_f32_e32 v252, v155
	s_nop 0
	v_mul_f32_e32 v253, v155, v252
	v_mul_f32_e32 v253, v253, v252
	v_fmaak_f32 v253, -0.5, v253, 0x3fc00000
	v_mul_f32_e32 v252, v252, v253
	s_nop 1
	s_nop 0
	s_nop 1
	s_nop 1
	s_nop 1
	v_lshl_add_u64 v[140:141], s[10:11], 0, v[136:137]
	v_mov_b32_e32 v142, v252
	v_pk_mul_f32 v[124:125], v[124:125], v[142:143] op_sel_hi:[1,0]
	v_pk_mul_f32 v[126:127], v[126:127], v[142:143] op_sel_hi:[1,0]
	v_pk_mul_f32 v[120:121], v[120:121], v[142:143] op_sel_hi:[1,0]
	v_pk_mul_f32 v[122:123], v[122:123], v[142:143] op_sel_hi:[1,0]
	s_waitcnt vmcnt(1)
	v_pk_fma_f32 v[130:131], v[110:111], v[126:127], v[130:131]
	v_pk_fma_f32 v[128:129], v[108:109], v[124:125], v[128:129]
	s_waitcnt vmcnt(0)
; DI unsigned pk_bf16(float lo, float hi) { f32x2 v = {lo, hi}; bf16x2_t b = __builtin_convertvector(v, bf16x2_t); return __builtin_bit_cast(unsigned, b); }
; DI float bflo(unsigned w) { return __uint_as_float(w << 16); }
; DI float bfhi(unsigned w) { return __uint_as_float(w & 0xffff0000u); }
;     __device__ __forceinline__ void fused(f32x4 (&acc)[2][2][4][2], const pg8::Unit& u, int wr, int wc, int fr, int fq, PG8_LAS unsigned char* lds, int wid, int lane) const {
;     ...
;                 const int rl = ai * 128 + wr * 64 + m * 16 + fr; const size_t row = (size_t)u.pm * 256 + rl;
;                 const float rm = 1.f / sqrtf(__hip_atomic_load(ssqm + row, __ATOMIC_RELAXED, __HIP_MEMORY_SCOPE_AGENT) * (1.f / DM) + RMS_EPS);
;                 float sh = 0.f;
; #pragma unroll
;                 for (int bj = 0; bj < 2; ++bj) {
;                     const size_t off = row * DM + colb + bj * 128;
;                     f32x4 h0, h1;
;                     if (IN16) { const u32x4 hw = *(const u32x4*)((const bf16_t*)hin + off); h0 = (f32x4){bflo(hw.x), bfhi(hw.x), bflo(hw.y), bfhi(hw.y)}; h1 = (f32x4){bflo(hw.z), bfhi(hw.z), bflo(hw.w), bfhi(hw.w)}; }
;                     else { h0 = *(const f32x4*)((const float*)hin + off); h1 = *(const f32x4*)((const float*)hin + off + 4); }
;                     h0 = h0 + acc[ai][bj][m][0] * rm * gv[bj][0]; h1 = h1 + acc[ai][bj][m][1] * rm * gv[bj][1];
;                     sh += ((h0[0] * h0[0] + h0[1] * h0[1]) + (h0[2] * h0[2] + h0[3] * h0[3])) + ((h1[0] * h1[0] + h1[1] * h1[1]) + (h1[2] * h1[2] + h1[3] * h1[3]));
;                     if (OUT16) { u32x4 w; w.x = pk_bf16(h0[0], h0[1]); w.y = pk_bf16(h0[2], h0[3]); w.z = pk_bf16(h1[0], h1[1]); w.w = pk_bf16(h1[2], h1[3]); *(u32x4*)((bf16_t*)hout + off) = w; }
;                     else { *(f32x4*)((float*)hout + off) = h0; *(f32x4*)((float*)hout + off + 4) = h1; }
;                 }
;                 if (ssqh) { sh += __shfl_xor(sh, 16); sh += __shfl_xor(sh, 32); if (fq == 0) red[rl * 4 + wc] = sh; }
	v_pk_fma_f32 v[134:135], v[106:107], v[122:123], v[134:135]
	v_pk_fma_f32 v[132:133], v[104:105], v[120:121], v[132:133]
	v_cvt_pk_bf16_f32 v120, v128, v129
	v_cvt_pk_bf16_f32 v121, v130, v131
	v_cvt_pk_bf16_f32 v122, v132, v133
	v_cvt_pk_bf16_f32 v123, v134, v135
	global_store_dwordx4 v[140:141], v[120:123], off
	global_load_dwordx4 v[120:123], v[138:139], off offset:512
	s_nop 0
	global_load_dwordx4 v[124:127], v[138:139], off offset:528
	v_pk_mul_f32 v[116:117], v[116:117], v[142:143] op_sel_hi:[1,0]
	v_pk_mul_f32 v[118:119], v[118:119], v[142:143] op_sel_hi:[1,0]
	v_pk_mul_f32 v[112:113], v[112:113], v[142:143] op_sel_hi:[1,0]
	v_pk_mul_f32 v[114:115], v[114:115], v[142:143] op_sel_hi:[1,0]
	v_mul_f32_e32 v129, v129, v129
	v_mul_f32_e32 v131, v131, v131
	v_mul_f32_e32 v133, v133, v133
	v_mul_f32_e32 v135, v135, v135
	v_fmac_f32_e32 v129, v128, v128
	v_fmac_f32_e32 v131, v130, v130
	v_fmac_f32_e32 v133, v132, v132
	v_fmac_f32_e32 v135, v134, v134
	v_add_f32_e32 v128, v129, v131
	v_add_f32_e32 v129, v133, v135
	v_add_f32_e32 v128, v128, v129
	v_or_b32_e32 v136, 0x100, v136
	s_waitcnt vmcnt(1)
	v_pk_fma_f32 v[118:119], v[102:103], v[118:119], v[122:123]
	v_pk_fma_f32 v[116:117], v[100:101], v[116:117], v[120:121]
	s_waitcnt vmcnt(0)
	v_pk_fma_f32 v[120:121], v[98:99], v[114:115], v[126:127]
	v_pk_fma_f32 v[112:113], v[96:97], v[112:113], v[124:125]
	v_mul_f32_e32 v114, v117, v117
	v_mul_f32_e32 v115, v119, v119
	v_mul_f32_e32 v122, v113, v113
	v_mul_f32_e32 v123, v121, v121
	v_fmac_f32_e32 v114, v116, v116
	v_fmac_f32_e32 v115, v118, v118
	v_fmac_f32_e32 v122, v112, v112
	v_fmac_f32_e32 v123, v120, v120
	v_add_f32_e32 v114, v114, v115
	v_add_f32_e32 v115, v122, v123
	v_add_f32_e32 v114, v114, v115
	v_add_f32_e32 v122, v128, v114
	ds_bpermute_b32 v123, v150, v122
	v_cvt_pk_bf16_f32 v114, v116, v117
	v_cvt_pk_bf16_f32 v116, v112, v113
	v_cvt_pk_bf16_f32 v115, v118, v119
	v_cvt_pk_bf16_f32 v117, v120, v121
	s_waitcnt lgkmcnt(0)
	v_add_f32_e32 v112, v122, v123
	ds_bpermute_b32 v113, v151, v112
	v_lshl_add_u64 v[118:119], s[10:11], 0, v[136:137]
	global_store_dwordx4 v[118:119], v[114:117], off
	s_and_saveexec_b64 s[0:1], s[4:5]
	s_cbranch_execz .LBB0_970
	v_lshl_add_u32 v114, v148, 4, s22
	s_waitcnt lgkmcnt(0)
	v_add_f32_e32 v112, v112, v113
	ds_write_b32 v114, v112
.LBB0_970:
	s_or_b64 exec, exec, s[0:1]
	v_or_b32_e32 v112, 32, v152
	s_waitcnt lgkmcnt(0)
	v_mov_b32_e32 v113, 0
	v_lshl_add_u64 v[114:115], s[14:15], 0, v[112:113]
	v_lshl_add_u64 v[116:117], v[114:115], 2, s[12:13]
	global_load_dword v128, v[116:117], off sc1
	v_lshlrev_b64 v[114:115], 10, v[114:115]
	v_lshl_add_u64 v[124:125], v[114:115], 0, v[146:147]
	v_lshl_add_u64 v[126:127], v[124:125], 2, s[36:37]
	global_load_dwordx4 v[116:119], v[126:127], off
	global_load_dwordx4 v[120:123], v[126:127], off offset:16
	v_mov_b32_e32 v115, 0x358637bd
	v_lshlrev_b64 v[124:125], 1, v[124:125]
	s_waitcnt vmcnt(2)
	v_fmamk_f32 v114, v128, 0x3a800000, v115
	v_rsq_f32_e32 v252, v114
	s_nop 0
	v_mul_f32_e32 v253, v114, v252
	v_mul_f32_e32 v253, v253, v252
	v_fmaak_f32 v253, -0.5, v253, 0x3fc00000
	v_mul_f32_e32 v252, v252, v253
	s_nop 1
	v_mov_b32_e32 v114, 0x260
	s_nop 1
	s_nop 1
	s_nop 1
	v_lshl_add_u64 v[128:129], s[10:11], 0, v[124:125]
	v_mov_b32_e32 v130, v252
	v_pk_mul_f32 v[92:93], v[92:93], v[130:131] op_sel_hi:[1,0]
	v_pk_mul_f32 v[94:95], v[94:95], v[130:131] op_sel_hi:[1,0]
	v_pk_mul_f32 v[88:89], v[88:89], v[130:131] op_sel_hi:[1,0]
	v_pk_mul_f32 v[90:91], v[90:91], v[130:131] op_sel_hi:[1,0]
	s_waitcnt vmcnt(1)
	v_pk_fma_f32 v[118:119], v[110:111], v[94:95], v[118:119]
	v_pk_fma_f32 v[116:117], v[108:109], v[92:93], v[116:117]
	s_waitcnt vmcnt(0)
	v_pk_fma_f32 v[122:123], v[106:107], v[90:91], v[122:123]
	v_pk_fma_f32 v[120:121], v[104:105], v[88:89], v[120:121]
	v_cvt_pk_bf16_f32 v88, v116, v117
	v_cvt_pk_bf16_f32 v89, v118, v119
	v_cvt_pk_bf16_f32 v90, v120, v121
	v_cvt_pk_bf16_f32 v91, v122, v123
	global_store_dwordx4 v[128:129], v[88:91], off
	global_load_dwordx4 v[88:91], v[126:127], off offset:512
	s_nop 0
	global_load_dwordx4 v[92:95], v[126:127], off offset:528
	v_pk_mul_f32 v[84:85], v[84:85], v[130:131] op_sel_hi:[1,0]
	v_pk_mul_f32 v[86:87], v[86:87], v[130:131] op_sel_hi:[1,0]
	v_pk_mul_f32 v[80:81], v[80:81], v[130:131] op_sel_hi:[1,0]
	v_pk_mul_f32 v[82:83], v[82:83], v[130:131] op_sel_hi:[1,0]
	v_mul_f32_e32 v117, v117, v117
	v_mul_f32_e32 v119, v119, v119
	v_mul_f32_e32 v121, v121, v121
	v_mul_f32_e32 v123, v123, v123
	v_fmac_f32_e32 v117, v116, v116
	v_fmac_f32_e32 v119, v118, v118
	v_fmac_f32_e32 v121, v120, v120
	v_fmac_f32_e32 v123, v122, v122
	v_add_f32_e32 v116, v117, v119
	v_add_f32_e32 v117, v121, v123
	v_add_f32_e32 v116, v116, v117
	v_or_b32_e32 v124, 0x100, v124
	s_waitcnt vmcnt(1)
	v_pk_fma_f32 v[86:87], v[102:103], v[86:87], v[90:91]
	v_pk_fma_f32 v[84:85], v[100:101], v[84:85], v[88:89]
	s_waitcnt vmcnt(0)
	v_pk_fma_f32 v[88:89], v[98:99], v[82:83], v[94:95]
	v_pk_fma_f32 v[80:81], v[96:97], v[80:81], v[92:93]
	v_mul_f32_e32 v82, v85, v85
	v_mul_f32_e32 v83, v87, v87
	v_mul_f32_e32 v90, v81, v81
	v_mul_f32_e32 v91, v89, v89
	v_fmac_f32_e32 v82, v84, v84
	v_fmac_f32_e32 v83, v86, v86
	v_fmac_f32_e32 v90, v80, v80
	v_fmac_f32_e32 v91, v88, v88
	v_add_f32_e32 v82, v82, v83
	v_add_f32_e32 v83, v90, v91
	v_add_f32_e32 v82, v82, v83
	v_add_f32_e32 v90, v116, v82
	ds_bpermute_b32 v91, v150, v90
	v_cvt_pk_bf16_f32 v82, v84, v85
	v_cvt_pk_bf16_f32 v84, v80, v81
	v_cvt_pk_bf16_f32 v83, v86, v87
	v_cvt_pk_bf16_f32 v85, v88, v89
	s_waitcnt lgkmcnt(0)
	v_add_f32_e32 v80, v90, v91
	ds_bpermute_b32 v81, v151, v80
	v_lshl_add_u64 v[86:87], s[10:11], 0, v[124:125]
	global_store_dwordx4 v[86:87], v[82:85], off
	s_and_saveexec_b64 s[0:1], s[4:5]
	s_cbranch_execz .LBB0_972
	v_lshl_add_u32 v82, v112, 4, s22
	s_waitcnt lgkmcnt(0)
	v_add_f32_e32 v80, v80, v81
	ds_write_b32 v82, v80
; DI unsigned pk_bf16(float lo, float hi) { f32x2 v = {lo, hi}; bf16x2_t b = __builtin_convertvector(v, bf16x2_t); return __builtin_bit_cast(unsigned, b); }
; DI float bflo(unsigned w) { return __uint_as_float(w << 16); }
; DI float bfhi(unsigned w) { return __uint_as_float(w & 0xffff0000u); }
;     __device__ __forceinline__ void fused(f32x4 (&acc)[2][2][4][2], const pg8::Unit& u, int wr, int wc, int fr, int fq, PG8_LAS unsigned char* lds, int wid, int lane) const {
;     ...
;                 const int rl = ai * 128 + wr * 64 + m * 16 + fr; const size_t row = (size_t)u.pm * 256 + rl;
;                 const float rm = 1.f / sqrtf(__hip_atomic_load(ssqm + row, __ATOMIC_RELAXED, __HIP_MEMORY_SCOPE_AGENT) * (1.f / DM) + RMS_EPS);
;                 float sh = 0.f;
; #pragma unroll
;                 for (int bj = 0; bj < 2; ++bj) {
;                     const size_t off = row * DM + colb + bj * 128;
;                     f32x4 h0, h1;
;                     if (IN16) { const u32x4 hw = *(const u32x4*)((const bf16_t*)hin + off); h0 = (f32x4){bflo(hw.x), bfhi(hw.x), bflo(hw.y), bfhi(hw.y)}; h1 = (f32x4){bflo(hw.z), bfhi(hw.z), bflo(hw.w), bfhi(hw.w)}; }
;                     else { h0 = *(const f32x4*)((const float*)hin + off); h1 = *(const f32x4*)((const float*)hin + off + 4); }
;                     h0 = h0 + acc[ai][bj][m][0] * rm * gv[bj][0]; h1 = h1 + acc[ai][bj][m][1] * rm * gv[bj][1];
;                     sh += ((h0[0] * h0[0] + h0[1] * h0[1]) + (h0[2] * h0[2] + h0[3] * h0[3])) + ((h1[0] * h1[0] + h1[1] * h1[1]) + (h1[2] * h1[2] + h1[3] * h1[3]));
;                     if (OUT16) { u32x4 w; w.x = pk_bf16(h0[0], h0[1]); w.y = pk_bf16(h0[2], h0[3]); w.z = pk_bf16(h1[0], h1[1]); w.w = pk_bf16(h1[2], h1[3]); *(u32x4*)((bf16_t*)hout + off) = w; }
;                     else { *(f32x4*)((float*)hout + off) = h0; *(f32x4*)((float*)hout + off + 4) = h1; }
;                 }
;                 if (ssqh) { sh += __shfl_xor(sh, 16); sh += __shfl_xor(sh, 32); if (fq == 0) red[rl * 4 + wc] = sh; }
.LBB0_972:
	s_or_b64 exec, exec, s[0:1]
	v_or_b32_e32 v112, 48, v152
	s_waitcnt lgkmcnt(0)
	v_lshl_add_u64 v[80:81], s[14:15], 0, v[112:113]
	v_lshl_add_u64 v[82:83], v[80:81], 2, s[12:13]
	global_load_dword v92, v[82:83], off sc1
	v_lshlrev_b64 v[80:81], 10, v[80:81]
	v_lshl_add_u64 v[88:89], v[80:81], 0, v[146:147]
	v_lshl_add_u64 v[90:91], v[88:89], 2, s[36:37]
	global_load_dwordx4 v[80:83], v[90:91], off
	global_load_dwordx4 v[84:87], v[90:91], off offset:16
	v_lshlrev_b64 v[88:89], 1, v[88:89]
	s_waitcnt vmcnt(2)
	v_fmac_f32_e32 v115, 0x3a800000, v92
	v_rsq_f32_e32 v252, v115
	s_nop 0
	v_mul_f32_e32 v253, v115, v252
	v_mul_f32_e32 v253, v253, v252
	v_fmaak_f32 v253, -0.5, v253, 0x3fc00000
	v_mul_f32_e32 v252, v252, v253
	s_nop 1
	s_nop 0
	s_nop 1
	s_nop 1
	s_nop 1
	v_lshl_add_u64 v[92:93], s[10:11], 0, v[88:89]
	v_mov_b32_e32 v94, v252
	v_pk_mul_f32 v[76:77], v[76:77], v[94:95] op_sel_hi:[1,0]
	v_pk_mul_f32 v[78:79], v[78:79], v[94:95] op_sel_hi:[1,0]
	v_pk_mul_f32 v[72:73], v[72:73], v[94:95] op_sel_hi:[1,0]
	v_pk_mul_f32 v[74:75], v[74:75], v[94:95] op_sel_hi:[1,0]
	s_waitcnt vmcnt(1)
	v_pk_fma_f32 v[82:83], v[110:111], v[78:79], v[82:83]
	v_pk_fma_f32 v[80:81], v[108:109], v[76:77], v[80:81]
	s_waitcnt vmcnt(0)
	v_pk_fma_f32 v[86:87], v[106:107], v[74:75], v[86:87]
	v_pk_fma_f32 v[84:85], v[104:105], v[72:73], v[84:85]
	v_cvt_pk_bf16_f32 v72, v80, v81
	v_cvt_pk_bf16_f32 v73, v82, v83
	v_cvt_pk_bf16_f32 v74, v84, v85
	v_cvt_pk_bf16_f32 v75, v86, v87
	global_store_dwordx4 v[92:93], v[72:75], off
	global_load_dwordx4 v[72:75], v[90:91], off offset:512
	s_nop 0
	global_load_dwordx4 v[76:79], v[90:91], off offset:528
	v_pk_mul_f32 v[68:69], v[68:69], v[94:95] op_sel_hi:[1,0]
	v_pk_mul_f32 v[70:71], v[70:71], v[94:95] op_sel_hi:[1,0]
	v_pk_mul_f32 v[64:65], v[64:65], v[94:95] op_sel_hi:[1,0]
	v_pk_mul_f32 v[66:67], v[66:67], v[94:95] op_sel_hi:[1,0]
	v_mul_f32_e32 v81, v81, v81
	v_mul_f32_e32 v83, v83, v83
	v_mul_f32_e32 v85, v85, v85
	v_mul_f32_e32 v87, v87, v87
	v_fmac_f32_e32 v81, v80, v80
	v_fmac_f32_e32 v83, v82, v82
	v_fmac_f32_e32 v85, v84, v84
	v_fmac_f32_e32 v87, v86, v86
	v_add_f32_e32 v80, v81, v83
	v_add_f32_e32 v81, v85, v87
	v_add_f32_e32 v80, v80, v81
	v_or_b32_e32 v88, 0x100, v88
	s_waitcnt vmcnt(1)
	v_pk_fma_f32 v[70:71], v[102:103], v[70:71], v[74:75]
	v_pk_fma_f32 v[68:69], v[100:101], v[68:69], v[72:73]
	s_waitcnt vmcnt(0)
	v_pk_fma_f32 v[72:73], v[98:99], v[66:67], v[78:79]
	v_pk_fma_f32 v[64:65], v[96:97], v[64:65], v[76:77]
	v_mul_f32_e32 v66, v69, v69
	v_mul_f32_e32 v67, v71, v71
	v_mul_f32_e32 v74, v65, v65
	v_mul_f32_e32 v75, v73, v73
	v_fmac_f32_e32 v66, v68, v68
	v_fmac_f32_e32 v67, v70, v70
	v_fmac_f32_e32 v74, v64, v64
	v_fmac_f32_e32 v75, v72, v72
	v_add_f32_e32 v66, v66, v67
	v_add_f32_e32 v67, v74, v75
	v_add_f32_e32 v66, v66, v67
	v_add_f32_e32 v74, v80, v66
	ds_bpermute_b32 v75, v150, v74
	v_cvt_pk_bf16_f32 v66, v68, v69
	v_cvt_pk_bf16_f32 v68, v64, v65
	v_cvt_pk_bf16_f32 v67, v70, v71
	v_cvt_pk_bf16_f32 v69, v72, v73
	s_waitcnt lgkmcnt(0)
	v_add_f32_e32 v64, v74, v75
	ds_bpermute_b32 v65, v151, v64
	v_lshl_add_u64 v[70:71], s[10:11], 0, v[88:89]
	global_store_dwordx4 v[70:71], v[66:69], off
	s_and_saveexec_b64 s[0:1], s[4:5]
	s_cbranch_execz .LBB0_974
	v_lshl_add_u32 v66, v112, 4, s22
	s_waitcnt lgkmcnt(0)
	v_add_f32_e32 v64, v64, v65
	ds_write_b32 v66, v64
.LBB0_974:
	s_or_b64 exec, exec, s[0:1]
	v_add_u32_e32 v64, 0x80, v152
	s_waitcnt lgkmcnt(0)
	v_mov_b32_e32 v65, 0
	v_lshl_add_u64 v[66:67], s[14:15], 0, v[64:65]
	v_lshl_add_u64 v[68:69], v[66:67], 2, s[12:13]
	global_load_dword v80, v[68:69], off sc1
	v_lshlrev_b64 v[66:67], 10, v[66:67]
	v_lshl_add_u64 v[76:77], v[66:67], 0, v[146:147]
	v_lshl_add_u64 v[78:79], v[76:77], 2, s[36:37]
	global_load_dwordx4 v[68:71], v[78:79], off
	global_load_dwordx4 v[72:75], v[78:79], off offset:16
	v_mov_b32_e32 v67, 0x358637bd
	v_lshlrev_b64 v[76:77], 1, v[76:77]
	s_waitcnt vmcnt(2)
	v_fmamk_f32 v66, v80, 0x3a800000, v67
	v_rsq_f32_e32 v252, v66
	s_nop 0
	v_mul_f32_e32 v253, v66, v252
	v_mul_f32_e32 v253, v253, v252
	v_fmaak_f32 v253, -0.5, v253, 0x3fc00000
	v_mul_f32_e32 v252, v252, v253
	s_nop 1
	v_mov_b32_e32 v66, 0x260
	s_nop 1
	s_nop 1
	s_nop 1
	v_lshl_add_u64 v[80:81], s[10:11], 0, v[76:77]
	v_mov_b32_e32 v82, v252
	v_pk_mul_f32 v[60:61], v[60:61], v[82:83] op_sel_hi:[1,0]
	v_pk_mul_f32 v[62:63], v[62:63], v[82:83] op_sel_hi:[1,0]
	v_pk_mul_f32 v[56:57], v[56:57], v[82:83] op_sel_hi:[1,0]
	v_pk_mul_f32 v[58:59], v[58:59], v[82:83] op_sel_hi:[1,0]
	s_waitcnt vmcnt(1)
	v_pk_fma_f32 v[70:71], v[110:111], v[62:63], v[70:71]
	v_pk_fma_f32 v[68:69], v[108:109], v[60:61], v[68:69]
	s_waitcnt vmcnt(0)
	v_pk_fma_f32 v[74:75], v[106:107], v[58:59], v[74:75]
	v_pk_fma_f32 v[72:73], v[104:105], v[56:57], v[72:73]
	v_cvt_pk_bf16_f32 v56, v68, v69
	v_cvt_pk_bf16_f32 v57, v70, v71
	v_cvt_pk_bf16_f32 v58, v72, v73
	v_cvt_pk_bf16_f32 v59, v74, v75
	global_store_dwordx4 v[80:81], v[56:59], off
	global_load_dwordx4 v[56:59], v[78:79], off offset:512
	s_nop 0
	global_load_dwordx4 v[60:63], v[78:79], off offset:528
	v_pk_mul_f32 v[52:53], v[52:53], v[82:83] op_sel_hi:[1,0]
	v_pk_mul_f32 v[54:55], v[54:55], v[82:83] op_sel_hi:[1,0]
	v_pk_mul_f32 v[48:49], v[48:49], v[82:83] op_sel_hi:[1,0]
	v_pk_mul_f32 v[50:51], v[50:51], v[82:83] op_sel_hi:[1,0]
	v_mul_f32_e32 v69, v69, v69
	v_mul_f32_e32 v71, v71, v71
	v_mul_f32_e32 v73, v73, v73
	v_mul_f32_e32 v75, v75, v75
	v_fmac_f32_e32 v69, v68, v68
	v_fmac_f32_e32 v71, v70, v70
	v_fmac_f32_e32 v73, v72, v72
	v_fmac_f32_e32 v75, v74, v74
	v_add_f32_e32 v68, v69, v71
	v_add_f32_e32 v69, v73, v75
	v_add_f32_e32 v68, v68, v69
	v_or_b32_e32 v76, 0x100, v76
	s_waitcnt vmcnt(1)
	v_pk_fma_f32 v[54:55], v[102:103], v[54:55], v[58:59]
	v_pk_fma_f32 v[52:53], v[100:101], v[52:53], v[56:57]
	s_waitcnt vmcnt(0)
	v_pk_fma_f32 v[56:57], v[98:99], v[50:51], v[62:63]
	v_pk_fma_f32 v[48:49], v[96:97], v[48:49], v[60:61]
	v_mul_f32_e32 v50, v53, v53
	v_mul_f32_e32 v51, v55, v55
	v_mul_f32_e32 v58, v49, v49
	v_mul_f32_e32 v59, v57, v57
	v_fmac_f32_e32 v50, v52, v52
	v_fmac_f32_e32 v51, v54, v54
	v_fmac_f32_e32 v58, v48, v48
	v_fmac_f32_e32 v59, v56, v56
	v_add_f32_e32 v50, v50, v51
	v_add_f32_e32 v51, v58, v59
	v_add_f32_e32 v50, v50, v51
	v_add_f32_e32 v58, v68, v50
	ds_bpermute_b32 v59, v150, v58
	v_cvt_pk_bf16_f32 v50, v52, v53
	v_cvt_pk_bf16_f32 v52, v48, v49
	v_cvt_pk_bf16_f32 v51, v54, v55
	v_cvt_pk_bf16_f32 v53, v56, v57
	s_waitcnt lgkmcnt(0)
	v_add_f32_e32 v48, v58, v59
	ds_bpermute_b32 v49, v151, v48
	v_lshl_add_u64 v[54:55], s[10:11], 0, v[76:77]
	global_store_dwordx4 v[54:55], v[50:53], off
	s_and_saveexec_b64 s[0:1], s[4:5]
	s_cbranch_execz .LBB0_976
	v_lshl_add_u32 v50, v64, 4, s22
	s_waitcnt lgkmcnt(0)
	v_add_f32_e32 v48, v48, v49
	ds_write_b32 v50, v48
; DI unsigned pk_bf16(float lo, float hi) { f32x2 v = {lo, hi}; bf16x2_t b = __builtin_convertvector(v, bf16x2_t); return __builtin_bit_cast(unsigned, b); }
; DI float bflo(unsigned w) { return __uint_as_float(w << 16); }
; DI float bfhi(unsigned w) { return __uint_as_float(w & 0xffff0000u); }
;     __device__ __forceinline__ void fused(f32x4 (&acc)[2][2][4][2], const pg8::Unit& u, int wr, int wc, int fr, int fq, PG8_LAS unsigned char* lds, int wid, int lane) const {
;     ...
;                 const int rl = ai * 128 + wr * 64 + m * 16 + fr; const size_t row = (size_t)u.pm * 256 + rl;
;                 const float rm = 1.f / sqrtf(__hip_atomic_load(ssqm + row, __ATOMIC_RELAXED, __HIP_MEMORY_SCOPE_AGENT) * (1.f / DM) + RMS_EPS);
;                 float sh = 0.f;
; #pragma unroll
;                 for (int bj = 0; bj < 2; ++bj) {
;                     const size_t off = row * DM + colb + bj * 128;
;                     f32x4 h0, h1;
;                     if (IN16) { const u32x4 hw = *(const u32x4*)((const bf16_t*)hin + off); h0 = (f32x4){bflo(hw.x), bfhi(hw.x), bflo(hw.y), bfhi(hw.y)}; h1 = (f32x4){bflo(hw.z), bfhi(hw.z), bflo(hw.w), bfhi(hw.w)}; }
;                     else { h0 = *(const f32x4*)((const float*)hin + off); h1 = *(const f32x4*)((const float*)hin + off + 4); }
;                     h0 = h0 + acc[ai][bj][m][0] * rm * gv[bj][0]; h1 = h1 + acc[ai][bj][m][1] * rm * gv[bj][1];
;                     sh += ((h0[0] * h0[0] + h0[1] * h0[1]) + (h0[2] * h0[2] + h0[3] * h0[3])) + ((h1[0] * h1[0] + h1[1] * h1[1]) + (h1[2] * h1[2] + h1[3] * h1[3]));
;                     if (OUT16) { u32x4 w; w.x = pk_bf16(h0[0], h0[1]); w.y = pk_bf16(h0[2], h0[3]); w.z = pk_bf16(h1[0], h1[1]); w.w = pk_bf16(h1[2], h1[3]); *(u32x4*)((bf16_t*)hout + off) = w; }
;                     else { *(f32x4*)((float*)hout + off) = h0; *(f32x4*)((float*)hout + off + 4) = h1; }
;                 }
;                 if (ssqh) { sh += __shfl_xor(sh, 16); sh += __shfl_xor(sh, 32); if (fq == 0) red[rl * 4 + wc] = sh; }
.LBB0_976:
	s_or_b64 exec, exec, s[0:1]
	v_add_u32_e32 v64, 0x90, v152
	s_waitcnt lgkmcnt(0)
	v_lshl_add_u64 v[48:49], s[14:15], 0, v[64:65]
	v_lshl_add_u64 v[50:51], v[48:49], 2, s[12:13]
	global_load_dword v60, v[50:51], off sc1
	v_lshlrev_b64 v[48:49], 10, v[48:49]
	v_lshl_add_u64 v[56:57], v[48:49], 0, v[146:147]
	v_lshl_add_u64 v[58:59], v[56:57], 2, s[36:37]
	global_load_dwordx4 v[48:51], v[58:59], off
	global_load_dwordx4 v[52:55], v[58:59], off offset:16
	v_lshlrev_b64 v[56:57], 1, v[56:57]
	s_waitcnt vmcnt(2)
	v_fmac_f32_e32 v67, 0x3a800000, v60
	v_rsq_f32_e32 v252, v67
	s_nop 0
	v_mul_f32_e32 v253, v67, v252
	v_mul_f32_e32 v253, v253, v252
	v_fmaak_f32 v253, -0.5, v253, 0x3fc00000
	v_mul_f32_e32 v252, v252, v253
	s_nop 1
	s_nop 0
	s_nop 1
	s_nop 1
	s_nop 1
	v_lshl_add_u64 v[60:61], s[10:11], 0, v[56:57]
	v_mov_b32_e32 v62, v252
	v_pk_mul_f32 v[44:45], v[44:45], v[62:63] op_sel_hi:[1,0]
	v_pk_mul_f32 v[46:47], v[46:47], v[62:63] op_sel_hi:[1,0]
	v_pk_mul_f32 v[40:41], v[40:41], v[62:63] op_sel_hi:[1,0]
	v_pk_mul_f32 v[42:43], v[42:43], v[62:63] op_sel_hi:[1,0]
	s_waitcnt vmcnt(1)
	v_pk_fma_f32 v[50:51], v[110:111], v[46:47], v[50:51]
	v_pk_fma_f32 v[48:49], v[108:109], v[44:45], v[48:49]
	s_waitcnt vmcnt(0)
	v_pk_fma_f32 v[54:55], v[106:107], v[42:43], v[54:55]
	v_pk_fma_f32 v[52:53], v[104:105], v[40:41], v[52:53]
	v_cvt_pk_bf16_f32 v40, v48, v49
	v_cvt_pk_bf16_f32 v41, v50, v51
	v_cvt_pk_bf16_f32 v42, v52, v53
	v_cvt_pk_bf16_f32 v43, v54, v55
	global_store_dwordx4 v[60:61], v[40:43], off
	global_load_dwordx4 v[40:43], v[58:59], off offset:512
	s_nop 0
	global_load_dwordx4 v[44:47], v[58:59], off offset:528
	v_pk_mul_f32 v[36:37], v[36:37], v[62:63] op_sel_hi:[1,0]
	v_pk_mul_f32 v[38:39], v[38:39], v[62:63] op_sel_hi:[1,0]
	v_pk_mul_f32 v[32:33], v[32:33], v[62:63] op_sel_hi:[1,0]
	v_pk_mul_f32 v[34:35], v[34:35], v[62:63] op_sel_hi:[1,0]
	v_mul_f32_e32 v49, v49, v49
	v_mul_f32_e32 v51, v51, v51
	v_mul_f32_e32 v53, v53, v53
	v_mul_f32_e32 v55, v55, v55
	v_fmac_f32_e32 v49, v48, v48
	v_fmac_f32_e32 v51, v50, v50
	v_fmac_f32_e32 v53, v52, v52
	v_fmac_f32_e32 v55, v54, v54
	v_add_f32_e32 v48, v49, v51
	v_add_f32_e32 v49, v53, v55
	v_add_f32_e32 v48, v48, v49
	v_or_b32_e32 v56, 0x100, v56
	s_waitcnt vmcnt(1)
	v_pk_fma_f32 v[38:39], v[102:103], v[38:39], v[42:43]
	v_pk_fma_f32 v[36:37], v[100:101], v[36:37], v[40:41]
	s_waitcnt vmcnt(0)
	v_pk_fma_f32 v[40:41], v[98:99], v[34:35], v[46:47]
	v_pk_fma_f32 v[32:33], v[96:97], v[32:33], v[44:45]
	v_mul_f32_e32 v34, v37, v37
	v_mul_f32_e32 v35, v39, v39
	v_mul_f32_e32 v42, v33, v33
	v_mul_f32_e32 v43, v41, v41
	v_fmac_f32_e32 v34, v36, v36
	v_fmac_f32_e32 v35, v38, v38
	v_fmac_f32_e32 v42, v32, v32
	v_fmac_f32_e32 v43, v40, v40
	v_add_f32_e32 v34, v34, v35
	v_add_f32_e32 v35, v42, v43
	v_add_f32_e32 v34, v34, v35
	v_add_f32_e32 v42, v48, v34
	ds_bpermute_b32 v43, v150, v42
	v_cvt_pk_bf16_f32 v34, v36, v37
	v_cvt_pk_bf16_f32 v36, v32, v33
	v_cvt_pk_bf16_f32 v35, v38, v39
	v_cvt_pk_bf16_f32 v37, v40, v41
	s_waitcnt lgkmcnt(0)
	v_add_f32_e32 v32, v42, v43
	ds_bpermute_b32 v33, v151, v32
	v_lshl_add_u64 v[38:39], s[10:11], 0, v[56:57]
	global_store_dwordx4 v[38:39], v[34:37], off
	s_and_saveexec_b64 s[0:1], s[4:5]
	s_cbranch_execz .LBB0_978
	v_lshl_add_u32 v34, v64, 4, s22
	s_waitcnt lgkmcnt(0)
	v_add_f32_e32 v32, v32, v33
	ds_write_b32 v34, v32
; DI unsigned pk_bf16(float lo, float hi) { f32x2 v = {lo, hi}; bf16x2_t b = __builtin_convertvector(v, bf16x2_t); return __builtin_bit_cast(unsigned, b); }
; DI float bflo(unsigned w) { return __uint_as_float(w << 16); }
; DI float bfhi(unsigned w) { return __uint_as_float(w & 0xffff0000u); }
;     __device__ __forceinline__ void fused(f32x4 (&acc)[2][2][4][2], const pg8::Unit& u, int wr, int wc, int fr, int fq, PG8_LAS unsigned char* lds, int wid, int lane) const {
;     ...
;                 const int rl = ai * 128 + wr * 64 + m * 16 + fr; const size_t row = (size_t)u.pm * 256 + rl;
;                 const float rm = 1.f / sqrtf(__hip_atomic_load(ssqm + row, __ATOMIC_RELAXED, __HIP_MEMORY_SCOPE_AGENT) * (1.f / DM) + RMS_EPS);
;                 float sh = 0.f;
; #pragma unroll
;                 for (int bj = 0; bj < 2; ++bj) {
;                     const size_t off = row * DM + colb + bj * 128;
;                     f32x4 h0, h1;
;                     if (IN16) { const u32x4 hw = *(const u32x4*)((const bf16_t*)hin + off); h0 = (f32x4){bflo(hw.x), bfhi(hw.x), bflo(hw.y), bfhi(hw.y)}; h1 = (f32x4){bflo(hw.z), bfhi(hw.z), bflo(hw.w), bfhi(hw.w)}; }
;                     else { h0 = *(const f32x4*)((const float*)hin + off); h1 = *(const f32x4*)((const float*)hin + off + 4); }
;                     h0 = h0 + acc[ai][bj][m][0] * rm * gv[bj][0]; h1 = h1 + acc[ai][bj][m][1] * rm * gv[bj][1];
;                     sh += ((h0[0] * h0[0] + h0[1] * h0[1]) + (h0[2] * h0[2] + h0[3] * h0[3])) + ((h1[0] * h1[0] + h1[1] * h1[1]) + (h1[2] * h1[2] + h1[3] * h1[3]));
;                     if (OUT16) { u32x4 w; w.x = pk_bf16(h0[0], h0[1]); w.y = pk_bf16(h0[2], h0[3]); w.z = pk_bf16(h1[0], h1[1]); w.w = pk_bf16(h1[2], h1[3]); *(u32x4*)((bf16_t*)hout + off) = w; }
;                     else { *(f32x4*)((float*)hout + off) = h0; *(f32x4*)((float*)hout + off + 4) = h1; }
;                 }
;                 if (ssqh) { sh += __shfl_xor(sh, 16); sh += __shfl_xor(sh, 32); if (fq == 0) red[rl * 4 + wc] = sh; }
.LBB0_978:
	s_or_b64 exec, exec, s[0:1]
	v_add_u32_e32 v32, 0xa0, v152
	s_waitcnt lgkmcnt(0)
	v_mov_b32_e32 v33, 0
	v_lshl_add_u64 v[34:35], s[14:15], 0, v[32:33]
	v_lshl_add_u64 v[36:37], v[34:35], 2, s[12:13]
	global_load_dword v48, v[36:37], off sc1
	v_lshlrev_b64 v[34:35], 10, v[34:35]
	v_lshl_add_u64 v[44:45], v[34:35], 0, v[146:147]
	v_lshl_add_u64 v[46:47], v[44:45], 2, s[36:37]
	global_load_dwordx4 v[36:39], v[46:47], off
	global_load_dwordx4 v[40:43], v[46:47], off offset:16
	v_mov_b32_e32 v35, 0x358637bd
	v_lshlrev_b64 v[44:45], 1, v[44:45]
	s_waitcnt vmcnt(2)
	v_fmamk_f32 v34, v48, 0x3a800000, v35
	v_rsq_f32_e32 v252, v34
	s_nop 0
	v_mul_f32_e32 v253, v34, v252
	v_mul_f32_e32 v253, v253, v252
	v_fmaak_f32 v253, -0.5, v253, 0x3fc00000
	v_mul_f32_e32 v252, v252, v253
	s_nop 1
	v_mov_b32_e32 v34, 0x260
	s_nop 1
	s_nop 1
	s_nop 1
	v_lshl_add_u64 v[48:49], s[10:11], 0, v[44:45]
	v_mov_b32_e32 v50, v252
	v_pk_mul_f32 v[28:29], v[28:29], v[50:51] op_sel_hi:[1,0]
	v_pk_mul_f32 v[30:31], v[30:31], v[50:51] op_sel_hi:[1,0]
	v_pk_mul_f32 v[24:25], v[24:25], v[50:51] op_sel_hi:[1,0]
	v_pk_mul_f32 v[26:27], v[26:27], v[50:51] op_sel_hi:[1,0]
	s_waitcnt vmcnt(1)
	v_pk_fma_f32 v[38:39], v[110:111], v[30:31], v[38:39]
	v_pk_fma_f32 v[36:37], v[108:109], v[28:29], v[36:37]
	s_waitcnt vmcnt(0)
	v_pk_fma_f32 v[42:43], v[106:107], v[26:27], v[42:43]
	v_pk_fma_f32 v[40:41], v[104:105], v[24:25], v[40:41]
	v_cvt_pk_bf16_f32 v24, v36, v37
	v_cvt_pk_bf16_f32 v25, v38, v39
	v_cvt_pk_bf16_f32 v26, v40, v41
	v_cvt_pk_bf16_f32 v27, v42, v43
	global_store_dwordx4 v[48:49], v[24:27], off
	global_load_dwordx4 v[24:27], v[46:47], off offset:512
	s_nop 0
	global_load_dwordx4 v[28:31], v[46:47], off offset:528
	v_pk_mul_f32 v[20:21], v[20:21], v[50:51] op_sel_hi:[1,0]
	v_pk_mul_f32 v[22:23], v[22:23], v[50:51] op_sel_hi:[1,0]
	v_pk_mul_f32 v[16:17], v[16:17], v[50:51] op_sel_hi:[1,0]
	v_pk_mul_f32 v[18:19], v[18:19], v[50:51] op_sel_hi:[1,0]
	v_mul_f32_e32 v37, v37, v37
	v_mul_f32_e32 v39, v39, v39
	v_mul_f32_e32 v41, v41, v41
	v_mul_f32_e32 v43, v43, v43
	v_fmac_f32_e32 v37, v36, v36
	v_fmac_f32_e32 v39, v38, v38
	v_fmac_f32_e32 v41, v40, v40
	v_fmac_f32_e32 v43, v42, v42
	v_add_f32_e32 v36, v37, v39
	v_add_f32_e32 v37, v41, v43
	v_add_f32_e32 v36, v36, v37
	v_or_b32_e32 v44, 0x100, v44
	s_waitcnt vmcnt(1)
	v_pk_fma_f32 v[22:23], v[102:103], v[22:23], v[26:27]
	v_pk_fma_f32 v[20:21], v[100:101], v[20:21], v[24:25]
	s_waitcnt vmcnt(0)
	v_pk_fma_f32 v[24:25], v[98:99], v[18:19], v[30:31]
	v_pk_fma_f32 v[16:17], v[96:97], v[16:17], v[28:29]
	v_mul_f32_e32 v18, v21, v21
	v_mul_f32_e32 v19, v23, v23
	v_mul_f32_e32 v26, v17, v17
	v_mul_f32_e32 v27, v25, v25
	v_fmac_f32_e32 v18, v20, v20
	v_fmac_f32_e32 v19, v22, v22
	v_fmac_f32_e32 v26, v16, v16
	v_fmac_f32_e32 v27, v24, v24
	v_add_f32_e32 v18, v18, v19
	v_add_f32_e32 v19, v26, v27
	v_add_f32_e32 v18, v18, v19
	v_add_f32_e32 v26, v36, v18
	ds_bpermute_b32 v27, v150, v26
	v_cvt_pk_bf16_f32 v18, v20, v21
	v_cvt_pk_bf16_f32 v20, v16, v17
	v_cvt_pk_bf16_f32 v19, v22, v23
	v_cvt_pk_bf16_f32 v21, v24, v25
	s_waitcnt lgkmcnt(0)
	v_add_f32_e32 v16, v26, v27
	ds_bpermute_b32 v17, v151, v16
	v_lshl_add_u64 v[22:23], s[10:11], 0, v[44:45]
	global_store_dwordx4 v[22:23], v[18:21], off
	s_and_saveexec_b64 s[0:1], s[4:5]
	s_cbranch_execz .LBB0_980
	v_lshl_add_u32 v18, v32, 4, s22
	s_waitcnt lgkmcnt(0)
	v_add_f32_e32 v16, v16, v17
	ds_write_b32 v18, v16
.LBB0_980:
	s_or_b64 exec, exec, s[0:1]
	v_add_u32_e32 v32, 0xb0, v152
	s_waitcnt lgkmcnt(0)
	v_lshl_add_u64 v[16:17], s[14:15], 0, v[32:33]
	v_lshl_add_u64 v[18:19], v[16:17], 2, s[12:13]
	global_load_dword v28, v[18:19], off sc1
	v_lshlrev_b64 v[16:17], 10, v[16:17]
	v_lshl_add_u64 v[24:25], v[16:17], 0, v[146:147]
	v_lshl_add_u64 v[26:27], v[24:25], 2, s[36:37]
	global_load_dwordx4 v[16:19], v[26:27], off
	global_load_dwordx4 v[20:23], v[26:27], off offset:16
	v_lshlrev_b64 v[24:25], 1, v[24:25]
	s_waitcnt vmcnt(2)
	v_fmac_f32_e32 v35, 0x3a800000, v28
	v_rsq_f32_e32 v252, v35
	s_nop 0
	v_mul_f32_e32 v253, v35, v252
	v_mul_f32_e32 v253, v253, v252
	v_fmaak_f32 v253, -0.5, v253, 0x3fc00000
	v_mul_f32_e32 v252, v252, v253
	s_nop 1
	s_nop 0
	s_nop 1
	s_nop 1
	s_nop 1
	v_lshl_add_u64 v[28:29], s[10:11], 0, v[24:25]
	v_mov_b32_e32 v30, v252
	v_pk_mul_f32 v[12:13], v[12:13], v[30:31] op_sel_hi:[1,0]
	v_pk_mul_f32 v[14:15], v[14:15], v[30:31] op_sel_hi:[1,0]
	v_pk_mul_f32 v[8:9], v[8:9], v[30:31] op_sel_hi:[1,0]
	v_pk_mul_f32 v[10:11], v[10:11], v[30:31] op_sel_hi:[1,0]
	s_waitcnt vmcnt(1)
	v_pk_fma_f32 v[18:19], v[110:111], v[14:15], v[18:19]
	v_pk_fma_f32 v[16:17], v[108:109], v[12:13], v[16:17]
	s_waitcnt vmcnt(0)
	v_pk_fma_f32 v[22:23], v[106:107], v[10:11], v[22:23]
	v_pk_fma_f32 v[20:21], v[104:105], v[8:9], v[20:21]
	v_cvt_pk_bf16_f32 v8, v16, v17
	v_cvt_pk_bf16_f32 v9, v18, v19
	v_cvt_pk_bf16_f32 v10, v20, v21
	v_cvt_pk_bf16_f32 v11, v22, v23
	global_store_dwordx4 v[28:29], v[8:11], off
	global_load_dwordx4 v[8:11], v[26:27], off offset:512
	s_nop 0
	global_load_dwordx4 v[12:15], v[26:27], off offset:528
	v_pk_mul_f32 v[4:5], v[4:5], v[30:31] op_sel_hi:[1,0]
	v_pk_mul_f32 v[6:7], v[6:7], v[30:31] op_sel_hi:[1,0]
	v_pk_mul_f32 v[0:1], v[0:1], v[30:31] op_sel_hi:[1,0]
	v_pk_mul_f32 v[2:3], v[2:3], v[30:31] op_sel_hi:[1,0]
	v_mul_f32_e32 v17, v17, v17
	v_mul_f32_e32 v19, v19, v19
	v_mul_f32_e32 v21, v21, v21
	v_mul_f32_e32 v23, v23, v23
	v_fmac_f32_e32 v17, v16, v16
	v_fmac_f32_e32 v19, v18, v18
	v_fmac_f32_e32 v21, v20, v20
	v_fmac_f32_e32 v23, v22, v22
	v_add_f32_e32 v16, v17, v19
	v_add_f32_e32 v17, v21, v23
	v_add_f32_e32 v16, v16, v17
	v_or_b32_e32 v24, 0x100, v24
	s_waitcnt vmcnt(1)
	v_pk_fma_f32 v[6:7], v[102:103], v[6:7], v[10:11]
	v_pk_fma_f32 v[4:5], v[100:101], v[4:5], v[8:9]
	s_waitcnt vmcnt(0)
	v_pk_fma_f32 v[8:9], v[98:99], v[2:3], v[14:15]
	v_pk_fma_f32 v[0:1], v[96:97], v[0:1], v[12:13]
	v_mul_f32_e32 v2, v5, v5
	v_mul_f32_e32 v3, v7, v7
	v_mul_f32_e32 v10, v1, v1
	v_mul_f32_e32 v11, v9, v9
	v_fmac_f32_e32 v2, v4, v4
	v_fmac_f32_e32 v3, v6, v6
	v_fmac_f32_e32 v10, v0, v0
	v_fmac_f32_e32 v11, v8, v8
	v_add_f32_e32 v2, v2, v3
	v_add_f32_e32 v3, v10, v11
	v_add_f32_e32 v2, v2, v3
	v_add_f32_e32 v10, v16, v2
	ds_bpermute_b32 v11, v150, v10
	v_cvt_pk_bf16_f32 v2, v4, v5
	v_cvt_pk_bf16_f32 v4, v0, v1
	v_cvt_pk_bf16_f32 v3, v6, v7
	v_cvt_pk_bf16_f32 v5, v8, v9
	s_waitcnt lgkmcnt(0)
	v_add_f32_e32 v0, v10, v11
	ds_bpermute_b32 v1, v151, v0
	v_lshl_add_u64 v[6:7], s[10:11], 0, v[24:25]
	global_store_dwordx4 v[6:7], v[2:5], off
	s_and_saveexec_b64 s[0:1], s[4:5]
	s_cbranch_execz .LBB0_982
	v_lshl_add_u32 v2, v32, 4, s22
	s_waitcnt lgkmcnt(0)
	v_add_f32_e32 v0, v0, v1
	ds_write_b32 v2, v0

; DI unsigned pk_bf16(float lo, float hi) { f32x2 v = {lo, hi}; bf16x2_t b = __builtin_convertvector(v, bf16x2_t); return __builtin_bit_cast(unsigned, b); }
; DI float bflo(unsigned w) { return __uint_as_float(w << 16); }
; DI float bfhi(unsigned w) { return __uint_as_float(w & 0xffff0000u); }
;     __device__ __forceinline__ void fused(f32x4 (&acc)[2][2][4][2], const pg8::Unit& u, int wr, int wc, int fr, int fq, PG8_LAS unsigned char* lds, int wid, int lane) const {
;     ...
;         const int colb = u.pn * 256 + wc * 32 + 8 * fq;
;         f32x4 gv[2][2];
; #pragma unroll
;         for (int bj = 0; bj < 2; ++bj)
; #pragma unroll
;             for (int n = 0; n < 2; ++n) gv[bj][n] = *(const f32x4*)(gA + colb + bj * 128 + 4 * n);
; #pragma unroll
;         for (int ai = 0; ai < 2; ++ai)
; #pragma unroll
;             for (int m = 0; m < 4; ++m) {
;                 const int rl = ai * 128 + wr * 64 + m * 16 + fr; const size_t row = (size_t)u.pm * 256 + rl;
;                 const float rm = 1.f / sqrtf(__hip_atomic_load(ssqm + row, __ATOMIC_RELAXED, __HIP_MEMORY_SCOPE_AGENT) * (1.f / DM) + RMS_EPS);
;                 float sh = 0.f;
; #pragma unroll
;                 for (int bj = 0; bj < 2; ++bj) {
;                     const size_t off = row * DM + colb + bj * 128;
;                     f32x4 h0, h1;
;                     if (IN16) { const u32x4 hw = *(const u32x4*)((const bf16_t*)hin + off); h0 = (f32x4){bflo(hw.x), bfhi(hw.x), bflo(hw.y), bfhi(hw.y)}; h1 = (f32x4){bflo(hw.z), bfhi(hw.z), bflo(hw.w), bfhi(hw.w)}; }
;                     else { h0 = *(const f32x4*)((const float*)hin + off); h1 = *(const f32x4*)((const float*)hin + off + 4); }
;                     h0 = h0 + acc[ai][bj][m][0] * rm * gv[bj][0]; h1 = h1 + acc[ai][bj][m][1] * rm * gv[bj][1];
;                     sh += ((h0[0] * h0[0] + h0[1] * h0[1]) + (h0[2] * h0[2] + h0[3] * h0[3])) + ((h1[0] * h1[0] + h1[1] * h1[1]) + (h1[2] * h1[2] + h1[3] * h1[3]));
;                     if (OUT16) { u32x4 w; w.x = pk_bf16(h0[0], h0[1]); w.y = pk_bf16(h0[2], h0[3]); w.z = pk_bf16(h1[0], h1[1]); w.w = pk_bf16(h1[2], h1[3]); *(u32x4*)((bf16_t*)hout + off) = w; }
;                     else { *(f32x4*)((float*)hout + off) = h0; *(f32x4*)((float*)hout + off + 4) = h1; }
;                 }
;                 if (ssqh) { sh += __shfl_xor(sh, 16); sh += __shfl_xor(sh, 32); if (fq == 0) red[rl * 4 + wc] = sh; }
.LBB0_1147:
	s_or_b64 exec, exec, s[0:1]
	s_lshl_b32 s0, s37, 5
	s_lshl_b32 s1, s33, 8
	s_or_b32 s0, s1, s0
	v_mov_b32_e32 v159, 0
	v_or_b32_e32 v156, s0, v160
	s_lshl_b64 s[18:19], s[16:17], 8
	v_mov_b32_e32 v153, v159
	v_ashrrev_i32_e32 v157, 31, v156
	v_lshl_add_u64 v[168:169], s[18:19], 0, v[152:153]
	v_lshl_add_u64 v[108:109], v[156:157], 2, s[14:15]
	v_lshl_add_u64 v[170:171], v[168:169], 2, s[12:13]
	s_barrier
	global_load_dwordx4 v[100:103], v[108:109], off offset:16
	global_load_dwordx4 v[104:107], v[108:109], off
	global_load_dwordx4 v[96:99], v[108:109], off offset:528
	s_nop 0
	global_load_dwordx4 v[108:111], v[108:109], off offset:512
	v_lshlrev_b64 v[168:169], 11, v[168:169]
	global_load_dword v158, v[170:171], off sc1
	v_lshl_add_u64 v[168:169], s[10:11], 0, v[168:169]
	v_lshl_add_u64 v[176:177], v[156:157], 1, v[168:169]
	global_load_dwordx4 v[168:171], v[176:177], off
	global_load_dwordx4 v[172:175], v[176:177], off offset:256
	v_mov_b32_e32 v153, 0x358637bd
	s_mov_b32 s2, 0xf800000
	v_mov_b32_e32 v151, 0x260
	s_waitcnt vmcnt(2)
	v_fmamk_f32 v158, v158, 0x3a800000, v153
	v_rsq_f32_e32 v252, v158
	s_nop 0
	v_mul_f32_e32 v253, v158, v252
	v_mul_f32_e32 v253, v253, v252
	v_fmaak_f32 v253, -0.5, v253, 0x3fc00000
	v_mul_f32_e32 v252, v252, v253
	s_waitcnt vmcnt(1)
	v_lshlrev_b32_e32 v178, 16, v168
	v_and_b32_e32 v179, 0xffff0000, v168
	v_lshlrev_b32_e32 v168, 16, v169
	v_and_b32_e32 v169, 0xffff0000, v169
	v_lshlrev_b32_e32 v180, 16, v170
	v_and_b32_e32 v181, 0xffff0000, v170
	v_lshlrev_b32_e32 v170, 16, v171
	v_and_b32_e32 v171, 0xffff0000, v171
	s_waitcnt vmcnt(0)
	v_lshlrev_b32_e32 v182, 16, v172
	v_and_b32_e32 v183, 0xffff0000, v172
	v_lshlrev_b32_e32 v172, 16, v173
	v_and_b32_e32 v173, 0xffff0000, v173
	v_mov_b32_e32 v158, v252
	v_lshlrev_b32_e32 v184, 16, v174
	v_and_b32_e32 v185, 0xffff0000, v174
	v_lshlrev_b32_e32 v174, 16, v175
	v_and_b32_e32 v175, 0xffff0000, v175
	v_pk_mul_f32 v[140:141], v[140:141], v[158:159] op_sel_hi:[1,0]
	v_pk_mul_f32 v[142:143], v[142:143], v[158:159] op_sel_hi:[1,0]
	v_pk_mul_f32 v[136:137], v[136:137], v[158:159] op_sel_hi:[1,0]
	v_pk_mul_f32 v[138:139], v[138:139], v[158:159] op_sel_hi:[1,0]
	v_pk_mul_f32 v[132:133], v[132:133], v[158:159] op_sel_hi:[1,0]
	v_pk_mul_f32 v[134:135], v[134:135], v[158:159] op_sel_hi:[1,0]
	v_pk_mul_f32 v[128:129], v[128:129], v[158:159] op_sel_hi:[1,0]
	v_pk_mul_f32 v[130:131], v[130:131], v[158:159] op_sel_hi:[1,0]
	v_pk_fma_f32 v[142:143], v[106:107], v[142:143], v[168:169]
	v_pk_fma_f32 v[140:141], v[104:105], v[140:141], v[178:179]
	v_pk_fma_f32 v[138:139], v[102:103], v[138:139], v[170:171]
	v_pk_fma_f32 v[136:137], v[100:101], v[136:137], v[180:181]
	v_pk_fma_f32 v[134:135], v[110:111], v[134:135], v[172:173]
	v_pk_fma_f32 v[132:133], v[108:109], v[132:133], v[182:183]
	v_pk_fma_f32 v[168:169], v[98:99], v[130:131], v[174:175]
	v_pk_fma_f32 v[170:171], v[96:97], v[128:129], v[184:185]
	v_cvt_pk_bf16_f32 v128, v140, v141
	v_cvt_pk_bf16_f32 v129, v142, v143
	v_mul_f32_e32 v130, v141, v141
	v_mul_f32_e32 v131, v143, v143
	v_mul_f32_e32 v141, v137, v137
	v_mul_f32_e32 v143, v139, v139
	v_mul_f32_e32 v158, v133, v133
	v_mul_f32_e32 v172, v135, v135
	v_mul_f32_e32 v173, v171, v171
	v_mul_f32_e32 v174, v169, v169
	v_fmac_f32_e32 v130, v140, v140
	v_fmac_f32_e32 v131, v142, v142
	v_fmac_f32_e32 v141, v136, v136
	v_fmac_f32_e32 v143, v138, v138
	v_fmac_f32_e32 v158, v132, v132
	v_fmac_f32_e32 v172, v134, v134
	v_fmac_f32_e32 v173, v170, v170
	v_fmac_f32_e32 v174, v168, v168
	v_add_f32_e32 v130, v130, v131
	v_add_f32_e32 v131, v141, v143
	v_add_f32_e32 v140, v158, v172
	v_add_f32_e32 v141, v173, v174
	v_add_f32_e32 v130, v130, v131
	v_add_f32_e32 v131, v140, v141
	v_add_f32_e32 v140, v130, v131
	ds_bpermute_b32 v141, v145, v140
	v_cvt_pk_bf16_f32 v130, v136, v137
	v_cvt_pk_bf16_f32 v131, v138, v139
	global_store_dwordx4 v[176:177], v[128:131], off
	s_waitcnt lgkmcnt(0)
	s_nop 0
	v_add_f32_e32 v128, v140, v141
	ds_bpermute_b32 v129, v147, v128
	v_cvt_pk_bf16_f32 v130, v132, v133
	v_cvt_pk_bf16_f32 v131, v134, v135
	v_cvt_pk_bf16_f32 v132, v170, v171
	v_cvt_pk_bf16_f32 v133, v168, v169
	global_store_dwordx4 v[176:177], v[130:133], off offset:256
	s_and_saveexec_b64 s[0:1], s[4:5]
	s_cbranch_execz .LBB0_1149
	v_lshl_add_u32 v130, v152, 4, s22
	s_waitcnt lgkmcnt(0)
	v_add_f32_e32 v128, v128, v129
	ds_write_b32 v130, v128
; DI unsigned pk_bf16(float lo, float hi) { f32x2 v = {lo, hi}; bf16x2_t b = __builtin_convertvector(v, bf16x2_t); return __builtin_bit_cast(unsigned, b); }
; DI float bflo(unsigned w) { return __uint_as_float(w << 16); }
; DI float bfhi(unsigned w) { return __uint_as_float(w & 0xffff0000u); }
;     __device__ __forceinline__ void fused(f32x4 (&acc)[2][2][4][2], const pg8::Unit& u, int wr, int wc, int fr, int fq, PG8_LAS unsigned char* lds, int wid, int lane) const {
;     ...
;                 const int rl = ai * 128 + wr * 64 + m * 16 + fr; const size_t row = (size_t)u.pm * 256 + rl;
;                 const float rm = 1.f / sqrtf(__hip_atomic_load(ssqm + row, __ATOMIC_RELAXED, __HIP_MEMORY_SCOPE_AGENT) * (1.f / DM) + RMS_EPS);
;                 float sh = 0.f;
; #pragma unroll
;                 for (int bj = 0; bj < 2; ++bj) {
;                     const size_t off = row * DM + colb + bj * 128;
;                     f32x4 h0, h1;
;                     if (IN16) { const u32x4 hw = *(const u32x4*)((const bf16_t*)hin + off); h0 = (f32x4){bflo(hw.x), bfhi(hw.x), bflo(hw.y), bfhi(hw.y)}; h1 = (f32x4){bflo(hw.z), bfhi(hw.z), bflo(hw.w), bfhi(hw.w)}; }
;                     else { h0 = *(const f32x4*)((const float*)hin + off); h1 = *(const f32x4*)((const float*)hin + off + 4); }
;                     h0 = h0 + acc[ai][bj][m][0] * rm * gv[bj][0]; h1 = h1 + acc[ai][bj][m][1] * rm * gv[bj][1];
;                     sh += ((h0[0] * h0[0] + h0[1] * h0[1]) + (h0[2] * h0[2] + h0[3] * h0[3])) + ((h1[0] * h1[0] + h1[1] * h1[1]) + (h1[2] * h1[2] + h1[3] * h1[3]));
;                     if (OUT16) { u32x4 w; w.x = pk_bf16(h0[0], h0[1]); w.y = pk_bf16(h0[2], h0[3]); w.z = pk_bf16(h1[0], h1[1]); w.w = pk_bf16(h1[2], h1[3]); *(u32x4*)((bf16_t*)hout + off) = w; }
;                     else { *(f32x4*)((float*)hout + off) = h0; *(f32x4*)((float*)hout + off + 4) = h1; }
;                 }
;                 if (ssqh) { sh += __shfl_xor(sh, 16); sh += __shfl_xor(sh, 32); if (fq == 0) red[rl * 4 + wc] = sh; }
.LBB0_1149:
	s_or_b64 exec, exec, s[0:1]
	v_or_b32_e32 v158, 16, v152
	s_waitcnt lgkmcnt(0)
	v_lshl_add_u64 v[128:129], s[18:19], 0, v[158:159]
	v_lshl_add_u64 v[130:131], v[128:129], 2, s[12:13]
	global_load_dword v138, v[130:131], off sc1
	v_lshlrev_b64 v[128:129], 11, v[128:129]
	v_lshl_add_u64 v[128:129], s[10:11], 0, v[128:129]
	v_lshl_add_u64 v[136:137], v[156:157], 1, v[128:129]
	global_load_dwordx4 v[128:131], v[136:137], off
	global_load_dwordx4 v[132:135], v[136:137], off offset:256
	s_waitcnt vmcnt(2)
	v_fmac_f32_e32 v153, 0x3a800000, v138
	v_rsq_f32_e32 v252, v153
	s_nop 0
	v_mul_f32_e32 v253, v153, v252
	v_mul_f32_e32 v253, v253, v252
	v_fmaak_f32 v253, -0.5, v253, 0x3fc00000
	v_mul_f32_e32 v252, v252, v253
	s_waitcnt vmcnt(1)
	v_and_b32_e32 v139, 0xffff0000, v128
	v_lshlrev_b32_e32 v140, 16, v130
	v_lshlrev_b32_e32 v138, 16, v128
	v_lshlrev_b32_e32 v128, 16, v129
	v_and_b32_e32 v129, 0xffff0000, v129
	v_and_b32_e32 v141, 0xffff0000, v130
	v_lshlrev_b32_e32 v130, 16, v131
	v_and_b32_e32 v131, 0xffff0000, v131
	s_waitcnt vmcnt(0)
	v_lshlrev_b32_e32 v142, 16, v132
	v_and_b32_e32 v143, 0xffff0000, v132
	v_lshlrev_b32_e32 v132, 16, v133
	v_and_b32_e32 v133, 0xffff0000, v133
	v_mov_b32_e32 v170, v252
	v_lshlrev_b32_e32 v168, 16, v134
	v_and_b32_e32 v169, 0xffff0000, v134
	v_lshlrev_b32_e32 v134, 16, v135
	v_and_b32_e32 v135, 0xffff0000, v135
	v_pk_mul_f32 v[124:125], v[124:125], v[170:171] op_sel_hi:[1,0]
	v_pk_mul_f32 v[126:127], v[126:127], v[170:171] op_sel_hi:[1,0]
	v_pk_mul_f32 v[120:121], v[120:121], v[170:171] op_sel_hi:[1,0]
	v_pk_mul_f32 v[122:123], v[122:123], v[170:171] op_sel_hi:[1,0]
	v_pk_mul_f32 v[116:117], v[116:117], v[170:171] op_sel_hi:[1,0]
	v_pk_mul_f32 v[118:119], v[118:119], v[170:171] op_sel_hi:[1,0]
	v_pk_mul_f32 v[112:113], v[112:113], v[170:171] op_sel_hi:[1,0]
	v_pk_mul_f32 v[114:115], v[114:115], v[170:171] op_sel_hi:[1,0]
	v_pk_fma_f32 v[126:127], v[106:107], v[126:127], v[128:129]
	v_pk_fma_f32 v[124:125], v[104:105], v[124:125], v[138:139]
	v_pk_fma_f32 v[122:123], v[102:103], v[122:123], v[130:131]
	v_pk_fma_f32 v[120:121], v[100:101], v[120:121], v[140:141]
	v_pk_fma_f32 v[118:119], v[110:111], v[118:119], v[132:133]
	v_pk_fma_f32 v[116:117], v[108:109], v[116:117], v[142:143]
	v_pk_fma_f32 v[128:129], v[98:99], v[114:115], v[134:135]
	v_pk_fma_f32 v[130:131], v[96:97], v[112:113], v[168:169]
	v_cvt_pk_bf16_f32 v112, v124, v125
	v_cvt_pk_bf16_f32 v113, v126, v127
	v_mul_f32_e32 v114, v125, v125
	v_mul_f32_e32 v115, v127, v127
	v_mul_f32_e32 v125, v121, v121
	v_mul_f32_e32 v127, v123, v123
	v_mul_f32_e32 v132, v117, v117
	v_mul_f32_e32 v133, v119, v119
	v_mul_f32_e32 v134, v131, v131
	v_mul_f32_e32 v135, v129, v129
	v_fmac_f32_e32 v114, v124, v124
	v_fmac_f32_e32 v115, v126, v126
	v_fmac_f32_e32 v125, v120, v120
	v_fmac_f32_e32 v127, v122, v122
	v_fmac_f32_e32 v132, v116, v116
	v_fmac_f32_e32 v133, v118, v118
	v_fmac_f32_e32 v134, v130, v130
	v_fmac_f32_e32 v135, v128, v128
	v_add_f32_e32 v114, v114, v115
	v_add_f32_e32 v115, v125, v127
	v_add_f32_e32 v124, v132, v133
	v_add_f32_e32 v125, v134, v135
	v_add_f32_e32 v114, v114, v115
	v_add_f32_e32 v115, v124, v125
	v_add_f32_e32 v124, v114, v115
	ds_bpermute_b32 v125, v145, v124
	v_cvt_pk_bf16_f32 v114, v120, v121
	v_cvt_pk_bf16_f32 v115, v122, v123
	global_store_dwordx4 v[136:137], v[112:115], off
	s_waitcnt lgkmcnt(0)
	s_nop 0
	v_add_f32_e32 v112, v124, v125
	ds_bpermute_b32 v113, v147, v112
	v_cvt_pk_bf16_f32 v114, v116, v117
	v_cvt_pk_bf16_f32 v115, v118, v119
	v_cvt_pk_bf16_f32 v116, v130, v131
	v_cvt_pk_bf16_f32 v117, v128, v129
	global_store_dwordx4 v[136:137], v[114:117], off offset:256
	s_and_saveexec_b64 s[0:1], s[4:5]
	s_cbranch_execz .LBB0_1151
	v_lshl_add_u32 v114, v158, 4, s22
	s_waitcnt lgkmcnt(0)
	v_add_f32_e32 v112, v112, v113
	ds_write_b32 v114, v112
.LBB0_1151:
	s_or_b64 exec, exec, s[0:1]
	v_or_b32_e32 v112, 32, v152
	s_waitcnt lgkmcnt(0)
	v_mov_b32_e32 v113, 0
	v_lshl_add_u64 v[114:115], s[18:19], 0, v[112:113]
	v_lshl_add_u64 v[116:117], v[114:115], 2, s[12:13]
	global_load_dword v126, v[116:117], off sc1
	v_lshlrev_b64 v[114:115], 11, v[114:115]
	v_lshl_add_u64 v[114:115], s[10:11], 0, v[114:115]
	v_lshl_add_u64 v[124:125], v[156:157], 1, v[114:115]
	global_load_dwordx4 v[116:119], v[124:125], off
	global_load_dwordx4 v[120:123], v[124:125], off offset:256
	v_mov_b32_e32 v115, 0x358637bd
	v_mov_b32_e32 v114, 0x260
	s_waitcnt vmcnt(2)
	v_fmamk_f32 v126, v126, 0x3a800000, v115
	v_rsq_f32_e32 v252, v126
	s_nop 0
	v_mul_f32_e32 v253, v126, v252
	v_mul_f32_e32 v253, v253, v252
	v_fmaak_f32 v253, -0.5, v253, 0x3fc00000
	v_mul_f32_e32 v252, v252, v253
	s_waitcnt vmcnt(1)
	v_lshlrev_b32_e32 v128, 16, v118
	v_and_b32_e32 v129, 0xffff0000, v118
	v_lshlrev_b32_e32 v126, 16, v116
	v_and_b32_e32 v127, 0xffff0000, v116
	v_lshlrev_b32_e32 v116, 16, v117
	v_and_b32_e32 v117, 0xffff0000, v117
	v_lshlrev_b32_e32 v118, 16, v119
	v_and_b32_e32 v119, 0xffff0000, v119
	s_waitcnt vmcnt(0)
; DI unsigned pk_bf16(float lo, float hi) { f32x2 v = {lo, hi}; bf16x2_t b = __builtin_convertvector(v, bf16x2_t); return __builtin_bit_cast(unsigned, b); }
; DI float bflo(unsigned w) { return __uint_as_float(w << 16); }
; DI float bfhi(unsigned w) { return __uint_as_float(w & 0xffff0000u); }
;     __device__ __forceinline__ void fused(f32x4 (&acc)[2][2][4][2], const pg8::Unit& u, int wr, int wc, int fr, int fq, PG8_LAS unsigned char* lds, int wid, int lane) const {
;     ...
;                 const int rl = ai * 128 + wr * 64 + m * 16 + fr; const size_t row = (size_t)u.pm * 256 + rl;
;                 const float rm = 1.f / sqrtf(__hip_atomic_load(ssqm + row, __ATOMIC_RELAXED, __HIP_MEMORY_SCOPE_AGENT) * (1.f / DM) + RMS_EPS);
;                 float sh = 0.f;
; #pragma unroll
;                 for (int bj = 0; bj < 2; ++bj) {
;                     const size_t off = row * DM + colb + bj * 128;
;                     f32x4 h0, h1;
;                     if (IN16) { const u32x4 hw = *(const u32x4*)((const bf16_t*)hin + off); h0 = (f32x4){bflo(hw.x), bfhi(hw.x), bflo(hw.y), bfhi(hw.y)}; h1 = (f32x4){bflo(hw.z), bfhi(hw.z), bflo(hw.w), bfhi(hw.w)}; }
;                     else { h0 = *(const f32x4*)((const float*)hin + off); h1 = *(const f32x4*)((const float*)hin + off + 4); }
;                     h0 = h0 + acc[ai][bj][m][0] * rm * gv[bj][0]; h1 = h1 + acc[ai][bj][m][1] * rm * gv[bj][1];
;                     sh += ((h0[0] * h0[0] + h0[1] * h0[1]) + (h0[2] * h0[2] + h0[3] * h0[3])) + ((h1[0] * h1[0] + h1[1] * h1[1]) + (h1[2] * h1[2] + h1[3] * h1[3]));
;                     if (OUT16) { u32x4 w; w.x = pk_bf16(h0[0], h0[1]); w.y = pk_bf16(h0[2], h0[3]); w.z = pk_bf16(h1[0], h1[1]); w.w = pk_bf16(h1[2], h1[3]); *(u32x4*)((bf16_t*)hout + off) = w; }
;                     else { *(f32x4*)((float*)hout + off) = h0; *(f32x4*)((float*)hout + off + 4) = h1; }
;                 }
;                 if (ssqh) { sh += __shfl_xor(sh, 16); sh += __shfl_xor(sh, 32); if (fq == 0) red[rl * 4 + wc] = sh; }
	v_lshlrev_b32_e32 v130, 16, v120
	v_and_b32_e32 v131, 0xffff0000, v120
	v_lshlrev_b32_e32 v120, 16, v121
	v_and_b32_e32 v121, 0xffff0000, v121
	v_mov_b32_e32 v134, v252
	v_lshlrev_b32_e32 v132, 16, v122
	v_and_b32_e32 v133, 0xffff0000, v122
	v_lshlrev_b32_e32 v122, 16, v123
	v_and_b32_e32 v123, 0xffff0000, v123
	v_pk_mul_f32 v[92:93], v[92:93], v[134:135] op_sel_hi:[1,0]
	v_pk_mul_f32 v[94:95], v[94:95], v[134:135] op_sel_hi:[1,0]
	v_pk_mul_f32 v[88:89], v[88:89], v[134:135] op_sel_hi:[1,0]
	v_pk_mul_f32 v[90:91], v[90:91], v[134:135] op_sel_hi:[1,0]
	v_pk_mul_f32 v[84:85], v[84:85], v[134:135] op_sel_hi:[1,0]
	v_pk_mul_f32 v[86:87], v[86:87], v[134:135] op_sel_hi:[1,0]
	v_pk_mul_f32 v[80:81], v[80:81], v[134:135] op_sel_hi:[1,0]
	v_pk_mul_f32 v[82:83], v[82:83], v[134:135] op_sel_hi:[1,0]
	v_pk_fma_f32 v[94:95], v[106:107], v[94:95], v[116:117]
	v_pk_fma_f32 v[92:93], v[104:105], v[92:93], v[126:127]
	v_pk_fma_f32 v[90:91], v[102:103], v[90:91], v[118:119]
	v_pk_fma_f32 v[88:89], v[100:101], v[88:89], v[128:129]
	v_pk_fma_f32 v[86:87], v[110:111], v[86:87], v[120:121]
	v_pk_fma_f32 v[84:85], v[108:109], v[84:85], v[130:131]
	v_pk_fma_f32 v[116:117], v[98:99], v[82:83], v[122:123]
	v_pk_fma_f32 v[118:119], v[96:97], v[80:81], v[132:133]
	v_cvt_pk_bf16_f32 v80, v92, v93
	v_cvt_pk_bf16_f32 v81, v94, v95
	v_mul_f32_e32 v82, v93, v93
	v_mul_f32_e32 v83, v95, v95
	v_mul_f32_e32 v93, v89, v89
	v_mul_f32_e32 v95, v91, v91
	v_mul_f32_e32 v120, v85, v85
	v_mul_f32_e32 v121, v87, v87
	v_mul_f32_e32 v122, v119, v119
	v_mul_f32_e32 v123, v117, v117
	v_fmac_f32_e32 v82, v92, v92
	v_fmac_f32_e32 v83, v94, v94
	v_fmac_f32_e32 v93, v88, v88
	v_fmac_f32_e32 v95, v90, v90
	v_fmac_f32_e32 v120, v84, v84
	v_fmac_f32_e32 v121, v86, v86
	v_fmac_f32_e32 v122, v118, v118
	v_fmac_f32_e32 v123, v116, v116
	v_add_f32_e32 v82, v82, v83
	v_add_f32_e32 v83, v93, v95
	v_add_f32_e32 v92, v120, v121
	v_add_f32_e32 v93, v122, v123
	v_add_f32_e32 v82, v82, v83
	v_add_f32_e32 v83, v92, v93
	v_add_f32_e32 v92, v82, v83
	ds_bpermute_b32 v93, v145, v92
	v_cvt_pk_bf16_f32 v82, v88, v89
	v_cvt_pk_bf16_f32 v83, v90, v91
	global_store_dwordx4 v[124:125], v[80:83], off
	s_waitcnt lgkmcnt(0)
	s_nop 0
	v_add_f32_e32 v80, v92, v93
	ds_bpermute_b32 v81, v147, v80
	v_cvt_pk_bf16_f32 v82, v84, v85
	v_cvt_pk_bf16_f32 v83, v86, v87
	v_cvt_pk_bf16_f32 v84, v118, v119
	v_cvt_pk_bf16_f32 v85, v116, v117
	global_store_dwordx4 v[124:125], v[82:85], off offset:256
	s_and_saveexec_b64 s[0:1], s[4:5]
	s_cbranch_execz .LBB0_1153
	v_lshl_add_u32 v82, v112, 4, s22
	s_waitcnt lgkmcnt(0)
	v_add_f32_e32 v80, v80, v81
	ds_write_b32 v82, v80
.LBB0_1153:
	s_or_b64 exec, exec, s[0:1]
	v_or_b32_e32 v112, 48, v152
	s_waitcnt lgkmcnt(0)
	v_lshl_add_u64 v[80:81], s[18:19], 0, v[112:113]
	v_lshl_add_u64 v[82:83], v[80:81], 2, s[12:13]
	global_load_dword v90, v[82:83], off sc1
	v_lshlrev_b64 v[80:81], 11, v[80:81]
	v_lshl_add_u64 v[80:81], s[10:11], 0, v[80:81]
	v_lshl_add_u64 v[88:89], v[156:157], 1, v[80:81]
	global_load_dwordx4 v[80:83], v[88:89], off
	global_load_dwordx4 v[84:87], v[88:89], off offset:256
	s_waitcnt vmcnt(2)
	v_fmac_f32_e32 v115, 0x3a800000, v90
	v_rsq_f32_e32 v252, v115
	s_nop 0
	v_mul_f32_e32 v253, v115, v252
	v_mul_f32_e32 v253, v253, v252
	v_fmaak_f32 v253, -0.5, v253, 0x3fc00000
	v_mul_f32_e32 v252, v252, v253
	s_waitcnt vmcnt(1)
	v_and_b32_e32 v91, 0xffff0000, v80
	v_lshlrev_b32_e32 v92, 16, v82
	v_lshlrev_b32_e32 v90, 16, v80
	v_lshlrev_b32_e32 v80, 16, v81
	v_and_b32_e32 v81, 0xffff0000, v81
	v_and_b32_e32 v93, 0xffff0000, v82
	v_lshlrev_b32_e32 v82, 16, v83
	v_and_b32_e32 v83, 0xffff0000, v83
	s_waitcnt vmcnt(0)
	v_lshlrev_b32_e32 v94, 16, v84
	v_and_b32_e32 v95, 0xffff0000, v84
	v_lshlrev_b32_e32 v84, 16, v85
	v_and_b32_e32 v85, 0xffff0000, v85
	v_mov_b32_e32 v114, v252
	v_lshlrev_b32_e32 v116, 16, v86
	v_and_b32_e32 v117, 0xffff0000, v86
	v_lshlrev_b32_e32 v86, 16, v87
	v_and_b32_e32 v87, 0xffff0000, v87
	v_pk_mul_f32 v[76:77], v[76:77], v[114:115] op_sel_hi:[1,0]
	v_pk_mul_f32 v[78:79], v[78:79], v[114:115] op_sel_hi:[1,0]
	v_pk_mul_f32 v[72:73], v[72:73], v[114:115] op_sel_hi:[1,0]
	v_pk_mul_f32 v[74:75], v[74:75], v[114:115] op_sel_hi:[1,0]
	v_pk_mul_f32 v[68:69], v[68:69], v[114:115] op_sel_hi:[1,0]
	v_pk_mul_f32 v[70:71], v[70:71], v[114:115] op_sel_hi:[1,0]
	v_pk_mul_f32 v[64:65], v[64:65], v[114:115] op_sel_hi:[1,0]
	v_pk_mul_f32 v[66:67], v[66:67], v[114:115] op_sel_hi:[1,0]
	v_pk_fma_f32 v[78:79], v[106:107], v[78:79], v[80:81]
	v_pk_fma_f32 v[76:77], v[104:105], v[76:77], v[90:91]
	v_pk_fma_f32 v[74:75], v[102:103], v[74:75], v[82:83]
	v_pk_fma_f32 v[72:73], v[100:101], v[72:73], v[92:93]
	v_pk_fma_f32 v[70:71], v[110:111], v[70:71], v[84:85]
	v_pk_fma_f32 v[68:69], v[108:109], v[68:69], v[94:95]
	v_pk_fma_f32 v[80:81], v[98:99], v[66:67], v[86:87]
	v_pk_fma_f32 v[82:83], v[96:97], v[64:65], v[116:117]
	v_cvt_pk_bf16_f32 v64, v76, v77
	v_cvt_pk_bf16_f32 v65, v78, v79
	v_mul_f32_e32 v66, v77, v77
	v_mul_f32_e32 v67, v79, v79
	v_mul_f32_e32 v77, v73, v73
	v_mul_f32_e32 v79, v75, v75
	v_mul_f32_e32 v84, v69, v69
	v_mul_f32_e32 v85, v71, v71
	v_mul_f32_e32 v86, v83, v83
	v_mul_f32_e32 v87, v81, v81
	v_fmac_f32_e32 v66, v76, v76
	v_fmac_f32_e32 v67, v78, v78
	v_fmac_f32_e32 v77, v72, v72
	v_fmac_f32_e32 v79, v74, v74
	v_fmac_f32_e32 v84, v68, v68
	v_fmac_f32_e32 v85, v70, v70
	v_fmac_f32_e32 v86, v82, v82
	v_fmac_f32_e32 v87, v80, v80
	v_add_f32_e32 v66, v66, v67
	v_add_f32_e32 v67, v77, v79
	v_add_f32_e32 v76, v84, v85
	v_add_f32_e32 v77, v86, v87
	v_add_f32_e32 v66, v66, v67
	v_add_f32_e32 v67, v76, v77
	v_add_f32_e32 v76, v66, v67
	ds_bpermute_b32 v77, v145, v76
	v_cvt_pk_bf16_f32 v66, v72, v73
	v_cvt_pk_bf16_f32 v67, v74, v75
	global_store_dwordx4 v[88:89], v[64:67], off
	s_waitcnt lgkmcnt(0)
	s_nop 0
	v_add_f32_e32 v64, v76, v77
	ds_bpermute_b32 v65, v147, v64
	v_cvt_pk_bf16_f32 v66, v68, v69
	v_cvt_pk_bf16_f32 v67, v70, v71
	v_cvt_pk_bf16_f32 v68, v82, v83
	v_cvt_pk_bf16_f32 v69, v80, v81
	global_store_dwordx4 v[88:89], v[66:69], off offset:256
	s_and_saveexec_b64 s[0:1], s[4:5]
	s_cbranch_execz .LBB0_1155
	v_lshl_add_u32 v66, v112, 4, s22
	s_waitcnt lgkmcnt(0)
	v_add_f32_e32 v64, v64, v65
	ds_write_b32 v66, v64
; DI unsigned pk_bf16(float lo, float hi) { f32x2 v = {lo, hi}; bf16x2_t b = __builtin_convertvector(v, bf16x2_t); return __builtin_bit_cast(unsigned, b); }
; DI float bflo(unsigned w) { return __uint_as_float(w << 16); }
; DI float bfhi(unsigned w) { return __uint_as_float(w & 0xffff0000u); }
;     __device__ __forceinline__ void fused(f32x4 (&acc)[2][2][4][2], const pg8::Unit& u, int wr, int wc, int fr, int fq, PG8_LAS unsigned char* lds, int wid, int lane) const {
;     ...
;                 const int rl = ai * 128 + wr * 64 + m * 16 + fr; const size_t row = (size_t)u.pm * 256 + rl;
;                 const float rm = 1.f / sqrtf(__hip_atomic_load(ssqm + row, __ATOMIC_RELAXED, __HIP_MEMORY_SCOPE_AGENT) * (1.f / DM) + RMS_EPS);
;                 float sh = 0.f;
; #pragma unroll
;                 for (int bj = 0; bj < 2; ++bj) {
;                     const size_t off = row * DM + colb + bj * 128;
;                     f32x4 h0, h1;
;                     if (IN16) { const u32x4 hw = *(const u32x4*)((const bf16_t*)hin + off); h0 = (f32x4){bflo(hw.x), bfhi(hw.x), bflo(hw.y), bfhi(hw.y)}; h1 = (f32x4){bflo(hw.z), bfhi(hw.z), bflo(hw.w), bfhi(hw.w)}; }
;                     else { h0 = *(const f32x4*)((const float*)hin + off); h1 = *(const f32x4*)((const float*)hin + off + 4); }
;                     h0 = h0 + acc[ai][bj][m][0] * rm * gv[bj][0]; h1 = h1 + acc[ai][bj][m][1] * rm * gv[bj][1];
;                     sh += ((h0[0] * h0[0] + h0[1] * h0[1]) + (h0[2] * h0[2] + h0[3] * h0[3])) + ((h1[0] * h1[0] + h1[1] * h1[1]) + (h1[2] * h1[2] + h1[3] * h1[3]));
;                     if (OUT16) { u32x4 w; w.x = pk_bf16(h0[0], h0[1]); w.y = pk_bf16(h0[2], h0[3]); w.z = pk_bf16(h1[0], h1[1]); w.w = pk_bf16(h1[2], h1[3]); *(u32x4*)((bf16_t*)hout + off) = w; }
;                     else { *(f32x4*)((float*)hout + off) = h0; *(f32x4*)((float*)hout + off + 4) = h1; }
;                 }
;                 if (ssqh) { sh += __shfl_xor(sh, 16); sh += __shfl_xor(sh, 32); if (fq == 0) red[rl * 4 + wc] = sh; }
.LBB0_1155:
	s_or_b64 exec, exec, s[0:1]
	v_add_u32_e32 v64, 0x80, v152
	s_waitcnt lgkmcnt(0)
	v_mov_b32_e32 v65, 0
	v_lshl_add_u64 v[66:67], s[18:19], 0, v[64:65]
	v_lshl_add_u64 v[68:69], v[66:67], 2, s[12:13]
	global_load_dword v78, v[68:69], off sc1
	v_lshlrev_b64 v[66:67], 11, v[66:67]
	v_lshl_add_u64 v[66:67], s[10:11], 0, v[66:67]
	v_lshl_add_u64 v[76:77], v[156:157], 1, v[66:67]
	global_load_dwordx4 v[68:71], v[76:77], off
	global_load_dwordx4 v[72:75], v[76:77], off offset:256
	v_mov_b32_e32 v67, 0x358637bd
	v_mov_b32_e32 v66, 0x260
	s_waitcnt vmcnt(2)
	v_fmamk_f32 v78, v78, 0x3a800000, v67
	v_rsq_f32_e32 v252, v78
	s_nop 0
	v_mul_f32_e32 v253, v78, v252
	v_mul_f32_e32 v253, v253, v252
	v_fmaak_f32 v253, -0.5, v253, 0x3fc00000
	v_mul_f32_e32 v252, v252, v253
	s_waitcnt vmcnt(1)
	v_lshlrev_b32_e32 v80, 16, v70
	v_and_b32_e32 v81, 0xffff0000, v70
	v_lshlrev_b32_e32 v78, 16, v68
	v_and_b32_e32 v79, 0xffff0000, v68
	v_lshlrev_b32_e32 v68, 16, v69
	v_and_b32_e32 v69, 0xffff0000, v69
	v_lshlrev_b32_e32 v70, 16, v71
	v_and_b32_e32 v71, 0xffff0000, v71
	s_waitcnt vmcnt(0)
	v_lshlrev_b32_e32 v82, 16, v72
	v_and_b32_e32 v83, 0xffff0000, v72
	v_lshlrev_b32_e32 v72, 16, v73
	v_and_b32_e32 v73, 0xffff0000, v73
	v_mov_b32_e32 v86, v252
	v_lshlrev_b32_e32 v84, 16, v74
	v_and_b32_e32 v85, 0xffff0000, v74
	v_lshlrev_b32_e32 v74, 16, v75
	v_and_b32_e32 v75, 0xffff0000, v75
	v_pk_mul_f32 v[60:61], v[60:61], v[86:87] op_sel_hi:[1,0]
	v_pk_mul_f32 v[62:63], v[62:63], v[86:87] op_sel_hi:[1,0]
	v_pk_mul_f32 v[56:57], v[56:57], v[86:87] op_sel_hi:[1,0]
	v_pk_mul_f32 v[58:59], v[58:59], v[86:87] op_sel_hi:[1,0]
	v_pk_mul_f32 v[52:53], v[52:53], v[86:87] op_sel_hi:[1,0]
	v_pk_mul_f32 v[54:55], v[54:55], v[86:87] op_sel_hi:[1,0]
	v_pk_mul_f32 v[48:49], v[48:49], v[86:87] op_sel_hi:[1,0]
	v_pk_mul_f32 v[50:51], v[50:51], v[86:87] op_sel_hi:[1,0]
	v_pk_fma_f32 v[62:63], v[106:107], v[62:63], v[68:69]
	v_pk_fma_f32 v[60:61], v[104:105], v[60:61], v[78:79]
	v_pk_fma_f32 v[58:59], v[102:103], v[58:59], v[70:71]
	v_pk_fma_f32 v[56:57], v[100:101], v[56:57], v[80:81]
	v_pk_fma_f32 v[54:55], v[110:111], v[54:55], v[72:73]
	v_pk_fma_f32 v[52:53], v[108:109], v[52:53], v[82:83]
	v_pk_fma_f32 v[68:69], v[98:99], v[50:51], v[74:75]
	v_pk_fma_f32 v[70:71], v[96:97], v[48:49], v[84:85]
	v_cvt_pk_bf16_f32 v48, v60, v61
	v_cvt_pk_bf16_f32 v49, v62, v63
	v_mul_f32_e32 v50, v61, v61
	v_mul_f32_e32 v51, v63, v63
	v_mul_f32_e32 v61, v57, v57
	v_mul_f32_e32 v63, v59, v59
	v_mul_f32_e32 v72, v53, v53
	v_mul_f32_e32 v73, v55, v55
	v_mul_f32_e32 v74, v71, v71
	v_mul_f32_e32 v75, v69, v69
	v_fmac_f32_e32 v50, v60, v60
	v_fmac_f32_e32 v51, v62, v62
	v_fmac_f32_e32 v61, v56, v56
	v_fmac_f32_e32 v63, v58, v58
	v_fmac_f32_e32 v72, v52, v52
	v_fmac_f32_e32 v73, v54, v54
	v_fmac_f32_e32 v74, v70, v70
	v_fmac_f32_e32 v75, v68, v68
	v_add_f32_e32 v50, v50, v51
	v_add_f32_e32 v51, v61, v63
	v_add_f32_e32 v60, v72, v73
	v_add_f32_e32 v61, v74, v75
	v_add_f32_e32 v50, v50, v51
	v_add_f32_e32 v51, v60, v61
	v_add_f32_e32 v60, v50, v51
	ds_bpermute_b32 v61, v145, v60
	v_cvt_pk_bf16_f32 v50, v56, v57
	v_cvt_pk_bf16_f32 v51, v58, v59
	global_store_dwordx4 v[76:77], v[48:51], off
	s_waitcnt lgkmcnt(0)
	s_nop 0
	v_add_f32_e32 v48, v60, v61
	ds_bpermute_b32 v49, v147, v48
	v_cvt_pk_bf16_f32 v50, v52, v53
	v_cvt_pk_bf16_f32 v51, v54, v55
	v_cvt_pk_bf16_f32 v52, v70, v71
	v_cvt_pk_bf16_f32 v53, v68, v69
	global_store_dwordx4 v[76:77], v[50:53], off offset:256
	s_and_saveexec_b64 s[0:1], s[4:5]
	s_cbranch_execz .LBB0_1157
	v_lshl_add_u32 v50, v64, 4, s22
	s_waitcnt lgkmcnt(0)
	v_add_f32_e32 v48, v48, v49
	ds_write_b32 v50, v48
.LBB0_1157:
	s_or_b64 exec, exec, s[0:1]
	v_add_u32_e32 v64, 0x90, v152
	s_waitcnt lgkmcnt(0)
	v_lshl_add_u64 v[48:49], s[18:19], 0, v[64:65]
	v_lshl_add_u64 v[50:51], v[48:49], 2, s[12:13]
	global_load_dword v58, v[50:51], off sc1
	v_lshlrev_b64 v[48:49], 11, v[48:49]
	v_lshl_add_u64 v[48:49], s[10:11], 0, v[48:49]
	v_lshl_add_u64 v[56:57], v[156:157], 1, v[48:49]
	global_load_dwordx4 v[48:51], v[56:57], off
	global_load_dwordx4 v[52:55], v[56:57], off offset:256
	s_waitcnt vmcnt(2)
	v_fmac_f32_e32 v67, 0x3a800000, v58
	v_rsq_f32_e32 v252, v67
	s_nop 0
	v_mul_f32_e32 v253, v67, v252
	v_mul_f32_e32 v253, v253, v252
	v_fmaak_f32 v253, -0.5, v253, 0x3fc00000
	v_mul_f32_e32 v252, v252, v253
	s_waitcnt vmcnt(1)
	v_and_b32_e32 v59, 0xffff0000, v48
	v_lshlrev_b32_e32 v60, 16, v50
	v_lshlrev_b32_e32 v58, 16, v48
	v_lshlrev_b32_e32 v48, 16, v49
	v_and_b32_e32 v49, 0xffff0000, v49
	v_and_b32_e32 v61, 0xffff0000, v50
	v_lshlrev_b32_e32 v50, 16, v51
	v_and_b32_e32 v51, 0xffff0000, v51
	s_waitcnt vmcnt(0)
; DI unsigned pk_bf16(float lo, float hi) { f32x2 v = {lo, hi}; bf16x2_t b = __builtin_convertvector(v, bf16x2_t); return __builtin_bit_cast(unsigned, b); }
; DI float bflo(unsigned w) { return __uint_as_float(w << 16); }
; DI float bfhi(unsigned w) { return __uint_as_float(w & 0xffff0000u); }
;     __device__ __forceinline__ void fused(f32x4 (&acc)[2][2][4][2], const pg8::Unit& u, int wr, int wc, int fr, int fq, PG8_LAS unsigned char* lds, int wid, int lane) const {
;     ...
;                 const int rl = ai * 128 + wr * 64 + m * 16 + fr; const size_t row = (size_t)u.pm * 256 + rl;
;                 const float rm = 1.f / sqrtf(__hip_atomic_load(ssqm + row, __ATOMIC_RELAXED, __HIP_MEMORY_SCOPE_AGENT) * (1.f / DM) + RMS_EPS);
;                 float sh = 0.f;
; #pragma unroll
;                 for (int bj = 0; bj < 2; ++bj) {
;                     const size_t off = row * DM + colb + bj * 128;
;                     f32x4 h0, h1;
;                     if (IN16) { const u32x4 hw = *(const u32x4*)((const bf16_t*)hin + off); h0 = (f32x4){bflo(hw.x), bfhi(hw.x), bflo(hw.y), bfhi(hw.y)}; h1 = (f32x4){bflo(hw.z), bfhi(hw.z), bflo(hw.w), bfhi(hw.w)}; }
;                     else { h0 = *(const f32x4*)((const float*)hin + off); h1 = *(const f32x4*)((const float*)hin + off + 4); }
;                     h0 = h0 + acc[ai][bj][m][0] * rm * gv[bj][0]; h1 = h1 + acc[ai][bj][m][1] * rm * gv[bj][1];
;                     sh += ((h0[0] * h0[0] + h0[1] * h0[1]) + (h0[2] * h0[2] + h0[3] * h0[3])) + ((h1[0] * h1[0] + h1[1] * h1[1]) + (h1[2] * h1[2] + h1[3] * h1[3]));
;                     if (OUT16) { u32x4 w; w.x = pk_bf16(h0[0], h0[1]); w.y = pk_bf16(h0[2], h0[3]); w.z = pk_bf16(h1[0], h1[1]); w.w = pk_bf16(h1[2], h1[3]); *(u32x4*)((bf16_t*)hout + off) = w; }
;                     else { *(f32x4*)((float*)hout + off) = h0; *(f32x4*)((float*)hout + off + 4) = h1; }
;                 }
;                 if (ssqh) { sh += __shfl_xor(sh, 16); sh += __shfl_xor(sh, 32); if (fq == 0) red[rl * 4 + wc] = sh; }
	v_lshlrev_b32_e32 v62, 16, v52
	v_and_b32_e32 v63, 0xffff0000, v52
	v_lshlrev_b32_e32 v52, 16, v53
	v_and_b32_e32 v53, 0xffff0000, v53
	v_mov_b32_e32 v66, v252
	v_lshlrev_b32_e32 v68, 16, v54
	v_and_b32_e32 v69, 0xffff0000, v54
	v_lshlrev_b32_e32 v54, 16, v55
	v_and_b32_e32 v55, 0xffff0000, v55
	v_pk_mul_f32 v[44:45], v[44:45], v[66:67] op_sel_hi:[1,0]
	v_pk_mul_f32 v[46:47], v[46:47], v[66:67] op_sel_hi:[1,0]
	v_pk_mul_f32 v[40:41], v[40:41], v[66:67] op_sel_hi:[1,0]
	v_pk_mul_f32 v[42:43], v[42:43], v[66:67] op_sel_hi:[1,0]
	v_pk_mul_f32 v[36:37], v[36:37], v[66:67] op_sel_hi:[1,0]
	v_pk_mul_f32 v[38:39], v[38:39], v[66:67] op_sel_hi:[1,0]
	v_pk_mul_f32 v[32:33], v[32:33], v[66:67] op_sel_hi:[1,0]
	v_pk_mul_f32 v[34:35], v[34:35], v[66:67] op_sel_hi:[1,0]
	v_pk_fma_f32 v[46:47], v[106:107], v[46:47], v[48:49]
	v_pk_fma_f32 v[44:45], v[104:105], v[44:45], v[58:59]
	v_pk_fma_f32 v[42:43], v[102:103], v[42:43], v[50:51]
	v_pk_fma_f32 v[40:41], v[100:101], v[40:41], v[60:61]
	v_pk_fma_f32 v[38:39], v[110:111], v[38:39], v[52:53]
	v_pk_fma_f32 v[36:37], v[108:109], v[36:37], v[62:63]
	v_pk_fma_f32 v[48:49], v[98:99], v[34:35], v[54:55]
	v_pk_fma_f32 v[50:51], v[96:97], v[32:33], v[68:69]
	v_cvt_pk_bf16_f32 v32, v44, v45
	v_cvt_pk_bf16_f32 v33, v46, v47
	v_mul_f32_e32 v34, v45, v45
	v_mul_f32_e32 v35, v47, v47
	v_mul_f32_e32 v45, v41, v41
	v_mul_f32_e32 v47, v43, v43
	v_mul_f32_e32 v52, v37, v37
	v_mul_f32_e32 v53, v39, v39
	v_mul_f32_e32 v54, v51, v51
	v_mul_f32_e32 v55, v49, v49
	v_fmac_f32_e32 v34, v44, v44
	v_fmac_f32_e32 v35, v46, v46
	v_fmac_f32_e32 v45, v40, v40
	v_fmac_f32_e32 v47, v42, v42
	v_fmac_f32_e32 v52, v36, v36
	v_fmac_f32_e32 v53, v38, v38
	v_fmac_f32_e32 v54, v50, v50
	v_fmac_f32_e32 v55, v48, v48
	v_add_f32_e32 v34, v34, v35
	v_add_f32_e32 v35, v45, v47
	v_add_f32_e32 v44, v52, v53
	v_add_f32_e32 v45, v54, v55
	v_add_f32_e32 v34, v34, v35
	v_add_f32_e32 v35, v44, v45
	v_add_f32_e32 v44, v34, v35
	ds_bpermute_b32 v45, v145, v44
	v_cvt_pk_bf16_f32 v34, v40, v41
	v_cvt_pk_bf16_f32 v35, v42, v43
	global_store_dwordx4 v[56:57], v[32:35], off
	s_waitcnt lgkmcnt(0)
	s_nop 0
	v_add_f32_e32 v32, v44, v45
	ds_bpermute_b32 v33, v147, v32
	v_cvt_pk_bf16_f32 v34, v36, v37
	v_cvt_pk_bf16_f32 v35, v38, v39
	v_cvt_pk_bf16_f32 v36, v50, v51
	v_cvt_pk_bf16_f32 v37, v48, v49
	global_store_dwordx4 v[56:57], v[34:37], off offset:256
	s_and_saveexec_b64 s[0:1], s[4:5]
	s_cbranch_execz .LBB0_1159
	v_lshl_add_u32 v34, v64, 4, s22
	s_waitcnt lgkmcnt(0)
	v_add_f32_e32 v32, v32, v33
	ds_write_b32 v34, v32
.LBB0_1159:
	s_or_b64 exec, exec, s[0:1]
	v_add_u32_e32 v32, 0xa0, v152
	s_waitcnt lgkmcnt(0)
	v_mov_b32_e32 v33, 0
	v_lshl_add_u64 v[34:35], s[18:19], 0, v[32:33]
	v_lshl_add_u64 v[36:37], v[34:35], 2, s[12:13]
	global_load_dword v46, v[36:37], off sc1
	v_lshlrev_b64 v[34:35], 11, v[34:35]
	v_lshl_add_u64 v[34:35], s[10:11], 0, v[34:35]
	v_lshl_add_u64 v[44:45], v[156:157], 1, v[34:35]
	global_load_dwordx4 v[36:39], v[44:45], off
	global_load_dwordx4 v[40:43], v[44:45], off offset:256
	v_mov_b32_e32 v35, 0x358637bd
	v_mov_b32_e32 v34, 0x260
	s_waitcnt vmcnt(2)
	v_fmamk_f32 v46, v46, 0x3a800000, v35
	v_rsq_f32_e32 v252, v46
	s_nop 0
	v_mul_f32_e32 v253, v46, v252
	v_mul_f32_e32 v253, v253, v252
	v_fmaak_f32 v253, -0.5, v253, 0x3fc00000
	v_mul_f32_e32 v252, v252, v253
	s_waitcnt vmcnt(1)
	v_lshlrev_b32_e32 v48, 16, v38
	v_and_b32_e32 v49, 0xffff0000, v38
	v_lshlrev_b32_e32 v46, 16, v36
	v_and_b32_e32 v47, 0xffff0000, v36
	v_lshlrev_b32_e32 v36, 16, v37
	v_and_b32_e32 v37, 0xffff0000, v37
	v_lshlrev_b32_e32 v38, 16, v39
	v_and_b32_e32 v39, 0xffff0000, v39
	s_waitcnt vmcnt(0)
	v_lshlrev_b32_e32 v50, 16, v40
	v_and_b32_e32 v51, 0xffff0000, v40
	v_lshlrev_b32_e32 v40, 16, v41
	v_and_b32_e32 v41, 0xffff0000, v41
	v_mov_b32_e32 v54, v252
	v_lshlrev_b32_e32 v52, 16, v42
	v_and_b32_e32 v53, 0xffff0000, v42
	v_lshlrev_b32_e32 v42, 16, v43
	v_and_b32_e32 v43, 0xffff0000, v43
	v_pk_mul_f32 v[28:29], v[28:29], v[54:55] op_sel_hi:[1,0]
	v_pk_mul_f32 v[30:31], v[30:31], v[54:55] op_sel_hi:[1,0]
	v_pk_mul_f32 v[24:25], v[24:25], v[54:55] op_sel_hi:[1,0]
	v_pk_mul_f32 v[26:27], v[26:27], v[54:55] op_sel_hi:[1,0]
	v_pk_mul_f32 v[20:21], v[20:21], v[54:55] op_sel_hi:[1,0]
	v_pk_mul_f32 v[22:23], v[22:23], v[54:55] op_sel_hi:[1,0]
	v_pk_mul_f32 v[16:17], v[16:17], v[54:55] op_sel_hi:[1,0]
	v_pk_mul_f32 v[18:19], v[18:19], v[54:55] op_sel_hi:[1,0]
	v_pk_fma_f32 v[30:31], v[106:107], v[30:31], v[36:37]
	v_pk_fma_f32 v[28:29], v[104:105], v[28:29], v[46:47]
	v_pk_fma_f32 v[26:27], v[102:103], v[26:27], v[38:39]
	v_pk_fma_f32 v[24:25], v[100:101], v[24:25], v[48:49]
	v_pk_fma_f32 v[22:23], v[110:111], v[22:23], v[40:41]
	v_pk_fma_f32 v[20:21], v[108:109], v[20:21], v[50:51]
	v_pk_fma_f32 v[36:37], v[98:99], v[18:19], v[42:43]
	v_pk_fma_f32 v[38:39], v[96:97], v[16:17], v[52:53]
	v_cvt_pk_bf16_f32 v16, v28, v29
	v_cvt_pk_bf16_f32 v17, v30, v31
	v_mul_f32_e32 v18, v29, v29
	v_mul_f32_e32 v19, v31, v31
	v_mul_f32_e32 v29, v25, v25
	v_mul_f32_e32 v31, v27, v27
	v_mul_f32_e32 v40, v21, v21
	v_mul_f32_e32 v41, v23, v23
	v_mul_f32_e32 v42, v39, v39
	v_mul_f32_e32 v43, v37, v37
	v_fmac_f32_e32 v18, v28, v28
	v_fmac_f32_e32 v19, v30, v30
	v_fmac_f32_e32 v29, v24, v24
	v_fmac_f32_e32 v31, v26, v26
	v_fmac_f32_e32 v40, v20, v20
	v_fmac_f32_e32 v41, v22, v22
	v_fmac_f32_e32 v42, v38, v38
	v_fmac_f32_e32 v43, v36, v36
	v_add_f32_e32 v18, v18, v19
	v_add_f32_e32 v19, v29, v31
	v_add_f32_e32 v28, v40, v41
	v_add_f32_e32 v29, v42, v43
	v_add_f32_e32 v18, v18, v19
	v_add_f32_e32 v19, v28, v29
	v_add_f32_e32 v28, v18, v19
	ds_bpermute_b32 v29, v145, v28
	v_cvt_pk_bf16_f32 v18, v24, v25
	v_cvt_pk_bf16_f32 v19, v26, v27
	global_store_dwordx4 v[44:45], v[16:19], off
	s_waitcnt lgkmcnt(0)
	s_nop 0
	v_add_f32_e32 v16, v28, v29
	ds_bpermute_b32 v17, v147, v16
	v_cvt_pk_bf16_f32 v18, v20, v21
	v_cvt_pk_bf16_f32 v19, v22, v23
	v_cvt_pk_bf16_f32 v20, v38, v39
	v_cvt_pk_bf16_f32 v21, v36, v37
	global_store_dwordx4 v[44:45], v[18:21], off offset:256
	s_and_saveexec_b64 s[0:1], s[4:5]
	s_cbranch_execz .LBB0_1161
	v_lshl_add_u32 v18, v32, 4, s22
	s_waitcnt lgkmcnt(0)
	v_add_f32_e32 v16, v16, v17
	ds_write_b32 v18, v16
; DI unsigned pk_bf16(float lo, float hi) { f32x2 v = {lo, hi}; bf16x2_t b = __builtin_convertvector(v, bf16x2_t); return __builtin_bit_cast(unsigned, b); }
; DI float bflo(unsigned w) { return __uint_as_float(w << 16); }
; DI float bfhi(unsigned w) { return __uint_as_float(w & 0xffff0000u); }
;     __device__ __forceinline__ void fused(f32x4 (&acc)[2][2][4][2], const pg8::Unit& u, int wr, int wc, int fr, int fq, PG8_LAS unsigned char* lds, int wid, int lane) const {
;     ...
;                 const int rl = ai * 128 + wr * 64 + m * 16 + fr; const size_t row = (size_t)u.pm * 256 + rl;
;                 const float rm = 1.f / sqrtf(__hip_atomic_load(ssqm + row, __ATOMIC_RELAXED, __HIP_MEMORY_SCOPE_AGENT) * (1.f / DM) + RMS_EPS);
;                 float sh = 0.f;
; #pragma unroll
;                 for (int bj = 0; bj < 2; ++bj) {
;                     const size_t off = row * DM + colb + bj * 128;
;                     f32x4 h0, h1;
;                     if (IN16) { const u32x4 hw = *(const u32x4*)((const bf16_t*)hin + off); h0 = (f32x4){bflo(hw.x), bfhi(hw.x), bflo(hw.y), bfhi(hw.y)}; h1 = (f32x4){bflo(hw.z), bfhi(hw.z), bflo(hw.w), bfhi(hw.w)}; }
;                     else { h0 = *(const f32x4*)((const float*)hin + off); h1 = *(const f32x4*)((const float*)hin + off + 4); }
;                     h0 = h0 + acc[ai][bj][m][0] * rm * gv[bj][0]; h1 = h1 + acc[ai][bj][m][1] * rm * gv[bj][1];
;                     sh += ((h0[0] * h0[0] + h0[1] * h0[1]) + (h0[2] * h0[2] + h0[3] * h0[3])) + ((h1[0] * h1[0] + h1[1] * h1[1]) + (h1[2] * h1[2] + h1[3] * h1[3]));
;                     if (OUT16) { u32x4 w; w.x = pk_bf16(h0[0], h0[1]); w.y = pk_bf16(h0[2], h0[3]); w.z = pk_bf16(h1[0], h1[1]); w.w = pk_bf16(h1[2], h1[3]); *(u32x4*)((bf16_t*)hout + off) = w; }
;                     else { *(f32x4*)((float*)hout + off) = h0; *(f32x4*)((float*)hout + off + 4) = h1; }
;                 }
;                 if (ssqh) { sh += __shfl_xor(sh, 16); sh += __shfl_xor(sh, 32); if (fq == 0) red[rl * 4 + wc] = sh; }
.LBB0_1161:
	s_or_b64 exec, exec, s[0:1]
	v_add_u32_e32 v32, 0xb0, v152
	s_waitcnt lgkmcnt(0)
	v_lshl_add_u64 v[16:17], s[18:19], 0, v[32:33]
	v_lshl_add_u64 v[18:19], v[16:17], 2, s[12:13]
	global_load_dword v26, v[18:19], off sc1
	v_lshlrev_b64 v[16:17], 11, v[16:17]
	v_lshl_add_u64 v[16:17], s[10:11], 0, v[16:17]
	v_lshl_add_u64 v[24:25], v[156:157], 1, v[16:17]
	global_load_dwordx4 v[16:19], v[24:25], off
	global_load_dwordx4 v[20:23], v[24:25], off offset:256
	s_waitcnt vmcnt(2)
	v_fmac_f32_e32 v35, 0x3a800000, v26
	v_rsq_f32_e32 v252, v35
	s_nop 0
	v_mul_f32_e32 v253, v35, v252
	v_mul_f32_e32 v253, v253, v252
	v_fmaak_f32 v253, -0.5, v253, 0x3fc00000
	v_mul_f32_e32 v252, v252, v253
	s_waitcnt vmcnt(1)
	v_and_b32_e32 v27, 0xffff0000, v16
	v_lshlrev_b32_e32 v28, 16, v18
	v_lshlrev_b32_e32 v26, 16, v16
	v_lshlrev_b32_e32 v16, 16, v17
	v_and_b32_e32 v17, 0xffff0000, v17
	v_and_b32_e32 v29, 0xffff0000, v18
	v_lshlrev_b32_e32 v18, 16, v19
	v_and_b32_e32 v19, 0xffff0000, v19
	s_waitcnt vmcnt(0)
	v_lshlrev_b32_e32 v30, 16, v20
	v_and_b32_e32 v31, 0xffff0000, v20
	v_lshlrev_b32_e32 v20, 16, v21
	v_and_b32_e32 v21, 0xffff0000, v21
	v_mov_b32_e32 v34, v252
	v_lshlrev_b32_e32 v36, 16, v22
	v_and_b32_e32 v37, 0xffff0000, v22
	v_lshlrev_b32_e32 v22, 16, v23
	v_and_b32_e32 v23, 0xffff0000, v23
	v_pk_mul_f32 v[12:13], v[12:13], v[34:35] op_sel_hi:[1,0]
	v_pk_mul_f32 v[14:15], v[14:15], v[34:35] op_sel_hi:[1,0]
	v_pk_mul_f32 v[8:9], v[8:9], v[34:35] op_sel_hi:[1,0]
	v_pk_mul_f32 v[10:11], v[10:11], v[34:35] op_sel_hi:[1,0]
	v_pk_mul_f32 v[4:5], v[4:5], v[34:35] op_sel_hi:[1,0]
	v_pk_mul_f32 v[6:7], v[6:7], v[34:35] op_sel_hi:[1,0]
	v_pk_mul_f32 v[0:1], v[0:1], v[34:35] op_sel_hi:[1,0]
	v_pk_mul_f32 v[2:3], v[2:3], v[34:35] op_sel_hi:[1,0]
	v_pk_fma_f32 v[14:15], v[106:107], v[14:15], v[16:17]
	v_pk_fma_f32 v[12:13], v[104:105], v[12:13], v[26:27]
	v_pk_fma_f32 v[10:11], v[102:103], v[10:11], v[18:19]
	v_pk_fma_f32 v[8:9], v[100:101], v[8:9], v[28:29]
	v_pk_fma_f32 v[6:7], v[110:111], v[6:7], v[20:21]
	v_pk_fma_f32 v[4:5], v[108:109], v[4:5], v[30:31]
	v_pk_fma_f32 v[16:17], v[98:99], v[2:3], v[22:23]
	v_pk_fma_f32 v[18:19], v[96:97], v[0:1], v[36:37]
	v_cvt_pk_bf16_f32 v0, v12, v13
	v_cvt_pk_bf16_f32 v1, v14, v15
	v_mul_f32_e32 v2, v13, v13
	v_mul_f32_e32 v3, v15, v15
	v_mul_f32_e32 v13, v9, v9
	v_mul_f32_e32 v15, v11, v11
	v_mul_f32_e32 v20, v5, v5
	v_mul_f32_e32 v21, v7, v7
	v_mul_f32_e32 v22, v19, v19
	v_mul_f32_e32 v23, v17, v17
	v_fmac_f32_e32 v2, v12, v12
	v_fmac_f32_e32 v3, v14, v14
	v_fmac_f32_e32 v13, v8, v8
	v_fmac_f32_e32 v15, v10, v10
	v_fmac_f32_e32 v20, v4, v4
	v_fmac_f32_e32 v21, v6, v6
	v_fmac_f32_e32 v22, v18, v18
	v_fmac_f32_e32 v23, v16, v16
	v_add_f32_e32 v2, v2, v3
	v_add_f32_e32 v3, v13, v15
	v_add_f32_e32 v12, v20, v21
	v_add_f32_e32 v13, v22, v23
	v_add_f32_e32 v2, v2, v3
	v_add_f32_e32 v3, v12, v13
	v_add_f32_e32 v12, v2, v3
	ds_bpermute_b32 v13, v145, v12
	v_cvt_pk_bf16_f32 v2, v8, v9
	v_cvt_pk_bf16_f32 v3, v10, v11
	global_store_dwordx4 v[24:25], v[0:3], off
	s_waitcnt lgkmcnt(0)
	s_nop 0
	v_add_f32_e32 v0, v12, v13
	ds_bpermute_b32 v1, v147, v0
	v_cvt_pk_bf16_f32 v2, v4, v5
	v_cvt_pk_bf16_f32 v3, v6, v7
	v_cvt_pk_bf16_f32 v4, v18, v19
	v_cvt_pk_bf16_f32 v5, v16, v17
	global_store_dwordx4 v[24:25], v[2:5], off offset:256
	s_and_saveexec_b64 s[0:1], s[4:5]
	s_cbranch_execz .LBB0_1163
	v_lshl_add_u32 v2, v32, 4, s22
	s_waitcnt lgkmcnt(0)
	v_add_f32_e32 v0, v0, v1
	ds_write_b32 v2, v0

; DI unsigned pk_bf16(float lo, float hi) { f32x2 v = {lo, hi}; bf16x2_t b = __builtin_convertvector(v, bf16x2_t); return __builtin_bit_cast(unsigned, b); }
; DI float bflo(unsigned w) { return __uint_as_float(w << 16); }
; DI float bfhi(unsigned w) { return __uint_as_float(w & 0xffff0000u); }
;     __device__ __forceinline__ void fused(f32x4 (&acc)[2][2][4][2], const pg8::Unit& u, int wr, int wc, int fr, int fq, PG8_LAS unsigned char* lds, int wid, int lane) const {
;     ...
;         const int colb = u.pn * 256 + wc * 32 + 8 * fq;
;         f32x4 gv[2][2];
; #pragma unroll
;         for (int bj = 0; bj < 2; ++bj)
; #pragma unroll
;             for (int n = 0; n < 2; ++n) gv[bj][n] = *(const f32x4*)(gA + colb + bj * 128 + 4 * n);
; #pragma unroll
;         for (int ai = 0; ai < 2; ++ai)
; #pragma unroll
;             for (int m = 0; m < 4; ++m) {
;                 const int rl = ai * 128 + wr * 64 + m * 16 + fr; const size_t row = (size_t)u.pm * 256 + rl;
;                 const float rm = 1.f / sqrtf(__hip_atomic_load(ssqm + row, __ATOMIC_RELAXED, __HIP_MEMORY_SCOPE_AGENT) * (1.f / DM) + RMS_EPS);
;                 float sh = 0.f;
; #pragma unroll
;                 for (int bj = 0; bj < 2; ++bj) {
;                     const size_t off = row * DM + colb + bj * 128;
;                     f32x4 h0, h1;
;                     if (IN16) { const u32x4 hw = *(const u32x4*)((const bf16_t*)hin + off); h0 = (f32x4){bflo(hw.x), bfhi(hw.x), bflo(hw.y), bfhi(hw.y)}; h1 = (f32x4){bflo(hw.z), bfhi(hw.z), bflo(hw.w), bfhi(hw.w)}; }
;                     else { h0 = *(const f32x4*)((const float*)hin + off); h1 = *(const f32x4*)((const float*)hin + off + 4); }
;                     h0 = h0 + acc[ai][bj][m][0] * rm * gv[bj][0]; h1 = h1 + acc[ai][bj][m][1] * rm * gv[bj][1];
;                     sh += ((h0[0] * h0[0] + h0[1] * h0[1]) + (h0[2] * h0[2] + h0[3] * h0[3])) + ((h1[0] * h1[0] + h1[1] * h1[1]) + (h1[2] * h1[2] + h1[3] * h1[3]));
;                     if (OUT16) { u32x4 w; w.x = pk_bf16(h0[0], h0[1]); w.y = pk_bf16(h0[2], h0[3]); w.z = pk_bf16(h1[0], h1[1]); w.w = pk_bf16(h1[2], h1[3]); *(u32x4*)((bf16_t*)hout + off) = w; }
;                     else { *(f32x4*)((float*)hout + off) = h0; *(f32x4*)((float*)hout + off + 4) = h1; }
;                 }
;                 if (ssqh) { sh += __shfl_xor(sh, 16); sh += __shfl_xor(sh, 32); if (fq == 0) red[rl * 4 + wc] = sh; }
.LBB0_1202:
	s_or_b64 exec, exec, s[0:1]
	s_lshl_b32 s0, s28, 5
	s_lshl_b32 s1, s33, 8
	s_or_b32 s0, s1, s0
	v_or_b32_e32 v146, s0, v160
	v_ashrrev_i32_e32 v147, 31, v146
	v_mov_b32_e32 v149, 0
	v_lshl_add_u64 v[108:109], v[146:147], 2, s[14:15]
	s_lshl_b64 s[14:15], s[16:17], 8
	v_mov_b32_e32 v153, v149
	v_lshl_add_u64 v[156:157], s[14:15], 0, v[152:153]
	v_lshl_add_u64 v[158:159], v[156:157], 2, s[12:13]
	s_barrier
	global_load_dwordx4 v[100:103], v[108:109], off offset:16
	global_load_dwordx4 v[104:107], v[108:109], off
	global_load_dwordx4 v[96:99], v[108:109], off offset:528
	s_nop 0
	global_load_dwordx4 v[108:111], v[108:109], off offset:512
	v_lshlrev_b64 v[156:157], 11, v[156:157]
	global_load_dword v148, v[158:159], off sc1
	v_lshl_add_u64 v[156:157], s[10:11], 0, v[156:157]
	v_lshl_add_u64 v[164:165], v[146:147], 1, v[156:157]
	global_load_dwordx4 v[156:159], v[164:165], off
	global_load_dwordx4 v[160:163], v[164:165], off offset:256
	v_mov_b32_e32 v155, 0x358637bd
	s_mov_b32 s2, 0xf800000
	v_mov_b32_e32 v153, 0x260
	s_waitcnt vmcnt(2)
	v_fmamk_f32 v148, v148, 0x3a800000, v155
	v_rsq_f32_e32 v252, v148
	s_nop 0
	v_mul_f32_e32 v253, v148, v252
	v_mul_f32_e32 v253, v253, v252
	v_fmaak_f32 v253, -0.5, v253, 0x3fc00000
	v_mul_f32_e32 v252, v252, v253
	s_waitcnt vmcnt(1)
	v_lshlrev_b32_e32 v166, 16, v156
	v_and_b32_e32 v167, 0xffff0000, v156
	v_lshlrev_b32_e32 v156, 16, v157
	v_and_b32_e32 v157, 0xffff0000, v157
	v_lshlrev_b32_e32 v168, 16, v158
	v_and_b32_e32 v169, 0xffff0000, v158
	v_lshlrev_b32_e32 v158, 16, v159
	v_and_b32_e32 v159, 0xffff0000, v159
	s_waitcnt vmcnt(0)
	v_lshlrev_b32_e32 v170, 16, v160
	v_and_b32_e32 v171, 0xffff0000, v160
	v_lshlrev_b32_e32 v160, 16, v161
	v_and_b32_e32 v161, 0xffff0000, v161
	v_mov_b32_e32 v148, v252
	v_lshlrev_b32_e32 v172, 16, v162
	v_and_b32_e32 v173, 0xffff0000, v162
	v_lshlrev_b32_e32 v162, 16, v163
	v_and_b32_e32 v163, 0xffff0000, v163
	v_pk_mul_f32 v[140:141], v[140:141], v[148:149] op_sel_hi:[1,0]
	v_pk_mul_f32 v[142:143], v[142:143], v[148:149] op_sel_hi:[1,0]
	v_pk_mul_f32 v[136:137], v[136:137], v[148:149] op_sel_hi:[1,0]
	v_pk_mul_f32 v[138:139], v[138:139], v[148:149] op_sel_hi:[1,0]
	v_pk_mul_f32 v[132:133], v[132:133], v[148:149] op_sel_hi:[1,0]
	v_pk_mul_f32 v[134:135], v[134:135], v[148:149] op_sel_hi:[1,0]
	v_pk_mul_f32 v[128:129], v[128:129], v[148:149] op_sel_hi:[1,0]
	v_pk_mul_f32 v[130:131], v[130:131], v[148:149] op_sel_hi:[1,0]
	v_pk_fma_f32 v[142:143], v[106:107], v[142:143], v[156:157]
	v_pk_fma_f32 v[140:141], v[104:105], v[140:141], v[166:167]
	v_pk_fma_f32 v[138:139], v[102:103], v[138:139], v[158:159]
	v_pk_fma_f32 v[136:137], v[100:101], v[136:137], v[168:169]
	v_pk_fma_f32 v[134:135], v[110:111], v[134:135], v[160:161]
	v_pk_fma_f32 v[132:133], v[108:109], v[132:133], v[170:171]
	v_pk_fma_f32 v[156:157], v[98:99], v[130:131], v[162:163]
	v_pk_fma_f32 v[158:159], v[96:97], v[128:129], v[172:173]
	v_cvt_pk_bf16_f32 v128, v140, v141
	v_cvt_pk_bf16_f32 v129, v142, v143
	v_mul_f32_e32 v130, v141, v141
	v_mul_f32_e32 v131, v143, v143
	v_mul_f32_e32 v141, v137, v137
	v_mul_f32_e32 v143, v139, v139
	v_mul_f32_e32 v148, v133, v133
	v_mul_f32_e32 v160, v135, v135
	v_mul_f32_e32 v161, v159, v159
	v_mul_f32_e32 v162, v157, v157
	v_fmac_f32_e32 v130, v140, v140
	v_fmac_f32_e32 v131, v142, v142
	v_fmac_f32_e32 v141, v136, v136
	v_fmac_f32_e32 v143, v138, v138
	v_fmac_f32_e32 v148, v132, v132
	v_fmac_f32_e32 v160, v134, v134
	v_fmac_f32_e32 v161, v158, v158
	v_fmac_f32_e32 v162, v156, v156
	v_add_f32_e32 v130, v130, v131
	v_add_f32_e32 v131, v141, v143
	v_add_f32_e32 v140, v148, v160
	v_add_f32_e32 v141, v161, v162
	v_add_f32_e32 v130, v130, v131
	v_add_f32_e32 v131, v140, v141
	v_add_f32_e32 v140, v130, v131
	ds_bpermute_b32 v141, v150, v140
	v_cvt_pk_bf16_f32 v130, v136, v137
	v_cvt_pk_bf16_f32 v131, v138, v139
	global_store_dwordx4 v[164:165], v[128:131], off
	s_waitcnt lgkmcnt(0)
	s_nop 0
	v_add_f32_e32 v128, v140, v141
	ds_bpermute_b32 v129, v151, v128
	v_cvt_pk_bf16_f32 v130, v132, v133
	v_cvt_pk_bf16_f32 v131, v134, v135
	v_cvt_pk_bf16_f32 v132, v158, v159
	v_cvt_pk_bf16_f32 v133, v156, v157
	global_store_dwordx4 v[164:165], v[130:133], off offset:256
	s_and_saveexec_b64 s[0:1], s[4:5]
	s_cbranch_execz .LBB0_1204
	v_lshl_add_u32 v130, v152, 4, s22
	s_waitcnt lgkmcnt(0)
	v_add_f32_e32 v128, v128, v129
	ds_write_b32 v130, v128
; DI unsigned pk_bf16(float lo, float hi) { f32x2 v = {lo, hi}; bf16x2_t b = __builtin_convertvector(v, bf16x2_t); return __builtin_bit_cast(unsigned, b); }
; DI float bflo(unsigned w) { return __uint_as_float(w << 16); }
; DI float bfhi(unsigned w) { return __uint_as_float(w & 0xffff0000u); }
;     __device__ __forceinline__ void fused(f32x4 (&acc)[2][2][4][2], const pg8::Unit& u, int wr, int wc, int fr, int fq, PG8_LAS unsigned char* lds, int wid, int lane) const {
;     ...
;                 const int rl = ai * 128 + wr * 64 + m * 16 + fr; const size_t row = (size_t)u.pm * 256 + rl;
;                 const float rm = 1.f / sqrtf(__hip_atomic_load(ssqm + row, __ATOMIC_RELAXED, __HIP_MEMORY_SCOPE_AGENT) * (1.f / DM) + RMS_EPS);
;                 float sh = 0.f;
; #pragma unroll
;                 for (int bj = 0; bj < 2; ++bj) {
;                     const size_t off = row * DM + colb + bj * 128;
;                     f32x4 h0, h1;
;                     if (IN16) { const u32x4 hw = *(const u32x4*)((const bf16_t*)hin + off); h0 = (f32x4){bflo(hw.x), bfhi(hw.x), bflo(hw.y), bfhi(hw.y)}; h1 = (f32x4){bflo(hw.z), bfhi(hw.z), bflo(hw.w), bfhi(hw.w)}; }
;                     else { h0 = *(const f32x4*)((const float*)hin + off); h1 = *(const f32x4*)((const float*)hin + off + 4); }
;                     h0 = h0 + acc[ai][bj][m][0] * rm * gv[bj][0]; h1 = h1 + acc[ai][bj][m][1] * rm * gv[bj][1];
;                     sh += ((h0[0] * h0[0] + h0[1] * h0[1]) + (h0[2] * h0[2] + h0[3] * h0[3])) + ((h1[0] * h1[0] + h1[1] * h1[1]) + (h1[2] * h1[2] + h1[3] * h1[3]));
;                     if (OUT16) { u32x4 w; w.x = pk_bf16(h0[0], h0[1]); w.y = pk_bf16(h0[2], h0[3]); w.z = pk_bf16(h1[0], h1[1]); w.w = pk_bf16(h1[2], h1[3]); *(u32x4*)((bf16_t*)hout + off) = w; }
;                     else { *(f32x4*)((float*)hout + off) = h0; *(f32x4*)((float*)hout + off + 4) = h1; }
;                 }
;                 if (ssqh) { sh += __shfl_xor(sh, 16); sh += __shfl_xor(sh, 32); if (fq == 0) red[rl * 4 + wc] = sh; }
.LBB0_1204:
	s_or_b64 exec, exec, s[0:1]
	v_or_b32_e32 v148, 16, v152
	s_waitcnt lgkmcnt(0)
	v_lshl_add_u64 v[128:129], s[14:15], 0, v[148:149]
	v_lshl_add_u64 v[130:131], v[128:129], 2, s[12:13]
	global_load_dword v138, v[130:131], off sc1
	v_lshlrev_b64 v[128:129], 11, v[128:129]
	v_lshl_add_u64 v[128:129], s[10:11], 0, v[128:129]
	v_lshl_add_u64 v[136:137], v[146:147], 1, v[128:129]
	global_load_dwordx4 v[128:131], v[136:137], off
	global_load_dwordx4 v[132:135], v[136:137], off offset:256
	s_waitcnt vmcnt(2)
	v_fmac_f32_e32 v155, 0x3a800000, v138
	v_rsq_f32_e32 v252, v155
	s_nop 0
	v_mul_f32_e32 v253, v155, v252
	v_mul_f32_e32 v253, v253, v252
	v_fmaak_f32 v253, -0.5, v253, 0x3fc00000
	v_mul_f32_e32 v252, v252, v253
	s_waitcnt vmcnt(1)
	v_and_b32_e32 v139, 0xffff0000, v128
	v_lshlrev_b32_e32 v140, 16, v130
	v_lshlrev_b32_e32 v138, 16, v128
	v_lshlrev_b32_e32 v128, 16, v129
	v_and_b32_e32 v129, 0xffff0000, v129
	v_and_b32_e32 v141, 0xffff0000, v130
	v_lshlrev_b32_e32 v130, 16, v131
	v_and_b32_e32 v131, 0xffff0000, v131
	s_waitcnt vmcnt(0)
	v_lshlrev_b32_e32 v142, 16, v132
	v_and_b32_e32 v143, 0xffff0000, v132
	v_lshlrev_b32_e32 v132, 16, v133
	v_and_b32_e32 v133, 0xffff0000, v133
	v_mov_b32_e32 v158, v252
	v_lshlrev_b32_e32 v156, 16, v134
	v_and_b32_e32 v157, 0xffff0000, v134
	v_lshlrev_b32_e32 v134, 16, v135
	v_and_b32_e32 v135, 0xffff0000, v135
	v_pk_mul_f32 v[124:125], v[124:125], v[158:159] op_sel_hi:[1,0]
	v_pk_mul_f32 v[126:127], v[126:127], v[158:159] op_sel_hi:[1,0]
	v_pk_mul_f32 v[120:121], v[120:121], v[158:159] op_sel_hi:[1,0]
	v_pk_mul_f32 v[122:123], v[122:123], v[158:159] op_sel_hi:[1,0]
	v_pk_mul_f32 v[116:117], v[116:117], v[158:159] op_sel_hi:[1,0]
	v_pk_mul_f32 v[118:119], v[118:119], v[158:159] op_sel_hi:[1,0]
	v_pk_mul_f32 v[112:113], v[112:113], v[158:159] op_sel_hi:[1,0]
	v_pk_mul_f32 v[114:115], v[114:115], v[158:159] op_sel_hi:[1,0]
	v_pk_fma_f32 v[126:127], v[106:107], v[126:127], v[128:129]
	v_pk_fma_f32 v[124:125], v[104:105], v[124:125], v[138:139]
	v_pk_fma_f32 v[122:123], v[102:103], v[122:123], v[130:131]
	v_pk_fma_f32 v[120:121], v[100:101], v[120:121], v[140:141]
	v_pk_fma_f32 v[118:119], v[110:111], v[118:119], v[132:133]
	v_pk_fma_f32 v[116:117], v[108:109], v[116:117], v[142:143]
	v_pk_fma_f32 v[128:129], v[98:99], v[114:115], v[134:135]
	v_pk_fma_f32 v[130:131], v[96:97], v[112:113], v[156:157]
	v_cvt_pk_bf16_f32 v112, v124, v125
	v_cvt_pk_bf16_f32 v113, v126, v127
	v_mul_f32_e32 v114, v125, v125
	v_mul_f32_e32 v115, v127, v127
	v_mul_f32_e32 v125, v121, v121
	v_mul_f32_e32 v127, v123, v123
	v_mul_f32_e32 v132, v117, v117
	v_mul_f32_e32 v133, v119, v119
	v_mul_f32_e32 v134, v131, v131
	v_mul_f32_e32 v135, v129, v129
	v_fmac_f32_e32 v114, v124, v124
	v_fmac_f32_e32 v115, v126, v126
	v_fmac_f32_e32 v125, v120, v120
	v_fmac_f32_e32 v127, v122, v122
	v_fmac_f32_e32 v132, v116, v116
	v_fmac_f32_e32 v133, v118, v118
	v_fmac_f32_e32 v134, v130, v130
	v_fmac_f32_e32 v135, v128, v128
	v_add_f32_e32 v114, v114, v115
	v_add_f32_e32 v115, v125, v127
	v_add_f32_e32 v124, v132, v133
	v_add_f32_e32 v125, v134, v135
	v_add_f32_e32 v114, v114, v115
	v_add_f32_e32 v115, v124, v125
	v_add_f32_e32 v124, v114, v115
	ds_bpermute_b32 v125, v150, v124
	v_cvt_pk_bf16_f32 v114, v120, v121
	v_cvt_pk_bf16_f32 v115, v122, v123
	global_store_dwordx4 v[136:137], v[112:115], off
	s_waitcnt lgkmcnt(0)
	s_nop 0
	v_add_f32_e32 v112, v124, v125
	ds_bpermute_b32 v113, v151, v112
	v_cvt_pk_bf16_f32 v114, v116, v117
	v_cvt_pk_bf16_f32 v115, v118, v119
	v_cvt_pk_bf16_f32 v116, v130, v131
	v_cvt_pk_bf16_f32 v117, v128, v129
	global_store_dwordx4 v[136:137], v[114:117], off offset:256
	s_and_saveexec_b64 s[0:1], s[4:5]
	s_cbranch_execz .LBB0_1206
	v_lshl_add_u32 v114, v148, 4, s22
	s_waitcnt lgkmcnt(0)
	v_add_f32_e32 v112, v112, v113
	ds_write_b32 v114, v112
.LBB0_1206:
	s_or_b64 exec, exec, s[0:1]
	v_or_b32_e32 v112, 32, v152
	s_waitcnt lgkmcnt(0)
	v_mov_b32_e32 v113, 0
	v_lshl_add_u64 v[114:115], s[14:15], 0, v[112:113]
	v_lshl_add_u64 v[116:117], v[114:115], 2, s[12:13]
	global_load_dword v126, v[116:117], off sc1
	v_lshlrev_b64 v[114:115], 11, v[114:115]
	v_lshl_add_u64 v[114:115], s[10:11], 0, v[114:115]
	v_lshl_add_u64 v[124:125], v[146:147], 1, v[114:115]
	global_load_dwordx4 v[116:119], v[124:125], off
	global_load_dwordx4 v[120:123], v[124:125], off offset:256
	v_mov_b32_e32 v115, 0x358637bd
	v_mov_b32_e32 v114, 0x260
	s_waitcnt vmcnt(2)
	v_fmamk_f32 v126, v126, 0x3a800000, v115
	v_rsq_f32_e32 v252, v126
	s_nop 0
	v_mul_f32_e32 v253, v126, v252
	v_mul_f32_e32 v253, v253, v252
	v_fmaak_f32 v253, -0.5, v253, 0x3fc00000
	v_mul_f32_e32 v252, v252, v253
	s_waitcnt vmcnt(1)
	v_lshlrev_b32_e32 v128, 16, v118
	v_and_b32_e32 v129, 0xffff0000, v118
	v_lshlrev_b32_e32 v126, 16, v116
	v_and_b32_e32 v127, 0xffff0000, v116
	v_lshlrev_b32_e32 v116, 16, v117
	v_and_b32_e32 v117, 0xffff0000, v117
	v_lshlrev_b32_e32 v118, 16, v119
	v_and_b32_e32 v119, 0xffff0000, v119
	s_waitcnt vmcnt(0)
; DI unsigned pk_bf16(float lo, float hi) { f32x2 v = {lo, hi}; bf16x2_t b = __builtin_convertvector(v, bf16x2_t); return __builtin_bit_cast(unsigned, b); }
; DI float bflo(unsigned w) { return __uint_as_float(w << 16); }
; DI float bfhi(unsigned w) { return __uint_as_float(w & 0xffff0000u); }
;     __device__ __forceinline__ void fused(f32x4 (&acc)[2][2][4][2], const pg8::Unit& u, int wr, int wc, int fr, int fq, PG8_LAS unsigned char* lds, int wid, int lane) const {
;     ...
;                 const int rl = ai * 128 + wr * 64 + m * 16 + fr; const size_t row = (size_t)u.pm * 256 + rl;
;                 const float rm = 1.f / sqrtf(__hip_atomic_load(ssqm + row, __ATOMIC_RELAXED, __HIP_MEMORY_SCOPE_AGENT) * (1.f / DM) + RMS_EPS);
;                 float sh = 0.f;
; #pragma unroll
;                 for (int bj = 0; bj < 2; ++bj) {
;                     const size_t off = row * DM + colb + bj * 128;
;                     f32x4 h0, h1;
;                     if (IN16) { const u32x4 hw = *(const u32x4*)((const bf16_t*)hin + off); h0 = (f32x4){bflo(hw.x), bfhi(hw.x), bflo(hw.y), bfhi(hw.y)}; h1 = (f32x4){bflo(hw.z), bfhi(hw.z), bflo(hw.w), bfhi(hw.w)}; }
;                     else { h0 = *(const f32x4*)((const float*)hin + off); h1 = *(const f32x4*)((const float*)hin + off + 4); }
;                     h0 = h0 + acc[ai][bj][m][0] * rm * gv[bj][0]; h1 = h1 + acc[ai][bj][m][1] * rm * gv[bj][1];
;                     sh += ((h0[0] * h0[0] + h0[1] * h0[1]) + (h0[2] * h0[2] + h0[3] * h0[3])) + ((h1[0] * h1[0] + h1[1] * h1[1]) + (h1[2] * h1[2] + h1[3] * h1[3]));
;                     if (OUT16) { u32x4 w; w.x = pk_bf16(h0[0], h0[1]); w.y = pk_bf16(h0[2], h0[3]); w.z = pk_bf16(h1[0], h1[1]); w.w = pk_bf16(h1[2], h1[3]); *(u32x4*)((bf16_t*)hout + off) = w; }
;                     else { *(f32x4*)((float*)hout + off) = h0; *(f32x4*)((float*)hout + off + 4) = h1; }
;                 }
;                 if (ssqh) { sh += __shfl_xor(sh, 16); sh += __shfl_xor(sh, 32); if (fq == 0) red[rl * 4 + wc] = sh; }
	v_lshlrev_b32_e32 v130, 16, v120
	v_and_b32_e32 v131, 0xffff0000, v120
	v_lshlrev_b32_e32 v120, 16, v121
	v_and_b32_e32 v121, 0xffff0000, v121
	v_mov_b32_e32 v134, v252
	v_lshlrev_b32_e32 v132, 16, v122
	v_and_b32_e32 v133, 0xffff0000, v122
	v_lshlrev_b32_e32 v122, 16, v123
	v_and_b32_e32 v123, 0xffff0000, v123
	v_pk_mul_f32 v[92:93], v[92:93], v[134:135] op_sel_hi:[1,0]
	v_pk_mul_f32 v[94:95], v[94:95], v[134:135] op_sel_hi:[1,0]
	v_pk_mul_f32 v[88:89], v[88:89], v[134:135] op_sel_hi:[1,0]
	v_pk_mul_f32 v[90:91], v[90:91], v[134:135] op_sel_hi:[1,0]
	v_pk_mul_f32 v[84:85], v[84:85], v[134:135] op_sel_hi:[1,0]
	v_pk_mul_f32 v[86:87], v[86:87], v[134:135] op_sel_hi:[1,0]
	v_pk_mul_f32 v[80:81], v[80:81], v[134:135] op_sel_hi:[1,0]
	v_pk_mul_f32 v[82:83], v[82:83], v[134:135] op_sel_hi:[1,0]
	v_pk_fma_f32 v[94:95], v[106:107], v[94:95], v[116:117]
	v_pk_fma_f32 v[92:93], v[104:105], v[92:93], v[126:127]
	v_pk_fma_f32 v[90:91], v[102:103], v[90:91], v[118:119]
	v_pk_fma_f32 v[88:89], v[100:101], v[88:89], v[128:129]
	v_pk_fma_f32 v[86:87], v[110:111], v[86:87], v[120:121]
	v_pk_fma_f32 v[84:85], v[108:109], v[84:85], v[130:131]
	v_pk_fma_f32 v[116:117], v[98:99], v[82:83], v[122:123]
	v_pk_fma_f32 v[118:119], v[96:97], v[80:81], v[132:133]
	v_cvt_pk_bf16_f32 v80, v92, v93
	v_cvt_pk_bf16_f32 v81, v94, v95
	v_mul_f32_e32 v82, v93, v93
	v_mul_f32_e32 v83, v95, v95
	v_mul_f32_e32 v93, v89, v89
	v_mul_f32_e32 v95, v91, v91
	v_mul_f32_e32 v120, v85, v85
	v_mul_f32_e32 v121, v87, v87
	v_mul_f32_e32 v122, v119, v119
	v_mul_f32_e32 v123, v117, v117
	v_fmac_f32_e32 v82, v92, v92
	v_fmac_f32_e32 v83, v94, v94
	v_fmac_f32_e32 v93, v88, v88
	v_fmac_f32_e32 v95, v90, v90
	v_fmac_f32_e32 v120, v84, v84
	v_fmac_f32_e32 v121, v86, v86
	v_fmac_f32_e32 v122, v118, v118
	v_fmac_f32_e32 v123, v116, v116
	v_add_f32_e32 v82, v82, v83
	v_add_f32_e32 v83, v93, v95
	v_add_f32_e32 v92, v120, v121
	v_add_f32_e32 v93, v122, v123
	v_add_f32_e32 v82, v82, v83
	v_add_f32_e32 v83, v92, v93
	v_add_f32_e32 v92, v82, v83
	ds_bpermute_b32 v93, v150, v92
	v_cvt_pk_bf16_f32 v82, v88, v89
	v_cvt_pk_bf16_f32 v83, v90, v91
	global_store_dwordx4 v[124:125], v[80:83], off
	s_waitcnt lgkmcnt(0)
	s_nop 0
	v_add_f32_e32 v80, v92, v93
	ds_bpermute_b32 v81, v151, v80
	v_cvt_pk_bf16_f32 v82, v84, v85
	v_cvt_pk_bf16_f32 v83, v86, v87
	v_cvt_pk_bf16_f32 v84, v118, v119
	v_cvt_pk_bf16_f32 v85, v116, v117
	global_store_dwordx4 v[124:125], v[82:85], off offset:256
	s_and_saveexec_b64 s[0:1], s[4:5]
	s_cbranch_execz .LBB0_1208
	v_lshl_add_u32 v82, v112, 4, s22
	s_waitcnt lgkmcnt(0)
	v_add_f32_e32 v80, v80, v81
	ds_write_b32 v82, v80
.LBB0_1208:
	s_or_b64 exec, exec, s[0:1]
	v_or_b32_e32 v112, 48, v152
	s_waitcnt lgkmcnt(0)
	v_lshl_add_u64 v[80:81], s[14:15], 0, v[112:113]
	v_lshl_add_u64 v[82:83], v[80:81], 2, s[12:13]
	global_load_dword v90, v[82:83], off sc1
	v_lshlrev_b64 v[80:81], 11, v[80:81]
	v_lshl_add_u64 v[80:81], s[10:11], 0, v[80:81]
	v_lshl_add_u64 v[88:89], v[146:147], 1, v[80:81]
	global_load_dwordx4 v[80:83], v[88:89], off
	global_load_dwordx4 v[84:87], v[88:89], off offset:256
	s_waitcnt vmcnt(2)
	v_fmac_f32_e32 v115, 0x3a800000, v90
	v_rsq_f32_e32 v252, v115
	s_nop 0
	v_mul_f32_e32 v253, v115, v252
	v_mul_f32_e32 v253, v253, v252
	v_fmaak_f32 v253, -0.5, v253, 0x3fc00000
	v_mul_f32_e32 v252, v252, v253
	s_waitcnt vmcnt(1)
	v_and_b32_e32 v91, 0xffff0000, v80
	v_lshlrev_b32_e32 v92, 16, v82
	v_lshlrev_b32_e32 v90, 16, v80
	v_lshlrev_b32_e32 v80, 16, v81
	v_and_b32_e32 v81, 0xffff0000, v81
	v_and_b32_e32 v93, 0xffff0000, v82
	v_lshlrev_b32_e32 v82, 16, v83
	v_and_b32_e32 v83, 0xffff0000, v83
	s_waitcnt vmcnt(0)
	v_lshlrev_b32_e32 v94, 16, v84
	v_and_b32_e32 v95, 0xffff0000, v84
	v_lshlrev_b32_e32 v84, 16, v85
	v_and_b32_e32 v85, 0xffff0000, v85
	v_mov_b32_e32 v114, v252
	v_lshlrev_b32_e32 v116, 16, v86
	v_and_b32_e32 v117, 0xffff0000, v86
	v_lshlrev_b32_e32 v86, 16, v87
	v_and_b32_e32 v87, 0xffff0000, v87
	v_pk_mul_f32 v[76:77], v[76:77], v[114:115] op_sel_hi:[1,0]
	v_pk_mul_f32 v[78:79], v[78:79], v[114:115] op_sel_hi:[1,0]
	v_pk_mul_f32 v[72:73], v[72:73], v[114:115] op_sel_hi:[1,0]
	v_pk_mul_f32 v[74:75], v[74:75], v[114:115] op_sel_hi:[1,0]
	v_pk_mul_f32 v[68:69], v[68:69], v[114:115] op_sel_hi:[1,0]
	v_pk_mul_f32 v[70:71], v[70:71], v[114:115] op_sel_hi:[1,0]
	v_pk_mul_f32 v[64:65], v[64:65], v[114:115] op_sel_hi:[1,0]
	v_pk_mul_f32 v[66:67], v[66:67], v[114:115] op_sel_hi:[1,0]
	v_pk_fma_f32 v[78:79], v[106:107], v[78:79], v[80:81]
	v_pk_fma_f32 v[76:77], v[104:105], v[76:77], v[90:91]
	v_pk_fma_f32 v[74:75], v[102:103], v[74:75], v[82:83]
	v_pk_fma_f32 v[72:73], v[100:101], v[72:73], v[92:93]
	v_pk_fma_f32 v[70:71], v[110:111], v[70:71], v[84:85]
	v_pk_fma_f32 v[68:69], v[108:109], v[68:69], v[94:95]
	v_pk_fma_f32 v[80:81], v[98:99], v[66:67], v[86:87]
	v_pk_fma_f32 v[82:83], v[96:97], v[64:65], v[116:117]
	v_cvt_pk_bf16_f32 v64, v76, v77
	v_cvt_pk_bf16_f32 v65, v78, v79
	v_mul_f32_e32 v66, v77, v77
	v_mul_f32_e32 v67, v79, v79
	v_mul_f32_e32 v77, v73, v73
	v_mul_f32_e32 v79, v75, v75
	v_mul_f32_e32 v84, v69, v69
	v_mul_f32_e32 v85, v71, v71
	v_mul_f32_e32 v86, v83, v83
	v_mul_f32_e32 v87, v81, v81
	v_fmac_f32_e32 v66, v76, v76
	v_fmac_f32_e32 v67, v78, v78
	v_fmac_f32_e32 v77, v72, v72
	v_fmac_f32_e32 v79, v74, v74
	v_fmac_f32_e32 v84, v68, v68
	v_fmac_f32_e32 v85, v70, v70
	v_fmac_f32_e32 v86, v82, v82
	v_fmac_f32_e32 v87, v80, v80
	v_add_f32_e32 v66, v66, v67
	v_add_f32_e32 v67, v77, v79
	v_add_f32_e32 v76, v84, v85
	v_add_f32_e32 v77, v86, v87
	v_add_f32_e32 v66, v66, v67
	v_add_f32_e32 v67, v76, v77
	v_add_f32_e32 v76, v66, v67
	ds_bpermute_b32 v77, v150, v76
	v_cvt_pk_bf16_f32 v66, v72, v73
	v_cvt_pk_bf16_f32 v67, v74, v75
	global_store_dwordx4 v[88:89], v[64:67], off
	s_waitcnt lgkmcnt(0)
	s_nop 0
	v_add_f32_e32 v64, v76, v77
	ds_bpermute_b32 v65, v151, v64
	v_cvt_pk_bf16_f32 v66, v68, v69
	v_cvt_pk_bf16_f32 v67, v70, v71
	v_cvt_pk_bf16_f32 v68, v82, v83
	v_cvt_pk_bf16_f32 v69, v80, v81
	global_store_dwordx4 v[88:89], v[66:69], off offset:256
	s_and_saveexec_b64 s[0:1], s[4:5]
	s_cbranch_execz .LBB0_1210
	v_lshl_add_u32 v66, v112, 4, s22
	s_waitcnt lgkmcnt(0)
	v_add_f32_e32 v64, v64, v65
	ds_write_b32 v66, v64
; DI unsigned pk_bf16(float lo, float hi) { f32x2 v = {lo, hi}; bf16x2_t b = __builtin_convertvector(v, bf16x2_t); return __builtin_bit_cast(unsigned, b); }
; DI float bflo(unsigned w) { return __uint_as_float(w << 16); }
; DI float bfhi(unsigned w) { return __uint_as_float(w & 0xffff0000u); }
;     __device__ __forceinline__ void fused(f32x4 (&acc)[2][2][4][2], const pg8::Unit& u, int wr, int wc, int fr, int fq, PG8_LAS unsigned char* lds, int wid, int lane) const {
;     ...
;                 const int rl = ai * 128 + wr * 64 + m * 16 + fr; const size_t row = (size_t)u.pm * 256 + rl;
;                 const float rm = 1.f / sqrtf(__hip_atomic_load(ssqm + row, __ATOMIC_RELAXED, __HIP_MEMORY_SCOPE_AGENT) * (1.f / DM) + RMS_EPS);
;                 float sh = 0.f;
; #pragma unroll
;                 for (int bj = 0; bj < 2; ++bj) {
;                     const size_t off = row * DM + colb + bj * 128;
;                     f32x4 h0, h1;
;                     if (IN16) { const u32x4 hw = *(const u32x4*)((const bf16_t*)hin + off); h0 = (f32x4){bflo(hw.x), bfhi(hw.x), bflo(hw.y), bfhi(hw.y)}; h1 = (f32x4){bflo(hw.z), bfhi(hw.z), bflo(hw.w), bfhi(hw.w)}; }
;                     else { h0 = *(const f32x4*)((const float*)hin + off); h1 = *(const f32x4*)((const float*)hin + off + 4); }
;                     h0 = h0 + acc[ai][bj][m][0] * rm * gv[bj][0]; h1 = h1 + acc[ai][bj][m][1] * rm * gv[bj][1];
;                     sh += ((h0[0] * h0[0] + h0[1] * h0[1]) + (h0[2] * h0[2] + h0[3] * h0[3])) + ((h1[0] * h1[0] + h1[1] * h1[1]) + (h1[2] * h1[2] + h1[3] * h1[3]));
;                     if (OUT16) { u32x4 w; w.x = pk_bf16(h0[0], h0[1]); w.y = pk_bf16(h0[2], h0[3]); w.z = pk_bf16(h1[0], h1[1]); w.w = pk_bf16(h1[2], h1[3]); *(u32x4*)((bf16_t*)hout + off) = w; }
;                     else { *(f32x4*)((float*)hout + off) = h0; *(f32x4*)((float*)hout + off + 4) = h1; }
;                 }
;                 if (ssqh) { sh += __shfl_xor(sh, 16); sh += __shfl_xor(sh, 32); if (fq == 0) red[rl * 4 + wc] = sh; }
.LBB0_1210:
	s_or_b64 exec, exec, s[0:1]
	v_add_u32_e32 v64, 0x80, v152
	s_waitcnt lgkmcnt(0)
	v_mov_b32_e32 v65, 0
	v_lshl_add_u64 v[66:67], s[14:15], 0, v[64:65]
	v_lshl_add_u64 v[68:69], v[66:67], 2, s[12:13]
	global_load_dword v78, v[68:69], off sc1
	v_lshlrev_b64 v[66:67], 11, v[66:67]
	v_lshl_add_u64 v[66:67], s[10:11], 0, v[66:67]
	v_lshl_add_u64 v[76:77], v[146:147], 1, v[66:67]
	global_load_dwordx4 v[68:71], v[76:77], off
	global_load_dwordx4 v[72:75], v[76:77], off offset:256
	v_mov_b32_e32 v67, 0x358637bd
	v_mov_b32_e32 v66, 0x260
	s_waitcnt vmcnt(2)
	v_fmamk_f32 v78, v78, 0x3a800000, v67
	v_rsq_f32_e32 v252, v78
	s_nop 0
	v_mul_f32_e32 v253, v78, v252
	v_mul_f32_e32 v253, v253, v252
	v_fmaak_f32 v253, -0.5, v253, 0x3fc00000
	v_mul_f32_e32 v252, v252, v253
	s_waitcnt vmcnt(1)
	v_lshlrev_b32_e32 v80, 16, v70
	v_and_b32_e32 v81, 0xffff0000, v70
	v_lshlrev_b32_e32 v78, 16, v68
	v_and_b32_e32 v79, 0xffff0000, v68
	v_lshlrev_b32_e32 v68, 16, v69
	v_and_b32_e32 v69, 0xffff0000, v69
	v_lshlrev_b32_e32 v70, 16, v71
	v_and_b32_e32 v71, 0xffff0000, v71
	s_waitcnt vmcnt(0)
	v_lshlrev_b32_e32 v82, 16, v72
	v_and_b32_e32 v83, 0xffff0000, v72
	v_lshlrev_b32_e32 v72, 16, v73
	v_and_b32_e32 v73, 0xffff0000, v73
	v_mov_b32_e32 v86, v252
	v_lshlrev_b32_e32 v84, 16, v74
	v_and_b32_e32 v85, 0xffff0000, v74
	v_lshlrev_b32_e32 v74, 16, v75
	v_and_b32_e32 v75, 0xffff0000, v75
	v_pk_mul_f32 v[60:61], v[60:61], v[86:87] op_sel_hi:[1,0]
	v_pk_mul_f32 v[62:63], v[62:63], v[86:87] op_sel_hi:[1,0]
	v_pk_mul_f32 v[56:57], v[56:57], v[86:87] op_sel_hi:[1,0]
	v_pk_mul_f32 v[58:59], v[58:59], v[86:87] op_sel_hi:[1,0]
	v_pk_mul_f32 v[52:53], v[52:53], v[86:87] op_sel_hi:[1,0]
	v_pk_mul_f32 v[54:55], v[54:55], v[86:87] op_sel_hi:[1,0]
	v_pk_mul_f32 v[48:49], v[48:49], v[86:87] op_sel_hi:[1,0]
	v_pk_mul_f32 v[50:51], v[50:51], v[86:87] op_sel_hi:[1,0]
	v_pk_fma_f32 v[62:63], v[106:107], v[62:63], v[68:69]
	v_pk_fma_f32 v[60:61], v[104:105], v[60:61], v[78:79]
	v_pk_fma_f32 v[58:59], v[102:103], v[58:59], v[70:71]
	v_pk_fma_f32 v[56:57], v[100:101], v[56:57], v[80:81]
	v_pk_fma_f32 v[54:55], v[110:111], v[54:55], v[72:73]
	v_pk_fma_f32 v[52:53], v[108:109], v[52:53], v[82:83]
	v_pk_fma_f32 v[68:69], v[98:99], v[50:51], v[74:75]
	v_pk_fma_f32 v[70:71], v[96:97], v[48:49], v[84:85]
	v_cvt_pk_bf16_f32 v48, v60, v61
	v_cvt_pk_bf16_f32 v49, v62, v63
	v_mul_f32_e32 v50, v61, v61
	v_mul_f32_e32 v51, v63, v63
	v_mul_f32_e32 v61, v57, v57
	v_mul_f32_e32 v63, v59, v59
	v_mul_f32_e32 v72, v53, v53
	v_mul_f32_e32 v73, v55, v55
	v_mul_f32_e32 v74, v71, v71
	v_mul_f32_e32 v75, v69, v69
	v_fmac_f32_e32 v50, v60, v60
	v_fmac_f32_e32 v51, v62, v62
	v_fmac_f32_e32 v61, v56, v56
	v_fmac_f32_e32 v63, v58, v58
	v_fmac_f32_e32 v72, v52, v52
	v_fmac_f32_e32 v73, v54, v54
	v_fmac_f32_e32 v74, v70, v70
	v_fmac_f32_e32 v75, v68, v68
	v_add_f32_e32 v50, v50, v51
	v_add_f32_e32 v51, v61, v63
	v_add_f32_e32 v60, v72, v73
	v_add_f32_e32 v61, v74, v75
	v_add_f32_e32 v50, v50, v51
	v_add_f32_e32 v51, v60, v61
	v_add_f32_e32 v60, v50, v51
	ds_bpermute_b32 v61, v150, v60
	v_cvt_pk_bf16_f32 v50, v56, v57
	v_cvt_pk_bf16_f32 v51, v58, v59
	global_store_dwordx4 v[76:77], v[48:51], off
	s_waitcnt lgkmcnt(0)
	s_nop 0
	v_add_f32_e32 v48, v60, v61
	ds_bpermute_b32 v49, v151, v48
	v_cvt_pk_bf16_f32 v50, v52, v53
	v_cvt_pk_bf16_f32 v51, v54, v55
	v_cvt_pk_bf16_f32 v52, v70, v71
	v_cvt_pk_bf16_f32 v53, v68, v69
	global_store_dwordx4 v[76:77], v[50:53], off offset:256
	s_and_saveexec_b64 s[0:1], s[4:5]
	s_cbranch_execz .LBB0_1212
	v_lshl_add_u32 v50, v64, 4, s22
	s_waitcnt lgkmcnt(0)
	v_add_f32_e32 v48, v48, v49
	ds_write_b32 v50, v48
.LBB0_1212:
	s_or_b64 exec, exec, s[0:1]
	v_add_u32_e32 v64, 0x90, v152
	s_waitcnt lgkmcnt(0)
	v_lshl_add_u64 v[48:49], s[14:15], 0, v[64:65]
	v_lshl_add_u64 v[50:51], v[48:49], 2, s[12:13]
	global_load_dword v58, v[50:51], off sc1
	v_lshlrev_b64 v[48:49], 11, v[48:49]
	v_lshl_add_u64 v[48:49], s[10:11], 0, v[48:49]
	v_lshl_add_u64 v[56:57], v[146:147], 1, v[48:49]
	global_load_dwordx4 v[48:51], v[56:57], off
	global_load_dwordx4 v[52:55], v[56:57], off offset:256
	s_waitcnt vmcnt(2)
	v_fmac_f32_e32 v67, 0x3a800000, v58
	v_rsq_f32_e32 v252, v67
	s_nop 0
	v_mul_f32_e32 v253, v67, v252
	v_mul_f32_e32 v253, v253, v252
	v_fmaak_f32 v253, -0.5, v253, 0x3fc00000
	v_mul_f32_e32 v252, v252, v253
	s_waitcnt vmcnt(1)
	v_and_b32_e32 v59, 0xffff0000, v48
	v_lshlrev_b32_e32 v60, 16, v50
	v_lshlrev_b32_e32 v58, 16, v48
	v_lshlrev_b32_e32 v48, 16, v49
	v_and_b32_e32 v49, 0xffff0000, v49
	v_and_b32_e32 v61, 0xffff0000, v50
	v_lshlrev_b32_e32 v50, 16, v51
	v_and_b32_e32 v51, 0xffff0000, v51
	s_waitcnt vmcnt(0)
; DI unsigned pk_bf16(float lo, float hi) { f32x2 v = {lo, hi}; bf16x2_t b = __builtin_convertvector(v, bf16x2_t); return __builtin_bit_cast(unsigned, b); }
; DI float bflo(unsigned w) { return __uint_as_float(w << 16); }
; DI float bfhi(unsigned w) { return __uint_as_float(w & 0xffff0000u); }
;     __device__ __forceinline__ void fused(f32x4 (&acc)[2][2][4][2], const pg8::Unit& u, int wr, int wc, int fr, int fq, PG8_LAS unsigned char* lds, int wid, int lane) const {
;     ...
;                 const int rl = ai * 128 + wr * 64 + m * 16 + fr; const size_t row = (size_t)u.pm * 256 + rl;
;                 const float rm = 1.f / sqrtf(__hip_atomic_load(ssqm + row, __ATOMIC_RELAXED, __HIP_MEMORY_SCOPE_AGENT) * (1.f / DM) + RMS_EPS);
;                 float sh = 0.f;
; #pragma unroll
;                 for (int bj = 0; bj < 2; ++bj) {
;                     const size_t off = row * DM + colb + bj * 128;
;                     f32x4 h0, h1;
;                     if (IN16) { const u32x4 hw = *(const u32x4*)((const bf16_t*)hin + off); h0 = (f32x4){bflo(hw.x), bfhi(hw.x), bflo(hw.y), bfhi(hw.y)}; h1 = (f32x4){bflo(hw.z), bfhi(hw.z), bflo(hw.w), bfhi(hw.w)}; }
;                     else { h0 = *(const f32x4*)((const float*)hin + off); h1 = *(const f32x4*)((const float*)hin + off + 4); }
;                     h0 = h0 + acc[ai][bj][m][0] * rm * gv[bj][0]; h1 = h1 + acc[ai][bj][m][1] * rm * gv[bj][1];
;                     sh += ((h0[0] * h0[0] + h0[1] * h0[1]) + (h0[2] * h0[2] + h0[3] * h0[3])) + ((h1[0] * h1[0] + h1[1] * h1[1]) + (h1[2] * h1[2] + h1[3] * h1[3]));
;                     if (OUT16) { u32x4 w; w.x = pk_bf16(h0[0], h0[1]); w.y = pk_bf16(h0[2], h0[3]); w.z = pk_bf16(h1[0], h1[1]); w.w = pk_bf16(h1[2], h1[3]); *(u32x4*)((bf16_t*)hout + off) = w; }
;                     else { *(f32x4*)((float*)hout + off) = h0; *(f32x4*)((float*)hout + off + 4) = h1; }
;                 }
;                 if (ssqh) { sh += __shfl_xor(sh, 16); sh += __shfl_xor(sh, 32); if (fq == 0) red[rl * 4 + wc] = sh; }
	v_lshlrev_b32_e32 v62, 16, v52
	v_and_b32_e32 v63, 0xffff0000, v52
	v_lshlrev_b32_e32 v52, 16, v53
	v_and_b32_e32 v53, 0xffff0000, v53
	v_mov_b32_e32 v66, v252
	v_lshlrev_b32_e32 v68, 16, v54
	v_and_b32_e32 v69, 0xffff0000, v54
	v_lshlrev_b32_e32 v54, 16, v55
	v_and_b32_e32 v55, 0xffff0000, v55
	v_pk_mul_f32 v[44:45], v[44:45], v[66:67] op_sel_hi:[1,0]
	v_pk_mul_f32 v[46:47], v[46:47], v[66:67] op_sel_hi:[1,0]
	v_pk_mul_f32 v[40:41], v[40:41], v[66:67] op_sel_hi:[1,0]
	v_pk_mul_f32 v[42:43], v[42:43], v[66:67] op_sel_hi:[1,0]
	v_pk_mul_f32 v[36:37], v[36:37], v[66:67] op_sel_hi:[1,0]
	v_pk_mul_f32 v[38:39], v[38:39], v[66:67] op_sel_hi:[1,0]
	v_pk_mul_f32 v[32:33], v[32:33], v[66:67] op_sel_hi:[1,0]
	v_pk_mul_f32 v[34:35], v[34:35], v[66:67] op_sel_hi:[1,0]
	v_pk_fma_f32 v[46:47], v[106:107], v[46:47], v[48:49]
	v_pk_fma_f32 v[44:45], v[104:105], v[44:45], v[58:59]
	v_pk_fma_f32 v[42:43], v[102:103], v[42:43], v[50:51]
	v_pk_fma_f32 v[40:41], v[100:101], v[40:41], v[60:61]
	v_pk_fma_f32 v[38:39], v[110:111], v[38:39], v[52:53]
	v_pk_fma_f32 v[36:37], v[108:109], v[36:37], v[62:63]
	v_pk_fma_f32 v[48:49], v[98:99], v[34:35], v[54:55]
	v_pk_fma_f32 v[50:51], v[96:97], v[32:33], v[68:69]
	v_cvt_pk_bf16_f32 v32, v44, v45
	v_cvt_pk_bf16_f32 v33, v46, v47
	v_mul_f32_e32 v34, v45, v45
	v_mul_f32_e32 v35, v47, v47
	v_mul_f32_e32 v45, v41, v41
	v_mul_f32_e32 v47, v43, v43
	v_mul_f32_e32 v52, v37, v37
	v_mul_f32_e32 v53, v39, v39
	v_mul_f32_e32 v54, v51, v51
	v_mul_f32_e32 v55, v49, v49
	v_fmac_f32_e32 v34, v44, v44
	v_fmac_f32_e32 v35, v46, v46
	v_fmac_f32_e32 v45, v40, v40
	v_fmac_f32_e32 v47, v42, v42
	v_fmac_f32_e32 v52, v36, v36
	v_fmac_f32_e32 v53, v38, v38
	v_fmac_f32_e32 v54, v50, v50
	v_fmac_f32_e32 v55, v48, v48
	v_add_f32_e32 v34, v34, v35
	v_add_f32_e32 v35, v45, v47
	v_add_f32_e32 v44, v52, v53
	v_add_f32_e32 v45, v54, v55
	v_add_f32_e32 v34, v34, v35
	v_add_f32_e32 v35, v44, v45
	v_add_f32_e32 v44, v34, v35
	ds_bpermute_b32 v45, v150, v44
	v_cvt_pk_bf16_f32 v34, v40, v41
	v_cvt_pk_bf16_f32 v35, v42, v43
	global_store_dwordx4 v[56:57], v[32:35], off
	s_waitcnt lgkmcnt(0)
	s_nop 0
	v_add_f32_e32 v32, v44, v45
	ds_bpermute_b32 v33, v151, v32
	v_cvt_pk_bf16_f32 v34, v36, v37
	v_cvt_pk_bf16_f32 v35, v38, v39
	v_cvt_pk_bf16_f32 v36, v50, v51
	v_cvt_pk_bf16_f32 v37, v48, v49
	global_store_dwordx4 v[56:57], v[34:37], off offset:256
	s_and_saveexec_b64 s[0:1], s[4:5]
	s_cbranch_execz .LBB0_1214
	v_lshl_add_u32 v34, v64, 4, s22
	s_waitcnt lgkmcnt(0)
	v_add_f32_e32 v32, v32, v33
	ds_write_b32 v34, v32
.LBB0_1214:
	s_or_b64 exec, exec, s[0:1]
	v_add_u32_e32 v32, 0xa0, v152
	s_waitcnt lgkmcnt(0)
	v_mov_b32_e32 v33, 0
	v_lshl_add_u64 v[34:35], s[14:15], 0, v[32:33]
	v_lshl_add_u64 v[36:37], v[34:35], 2, s[12:13]
	global_load_dword v46, v[36:37], off sc1
	v_lshlrev_b64 v[34:35], 11, v[34:35]
	v_lshl_add_u64 v[34:35], s[10:11], 0, v[34:35]
	v_lshl_add_u64 v[44:45], v[146:147], 1, v[34:35]
	global_load_dwordx4 v[36:39], v[44:45], off
	global_load_dwordx4 v[40:43], v[44:45], off offset:256
	v_mov_b32_e32 v35, 0x358637bd
	v_mov_b32_e32 v34, 0x260
	s_waitcnt vmcnt(2)
	v_fmamk_f32 v46, v46, 0x3a800000, v35
	v_rsq_f32_e32 v252, v46
	s_nop 0
	v_mul_f32_e32 v253, v46, v252
	v_mul_f32_e32 v253, v253, v252
	v_fmaak_f32 v253, -0.5, v253, 0x3fc00000
	v_mul_f32_e32 v252, v252, v253
	s_waitcnt vmcnt(1)
	v_lshlrev_b32_e32 v48, 16, v38
	v_and_b32_e32 v49, 0xffff0000, v38
	v_lshlrev_b32_e32 v46, 16, v36
	v_and_b32_e32 v47, 0xffff0000, v36
	v_lshlrev_b32_e32 v36, 16, v37
	v_and_b32_e32 v37, 0xffff0000, v37
	v_lshlrev_b32_e32 v38, 16, v39
	v_and_b32_e32 v39, 0xffff0000, v39
	s_waitcnt vmcnt(0)
	v_lshlrev_b32_e32 v50, 16, v40
	v_and_b32_e32 v51, 0xffff0000, v40
	v_lshlrev_b32_e32 v40, 16, v41
	v_and_b32_e32 v41, 0xffff0000, v41
	v_mov_b32_e32 v54, v252
	v_lshlrev_b32_e32 v52, 16, v42
	v_and_b32_e32 v53, 0xffff0000, v42
	v_lshlrev_b32_e32 v42, 16, v43
	v_and_b32_e32 v43, 0xffff0000, v43
	v_pk_mul_f32 v[28:29], v[28:29], v[54:55] op_sel_hi:[1,0]
	v_pk_mul_f32 v[30:31], v[30:31], v[54:55] op_sel_hi:[1,0]
	v_pk_mul_f32 v[24:25], v[24:25], v[54:55] op_sel_hi:[1,0]
	v_pk_mul_f32 v[26:27], v[26:27], v[54:55] op_sel_hi:[1,0]
	v_pk_mul_f32 v[20:21], v[20:21], v[54:55] op_sel_hi:[1,0]
	v_pk_mul_f32 v[22:23], v[22:23], v[54:55] op_sel_hi:[1,0]
	v_pk_mul_f32 v[16:17], v[16:17], v[54:55] op_sel_hi:[1,0]
	v_pk_mul_f32 v[18:19], v[18:19], v[54:55] op_sel_hi:[1,0]
	v_pk_fma_f32 v[30:31], v[106:107], v[30:31], v[36:37]
	v_pk_fma_f32 v[28:29], v[104:105], v[28:29], v[46:47]
	v_pk_fma_f32 v[26:27], v[102:103], v[26:27], v[38:39]
	v_pk_fma_f32 v[24:25], v[100:101], v[24:25], v[48:49]
	v_pk_fma_f32 v[22:23], v[110:111], v[22:23], v[40:41]
	v_pk_fma_f32 v[20:21], v[108:109], v[20:21], v[50:51]
	v_pk_fma_f32 v[36:37], v[98:99], v[18:19], v[42:43]
	v_pk_fma_f32 v[38:39], v[96:97], v[16:17], v[52:53]
	v_cvt_pk_bf16_f32 v16, v28, v29
	v_cvt_pk_bf16_f32 v17, v30, v31
	v_mul_f32_e32 v18, v29, v29
	v_mul_f32_e32 v19, v31, v31
	v_mul_f32_e32 v29, v25, v25
	v_mul_f32_e32 v31, v27, v27
	v_mul_f32_e32 v40, v21, v21
	v_mul_f32_e32 v41, v23, v23
	v_mul_f32_e32 v42, v39, v39
	v_mul_f32_e32 v43, v37, v37
	v_fmac_f32_e32 v18, v28, v28
	v_fmac_f32_e32 v19, v30, v30
	v_fmac_f32_e32 v29, v24, v24
	v_fmac_f32_e32 v31, v26, v26
	v_fmac_f32_e32 v40, v20, v20
	v_fmac_f32_e32 v41, v22, v22
	v_fmac_f32_e32 v42, v38, v38
	v_fmac_f32_e32 v43, v36, v36
	v_add_f32_e32 v18, v18, v19
	v_add_f32_e32 v19, v29, v31
	v_add_f32_e32 v28, v40, v41
	v_add_f32_e32 v29, v42, v43
	v_add_f32_e32 v18, v18, v19
	v_add_f32_e32 v19, v28, v29
	v_add_f32_e32 v28, v18, v19
	ds_bpermute_b32 v29, v150, v28
	v_cvt_pk_bf16_f32 v18, v24, v25
	v_cvt_pk_bf16_f32 v19, v26, v27
	global_store_dwordx4 v[44:45], v[16:19], off
	s_waitcnt lgkmcnt(0)
	s_nop 0
	v_add_f32_e32 v16, v28, v29
	ds_bpermute_b32 v17, v151, v16
	v_cvt_pk_bf16_f32 v18, v20, v21
	v_cvt_pk_bf16_f32 v19, v22, v23
	v_cvt_pk_bf16_f32 v20, v38, v39
	v_cvt_pk_bf16_f32 v21, v36, v37
	global_store_dwordx4 v[44:45], v[18:21], off offset:256
	s_and_saveexec_b64 s[0:1], s[4:5]
	s_cbranch_execz .LBB0_1216
	v_lshl_add_u32 v18, v32, 4, s22
	s_waitcnt lgkmcnt(0)
	v_add_f32_e32 v16, v16, v17
	ds_write_b32 v18, v16
; DI unsigned pk_bf16(float lo, float hi) { f32x2 v = {lo, hi}; bf16x2_t b = __builtin_convertvector(v, bf16x2_t); return __builtin_bit_cast(unsigned, b); }
; DI float bflo(unsigned w) { return __uint_as_float(w << 16); }
; DI float bfhi(unsigned w) { return __uint_as_float(w & 0xffff0000u); }
;     __device__ __forceinline__ void fused(f32x4 (&acc)[2][2][4][2], const pg8::Unit& u, int wr, int wc, int fr, int fq, PG8_LAS unsigned char* lds, int wid, int lane) const {
;     ...
;                 const int rl = ai * 128 + wr * 64 + m * 16 + fr; const size_t row = (size_t)u.pm * 256 + rl;
;                 const float rm = 1.f / sqrtf(__hip_atomic_load(ssqm + row, __ATOMIC_RELAXED, __HIP_MEMORY_SCOPE_AGENT) * (1.f / DM) + RMS_EPS);
;                 float sh = 0.f;
; #pragma unroll
;                 for (int bj = 0; bj < 2; ++bj) {
;                     const size_t off = row * DM + colb + bj * 128;
;                     f32x4 h0, h1;
;                     if (IN16) { const u32x4 hw = *(const u32x4*)((const bf16_t*)hin + off); h0 = (f32x4){bflo(hw.x), bfhi(hw.x), bflo(hw.y), bfhi(hw.y)}; h1 = (f32x4){bflo(hw.z), bfhi(hw.z), bflo(hw.w), bfhi(hw.w)}; }
;                     else { h0 = *(const f32x4*)((const float*)hin + off); h1 = *(const f32x4*)((const float*)hin + off + 4); }
;                     h0 = h0 + acc[ai][bj][m][0] * rm * gv[bj][0]; h1 = h1 + acc[ai][bj][m][1] * rm * gv[bj][1];
;                     sh += ((h0[0] * h0[0] + h0[1] * h0[1]) + (h0[2] * h0[2] + h0[3] * h0[3])) + ((h1[0] * h1[0] + h1[1] * h1[1]) + (h1[2] * h1[2] + h1[3] * h1[3]));
;                     if (OUT16) { u32x4 w; w.x = pk_bf16(h0[0], h0[1]); w.y = pk_bf16(h0[2], h0[3]); w.z = pk_bf16(h1[0], h1[1]); w.w = pk_bf16(h1[2], h1[3]); *(u32x4*)((bf16_t*)hout + off) = w; }
;                     else { *(f32x4*)((float*)hout + off) = h0; *(f32x4*)((float*)hout + off + 4) = h1; }
;                 }
;                 if (ssqh) { sh += __shfl_xor(sh, 16); sh += __shfl_xor(sh, 32); if (fq == 0) red[rl * 4 + wc] = sh; }
.LBB0_1216:
	s_or_b64 exec, exec, s[0:1]
	v_add_u32_e32 v32, 0xb0, v152
	s_waitcnt lgkmcnt(0)
	v_lshl_add_u64 v[16:17], s[14:15], 0, v[32:33]
	v_lshl_add_u64 v[18:19], v[16:17], 2, s[12:13]
	global_load_dword v26, v[18:19], off sc1
	v_lshlrev_b64 v[16:17], 11, v[16:17]
	v_lshl_add_u64 v[16:17], s[10:11], 0, v[16:17]
	v_lshl_add_u64 v[24:25], v[146:147], 1, v[16:17]
	global_load_dwordx4 v[16:19], v[24:25], off
	global_load_dwordx4 v[20:23], v[24:25], off offset:256
	s_waitcnt vmcnt(2)
	v_fmac_f32_e32 v35, 0x3a800000, v26
	v_rsq_f32_e32 v252, v35
	s_nop 0
	v_mul_f32_e32 v253, v35, v252
	v_mul_f32_e32 v253, v253, v252
	v_fmaak_f32 v253, -0.5, v253, 0x3fc00000
	v_mul_f32_e32 v252, v252, v253
	s_waitcnt vmcnt(1)
	v_and_b32_e32 v27, 0xffff0000, v16
	v_lshlrev_b32_e32 v28, 16, v18
	v_lshlrev_b32_e32 v26, 16, v16
	v_lshlrev_b32_e32 v16, 16, v17
	v_and_b32_e32 v17, 0xffff0000, v17
	v_and_b32_e32 v29, 0xffff0000, v18
	v_lshlrev_b32_e32 v18, 16, v19
	v_and_b32_e32 v19, 0xffff0000, v19
	s_waitcnt vmcnt(0)
	v_lshlrev_b32_e32 v30, 16, v20
	v_and_b32_e32 v31, 0xffff0000, v20
	v_lshlrev_b32_e32 v20, 16, v21
	v_and_b32_e32 v21, 0xffff0000, v21
	v_mov_b32_e32 v34, v252
	v_lshlrev_b32_e32 v36, 16, v22
	v_and_b32_e32 v37, 0xffff0000, v22
	v_lshlrev_b32_e32 v22, 16, v23
	v_and_b32_e32 v23, 0xffff0000, v23
	v_pk_mul_f32 v[12:13], v[12:13], v[34:35] op_sel_hi:[1,0]
	v_pk_mul_f32 v[14:15], v[14:15], v[34:35] op_sel_hi:[1,0]
	v_pk_mul_f32 v[8:9], v[8:9], v[34:35] op_sel_hi:[1,0]
	v_pk_mul_f32 v[10:11], v[10:11], v[34:35] op_sel_hi:[1,0]
	v_pk_mul_f32 v[4:5], v[4:5], v[34:35] op_sel_hi:[1,0]
	v_pk_mul_f32 v[6:7], v[6:7], v[34:35] op_sel_hi:[1,0]
	v_pk_mul_f32 v[0:1], v[0:1], v[34:35] op_sel_hi:[1,0]
	v_pk_mul_f32 v[2:3], v[2:3], v[34:35] op_sel_hi:[1,0]
	v_pk_fma_f32 v[14:15], v[106:107], v[14:15], v[16:17]
	v_pk_fma_f32 v[12:13], v[104:105], v[12:13], v[26:27]
	v_pk_fma_f32 v[10:11], v[102:103], v[10:11], v[18:19]
	v_pk_fma_f32 v[8:9], v[100:101], v[8:9], v[28:29]
	v_pk_fma_f32 v[6:7], v[110:111], v[6:7], v[20:21]
	v_pk_fma_f32 v[4:5], v[108:109], v[4:5], v[30:31]
	v_pk_fma_f32 v[16:17], v[98:99], v[2:3], v[22:23]
	v_pk_fma_f32 v[18:19], v[96:97], v[0:1], v[36:37]
	v_cvt_pk_bf16_f32 v0, v12, v13
	v_cvt_pk_bf16_f32 v1, v14, v15
	v_mul_f32_e32 v2, v13, v13
	v_mul_f32_e32 v3, v15, v15
	v_mul_f32_e32 v13, v9, v9
	v_mul_f32_e32 v15, v11, v11
	v_mul_f32_e32 v20, v5, v5
	v_mul_f32_e32 v21, v7, v7
	v_mul_f32_e32 v22, v19, v19
	v_mul_f32_e32 v23, v17, v17
	v_fmac_f32_e32 v2, v12, v12
	v_fmac_f32_e32 v3, v14, v14
	v_fmac_f32_e32 v13, v8, v8
	v_fmac_f32_e32 v15, v10, v10
	v_fmac_f32_e32 v20, v4, v4
	v_fmac_f32_e32 v21, v6, v6
	v_fmac_f32_e32 v22, v18, v18
	v_fmac_f32_e32 v23, v16, v16
	v_add_f32_e32 v2, v2, v3
	v_add_f32_e32 v3, v13, v15
	v_add_f32_e32 v12, v20, v21
	v_add_f32_e32 v13, v22, v23
	v_add_f32_e32 v2, v2, v3
	v_add_f32_e32 v3, v12, v13
	v_add_f32_e32 v12, v2, v3
	ds_bpermute_b32 v13, v150, v12
	v_cvt_pk_bf16_f32 v2, v8, v9
	v_cvt_pk_bf16_f32 v3, v10, v11
	global_store_dwordx4 v[24:25], v[0:3], off
	s_waitcnt lgkmcnt(0)
	s_nop 0
	v_add_f32_e32 v0, v12, v13
	ds_bpermute_b32 v1, v151, v0
	v_cvt_pk_bf16_f32 v2, v4, v5
	v_cvt_pk_bf16_f32 v3, v6, v7
	v_cvt_pk_bf16_f32 v4, v18, v19
	v_cvt_pk_bf16_f32 v5, v16, v17
	global_store_dwordx4 v[24:25], v[2:5], off offset:256
	s_and_saveexec_b64 s[0:1], s[4:5]
	s_cbranch_execz .LBB0_1218
	v_lshl_add_u32 v2, v32, 4, s22
	s_waitcnt lgkmcnt(0)
	v_add_f32_e32 v0, v0, v1
	ds_write_b32 v2, v0

; DI unsigned pk_bf16(float lo, float hi) { f32x2 v = {lo, hi}; bf16x2_t b = __builtin_convertvector(v, bf16x2_t); return __builtin_bit_cast(unsigned, b); }
; DI float bflo(unsigned w) { return __uint_as_float(w << 16); }
; DI float bfhi(unsigned w) { return __uint_as_float(w & 0xffff0000u); }
;     __device__ __forceinline__ void fused(f32x4 (&acc)[2][2][4][2], const pg8::Unit& u, int wr, int wc, int fr, int fq, PG8_LAS unsigned char* lds, int wid, int lane) const {
;     ...
;         const int colb = u.pn * 256 + wc * 32 + 8 * fq;
;         f32x4 gv[2][2];
; #pragma unroll
;         for (int bj = 0; bj < 2; ++bj)
; #pragma unroll
;             for (int n = 0; n < 2; ++n) gv[bj][n] = *(const f32x4*)(gA + colb + bj * 128 + 4 * n);
; #pragma unroll
;         for (int ai = 0; ai < 2; ++ai)
; #pragma unroll
;             for (int m = 0; m < 4; ++m) {
;                 const int rl = ai * 128 + wr * 64 + m * 16 + fr; const size_t row = (size_t)u.pm * 256 + rl;
;                 const float rm = 1.f / sqrtf(__hip_atomic_load(ssqm + row, __ATOMIC_RELAXED, __HIP_MEMORY_SCOPE_AGENT) * (1.f / DM) + RMS_EPS);
;                 float sh = 0.f;
; #pragma unroll
;                 for (int bj = 0; bj < 2; ++bj) {
;                     const size_t off = row * DM + colb + bj * 128;
;                     f32x4 h0, h1;
;                     if (IN16) { const u32x4 hw = *(const u32x4*)((const bf16_t*)hin + off); h0 = (f32x4){bflo(hw.x), bfhi(hw.x), bflo(hw.y), bfhi(hw.y)}; h1 = (f32x4){bflo(hw.z), bfhi(hw.z), bflo(hw.w), bfhi(hw.w)}; }
;                     else { h0 = *(const f32x4*)((const float*)hin + off); h1 = *(const f32x4*)((const float*)hin + off + 4); }
;                     h0 = h0 + acc[ai][bj][m][0] * rm * gv[bj][0]; h1 = h1 + acc[ai][bj][m][1] * rm * gv[bj][1];
;                     sh += ((h0[0] * h0[0] + h0[1] * h0[1]) + (h0[2] * h0[2] + h0[3] * h0[3])) + ((h1[0] * h1[0] + h1[1] * h1[1]) + (h1[2] * h1[2] + h1[3] * h1[3]));
;                     if (OUT16) { u32x4 w; w.x = pk_bf16(h0[0], h0[1]); w.y = pk_bf16(h0[2], h0[3]); w.z = pk_bf16(h1[0], h1[1]); w.w = pk_bf16(h1[2], h1[3]); *(u32x4*)((bf16_t*)hout + off) = w; }
;                     else { *(f32x4*)((float*)hout + off) = h0; *(f32x4*)((float*)hout + off + 4) = h1; }
;                 }
;                 if (ssqh) { sh += __shfl_xor(sh, 16); sh += __shfl_xor(sh, 32); if (fq == 0) red[rl * 4 + wc] = sh; }
.LBB0_1393:
	s_or_b64 exec, exec, s[2:3]
	s_lshl_b32 s1, s1, 5
	s_lshl_b32 s0, s0, 8
	s_or_b32 s0, s0, s1
	v_mov_b32_e32 v159, 0
	v_or_b32_e32 v156, s0, v160
	s_lshl_b64 s[18:19], s[16:17], 8
	v_mov_b32_e32 v153, v159
	v_ashrrev_i32_e32 v157, 31, v156
	v_lshl_add_u64 v[164:165], s[18:19], 0, v[152:153]
	v_lshl_add_u64 v[108:109], v[156:157], 2, s[14:15]
	v_lshl_add_u64 v[166:167], v[164:165], 2, s[12:13]
	s_barrier
	global_load_dwordx4 v[100:103], v[108:109], off offset:16
	global_load_dwordx4 v[104:107], v[108:109], off
	global_load_dwordx4 v[96:99], v[108:109], off offset:528
	s_nop 0
	global_load_dwordx4 v[108:111], v[108:109], off offset:512
	v_lshlrev_b64 v[164:165], 11, v[164:165]
	global_load_dword v158, v[166:167], off sc1
	v_lshl_add_u64 v[164:165], s[10:11], 0, v[164:165]
	v_lshl_add_u64 v[172:173], v[156:157], 1, v[164:165]
	global_load_dwordx4 v[164:167], v[172:173], off
	global_load_dwordx4 v[168:171], v[172:173], off offset:256
	v_mov_b32_e32 v153, 0x358637bd
	s_mov_b32 s2, 0xf800000
	v_mov_b32_e32 v151, 0x260
	s_waitcnt vmcnt(2)
	v_fmamk_f32 v158, v158, 0x3a800000, v153
	v_rsq_f32_e32 v252, v158
	s_nop 0
	v_mul_f32_e32 v253, v158, v252
	v_mul_f32_e32 v253, v253, v252
	v_fmaak_f32 v253, -0.5, v253, 0x3fc00000
	v_mul_f32_e32 v252, v252, v253
	s_waitcnt vmcnt(1)
	v_lshlrev_b32_e32 v174, 16, v164
	v_and_b32_e32 v175, 0xffff0000, v164
	v_lshlrev_b32_e32 v164, 16, v165
	v_and_b32_e32 v165, 0xffff0000, v165
	v_lshlrev_b32_e32 v176, 16, v166
	v_and_b32_e32 v177, 0xffff0000, v166
	v_lshlrev_b32_e32 v166, 16, v167
	v_and_b32_e32 v167, 0xffff0000, v167
	s_waitcnt vmcnt(0)
	v_lshlrev_b32_e32 v178, 16, v168
	v_and_b32_e32 v179, 0xffff0000, v168
	v_lshlrev_b32_e32 v168, 16, v169
	v_and_b32_e32 v169, 0xffff0000, v169
	v_mov_b32_e32 v158, v252
	v_lshlrev_b32_e32 v180, 16, v170
	v_and_b32_e32 v181, 0xffff0000, v170
	v_lshlrev_b32_e32 v170, 16, v171
	v_and_b32_e32 v171, 0xffff0000, v171
	v_pk_mul_f32 v[140:141], v[140:141], v[158:159] op_sel_hi:[1,0]
	v_pk_mul_f32 v[142:143], v[142:143], v[158:159] op_sel_hi:[1,0]
	v_pk_mul_f32 v[136:137], v[136:137], v[158:159] op_sel_hi:[1,0]
	v_pk_mul_f32 v[138:139], v[138:139], v[158:159] op_sel_hi:[1,0]
	v_pk_mul_f32 v[132:133], v[132:133], v[158:159] op_sel_hi:[1,0]
	v_pk_mul_f32 v[134:135], v[134:135], v[158:159] op_sel_hi:[1,0]
	v_pk_mul_f32 v[128:129], v[128:129], v[158:159] op_sel_hi:[1,0]
	v_pk_mul_f32 v[130:131], v[130:131], v[158:159] op_sel_hi:[1,0]
	v_pk_fma_f32 v[142:143], v[106:107], v[142:143], v[164:165]
	v_pk_fma_f32 v[140:141], v[104:105], v[140:141], v[174:175]
	v_pk_fma_f32 v[138:139], v[102:103], v[138:139], v[166:167]
	v_pk_fma_f32 v[136:137], v[100:101], v[136:137], v[176:177]
	v_pk_fma_f32 v[134:135], v[110:111], v[134:135], v[168:169]
	v_pk_fma_f32 v[132:133], v[108:109], v[132:133], v[178:179]
	v_pk_fma_f32 v[164:165], v[98:99], v[130:131], v[170:171]
	v_pk_fma_f32 v[166:167], v[96:97], v[128:129], v[180:181]
	v_cvt_pk_bf16_f32 v128, v140, v141
	v_cvt_pk_bf16_f32 v129, v142, v143
	v_mul_f32_e32 v130, v141, v141
	v_mul_f32_e32 v131, v143, v143
	v_mul_f32_e32 v141, v137, v137
	v_mul_f32_e32 v143, v139, v139
	v_mul_f32_e32 v158, v133, v133
	v_mul_f32_e32 v168, v135, v135
	v_mul_f32_e32 v169, v167, v167
	v_mul_f32_e32 v170, v165, v165
	v_fmac_f32_e32 v130, v140, v140
	v_fmac_f32_e32 v131, v142, v142
	v_fmac_f32_e32 v141, v136, v136
	v_fmac_f32_e32 v143, v138, v138
	v_fmac_f32_e32 v158, v132, v132
	v_fmac_f32_e32 v168, v134, v134
	v_fmac_f32_e32 v169, v166, v166
	v_fmac_f32_e32 v170, v164, v164
	v_add_f32_e32 v130, v130, v131
	v_add_f32_e32 v131, v141, v143
	v_add_f32_e32 v140, v158, v168
	v_add_f32_e32 v141, v169, v170
	v_add_f32_e32 v130, v130, v131
	v_add_f32_e32 v131, v140, v141
	v_add_f32_e32 v140, v130, v131
	ds_bpermute_b32 v141, v145, v140
	v_cvt_pk_bf16_f32 v130, v136, v137
	v_cvt_pk_bf16_f32 v131, v138, v139
	global_store_dwordx4 v[172:173], v[128:131], off
	s_waitcnt lgkmcnt(0)
	s_nop 0
	v_add_f32_e32 v128, v140, v141
	ds_bpermute_b32 v129, v147, v128
	v_cvt_pk_bf16_f32 v130, v132, v133
	v_cvt_pk_bf16_f32 v131, v134, v135
	v_cvt_pk_bf16_f32 v132, v166, v167
	v_cvt_pk_bf16_f32 v133, v164, v165
	global_store_dwordx4 v[172:173], v[130:133], off offset:256
	s_and_saveexec_b64 s[0:1], s[4:5]
	s_cbranch_execz .LBB0_1395
	v_lshl_add_u32 v130, v152, 4, s24
	s_waitcnt lgkmcnt(0)
	v_add_f32_e32 v128, v128, v129
	ds_write_b32 v130, v128
; DI unsigned pk_bf16(float lo, float hi) { f32x2 v = {lo, hi}; bf16x2_t b = __builtin_convertvector(v, bf16x2_t); return __builtin_bit_cast(unsigned, b); }
; DI float bflo(unsigned w) { return __uint_as_float(w << 16); }
; DI float bfhi(unsigned w) { return __uint_as_float(w & 0xffff0000u); }
;     __device__ __forceinline__ void fused(f32x4 (&acc)[2][2][4][2], const pg8::Unit& u, int wr, int wc, int fr, int fq, PG8_LAS unsigned char* lds, int wid, int lane) const {
;     ...
;         const int colb = u.pn * 256 + wc * 32 + 8 * fq;
;         f32x4 gv[2][2];
; #pragma unroll
;         for (int bj = 0; bj < 2; ++bj)
; #pragma unroll
;             for (int n = 0; n < 2; ++n) gv[bj][n] = *(const f32x4*)(gA + colb + bj * 128 + 4 * n);
; #pragma unroll
;         for (int ai = 0; ai < 2; ++ai)
; #pragma unroll
;             for (int m = 0; m < 4; ++m) {
;                 const int rl = ai * 128 + wr * 64 + m * 16 + fr; const size_t row = (size_t)u.pm * 256 + rl;
;                 const float rm = 1.f / sqrtf(__hip_atomic_load(ssqm + row, __ATOMIC_RELAXED, __HIP_MEMORY_SCOPE_AGENT) * (1.f / DM) + RMS_EPS);
;                 float sh = 0.f;
; #pragma unroll
;                 for (int bj = 0; bj < 2; ++bj) {
;                     const size_t off = row * DM + colb + bj * 128;
;                     f32x4 h0, h1;
;                     if (IN16) { const u32x4 hw = *(const u32x4*)((const bf16_t*)hin + off); h0 = (f32x4){bflo(hw.x), bfhi(hw.x), bflo(hw.y), bfhi(hw.y)}; h1 = (f32x4){bflo(hw.z), bfhi(hw.z), bflo(hw.w), bfhi(hw.w)}; }
;                     else { h0 = *(const f32x4*)((const float*)hin + off); h1 = *(const f32x4*)((const float*)hin + off + 4); }
;                     h0 = h0 + acc[ai][bj][m][0] * rm * gv[bj][0]; h1 = h1 + acc[ai][bj][m][1] * rm * gv[bj][1];
;                     sh += ((h0[0] * h0[0] + h0[1] * h0[1]) + (h0[2] * h0[2] + h0[3] * h0[3])) + ((h1[0] * h1[0] + h1[1] * h1[1]) + (h1[2] * h1[2] + h1[3] * h1[3]));
;                     if (OUT16) { u32x4 w; w.x = pk_bf16(h0[0], h0[1]); w.y = pk_bf16(h0[2], h0[3]); w.z = pk_bf16(h1[0], h1[1]); w.w = pk_bf16(h1[2], h1[3]); *(u32x4*)((bf16_t*)hout + off) = w; }
;                     else { *(f32x4*)((float*)hout + off) = h0; *(f32x4*)((float*)hout + off + 4) = h1; }
;                 }
;                 if (ssqh) { sh += __shfl_xor(sh, 16); sh += __shfl_xor(sh, 32); if (fq == 0) red[rl * 4 + wc] = sh; }
.LBB0_1395:
	s_or_b64 exec, exec, s[0:1]
	v_or_b32_e32 v158, 16, v152
	s_waitcnt lgkmcnt(0)
	v_lshl_add_u64 v[128:129], s[18:19], 0, v[158:159]
	v_lshl_add_u64 v[130:131], v[128:129], 2, s[12:13]
	global_load_dword v138, v[130:131], off sc1
	v_lshlrev_b64 v[128:129], 11, v[128:129]
	v_lshl_add_u64 v[128:129], s[10:11], 0, v[128:129]
	v_lshl_add_u64 v[136:137], v[156:157], 1, v[128:129]
	global_load_dwordx4 v[128:131], v[136:137], off
	global_load_dwordx4 v[132:135], v[136:137], off offset:256
	s_waitcnt vmcnt(2)
	v_fmac_f32_e32 v153, 0x3a800000, v138
	v_rsq_f32_e32 v252, v153
	s_nop 0
	v_mul_f32_e32 v253, v153, v252
	v_mul_f32_e32 v253, v253, v252
	v_fmaak_f32 v253, -0.5, v253, 0x3fc00000
	v_mul_f32_e32 v252, v252, v253
	s_waitcnt vmcnt(1)
	v_and_b32_e32 v139, 0xffff0000, v128
	v_lshlrev_b32_e32 v140, 16, v130
	v_lshlrev_b32_e32 v138, 16, v128
	v_lshlrev_b32_e32 v128, 16, v129
	v_and_b32_e32 v129, 0xffff0000, v129
	v_and_b32_e32 v141, 0xffff0000, v130
	v_lshlrev_b32_e32 v130, 16, v131
	v_and_b32_e32 v131, 0xffff0000, v131
	s_waitcnt vmcnt(0)
	v_lshlrev_b32_e32 v142, 16, v132
	v_and_b32_e32 v143, 0xffff0000, v132
	v_lshlrev_b32_e32 v132, 16, v133
	v_and_b32_e32 v133, 0xffff0000, v133
	v_mov_b32_e32 v166, v252
	v_lshlrev_b32_e32 v164, 16, v134
	v_and_b32_e32 v165, 0xffff0000, v134
	v_lshlrev_b32_e32 v134, 16, v135
	v_and_b32_e32 v135, 0xffff0000, v135
	v_pk_mul_f32 v[124:125], v[124:125], v[166:167] op_sel_hi:[1,0]
	v_pk_mul_f32 v[126:127], v[126:127], v[166:167] op_sel_hi:[1,0]
	v_pk_mul_f32 v[120:121], v[120:121], v[166:167] op_sel_hi:[1,0]
	v_pk_mul_f32 v[122:123], v[122:123], v[166:167] op_sel_hi:[1,0]
	v_pk_mul_f32 v[116:117], v[116:117], v[166:167] op_sel_hi:[1,0]
	v_pk_mul_f32 v[118:119], v[118:119], v[166:167] op_sel_hi:[1,0]
	v_pk_mul_f32 v[112:113], v[112:113], v[166:167] op_sel_hi:[1,0]
	v_pk_mul_f32 v[114:115], v[114:115], v[166:167] op_sel_hi:[1,0]
	v_pk_fma_f32 v[126:127], v[106:107], v[126:127], v[128:129]
	v_pk_fma_f32 v[124:125], v[104:105], v[124:125], v[138:139]
	v_pk_fma_f32 v[122:123], v[102:103], v[122:123], v[130:131]
	v_pk_fma_f32 v[120:121], v[100:101], v[120:121], v[140:141]
	v_pk_fma_f32 v[118:119], v[110:111], v[118:119], v[132:133]
	v_pk_fma_f32 v[116:117], v[108:109], v[116:117], v[142:143]
	v_pk_fma_f32 v[128:129], v[98:99], v[114:115], v[134:135]
	v_pk_fma_f32 v[130:131], v[96:97], v[112:113], v[164:165]
	v_cvt_pk_bf16_f32 v112, v124, v125
	v_cvt_pk_bf16_f32 v113, v126, v127
	v_mul_f32_e32 v114, v125, v125
	v_mul_f32_e32 v115, v127, v127
	v_mul_f32_e32 v125, v121, v121
	v_mul_f32_e32 v127, v123, v123
	v_mul_f32_e32 v132, v117, v117
	v_mul_f32_e32 v133, v119, v119
	v_mul_f32_e32 v134, v131, v131
	v_mul_f32_e32 v135, v129, v129
	v_fmac_f32_e32 v114, v124, v124
	v_fmac_f32_e32 v115, v126, v126
	v_fmac_f32_e32 v125, v120, v120
	v_fmac_f32_e32 v127, v122, v122
	v_fmac_f32_e32 v132, v116, v116
	v_fmac_f32_e32 v133, v118, v118
	v_fmac_f32_e32 v134, v130, v130
	v_fmac_f32_e32 v135, v128, v128
	v_add_f32_e32 v114, v114, v115
	v_add_f32_e32 v115, v125, v127
	v_add_f32_e32 v124, v132, v133
	v_add_f32_e32 v125, v134, v135
	v_add_f32_e32 v114, v114, v115
	v_add_f32_e32 v115, v124, v125
	v_add_f32_e32 v124, v114, v115
	ds_bpermute_b32 v125, v145, v124
	v_cvt_pk_bf16_f32 v114, v120, v121
	v_cvt_pk_bf16_f32 v115, v122, v123
	global_store_dwordx4 v[136:137], v[112:115], off
	s_waitcnt lgkmcnt(0)
	s_nop 0
	v_add_f32_e32 v112, v124, v125
	ds_bpermute_b32 v113, v147, v112
	v_cvt_pk_bf16_f32 v114, v116, v117
	v_cvt_pk_bf16_f32 v115, v118, v119
	v_cvt_pk_bf16_f32 v116, v130, v131
	v_cvt_pk_bf16_f32 v117, v128, v129
	global_store_dwordx4 v[136:137], v[114:117], off offset:256
	s_and_saveexec_b64 s[0:1], s[4:5]
	s_cbranch_execz .LBB0_1397
	v_lshl_add_u32 v114, v158, 4, s24
	s_waitcnt lgkmcnt(0)
	v_add_f32_e32 v112, v112, v113
	ds_write_b32 v114, v112
.LBB0_1397:
	s_or_b64 exec, exec, s[0:1]
	v_or_b32_e32 v112, 32, v152
	s_waitcnt lgkmcnt(0)
	v_mov_b32_e32 v113, 0
	v_lshl_add_u64 v[114:115], s[18:19], 0, v[112:113]
	v_lshl_add_u64 v[116:117], v[114:115], 2, s[12:13]
	global_load_dword v126, v[116:117], off sc1
	v_lshlrev_b64 v[114:115], 11, v[114:115]
	v_lshl_add_u64 v[114:115], s[10:11], 0, v[114:115]
	v_lshl_add_u64 v[124:125], v[156:157], 1, v[114:115]
	global_load_dwordx4 v[116:119], v[124:125], off
	global_load_dwordx4 v[120:123], v[124:125], off offset:256
	v_mov_b32_e32 v115, 0x358637bd
	v_mov_b32_e32 v114, 0x260
	s_waitcnt vmcnt(2)
	v_fmamk_f32 v126, v126, 0x3a800000, v115
	v_rsq_f32_e32 v252, v126
	s_nop 0
	v_mul_f32_e32 v253, v126, v252
	v_mul_f32_e32 v253, v253, v252
	v_fmaak_f32 v253, -0.5, v253, 0x3fc00000
	v_mul_f32_e32 v252, v252, v253
	s_waitcnt vmcnt(1)
	v_lshlrev_b32_e32 v128, 16, v118
	v_and_b32_e32 v129, 0xffff0000, v118
	v_lshlrev_b32_e32 v126, 16, v116
	v_and_b32_e32 v127, 0xffff0000, v116
	v_lshlrev_b32_e32 v116, 16, v117
	v_and_b32_e32 v117, 0xffff0000, v117
	v_lshlrev_b32_e32 v118, 16, v119
	v_and_b32_e32 v119, 0xffff0000, v119
	s_waitcnt vmcnt(0)
; DI unsigned pk_bf16(float lo, float hi) { f32x2 v = {lo, hi}; bf16x2_t b = __builtin_convertvector(v, bf16x2_t); return __builtin_bit_cast(unsigned, b); }
; DI float bflo(unsigned w) { return __uint_as_float(w << 16); }
; DI float bfhi(unsigned w) { return __uint_as_float(w & 0xffff0000u); }
;     __device__ __forceinline__ void fused(f32x4 (&acc)[2][2][4][2], const pg8::Unit& u, int wr, int wc, int fr, int fq, PG8_LAS unsigned char* lds, int wid, int lane) const {
;     ...
;         const int colb = u.pn * 256 + wc * 32 + 8 * fq;
;         f32x4 gv[2][2];
; #pragma unroll
;         for (int bj = 0; bj < 2; ++bj)
; #pragma unroll
;             for (int n = 0; n < 2; ++n) gv[bj][n] = *(const f32x4*)(gA + colb + bj * 128 + 4 * n);
; #pragma unroll
;         for (int ai = 0; ai < 2; ++ai)
; #pragma unroll
;             for (int m = 0; m < 4; ++m) {
;                 const int rl = ai * 128 + wr * 64 + m * 16 + fr; const size_t row = (size_t)u.pm * 256 + rl;
;                 const float rm = 1.f / sqrtf(__hip_atomic_load(ssqm + row, __ATOMIC_RELAXED, __HIP_MEMORY_SCOPE_AGENT) * (1.f / DM) + RMS_EPS);
;                 float sh = 0.f;
; #pragma unroll
;                 for (int bj = 0; bj < 2; ++bj) {
;                     const size_t off = row * DM + colb + bj * 128;
;                     f32x4 h0, h1;
;                     if (IN16) { const u32x4 hw = *(const u32x4*)((const bf16_t*)hin + off); h0 = (f32x4){bflo(hw.x), bfhi(hw.x), bflo(hw.y), bfhi(hw.y)}; h1 = (f32x4){bflo(hw.z), bfhi(hw.z), bflo(hw.w), bfhi(hw.w)}; }
;                     else { h0 = *(const f32x4*)((const float*)hin + off); h1 = *(const f32x4*)((const float*)hin + off + 4); }
;                     h0 = h0 + acc[ai][bj][m][0] * rm * gv[bj][0]; h1 = h1 + acc[ai][bj][m][1] * rm * gv[bj][1];
;                     sh += ((h0[0] * h0[0] + h0[1] * h0[1]) + (h0[2] * h0[2] + h0[3] * h0[3])) + ((h1[0] * h1[0] + h1[1] * h1[1]) + (h1[2] * h1[2] + h1[3] * h1[3]));
;                     if (OUT16) { u32x4 w; w.x = pk_bf16(h0[0], h0[1]); w.y = pk_bf16(h0[2], h0[3]); w.z = pk_bf16(h1[0], h1[1]); w.w = pk_bf16(h1[2], h1[3]); *(u32x4*)((bf16_t*)hout + off) = w; }
;                     else { *(f32x4*)((float*)hout + off) = h0; *(f32x4*)((float*)hout + off + 4) = h1; }
;                 }
;                 if (ssqh) { sh += __shfl_xor(sh, 16); sh += __shfl_xor(sh, 32); if (fq == 0) red[rl * 4 + wc] = sh; }
	v_lshlrev_b32_e32 v130, 16, v120
	v_and_b32_e32 v131, 0xffff0000, v120
	v_lshlrev_b32_e32 v120, 16, v121
	v_and_b32_e32 v121, 0xffff0000, v121
	v_mov_b32_e32 v134, v252
	v_lshlrev_b32_e32 v132, 16, v122
	v_and_b32_e32 v133, 0xffff0000, v122
	v_lshlrev_b32_e32 v122, 16, v123
	v_and_b32_e32 v123, 0xffff0000, v123
	v_pk_mul_f32 v[92:93], v[92:93], v[134:135] op_sel_hi:[1,0]
	v_pk_mul_f32 v[94:95], v[94:95], v[134:135] op_sel_hi:[1,0]
	v_pk_mul_f32 v[88:89], v[88:89], v[134:135] op_sel_hi:[1,0]
	v_pk_mul_f32 v[90:91], v[90:91], v[134:135] op_sel_hi:[1,0]
	v_pk_mul_f32 v[84:85], v[84:85], v[134:135] op_sel_hi:[1,0]
	v_pk_mul_f32 v[86:87], v[86:87], v[134:135] op_sel_hi:[1,0]
	v_pk_mul_f32 v[80:81], v[80:81], v[134:135] op_sel_hi:[1,0]
	v_pk_mul_f32 v[82:83], v[82:83], v[134:135] op_sel_hi:[1,0]
	v_pk_fma_f32 v[94:95], v[106:107], v[94:95], v[116:117]
	v_pk_fma_f32 v[92:93], v[104:105], v[92:93], v[126:127]
	v_pk_fma_f32 v[90:91], v[102:103], v[90:91], v[118:119]
	v_pk_fma_f32 v[88:89], v[100:101], v[88:89], v[128:129]
	v_pk_fma_f32 v[86:87], v[110:111], v[86:87], v[120:121]
	v_pk_fma_f32 v[84:85], v[108:109], v[84:85], v[130:131]
	v_pk_fma_f32 v[116:117], v[98:99], v[82:83], v[122:123]
	v_pk_fma_f32 v[118:119], v[96:97], v[80:81], v[132:133]
	v_cvt_pk_bf16_f32 v80, v92, v93
	v_cvt_pk_bf16_f32 v81, v94, v95
	v_mul_f32_e32 v82, v93, v93
	v_mul_f32_e32 v83, v95, v95
	v_mul_f32_e32 v93, v89, v89
	v_mul_f32_e32 v95, v91, v91
	v_mul_f32_e32 v120, v85, v85
	v_mul_f32_e32 v121, v87, v87
	v_mul_f32_e32 v122, v119, v119
	v_mul_f32_e32 v123, v117, v117
	v_fmac_f32_e32 v82, v92, v92
	v_fmac_f32_e32 v83, v94, v94
	v_fmac_f32_e32 v93, v88, v88
	v_fmac_f32_e32 v95, v90, v90
	v_fmac_f32_e32 v120, v84, v84
	v_fmac_f32_e32 v121, v86, v86
	v_fmac_f32_e32 v122, v118, v118
	v_fmac_f32_e32 v123, v116, v116
	v_add_f32_e32 v82, v82, v83
	v_add_f32_e32 v83, v93, v95
	v_add_f32_e32 v92, v120, v121
	v_add_f32_e32 v93, v122, v123
	v_add_f32_e32 v82, v82, v83
	v_add_f32_e32 v83, v92, v93
	v_add_f32_e32 v92, v82, v83
	ds_bpermute_b32 v93, v145, v92
	v_cvt_pk_bf16_f32 v82, v88, v89
	v_cvt_pk_bf16_f32 v83, v90, v91
	global_store_dwordx4 v[124:125], v[80:83], off
	s_waitcnt lgkmcnt(0)
	s_nop 0
	v_add_f32_e32 v80, v92, v93
	ds_bpermute_b32 v81, v147, v80
	v_cvt_pk_bf16_f32 v82, v84, v85
	v_cvt_pk_bf16_f32 v83, v86, v87
	v_cvt_pk_bf16_f32 v84, v118, v119
	v_cvt_pk_bf16_f32 v85, v116, v117
	global_store_dwordx4 v[124:125], v[82:85], off offset:256
	s_and_saveexec_b64 s[0:1], s[4:5]
	s_cbranch_execz .LBB0_1399
	v_lshl_add_u32 v82, v112, 4, s24
	s_waitcnt lgkmcnt(0)
	v_add_f32_e32 v80, v80, v81
	ds_write_b32 v82, v80
.LBB0_1399:
	s_or_b64 exec, exec, s[0:1]
	v_or_b32_e32 v112, 48, v152
	s_waitcnt lgkmcnt(0)
	v_lshl_add_u64 v[80:81], s[18:19], 0, v[112:113]
	v_lshl_add_u64 v[82:83], v[80:81], 2, s[12:13]
	global_load_dword v90, v[82:83], off sc1
	v_lshlrev_b64 v[80:81], 11, v[80:81]
	v_lshl_add_u64 v[80:81], s[10:11], 0, v[80:81]
	v_lshl_add_u64 v[88:89], v[156:157], 1, v[80:81]
	global_load_dwordx4 v[80:83], v[88:89], off
	global_load_dwordx4 v[84:87], v[88:89], off offset:256
	s_waitcnt vmcnt(2)
	v_fmac_f32_e32 v115, 0x3a800000, v90
	v_rsq_f32_e32 v252, v115
	s_nop 0
	v_mul_f32_e32 v253, v115, v252
	v_mul_f32_e32 v253, v253, v252
	v_fmaak_f32 v253, -0.5, v253, 0x3fc00000
	v_mul_f32_e32 v252, v252, v253
	s_waitcnt vmcnt(1)
	v_and_b32_e32 v91, 0xffff0000, v80
	v_lshlrev_b32_e32 v92, 16, v82
	v_lshlrev_b32_e32 v90, 16, v80
	v_lshlrev_b32_e32 v80, 16, v81
	v_and_b32_e32 v81, 0xffff0000, v81
	v_and_b32_e32 v93, 0xffff0000, v82
	v_lshlrev_b32_e32 v82, 16, v83
	v_and_b32_e32 v83, 0xffff0000, v83
	s_waitcnt vmcnt(0)
	v_lshlrev_b32_e32 v94, 16, v84
	v_and_b32_e32 v95, 0xffff0000, v84
	v_lshlrev_b32_e32 v84, 16, v85
	v_and_b32_e32 v85, 0xffff0000, v85
	v_mov_b32_e32 v114, v252
	v_lshlrev_b32_e32 v116, 16, v86
	v_and_b32_e32 v117, 0xffff0000, v86
	v_lshlrev_b32_e32 v86, 16, v87
	v_and_b32_e32 v87, 0xffff0000, v87
	v_pk_mul_f32 v[76:77], v[76:77], v[114:115] op_sel_hi:[1,0]
	v_pk_mul_f32 v[78:79], v[78:79], v[114:115] op_sel_hi:[1,0]
	v_pk_mul_f32 v[72:73], v[72:73], v[114:115] op_sel_hi:[1,0]
	v_pk_mul_f32 v[74:75], v[74:75], v[114:115] op_sel_hi:[1,0]
	v_pk_mul_f32 v[68:69], v[68:69], v[114:115] op_sel_hi:[1,0]
	v_pk_mul_f32 v[70:71], v[70:71], v[114:115] op_sel_hi:[1,0]
	v_pk_mul_f32 v[64:65], v[64:65], v[114:115] op_sel_hi:[1,0]
	v_pk_mul_f32 v[66:67], v[66:67], v[114:115] op_sel_hi:[1,0]
	v_pk_fma_f32 v[78:79], v[106:107], v[78:79], v[80:81]
	v_pk_fma_f32 v[76:77], v[104:105], v[76:77], v[90:91]
	v_pk_fma_f32 v[74:75], v[102:103], v[74:75], v[82:83]
	v_pk_fma_f32 v[72:73], v[100:101], v[72:73], v[92:93]
	v_pk_fma_f32 v[70:71], v[110:111], v[70:71], v[84:85]
	v_pk_fma_f32 v[68:69], v[108:109], v[68:69], v[94:95]
	v_pk_fma_f32 v[80:81], v[98:99], v[66:67], v[86:87]
	v_pk_fma_f32 v[82:83], v[96:97], v[64:65], v[116:117]
	v_cvt_pk_bf16_f32 v64, v76, v77
	v_cvt_pk_bf16_f32 v65, v78, v79
	v_mul_f32_e32 v66, v77, v77
	v_mul_f32_e32 v67, v79, v79
	v_mul_f32_e32 v77, v73, v73
	v_mul_f32_e32 v79, v75, v75
	v_mul_f32_e32 v84, v69, v69
	v_mul_f32_e32 v85, v71, v71
	v_mul_f32_e32 v86, v83, v83
	v_mul_f32_e32 v87, v81, v81
	v_fmac_f32_e32 v66, v76, v76
	v_fmac_f32_e32 v67, v78, v78
	v_fmac_f32_e32 v77, v72, v72
	v_fmac_f32_e32 v79, v74, v74
	v_fmac_f32_e32 v84, v68, v68
	v_fmac_f32_e32 v85, v70, v70
	v_fmac_f32_e32 v86, v82, v82
	v_fmac_f32_e32 v87, v80, v80
	v_add_f32_e32 v66, v66, v67
	v_add_f32_e32 v67, v77, v79
	v_add_f32_e32 v76, v84, v85
	v_add_f32_e32 v77, v86, v87
	v_add_f32_e32 v66, v66, v67
	v_add_f32_e32 v67, v76, v77
	v_add_f32_e32 v76, v66, v67
	ds_bpermute_b32 v77, v145, v76
	v_cvt_pk_bf16_f32 v66, v72, v73
	v_cvt_pk_bf16_f32 v67, v74, v75
	global_store_dwordx4 v[88:89], v[64:67], off
	s_waitcnt lgkmcnt(0)
	s_nop 0
	v_add_f32_e32 v64, v76, v77
	ds_bpermute_b32 v65, v147, v64
	v_cvt_pk_bf16_f32 v66, v68, v69
	v_cvt_pk_bf16_f32 v67, v70, v71
	v_cvt_pk_bf16_f32 v68, v82, v83
	v_cvt_pk_bf16_f32 v69, v80, v81
	global_store_dwordx4 v[88:89], v[66:69], off offset:256
	s_and_saveexec_b64 s[0:1], s[4:5]
	s_cbranch_execz .LBB0_1401
	v_lshl_add_u32 v66, v112, 4, s24
	s_waitcnt lgkmcnt(0)
	v_add_f32_e32 v64, v64, v65
	ds_write_b32 v66, v64
; DI unsigned pk_bf16(float lo, float hi) { f32x2 v = {lo, hi}; bf16x2_t b = __builtin_convertvector(v, bf16x2_t); return __builtin_bit_cast(unsigned, b); }
; DI float bflo(unsigned w) { return __uint_as_float(w << 16); }
; DI float bfhi(unsigned w) { return __uint_as_float(w & 0xffff0000u); }
;     __device__ __forceinline__ void fused(f32x4 (&acc)[2][2][4][2], const pg8::Unit& u, int wr, int wc, int fr, int fq, PG8_LAS unsigned char* lds, int wid, int lane) const {
;     ...
;         const int colb = u.pn * 256 + wc * 32 + 8 * fq;
;         f32x4 gv[2][2];
; #pragma unroll
;         for (int bj = 0; bj < 2; ++bj)
; #pragma unroll
;             for (int n = 0; n < 2; ++n) gv[bj][n] = *(const f32x4*)(gA + colb + bj * 128 + 4 * n);
; #pragma unroll
;         for (int ai = 0; ai < 2; ++ai)
; #pragma unroll
;             for (int m = 0; m < 4; ++m) {
;                 const int rl = ai * 128 + wr * 64 + m * 16 + fr; const size_t row = (size_t)u.pm * 256 + rl;
;                 const float rm = 1.f / sqrtf(__hip_atomic_load(ssqm + row, __ATOMIC_RELAXED, __HIP_MEMORY_SCOPE_AGENT) * (1.f / DM) + RMS_EPS);
;                 float sh = 0.f;
; #pragma unroll
;                 for (int bj = 0; bj < 2; ++bj) {
;                     const size_t off = row * DM + colb + bj * 128;
;                     f32x4 h0, h1;
;                     if (IN16) { const u32x4 hw = *(const u32x4*)((const bf16_t*)hin + off); h0 = (f32x4){bflo(hw.x), bfhi(hw.x), bflo(hw.y), bfhi(hw.y)}; h1 = (f32x4){bflo(hw.z), bfhi(hw.z), bflo(hw.w), bfhi(hw.w)}; }
;                     else { h0 = *(const f32x4*)((const float*)hin + off); h1 = *(const f32x4*)((const float*)hin + off + 4); }
;                     h0 = h0 + acc[ai][bj][m][0] * rm * gv[bj][0]; h1 = h1 + acc[ai][bj][m][1] * rm * gv[bj][1];
;                     sh += ((h0[0] * h0[0] + h0[1] * h0[1]) + (h0[2] * h0[2] + h0[3] * h0[3])) + ((h1[0] * h1[0] + h1[1] * h1[1]) + (h1[2] * h1[2] + h1[3] * h1[3]));
;                     if (OUT16) { u32x4 w; w.x = pk_bf16(h0[0], h0[1]); w.y = pk_bf16(h0[2], h0[3]); w.z = pk_bf16(h1[0], h1[1]); w.w = pk_bf16(h1[2], h1[3]); *(u32x4*)((bf16_t*)hout + off) = w; }
;                     else { *(f32x4*)((float*)hout + off) = h0; *(f32x4*)((float*)hout + off + 4) = h1; }
;                 }
;                 if (ssqh) { sh += __shfl_xor(sh, 16); sh += __shfl_xor(sh, 32); if (fq == 0) red[rl * 4 + wc] = sh; }
.LBB0_1401:
	s_or_b64 exec, exec, s[0:1]
	v_add_u32_e32 v64, 0x80, v152
	s_waitcnt lgkmcnt(0)
	v_mov_b32_e32 v65, 0
	v_lshl_add_u64 v[66:67], s[18:19], 0, v[64:65]
	v_lshl_add_u64 v[68:69], v[66:67], 2, s[12:13]
	global_load_dword v78, v[68:69], off sc1
	v_lshlrev_b64 v[66:67], 11, v[66:67]
	v_lshl_add_u64 v[66:67], s[10:11], 0, v[66:67]
	v_lshl_add_u64 v[76:77], v[156:157], 1, v[66:67]
	global_load_dwordx4 v[68:71], v[76:77], off
	global_load_dwordx4 v[72:75], v[76:77], off offset:256
	v_mov_b32_e32 v67, 0x358637bd
	v_mov_b32_e32 v66, 0x260
	s_waitcnt vmcnt(2)
	v_fmamk_f32 v78, v78, 0x3a800000, v67
	v_rsq_f32_e32 v252, v78
	s_nop 0
	v_mul_f32_e32 v253, v78, v252
	v_mul_f32_e32 v253, v253, v252
	v_fmaak_f32 v253, -0.5, v253, 0x3fc00000
	v_mul_f32_e32 v252, v252, v253
	s_waitcnt vmcnt(1)
	v_lshlrev_b32_e32 v80, 16, v70
	v_and_b32_e32 v81, 0xffff0000, v70
	v_lshlrev_b32_e32 v78, 16, v68
	v_and_b32_e32 v79, 0xffff0000, v68
	v_lshlrev_b32_e32 v68, 16, v69
	v_and_b32_e32 v69, 0xffff0000, v69
	v_lshlrev_b32_e32 v70, 16, v71
	v_and_b32_e32 v71, 0xffff0000, v71
	s_waitcnt vmcnt(0)
	v_lshlrev_b32_e32 v82, 16, v72
	v_and_b32_e32 v83, 0xffff0000, v72
	v_lshlrev_b32_e32 v72, 16, v73
	v_and_b32_e32 v73, 0xffff0000, v73
	v_mov_b32_e32 v86, v252
	v_lshlrev_b32_e32 v84, 16, v74
	v_and_b32_e32 v85, 0xffff0000, v74
	v_lshlrev_b32_e32 v74, 16, v75
	v_and_b32_e32 v75, 0xffff0000, v75
	v_pk_mul_f32 v[60:61], v[60:61], v[86:87] op_sel_hi:[1,0]
	v_pk_mul_f32 v[62:63], v[62:63], v[86:87] op_sel_hi:[1,0]
	v_pk_mul_f32 v[56:57], v[56:57], v[86:87] op_sel_hi:[1,0]
	v_pk_mul_f32 v[58:59], v[58:59], v[86:87] op_sel_hi:[1,0]
	v_pk_mul_f32 v[52:53], v[52:53], v[86:87] op_sel_hi:[1,0]
	v_pk_mul_f32 v[54:55], v[54:55], v[86:87] op_sel_hi:[1,0]
	v_pk_mul_f32 v[48:49], v[48:49], v[86:87] op_sel_hi:[1,0]
	v_pk_mul_f32 v[50:51], v[50:51], v[86:87] op_sel_hi:[1,0]
	v_pk_fma_f32 v[62:63], v[106:107], v[62:63], v[68:69]
	v_pk_fma_f32 v[60:61], v[104:105], v[60:61], v[78:79]
	v_pk_fma_f32 v[58:59], v[102:103], v[58:59], v[70:71]
	v_pk_fma_f32 v[56:57], v[100:101], v[56:57], v[80:81]
	v_pk_fma_f32 v[54:55], v[110:111], v[54:55], v[72:73]
	v_pk_fma_f32 v[52:53], v[108:109], v[52:53], v[82:83]
	v_pk_fma_f32 v[68:69], v[98:99], v[50:51], v[74:75]
	v_pk_fma_f32 v[70:71], v[96:97], v[48:49], v[84:85]
	v_cvt_pk_bf16_f32 v48, v60, v61
	v_cvt_pk_bf16_f32 v49, v62, v63
	v_mul_f32_e32 v50, v61, v61
	v_mul_f32_e32 v51, v63, v63
	v_mul_f32_e32 v61, v57, v57
	v_mul_f32_e32 v63, v59, v59
	v_mul_f32_e32 v72, v53, v53
	v_mul_f32_e32 v73, v55, v55
	v_mul_f32_e32 v74, v71, v71
	v_mul_f32_e32 v75, v69, v69
	v_fmac_f32_e32 v50, v60, v60
	v_fmac_f32_e32 v51, v62, v62
	v_fmac_f32_e32 v61, v56, v56
	v_fmac_f32_e32 v63, v58, v58
	v_fmac_f32_e32 v72, v52, v52
	v_fmac_f32_e32 v73, v54, v54
	v_fmac_f32_e32 v74, v70, v70
	v_fmac_f32_e32 v75, v68, v68
	v_add_f32_e32 v50, v50, v51
	v_add_f32_e32 v51, v61, v63
	v_add_f32_e32 v60, v72, v73
	v_add_f32_e32 v61, v74, v75
	v_add_f32_e32 v50, v50, v51
	v_add_f32_e32 v51, v60, v61
	v_add_f32_e32 v60, v50, v51
	ds_bpermute_b32 v61, v145, v60
	v_cvt_pk_bf16_f32 v50, v56, v57
	v_cvt_pk_bf16_f32 v51, v58, v59
	global_store_dwordx4 v[76:77], v[48:51], off
	s_waitcnt lgkmcnt(0)
	s_nop 0
	v_add_f32_e32 v48, v60, v61
	ds_bpermute_b32 v49, v147, v48
	v_cvt_pk_bf16_f32 v50, v52, v53
	v_cvt_pk_bf16_f32 v51, v54, v55
	v_cvt_pk_bf16_f32 v52, v70, v71
	v_cvt_pk_bf16_f32 v53, v68, v69
	global_store_dwordx4 v[76:77], v[50:53], off offset:256
	s_and_saveexec_b64 s[0:1], s[4:5]
	s_cbranch_execz .LBB0_1403
	v_lshl_add_u32 v50, v64, 4, s24
	s_waitcnt lgkmcnt(0)
	v_add_f32_e32 v48, v48, v49
	ds_write_b32 v50, v48
.LBB0_1403:
	s_or_b64 exec, exec, s[0:1]
	v_add_u32_e32 v64, 0x90, v152
	s_waitcnt lgkmcnt(0)
	v_lshl_add_u64 v[48:49], s[18:19], 0, v[64:65]
	v_lshl_add_u64 v[50:51], v[48:49], 2, s[12:13]
	global_load_dword v58, v[50:51], off sc1
	v_lshlrev_b64 v[48:49], 11, v[48:49]
	v_lshl_add_u64 v[48:49], s[10:11], 0, v[48:49]
	v_lshl_add_u64 v[56:57], v[156:157], 1, v[48:49]
	global_load_dwordx4 v[48:51], v[56:57], off
	global_load_dwordx4 v[52:55], v[56:57], off offset:256
	s_waitcnt vmcnt(2)
	v_fmac_f32_e32 v67, 0x3a800000, v58
	v_rsq_f32_e32 v252, v67
	s_nop 0
	v_mul_f32_e32 v253, v67, v252
	v_mul_f32_e32 v253, v253, v252
	v_fmaak_f32 v253, -0.5, v253, 0x3fc00000
	v_mul_f32_e32 v252, v252, v253
	s_waitcnt vmcnt(1)
	v_and_b32_e32 v59, 0xffff0000, v48
	v_lshlrev_b32_e32 v60, 16, v50
	v_lshlrev_b32_e32 v58, 16, v48
	v_lshlrev_b32_e32 v48, 16, v49
	v_and_b32_e32 v49, 0xffff0000, v49
	v_and_b32_e32 v61, 0xffff0000, v50
	v_lshlrev_b32_e32 v50, 16, v51
	v_and_b32_e32 v51, 0xffff0000, v51
	s_waitcnt vmcnt(0)
; DI unsigned pk_bf16(float lo, float hi) { f32x2 v = {lo, hi}; bf16x2_t b = __builtin_convertvector(v, bf16x2_t); return __builtin_bit_cast(unsigned, b); }
; DI float bflo(unsigned w) { return __uint_as_float(w << 16); }
; DI float bfhi(unsigned w) { return __uint_as_float(w & 0xffff0000u); }
;     __device__ __forceinline__ void fused(f32x4 (&acc)[2][2][4][2], const pg8::Unit& u, int wr, int wc, int fr, int fq, PG8_LAS unsigned char* lds, int wid, int lane) const {
;     ...
;         const int colb = u.pn * 256 + wc * 32 + 8 * fq;
;         f32x4 gv[2][2];
; #pragma unroll
;         for (int bj = 0; bj < 2; ++bj)
; #pragma unroll
;             for (int n = 0; n < 2; ++n) gv[bj][n] = *(const f32x4*)(gA + colb + bj * 128 + 4 * n);
; #pragma unroll
;         for (int ai = 0; ai < 2; ++ai)
; #pragma unroll
;             for (int m = 0; m < 4; ++m) {
;                 const int rl = ai * 128 + wr * 64 + m * 16 + fr; const size_t row = (size_t)u.pm * 256 + rl;
;                 const float rm = 1.f / sqrtf(__hip_atomic_load(ssqm + row, __ATOMIC_RELAXED, __HIP_MEMORY_SCOPE_AGENT) * (1.f / DM) + RMS_EPS);
;                 float sh = 0.f;
; #pragma unroll
;                 for (int bj = 0; bj < 2; ++bj) {
;                     const size_t off = row * DM + colb + bj * 128;
;                     f32x4 h0, h1;
;                     if (IN16) { const u32x4 hw = *(const u32x4*)((const bf16_t*)hin + off); h0 = (f32x4){bflo(hw.x), bfhi(hw.x), bflo(hw.y), bfhi(hw.y)}; h1 = (f32x4){bflo(hw.z), bfhi(hw.z), bflo(hw.w), bfhi(hw.w)}; }
;                     else { h0 = *(const f32x4*)((const float*)hin + off); h1 = *(const f32x4*)((const float*)hin + off + 4); }
;                     h0 = h0 + acc[ai][bj][m][0] * rm * gv[bj][0]; h1 = h1 + acc[ai][bj][m][1] * rm * gv[bj][1];
;                     sh += ((h0[0] * h0[0] + h0[1] * h0[1]) + (h0[2] * h0[2] + h0[3] * h0[3])) + ((h1[0] * h1[0] + h1[1] * h1[1]) + (h1[2] * h1[2] + h1[3] * h1[3]));
;                     if (OUT16) { u32x4 w; w.x = pk_bf16(h0[0], h0[1]); w.y = pk_bf16(h0[2], h0[3]); w.z = pk_bf16(h1[0], h1[1]); w.w = pk_bf16(h1[2], h1[3]); *(u32x4*)((bf16_t*)hout + off) = w; }
;                     else { *(f32x4*)((float*)hout + off) = h0; *(f32x4*)((float*)hout + off + 4) = h1; }
;                 }
;                 if (ssqh) { sh += __shfl_xor(sh, 16); sh += __shfl_xor(sh, 32); if (fq == 0) red[rl * 4 + wc] = sh; }
	v_lshlrev_b32_e32 v62, 16, v52
	v_and_b32_e32 v63, 0xffff0000, v52
	v_lshlrev_b32_e32 v52, 16, v53
	v_and_b32_e32 v53, 0xffff0000, v53
	v_mov_b32_e32 v66, v252
	v_lshlrev_b32_e32 v68, 16, v54
	v_and_b32_e32 v69, 0xffff0000, v54
	v_lshlrev_b32_e32 v54, 16, v55
	v_and_b32_e32 v55, 0xffff0000, v55
	v_pk_mul_f32 v[44:45], v[44:45], v[66:67] op_sel_hi:[1,0]
	v_pk_mul_f32 v[46:47], v[46:47], v[66:67] op_sel_hi:[1,0]
	v_pk_mul_f32 v[40:41], v[40:41], v[66:67] op_sel_hi:[1,0]
	v_pk_mul_f32 v[42:43], v[42:43], v[66:67] op_sel_hi:[1,0]
	v_pk_mul_f32 v[36:37], v[36:37], v[66:67] op_sel_hi:[1,0]
	v_pk_mul_f32 v[38:39], v[38:39], v[66:67] op_sel_hi:[1,0]
	v_pk_mul_f32 v[32:33], v[32:33], v[66:67] op_sel_hi:[1,0]
	v_pk_mul_f32 v[34:35], v[34:35], v[66:67] op_sel_hi:[1,0]
	v_pk_fma_f32 v[46:47], v[106:107], v[46:47], v[48:49]
	v_pk_fma_f32 v[44:45], v[104:105], v[44:45], v[58:59]
	v_pk_fma_f32 v[42:43], v[102:103], v[42:43], v[50:51]
	v_pk_fma_f32 v[40:41], v[100:101], v[40:41], v[60:61]
	v_pk_fma_f32 v[38:39], v[110:111], v[38:39], v[52:53]
	v_pk_fma_f32 v[36:37], v[108:109], v[36:37], v[62:63]
	v_pk_fma_f32 v[48:49], v[98:99], v[34:35], v[54:55]
	v_pk_fma_f32 v[50:51], v[96:97], v[32:33], v[68:69]
	v_cvt_pk_bf16_f32 v32, v44, v45
	v_cvt_pk_bf16_f32 v33, v46, v47
	v_mul_f32_e32 v34, v45, v45
	v_mul_f32_e32 v35, v47, v47
	v_mul_f32_e32 v45, v41, v41
	v_mul_f32_e32 v47, v43, v43
	v_mul_f32_e32 v52, v37, v37
	v_mul_f32_e32 v53, v39, v39
	v_mul_f32_e32 v54, v51, v51
	v_mul_f32_e32 v55, v49, v49
	v_fmac_f32_e32 v34, v44, v44
	v_fmac_f32_e32 v35, v46, v46
	v_fmac_f32_e32 v45, v40, v40
	v_fmac_f32_e32 v47, v42, v42
	v_fmac_f32_e32 v52, v36, v36
	v_fmac_f32_e32 v53, v38, v38
	v_fmac_f32_e32 v54, v50, v50
	v_fmac_f32_e32 v55, v48, v48
	v_add_f32_e32 v34, v34, v35
	v_add_f32_e32 v35, v45, v47
	v_add_f32_e32 v44, v52, v53
	v_add_f32_e32 v45, v54, v55
	v_add_f32_e32 v34, v34, v35
	v_add_f32_e32 v35, v44, v45
	v_add_f32_e32 v44, v34, v35
	ds_bpermute_b32 v45, v145, v44
	v_cvt_pk_bf16_f32 v34, v40, v41
	v_cvt_pk_bf16_f32 v35, v42, v43
	global_store_dwordx4 v[56:57], v[32:35], off
	s_waitcnt lgkmcnt(0)
	s_nop 0
	v_add_f32_e32 v32, v44, v45
	ds_bpermute_b32 v33, v147, v32
	v_cvt_pk_bf16_f32 v34, v36, v37
	v_cvt_pk_bf16_f32 v35, v38, v39
	v_cvt_pk_bf16_f32 v36, v50, v51
	v_cvt_pk_bf16_f32 v37, v48, v49
	global_store_dwordx4 v[56:57], v[34:37], off offset:256
	s_and_saveexec_b64 s[0:1], s[4:5]
	s_cbranch_execz .LBB0_1405
	v_lshl_add_u32 v34, v64, 4, s24
	s_waitcnt lgkmcnt(0)
	v_add_f32_e32 v32, v32, v33
	ds_write_b32 v34, v32
.LBB0_1405:
	s_or_b64 exec, exec, s[0:1]
	v_add_u32_e32 v32, 0xa0, v152
	s_waitcnt lgkmcnt(0)
	v_mov_b32_e32 v33, 0
	v_lshl_add_u64 v[34:35], s[18:19], 0, v[32:33]
	v_lshl_add_u64 v[36:37], v[34:35], 2, s[12:13]
	global_load_dword v46, v[36:37], off sc1
	v_lshlrev_b64 v[34:35], 11, v[34:35]
	v_lshl_add_u64 v[34:35], s[10:11], 0, v[34:35]
	v_lshl_add_u64 v[44:45], v[156:157], 1, v[34:35]
	global_load_dwordx4 v[36:39], v[44:45], off
	global_load_dwordx4 v[40:43], v[44:45], off offset:256
	v_mov_b32_e32 v35, 0x358637bd
	v_mov_b32_e32 v34, 0x260
	s_waitcnt vmcnt(2)
	v_fmamk_f32 v46, v46, 0x3a800000, v35
	v_rsq_f32_e32 v252, v46
	s_nop 0
	v_mul_f32_e32 v253, v46, v252
	v_mul_f32_e32 v253, v253, v252
	v_fmaak_f32 v253, -0.5, v253, 0x3fc00000
	v_mul_f32_e32 v252, v252, v253
	s_waitcnt vmcnt(1)
	v_lshlrev_b32_e32 v48, 16, v38
	v_and_b32_e32 v49, 0xffff0000, v38
	v_lshlrev_b32_e32 v46, 16, v36
	v_and_b32_e32 v47, 0xffff0000, v36
	v_lshlrev_b32_e32 v36, 16, v37
	v_and_b32_e32 v37, 0xffff0000, v37
	v_lshlrev_b32_e32 v38, 16, v39
	v_and_b32_e32 v39, 0xffff0000, v39
	s_waitcnt vmcnt(0)
	v_lshlrev_b32_e32 v50, 16, v40
	v_and_b32_e32 v51, 0xffff0000, v40
	v_lshlrev_b32_e32 v40, 16, v41
	v_and_b32_e32 v41, 0xffff0000, v41
	v_mov_b32_e32 v54, v252
	v_lshlrev_b32_e32 v52, 16, v42
	v_and_b32_e32 v53, 0xffff0000, v42
	v_lshlrev_b32_e32 v42, 16, v43
	v_and_b32_e32 v43, 0xffff0000, v43
	v_pk_mul_f32 v[28:29], v[28:29], v[54:55] op_sel_hi:[1,0]
	v_pk_mul_f32 v[30:31], v[30:31], v[54:55] op_sel_hi:[1,0]
	v_pk_mul_f32 v[24:25], v[24:25], v[54:55] op_sel_hi:[1,0]
	v_pk_mul_f32 v[26:27], v[26:27], v[54:55] op_sel_hi:[1,0]
	v_pk_mul_f32 v[20:21], v[20:21], v[54:55] op_sel_hi:[1,0]
	v_pk_mul_f32 v[22:23], v[22:23], v[54:55] op_sel_hi:[1,0]
	v_pk_mul_f32 v[16:17], v[16:17], v[54:55] op_sel_hi:[1,0]
	v_pk_mul_f32 v[18:19], v[18:19], v[54:55] op_sel_hi:[1,0]
	v_pk_fma_f32 v[30:31], v[106:107], v[30:31], v[36:37]
	v_pk_fma_f32 v[28:29], v[104:105], v[28:29], v[46:47]
	v_pk_fma_f32 v[26:27], v[102:103], v[26:27], v[38:39]
	v_pk_fma_f32 v[24:25], v[100:101], v[24:25], v[48:49]
	v_pk_fma_f32 v[22:23], v[110:111], v[22:23], v[40:41]
	v_pk_fma_f32 v[20:21], v[108:109], v[20:21], v[50:51]
	v_pk_fma_f32 v[36:37], v[98:99], v[18:19], v[42:43]
	v_pk_fma_f32 v[38:39], v[96:97], v[16:17], v[52:53]
	v_cvt_pk_bf16_f32 v16, v28, v29
	v_cvt_pk_bf16_f32 v17, v30, v31
	v_mul_f32_e32 v18, v29, v29
	v_mul_f32_e32 v19, v31, v31
	v_mul_f32_e32 v29, v25, v25
	v_mul_f32_e32 v31, v27, v27
	v_mul_f32_e32 v40, v21, v21
	v_mul_f32_e32 v41, v23, v23
	v_mul_f32_e32 v42, v39, v39
	v_mul_f32_e32 v43, v37, v37
	v_fmac_f32_e32 v18, v28, v28
	v_fmac_f32_e32 v19, v30, v30
	v_fmac_f32_e32 v29, v24, v24
	v_fmac_f32_e32 v31, v26, v26
	v_fmac_f32_e32 v40, v20, v20
	v_fmac_f32_e32 v41, v22, v22
	v_fmac_f32_e32 v42, v38, v38
	v_fmac_f32_e32 v43, v36, v36
	v_add_f32_e32 v18, v18, v19
	v_add_f32_e32 v19, v29, v31
	v_add_f32_e32 v28, v40, v41
	v_add_f32_e32 v29, v42, v43
	v_add_f32_e32 v18, v18, v19
	v_add_f32_e32 v19, v28, v29
	v_add_f32_e32 v28, v18, v19
	ds_bpermute_b32 v29, v145, v28
	v_cvt_pk_bf16_f32 v18, v24, v25
	v_cvt_pk_bf16_f32 v19, v26, v27
	global_store_dwordx4 v[44:45], v[16:19], off
	s_waitcnt lgkmcnt(0)
	s_nop 0
	v_add_f32_e32 v16, v28, v29
	ds_bpermute_b32 v17, v147, v16
	v_cvt_pk_bf16_f32 v18, v20, v21
	v_cvt_pk_bf16_f32 v19, v22, v23
	v_cvt_pk_bf16_f32 v20, v38, v39
	v_cvt_pk_bf16_f32 v21, v36, v37
	global_store_dwordx4 v[44:45], v[18:21], off offset:256
	s_and_saveexec_b64 s[0:1], s[4:5]
	s_cbranch_execz .LBB0_1407
	v_lshl_add_u32 v18, v32, 4, s24
	s_waitcnt lgkmcnt(0)
	v_add_f32_e32 v16, v16, v17
	ds_write_b32 v18, v16
; DI unsigned pk_bf16(float lo, float hi) { f32x2 v = {lo, hi}; bf16x2_t b = __builtin_convertvector(v, bf16x2_t); return __builtin_bit_cast(unsigned, b); }
; DI float bflo(unsigned w) { return __uint_as_float(w << 16); }
; DI float bfhi(unsigned w) { return __uint_as_float(w & 0xffff0000u); }
;     __device__ __forceinline__ void fused(f32x4 (&acc)[2][2][4][2], const pg8::Unit& u, int wr, int wc, int fr, int fq, PG8_LAS unsigned char* lds, int wid, int lane) const {
;     ...
;         const int colb = u.pn * 256 + wc * 32 + 8 * fq;
;         f32x4 gv[2][2];
; #pragma unroll
;         for (int bj = 0; bj < 2; ++bj)
; #pragma unroll
;             for (int n = 0; n < 2; ++n) gv[bj][n] = *(const f32x4*)(gA + colb + bj * 128 + 4 * n);
; #pragma unroll
;         for (int ai = 0; ai < 2; ++ai)
; #pragma unroll
;             for (int m = 0; m < 4; ++m) {
;                 const int rl = ai * 128 + wr * 64 + m * 16 + fr; const size_t row = (size_t)u.pm * 256 + rl;
;                 const float rm = 1.f / sqrtf(__hip_atomic_load(ssqm + row, __ATOMIC_RELAXED, __HIP_MEMORY_SCOPE_AGENT) * (1.f / DM) + RMS_EPS);
;                 float sh = 0.f;
; #pragma unroll
;                 for (int bj = 0; bj < 2; ++bj) {
;                     const size_t off = row * DM + colb + bj * 128;
;                     f32x4 h0, h1;
;                     if (IN16) { const u32x4 hw = *(const u32x4*)((const bf16_t*)hin + off); h0 = (f32x4){bflo(hw.x), bfhi(hw.x), bflo(hw.y), bfhi(hw.y)}; h1 = (f32x4){bflo(hw.z), bfhi(hw.z), bflo(hw.w), bfhi(hw.w)}; }
;                     else { h0 = *(const f32x4*)((const float*)hin + off); h1 = *(const f32x4*)((const float*)hin + off + 4); }
;                     h0 = h0 + acc[ai][bj][m][0] * rm * gv[bj][0]; h1 = h1 + acc[ai][bj][m][1] * rm * gv[bj][1];
;                     sh += ((h0[0] * h0[0] + h0[1] * h0[1]) + (h0[2] * h0[2] + h0[3] * h0[3])) + ((h1[0] * h1[0] + h1[1] * h1[1]) + (h1[2] * h1[2] + h1[3] * h1[3]));
;                     if (OUT16) { u32x4 w; w.x = pk_bf16(h0[0], h0[1]); w.y = pk_bf16(h0[2], h0[3]); w.z = pk_bf16(h1[0], h1[1]); w.w = pk_bf16(h1[2], h1[3]); *(u32x4*)((bf16_t*)hout + off) = w; }
;                     else { *(f32x4*)((float*)hout + off) = h0; *(f32x4*)((float*)hout + off + 4) = h1; }
;                 }
;                 if (ssqh) { sh += __shfl_xor(sh, 16); sh += __shfl_xor(sh, 32); if (fq == 0) red[rl * 4 + wc] = sh; }
.LBB0_1407:
	s_or_b64 exec, exec, s[0:1]
	v_add_u32_e32 v32, 0xb0, v152
	s_waitcnt lgkmcnt(0)
	v_lshl_add_u64 v[16:17], s[18:19], 0, v[32:33]
	v_lshl_add_u64 v[18:19], v[16:17], 2, s[12:13]
	global_load_dword v26, v[18:19], off sc1
	v_lshlrev_b64 v[16:17], 11, v[16:17]
	v_lshl_add_u64 v[16:17], s[10:11], 0, v[16:17]
	v_lshl_add_u64 v[24:25], v[156:157], 1, v[16:17]
	global_load_dwordx4 v[16:19], v[24:25], off
	global_load_dwordx4 v[20:23], v[24:25], off offset:256
	s_waitcnt vmcnt(2)
	v_fmac_f32_e32 v35, 0x3a800000, v26
	v_rsq_f32_e32 v252, v35
	s_nop 0
	v_mul_f32_e32 v253, v35, v252
	v_mul_f32_e32 v253, v253, v252
	v_fmaak_f32 v253, -0.5, v253, 0x3fc00000
	v_mul_f32_e32 v252, v252, v253
	s_waitcnt vmcnt(1)
	v_and_b32_e32 v27, 0xffff0000, v16
	v_lshlrev_b32_e32 v28, 16, v18
	v_lshlrev_b32_e32 v26, 16, v16
	v_lshlrev_b32_e32 v16, 16, v17
	v_and_b32_e32 v17, 0xffff0000, v17
	v_and_b32_e32 v29, 0xffff0000, v18
	v_lshlrev_b32_e32 v18, 16, v19
	v_and_b32_e32 v19, 0xffff0000, v19
	s_waitcnt vmcnt(0)
	v_lshlrev_b32_e32 v30, 16, v20
	v_and_b32_e32 v31, 0xffff0000, v20
	v_lshlrev_b32_e32 v20, 16, v21
	v_and_b32_e32 v21, 0xffff0000, v21
	v_mov_b32_e32 v34, v252
	v_lshlrev_b32_e32 v36, 16, v22
	v_and_b32_e32 v37, 0xffff0000, v22
	v_lshlrev_b32_e32 v22, 16, v23
	v_and_b32_e32 v23, 0xffff0000, v23
	v_pk_mul_f32 v[12:13], v[12:13], v[34:35] op_sel_hi:[1,0]
	v_pk_mul_f32 v[14:15], v[14:15], v[34:35] op_sel_hi:[1,0]
	v_pk_mul_f32 v[8:9], v[8:9], v[34:35] op_sel_hi:[1,0]
	v_pk_mul_f32 v[10:11], v[10:11], v[34:35] op_sel_hi:[1,0]
	v_pk_mul_f32 v[4:5], v[4:5], v[34:35] op_sel_hi:[1,0]
	v_pk_mul_f32 v[6:7], v[6:7], v[34:35] op_sel_hi:[1,0]
	v_pk_mul_f32 v[0:1], v[0:1], v[34:35] op_sel_hi:[1,0]
	v_pk_mul_f32 v[2:3], v[2:3], v[34:35] op_sel_hi:[1,0]
	v_pk_fma_f32 v[14:15], v[106:107], v[14:15], v[16:17]
	v_pk_fma_f32 v[12:13], v[104:105], v[12:13], v[26:27]
	v_pk_fma_f32 v[10:11], v[102:103], v[10:11], v[18:19]
	v_pk_fma_f32 v[8:9], v[100:101], v[8:9], v[28:29]
	v_pk_fma_f32 v[6:7], v[110:111], v[6:7], v[20:21]
	v_pk_fma_f32 v[4:5], v[108:109], v[4:5], v[30:31]
	v_pk_fma_f32 v[16:17], v[98:99], v[2:3], v[22:23]
	v_pk_fma_f32 v[18:19], v[96:97], v[0:1], v[36:37]
	v_cvt_pk_bf16_f32 v0, v12, v13
	v_cvt_pk_bf16_f32 v1, v14, v15
	v_mul_f32_e32 v2, v13, v13
	v_mul_f32_e32 v3, v15, v15
	v_mul_f32_e32 v13, v9, v9
	v_mul_f32_e32 v15, v11, v11
	v_mul_f32_e32 v20, v5, v5
	v_mul_f32_e32 v21, v7, v7
	v_mul_f32_e32 v22, v19, v19
	v_mul_f32_e32 v23, v17, v17
	v_fmac_f32_e32 v2, v12, v12
	v_fmac_f32_e32 v3, v14, v14
	v_fmac_f32_e32 v13, v8, v8
	v_fmac_f32_e32 v15, v10, v10
	v_fmac_f32_e32 v20, v4, v4
	v_fmac_f32_e32 v21, v6, v6
	v_fmac_f32_e32 v22, v18, v18
	v_fmac_f32_e32 v23, v16, v16
	v_add_f32_e32 v2, v2, v3
	v_add_f32_e32 v3, v13, v15
	v_add_f32_e32 v12, v20, v21
	v_add_f32_e32 v13, v22, v23
	v_add_f32_e32 v2, v2, v3
	v_add_f32_e32 v3, v12, v13
	v_add_f32_e32 v12, v2, v3
	ds_bpermute_b32 v13, v145, v12
	v_cvt_pk_bf16_f32 v2, v8, v9
	v_cvt_pk_bf16_f32 v3, v10, v11
	global_store_dwordx4 v[24:25], v[0:3], off
	s_waitcnt lgkmcnt(0)
	s_nop 0
	v_add_f32_e32 v0, v12, v13
	ds_bpermute_b32 v1, v147, v0
	v_cvt_pk_bf16_f32 v2, v4, v5
	v_cvt_pk_bf16_f32 v3, v6, v7
	v_cvt_pk_bf16_f32 v4, v18, v19
	v_cvt_pk_bf16_f32 v5, v16, v17
	global_store_dwordx4 v[24:25], v[2:5], off offset:256
	s_and_saveexec_b64 s[0:1], s[4:5]
	s_cbranch_execz .LBB0_1409
	v_lshl_add_u32 v2, v32, 4, s24
	s_waitcnt lgkmcnt(0)
	v_add_f32_e32 v0, v0, v1
	ds_write_b32 v2, v0

; DI unsigned pk_bf16(float lo, float hi) { f32x2 v = {lo, hi}; bf16x2_t b = __builtin_convertvector(v, bf16x2_t); return __builtin_bit_cast(unsigned, b); }
; DI float bflo(unsigned w) { return __uint_as_float(w << 16); }
; DI float bfhi(unsigned w) { return __uint_as_float(w & 0xffff0000u); }
;     __device__ __forceinline__ void fused(f32x4 (&acc)[2][2][4][2], const pg8::Unit& u, int wr, int wc, int fr, int fq, PG8_LAS unsigned char* lds, int wid, int lane) const {
;     ...
;         const int colb = u.pn * 256 + wc * 32 + 8 * fq;
;         f32x4 gv[2][2];
; #pragma unroll
;         for (int bj = 0; bj < 2; ++bj)
; #pragma unroll
;             for (int n = 0; n < 2; ++n) gv[bj][n] = *(const f32x4*)(gA + colb + bj * 128 + 4 * n);
; #pragma unroll
;         for (int ai = 0; ai < 2; ++ai)
; #pragma unroll
;             for (int m = 0; m < 4; ++m) {
;                 const int rl = ai * 128 + wr * 64 + m * 16 + fr; const size_t row = (size_t)u.pm * 256 + rl;
;                 const float rm = 1.f / sqrtf(__hip_atomic_load(ssqm + row, __ATOMIC_RELAXED, __HIP_MEMORY_SCOPE_AGENT) * (1.f / DM) + RMS_EPS);
;                 float sh = 0.f;
; #pragma unroll
;                 for (int bj = 0; bj < 2; ++bj) {
;                     const size_t off = row * DM + colb + bj * 128;
;                     f32x4 h0, h1;
;                     if (IN16) { const u32x4 hw = *(const u32x4*)((const bf16_t*)hin + off); h0 = (f32x4){bflo(hw.x), bfhi(hw.x), bflo(hw.y), bfhi(hw.y)}; h1 = (f32x4){bflo(hw.z), bfhi(hw.z), bflo(hw.w), bfhi(hw.w)}; }
;                     else { h0 = *(const f32x4*)((const float*)hin + off); h1 = *(const f32x4*)((const float*)hin + off + 4); }
;                     h0 = h0 + acc[ai][bj][m][0] * rm * gv[bj][0]; h1 = h1 + acc[ai][bj][m][1] * rm * gv[bj][1];
;                     sh += ((h0[0] * h0[0] + h0[1] * h0[1]) + (h0[2] * h0[2] + h0[3] * h0[3])) + ((h1[0] * h1[0] + h1[1] * h1[1]) + (h1[2] * h1[2] + h1[3] * h1[3]));
;                     if (OUT16) { u32x4 w; w.x = pk_bf16(h0[0], h0[1]); w.y = pk_bf16(h0[2], h0[3]); w.z = pk_bf16(h1[0], h1[1]); w.w = pk_bf16(h1[2], h1[3]); *(u32x4*)((bf16_t*)hout + off) = w; }
;                     else { *(f32x4*)((float*)hout + off) = h0; *(f32x4*)((float*)hout + off + 4) = h1; }
;                 }
;                 if (ssqh) { sh += __shfl_xor(sh, 16); sh += __shfl_xor(sh, 32); if (fq == 0) red[rl * 4 + wc] = sh; }
.LBB0_1448:
	s_or_b64 exec, exec, s[2:3]
	s_lshl_b32 s1, s1, 5
	s_lshl_b32 s0, s0, 8
	s_or_b32 s0, s0, s1
	v_or_b32_e32 v146, s0, v160
	v_ashrrev_i32_e32 v147, 31, v146
	v_mov_b32_e32 v149, 0
	v_lshl_add_u64 v[108:109], v[146:147], 2, s[14:15]
	s_lshl_b64 s[14:15], s[16:17], 8
	v_mov_b32_e32 v153, v149
	v_lshl_add_u64 v[156:157], s[14:15], 0, v[152:153]
	v_lshl_add_u64 v[158:159], v[156:157], 2, s[12:13]
	s_barrier
	global_load_dwordx4 v[100:103], v[108:109], off offset:16
	global_load_dwordx4 v[104:107], v[108:109], off
	global_load_dwordx4 v[96:99], v[108:109], off offset:528
	s_nop 0
	global_load_dwordx4 v[108:111], v[108:109], off offset:512
	v_lshlrev_b64 v[156:157], 11, v[156:157]
	global_load_dword v148, v[158:159], off sc1
	v_lshl_add_u64 v[156:157], s[10:11], 0, v[156:157]
	v_lshl_add_u64 v[164:165], v[146:147], 1, v[156:157]
	global_load_dwordx4 v[156:159], v[164:165], off
	global_load_dwordx4 v[160:163], v[164:165], off offset:256
	v_mov_b32_e32 v155, 0x358637bd
	s_mov_b32 s2, 0xf800000
	v_mov_b32_e32 v153, 0x260
	s_waitcnt vmcnt(2)
	v_fmamk_f32 v148, v148, 0x3a800000, v155
	v_rsq_f32_e32 v252, v148
	s_nop 0
	v_mul_f32_e32 v253, v148, v252
	v_mul_f32_e32 v253, v253, v252
	v_fmaak_f32 v253, -0.5, v253, 0x3fc00000
	v_mul_f32_e32 v252, v252, v253
	s_waitcnt vmcnt(1)
	v_lshlrev_b32_e32 v166, 16, v156
	v_and_b32_e32 v167, 0xffff0000, v156
	v_lshlrev_b32_e32 v156, 16, v157
	v_and_b32_e32 v157, 0xffff0000, v157
	v_lshlrev_b32_e32 v168, 16, v158
	v_and_b32_e32 v169, 0xffff0000, v158
	v_lshlrev_b32_e32 v158, 16, v159
	v_and_b32_e32 v159, 0xffff0000, v159
	s_waitcnt vmcnt(0)
	v_lshlrev_b32_e32 v170, 16, v160
	v_and_b32_e32 v171, 0xffff0000, v160
	v_lshlrev_b32_e32 v160, 16, v161
	v_and_b32_e32 v161, 0xffff0000, v161
	v_mov_b32_e32 v148, v252
	v_lshlrev_b32_e32 v172, 16, v162
	v_and_b32_e32 v173, 0xffff0000, v162
	v_lshlrev_b32_e32 v162, 16, v163
	v_and_b32_e32 v163, 0xffff0000, v163
	v_pk_mul_f32 v[140:141], v[140:141], v[148:149] op_sel_hi:[1,0]
	v_pk_mul_f32 v[142:143], v[142:143], v[148:149] op_sel_hi:[1,0]
	v_pk_mul_f32 v[136:137], v[136:137], v[148:149] op_sel_hi:[1,0]
	v_pk_mul_f32 v[138:139], v[138:139], v[148:149] op_sel_hi:[1,0]
	v_pk_mul_f32 v[132:133], v[132:133], v[148:149] op_sel_hi:[1,0]
	v_pk_mul_f32 v[134:135], v[134:135], v[148:149] op_sel_hi:[1,0]
	v_pk_mul_f32 v[128:129], v[128:129], v[148:149] op_sel_hi:[1,0]
	v_pk_mul_f32 v[130:131], v[130:131], v[148:149] op_sel_hi:[1,0]
	v_pk_fma_f32 v[142:143], v[106:107], v[142:143], v[156:157]
	v_pk_fma_f32 v[140:141], v[104:105], v[140:141], v[166:167]
	v_pk_fma_f32 v[138:139], v[102:103], v[138:139], v[158:159]
	v_pk_fma_f32 v[136:137], v[100:101], v[136:137], v[168:169]
	v_pk_fma_f32 v[134:135], v[110:111], v[134:135], v[160:161]
	v_pk_fma_f32 v[132:133], v[108:109], v[132:133], v[170:171]
	v_pk_fma_f32 v[156:157], v[98:99], v[130:131], v[162:163]
	v_pk_fma_f32 v[158:159], v[96:97], v[128:129], v[172:173]
	v_cvt_pk_bf16_f32 v128, v140, v141
	v_cvt_pk_bf16_f32 v129, v142, v143
	v_mul_f32_e32 v130, v141, v141
	v_mul_f32_e32 v131, v143, v143
	v_mul_f32_e32 v141, v137, v137
	v_mul_f32_e32 v143, v139, v139
	v_mul_f32_e32 v148, v133, v133
	v_mul_f32_e32 v160, v135, v135
	v_mul_f32_e32 v161, v159, v159
	v_mul_f32_e32 v162, v157, v157
	v_fmac_f32_e32 v130, v140, v140
	v_fmac_f32_e32 v131, v142, v142
	v_fmac_f32_e32 v141, v136, v136
	v_fmac_f32_e32 v143, v138, v138
	v_fmac_f32_e32 v148, v132, v132
	v_fmac_f32_e32 v160, v134, v134
	v_fmac_f32_e32 v161, v158, v158
	v_fmac_f32_e32 v162, v156, v156
	v_add_f32_e32 v130, v130, v131
	v_add_f32_e32 v131, v141, v143
	v_add_f32_e32 v140, v148, v160
	v_add_f32_e32 v141, v161, v162
	v_add_f32_e32 v130, v130, v131
	v_add_f32_e32 v131, v140, v141
	v_add_f32_e32 v140, v130, v131
	ds_bpermute_b32 v141, v150, v140
	v_cvt_pk_bf16_f32 v130, v136, v137
	v_cvt_pk_bf16_f32 v131, v138, v139
	global_store_dwordx4 v[164:165], v[128:131], off
	s_waitcnt lgkmcnt(0)
	s_nop 0
	v_add_f32_e32 v128, v140, v141
	ds_bpermute_b32 v129, v151, v128
	v_cvt_pk_bf16_f32 v130, v132, v133
	v_cvt_pk_bf16_f32 v131, v134, v135
	v_cvt_pk_bf16_f32 v132, v158, v159
	v_cvt_pk_bf16_f32 v133, v156, v157
	global_store_dwordx4 v[164:165], v[130:133], off offset:256
	s_and_saveexec_b64 s[0:1], s[4:5]
	s_cbranch_execz .LBB0_1450
	v_lshl_add_u32 v130, v152, 4, s24
	s_waitcnt lgkmcnt(0)
	v_add_f32_e32 v128, v128, v129
	ds_write_b32 v130, v128
; DI unsigned pk_bf16(float lo, float hi) { f32x2 v = {lo, hi}; bf16x2_t b = __builtin_convertvector(v, bf16x2_t); return __builtin_bit_cast(unsigned, b); }
; DI float bflo(unsigned w) { return __uint_as_float(w << 16); }
; DI float bfhi(unsigned w) { return __uint_as_float(w & 0xffff0000u); }
;     __device__ __forceinline__ void fused(f32x4 (&acc)[2][2][4][2], const pg8::Unit& u, int wr, int wc, int fr, int fq, PG8_LAS unsigned char* lds, int wid, int lane) const {
;     ...
;         const int colb = u.pn * 256 + wc * 32 + 8 * fq;
;         f32x4 gv[2][2];
; #pragma unroll
;         for (int bj = 0; bj < 2; ++bj)
; #pragma unroll
;             for (int n = 0; n < 2; ++n) gv[bj][n] = *(const f32x4*)(gA + colb + bj * 128 + 4 * n);
; #pragma unroll
;         for (int ai = 0; ai < 2; ++ai)
; #pragma unroll
;             for (int m = 0; m < 4; ++m) {
;                 const int rl = ai * 128 + wr * 64 + m * 16 + fr; const size_t row = (size_t)u.pm * 256 + rl;
;                 const float rm = 1.f / sqrtf(__hip_atomic_load(ssqm + row, __ATOMIC_RELAXED, __HIP_MEMORY_SCOPE_AGENT) * (1.f / DM) + RMS_EPS);
;                 float sh = 0.f;
; #pragma unroll
;                 for (int bj = 0; bj < 2; ++bj) {
;                     const size_t off = row * DM + colb + bj * 128;
;                     f32x4 h0, h1;
;                     if (IN16) { const u32x4 hw = *(const u32x4*)((const bf16_t*)hin + off); h0 = (f32x4){bflo(hw.x), bfhi(hw.x), bflo(hw.y), bfhi(hw.y)}; h1 = (f32x4){bflo(hw.z), bfhi(hw.z), bflo(hw.w), bfhi(hw.w)}; }
;                     else { h0 = *(const f32x4*)((const float*)hin + off); h1 = *(const f32x4*)((const float*)hin + off + 4); }
;                     h0 = h0 + acc[ai][bj][m][0] * rm * gv[bj][0]; h1 = h1 + acc[ai][bj][m][1] * rm * gv[bj][1];
;                     sh += ((h0[0] * h0[0] + h0[1] * h0[1]) + (h0[2] * h0[2] + h0[3] * h0[3])) + ((h1[0] * h1[0] + h1[1] * h1[1]) + (h1[2] * h1[2] + h1[3] * h1[3]));
;                     if (OUT16) { u32x4 w; w.x = pk_bf16(h0[0], h0[1]); w.y = pk_bf16(h0[2], h0[3]); w.z = pk_bf16(h1[0], h1[1]); w.w = pk_bf16(h1[2], h1[3]); *(u32x4*)((bf16_t*)hout + off) = w; }
;                     else { *(f32x4*)((float*)hout + off) = h0; *(f32x4*)((float*)hout + off + 4) = h1; }
;                 }
;                 if (ssqh) { sh += __shfl_xor(sh, 16); sh += __shfl_xor(sh, 32); if (fq == 0) red[rl * 4 + wc] = sh; }
.LBB0_1450:
	s_or_b64 exec, exec, s[0:1]
	v_or_b32_e32 v148, 16, v152
	s_waitcnt lgkmcnt(0)
	v_lshl_add_u64 v[128:129], s[14:15], 0, v[148:149]
	v_lshl_add_u64 v[130:131], v[128:129], 2, s[12:13]
	global_load_dword v138, v[130:131], off sc1
	v_lshlrev_b64 v[128:129], 11, v[128:129]
	v_lshl_add_u64 v[128:129], s[10:11], 0, v[128:129]
	v_lshl_add_u64 v[136:137], v[146:147], 1, v[128:129]
	global_load_dwordx4 v[128:131], v[136:137], off
	global_load_dwordx4 v[132:135], v[136:137], off offset:256
	s_waitcnt vmcnt(2)
	v_fmac_f32_e32 v155, 0x3a800000, v138
	v_rsq_f32_e32 v252, v155
	s_nop 0
	v_mul_f32_e32 v253, v155, v252
	v_mul_f32_e32 v253, v253, v252
	v_fmaak_f32 v253, -0.5, v253, 0x3fc00000
	v_mul_f32_e32 v252, v252, v253
	s_waitcnt vmcnt(1)
	v_and_b32_e32 v139, 0xffff0000, v128
	v_lshlrev_b32_e32 v140, 16, v130
	v_lshlrev_b32_e32 v138, 16, v128
	v_lshlrev_b32_e32 v128, 16, v129
	v_and_b32_e32 v129, 0xffff0000, v129
	v_and_b32_e32 v141, 0xffff0000, v130
	v_lshlrev_b32_e32 v130, 16, v131
	v_and_b32_e32 v131, 0xffff0000, v131
	s_waitcnt vmcnt(0)
	v_lshlrev_b32_e32 v142, 16, v132
	v_and_b32_e32 v143, 0xffff0000, v132
	v_lshlrev_b32_e32 v132, 16, v133
	v_and_b32_e32 v133, 0xffff0000, v133
	v_mov_b32_e32 v158, v252
	v_lshlrev_b32_e32 v156, 16, v134
	v_and_b32_e32 v157, 0xffff0000, v134
	v_lshlrev_b32_e32 v134, 16, v135
	v_and_b32_e32 v135, 0xffff0000, v135
	v_pk_mul_f32 v[124:125], v[124:125], v[158:159] op_sel_hi:[1,0]
	v_pk_mul_f32 v[126:127], v[126:127], v[158:159] op_sel_hi:[1,0]
	v_pk_mul_f32 v[120:121], v[120:121], v[158:159] op_sel_hi:[1,0]
	v_pk_mul_f32 v[122:123], v[122:123], v[158:159] op_sel_hi:[1,0]
	v_pk_mul_f32 v[116:117], v[116:117], v[158:159] op_sel_hi:[1,0]
	v_pk_mul_f32 v[118:119], v[118:119], v[158:159] op_sel_hi:[1,0]
	v_pk_mul_f32 v[112:113], v[112:113], v[158:159] op_sel_hi:[1,0]
	v_pk_mul_f32 v[114:115], v[114:115], v[158:159] op_sel_hi:[1,0]
	v_pk_fma_f32 v[126:127], v[106:107], v[126:127], v[128:129]
	v_pk_fma_f32 v[124:125], v[104:105], v[124:125], v[138:139]
	v_pk_fma_f32 v[122:123], v[102:103], v[122:123], v[130:131]
	v_pk_fma_f32 v[120:121], v[100:101], v[120:121], v[140:141]
	v_pk_fma_f32 v[118:119], v[110:111], v[118:119], v[132:133]
	v_pk_fma_f32 v[116:117], v[108:109], v[116:117], v[142:143]
	v_pk_fma_f32 v[128:129], v[98:99], v[114:115], v[134:135]
	v_pk_fma_f32 v[130:131], v[96:97], v[112:113], v[156:157]
	v_cvt_pk_bf16_f32 v112, v124, v125
	v_cvt_pk_bf16_f32 v113, v126, v127
	v_mul_f32_e32 v114, v125, v125
	v_mul_f32_e32 v115, v127, v127
	v_mul_f32_e32 v125, v121, v121
	v_mul_f32_e32 v127, v123, v123
	v_mul_f32_e32 v132, v117, v117
	v_mul_f32_e32 v133, v119, v119
	v_mul_f32_e32 v134, v131, v131
	v_mul_f32_e32 v135, v129, v129
	v_fmac_f32_e32 v114, v124, v124
	v_fmac_f32_e32 v115, v126, v126
	v_fmac_f32_e32 v125, v120, v120
	v_fmac_f32_e32 v127, v122, v122
	v_fmac_f32_e32 v132, v116, v116
	v_fmac_f32_e32 v133, v118, v118
	v_fmac_f32_e32 v134, v130, v130
	v_fmac_f32_e32 v135, v128, v128
	v_add_f32_e32 v114, v114, v115
	v_add_f32_e32 v115, v125, v127
	v_add_f32_e32 v124, v132, v133
	v_add_f32_e32 v125, v134, v135
	v_add_f32_e32 v114, v114, v115
	v_add_f32_e32 v115, v124, v125
	v_add_f32_e32 v124, v114, v115
	ds_bpermute_b32 v125, v150, v124
	v_cvt_pk_bf16_f32 v114, v120, v121
	v_cvt_pk_bf16_f32 v115, v122, v123
	global_store_dwordx4 v[136:137], v[112:115], off
	s_waitcnt lgkmcnt(0)
	s_nop 0
	v_add_f32_e32 v112, v124, v125
	ds_bpermute_b32 v113, v151, v112
	v_cvt_pk_bf16_f32 v114, v116, v117
	v_cvt_pk_bf16_f32 v115, v118, v119
	v_cvt_pk_bf16_f32 v116, v130, v131
	v_cvt_pk_bf16_f32 v117, v128, v129
	global_store_dwordx4 v[136:137], v[114:117], off offset:256
	s_and_saveexec_b64 s[0:1], s[4:5]
	s_cbranch_execz .LBB0_1452
	v_lshl_add_u32 v114, v148, 4, s24
	s_waitcnt lgkmcnt(0)
	v_add_f32_e32 v112, v112, v113
	ds_write_b32 v114, v112
.LBB0_1452:
	s_or_b64 exec, exec, s[0:1]
	v_or_b32_e32 v112, 32, v152
	s_waitcnt lgkmcnt(0)
	v_mov_b32_e32 v113, 0
	v_lshl_add_u64 v[114:115], s[14:15], 0, v[112:113]
	v_lshl_add_u64 v[116:117], v[114:115], 2, s[12:13]
	global_load_dword v126, v[116:117], off sc1
	v_lshlrev_b64 v[114:115], 11, v[114:115]
	v_lshl_add_u64 v[114:115], s[10:11], 0, v[114:115]
	v_lshl_add_u64 v[124:125], v[146:147], 1, v[114:115]
	global_load_dwordx4 v[116:119], v[124:125], off
	global_load_dwordx4 v[120:123], v[124:125], off offset:256
	v_mov_b32_e32 v115, 0x358637bd
	v_mov_b32_e32 v114, 0x260
	s_waitcnt vmcnt(2)
	v_fmamk_f32 v126, v126, 0x3a800000, v115
	v_rsq_f32_e32 v252, v126
	s_nop 0
	v_mul_f32_e32 v253, v126, v252
	v_mul_f32_e32 v253, v253, v252
	v_fmaak_f32 v253, -0.5, v253, 0x3fc00000
	v_mul_f32_e32 v252, v252, v253
	s_waitcnt vmcnt(1)
	v_lshlrev_b32_e32 v128, 16, v118
	v_and_b32_e32 v129, 0xffff0000, v118
	v_lshlrev_b32_e32 v126, 16, v116
	v_and_b32_e32 v127, 0xffff0000, v116
	v_lshlrev_b32_e32 v116, 16, v117
	v_and_b32_e32 v117, 0xffff0000, v117
	v_lshlrev_b32_e32 v118, 16, v119
	v_and_b32_e32 v119, 0xffff0000, v119
	s_waitcnt vmcnt(0)
; DI unsigned pk_bf16(float lo, float hi) { f32x2 v = {lo, hi}; bf16x2_t b = __builtin_convertvector(v, bf16x2_t); return __builtin_bit_cast(unsigned, b); }
; DI float bflo(unsigned w) { return __uint_as_float(w << 16); }
; DI float bfhi(unsigned w) { return __uint_as_float(w & 0xffff0000u); }
;     __device__ __forceinline__ void fused(f32x4 (&acc)[2][2][4][2], const pg8::Unit& u, int wr, int wc, int fr, int fq, PG8_LAS unsigned char* lds, int wid, int lane) const {
;     ...
;         const int colb = u.pn * 256 + wc * 32 + 8 * fq;
;         f32x4 gv[2][2];
; #pragma unroll
;         for (int bj = 0; bj < 2; ++bj)
; #pragma unroll
;             for (int n = 0; n < 2; ++n) gv[bj][n] = *(const f32x4*)(gA + colb + bj * 128 + 4 * n);
; #pragma unroll
;         for (int ai = 0; ai < 2; ++ai)
; #pragma unroll
;             for (int m = 0; m < 4; ++m) {
;                 const int rl = ai * 128 + wr * 64 + m * 16 + fr; const size_t row = (size_t)u.pm * 256 + rl;
;                 const float rm = 1.f / sqrtf(__hip_atomic_load(ssqm + row, __ATOMIC_RELAXED, __HIP_MEMORY_SCOPE_AGENT) * (1.f / DM) + RMS_EPS);
;                 float sh = 0.f;
; #pragma unroll
;                 for (int bj = 0; bj < 2; ++bj) {
;                     const size_t off = row * DM + colb + bj * 128;
;                     f32x4 h0, h1;
;                     if (IN16) { const u32x4 hw = *(const u32x4*)((const bf16_t*)hin + off); h0 = (f32x4){bflo(hw.x), bfhi(hw.x), bflo(hw.y), bfhi(hw.y)}; h1 = (f32x4){bflo(hw.z), bfhi(hw.z), bflo(hw.w), bfhi(hw.w)}; }
;                     else { h0 = *(const f32x4*)((const float*)hin + off); h1 = *(const f32x4*)((const float*)hin + off + 4); }
;                     h0 = h0 + acc[ai][bj][m][0] * rm * gv[bj][0]; h1 = h1 + acc[ai][bj][m][1] * rm * gv[bj][1];
;                     sh += ((h0[0] * h0[0] + h0[1] * h0[1]) + (h0[2] * h0[2] + h0[3] * h0[3])) + ((h1[0] * h1[0] + h1[1] * h1[1]) + (h1[2] * h1[2] + h1[3] * h1[3]));
;                     if (OUT16) { u32x4 w; w.x = pk_bf16(h0[0], h0[1]); w.y = pk_bf16(h0[2], h0[3]); w.z = pk_bf16(h1[0], h1[1]); w.w = pk_bf16(h1[2], h1[3]); *(u32x4*)((bf16_t*)hout + off) = w; }
;                     else { *(f32x4*)((float*)hout + off) = h0; *(f32x4*)((float*)hout + off + 4) = h1; }
;                 }
;                 if (ssqh) { sh += __shfl_xor(sh, 16); sh += __shfl_xor(sh, 32); if (fq == 0) red[rl * 4 + wc] = sh; }
	v_lshlrev_b32_e32 v130, 16, v120
	v_and_b32_e32 v131, 0xffff0000, v120
	v_lshlrev_b32_e32 v120, 16, v121
	v_and_b32_e32 v121, 0xffff0000, v121
	v_mov_b32_e32 v134, v252
	v_lshlrev_b32_e32 v132, 16, v122
	v_and_b32_e32 v133, 0xffff0000, v122
	v_lshlrev_b32_e32 v122, 16, v123
	v_and_b32_e32 v123, 0xffff0000, v123
	v_pk_mul_f32 v[92:93], v[92:93], v[134:135] op_sel_hi:[1,0]
	v_pk_mul_f32 v[94:95], v[94:95], v[134:135] op_sel_hi:[1,0]
	v_pk_mul_f32 v[88:89], v[88:89], v[134:135] op_sel_hi:[1,0]
	v_pk_mul_f32 v[90:91], v[90:91], v[134:135] op_sel_hi:[1,0]
	v_pk_mul_f32 v[84:85], v[84:85], v[134:135] op_sel_hi:[1,0]
	v_pk_mul_f32 v[86:87], v[86:87], v[134:135] op_sel_hi:[1,0]
	v_pk_mul_f32 v[80:81], v[80:81], v[134:135] op_sel_hi:[1,0]
	v_pk_mul_f32 v[82:83], v[82:83], v[134:135] op_sel_hi:[1,0]
	v_pk_fma_f32 v[94:95], v[106:107], v[94:95], v[116:117]
	v_pk_fma_f32 v[92:93], v[104:105], v[92:93], v[126:127]
	v_pk_fma_f32 v[90:91], v[102:103], v[90:91], v[118:119]
	v_pk_fma_f32 v[88:89], v[100:101], v[88:89], v[128:129]
	v_pk_fma_f32 v[86:87], v[110:111], v[86:87], v[120:121]
	v_pk_fma_f32 v[84:85], v[108:109], v[84:85], v[130:131]
	v_pk_fma_f32 v[116:117], v[98:99], v[82:83], v[122:123]
	v_pk_fma_f32 v[118:119], v[96:97], v[80:81], v[132:133]
	v_cvt_pk_bf16_f32 v80, v92, v93
	v_cvt_pk_bf16_f32 v81, v94, v95
	v_mul_f32_e32 v82, v93, v93
	v_mul_f32_e32 v83, v95, v95
	v_mul_f32_e32 v93, v89, v89
	v_mul_f32_e32 v95, v91, v91
	v_mul_f32_e32 v120, v85, v85
	v_mul_f32_e32 v121, v87, v87
	v_mul_f32_e32 v122, v119, v119
	v_mul_f32_e32 v123, v117, v117
	v_fmac_f32_e32 v82, v92, v92
	v_fmac_f32_e32 v83, v94, v94
	v_fmac_f32_e32 v93, v88, v88
	v_fmac_f32_e32 v95, v90, v90
	v_fmac_f32_e32 v120, v84, v84
	v_fmac_f32_e32 v121, v86, v86
	v_fmac_f32_e32 v122, v118, v118
	v_fmac_f32_e32 v123, v116, v116
	v_add_f32_e32 v82, v82, v83
	v_add_f32_e32 v83, v93, v95
	v_add_f32_e32 v92, v120, v121
	v_add_f32_e32 v93, v122, v123
	v_add_f32_e32 v82, v82, v83
	v_add_f32_e32 v83, v92, v93
	v_add_f32_e32 v92, v82, v83
	ds_bpermute_b32 v93, v150, v92
	v_cvt_pk_bf16_f32 v82, v88, v89
	v_cvt_pk_bf16_f32 v83, v90, v91
	global_store_dwordx4 v[124:125], v[80:83], off
	s_waitcnt lgkmcnt(0)
	s_nop 0
	v_add_f32_e32 v80, v92, v93
	ds_bpermute_b32 v81, v151, v80
	v_cvt_pk_bf16_f32 v82, v84, v85
	v_cvt_pk_bf16_f32 v83, v86, v87
	v_cvt_pk_bf16_f32 v84, v118, v119
	v_cvt_pk_bf16_f32 v85, v116, v117
	global_store_dwordx4 v[124:125], v[82:85], off offset:256
	s_and_saveexec_b64 s[0:1], s[4:5]
	s_cbranch_execz .LBB0_1454
	v_lshl_add_u32 v82, v112, 4, s24
	s_waitcnt lgkmcnt(0)
	v_add_f32_e32 v80, v80, v81
	ds_write_b32 v82, v80
.LBB0_1454:
	s_or_b64 exec, exec, s[0:1]
	v_or_b32_e32 v112, 48, v152
	s_waitcnt lgkmcnt(0)
	v_lshl_add_u64 v[80:81], s[14:15], 0, v[112:113]
	v_lshl_add_u64 v[82:83], v[80:81], 2, s[12:13]
	global_load_dword v90, v[82:83], off sc1
	v_lshlrev_b64 v[80:81], 11, v[80:81]
	v_lshl_add_u64 v[80:81], s[10:11], 0, v[80:81]
	v_lshl_add_u64 v[88:89], v[146:147], 1, v[80:81]
	global_load_dwordx4 v[80:83], v[88:89], off
	global_load_dwordx4 v[84:87], v[88:89], off offset:256
	s_waitcnt vmcnt(2)
	v_fmac_f32_e32 v115, 0x3a800000, v90
	v_rsq_f32_e32 v252, v115
	s_nop 0
	v_mul_f32_e32 v253, v115, v252
	v_mul_f32_e32 v253, v253, v252
	v_fmaak_f32 v253, -0.5, v253, 0x3fc00000
	v_mul_f32_e32 v252, v252, v253
	s_waitcnt vmcnt(1)
	v_and_b32_e32 v91, 0xffff0000, v80
	v_lshlrev_b32_e32 v92, 16, v82
	v_lshlrev_b32_e32 v90, 16, v80
	v_lshlrev_b32_e32 v80, 16, v81
	v_and_b32_e32 v81, 0xffff0000, v81
	v_and_b32_e32 v93, 0xffff0000, v82
	v_lshlrev_b32_e32 v82, 16, v83
	v_and_b32_e32 v83, 0xffff0000, v83
	s_waitcnt vmcnt(0)
	v_lshlrev_b32_e32 v94, 16, v84
	v_and_b32_e32 v95, 0xffff0000, v84
	v_lshlrev_b32_e32 v84, 16, v85
	v_and_b32_e32 v85, 0xffff0000, v85
	v_mov_b32_e32 v114, v252
	v_lshlrev_b32_e32 v116, 16, v86
	v_and_b32_e32 v117, 0xffff0000, v86
	v_lshlrev_b32_e32 v86, 16, v87
	v_and_b32_e32 v87, 0xffff0000, v87
	v_pk_mul_f32 v[76:77], v[76:77], v[114:115] op_sel_hi:[1,0]
	v_pk_mul_f32 v[78:79], v[78:79], v[114:115] op_sel_hi:[1,0]
	v_pk_mul_f32 v[72:73], v[72:73], v[114:115] op_sel_hi:[1,0]
	v_pk_mul_f32 v[74:75], v[74:75], v[114:115] op_sel_hi:[1,0]
	v_pk_mul_f32 v[68:69], v[68:69], v[114:115] op_sel_hi:[1,0]
	v_pk_mul_f32 v[70:71], v[70:71], v[114:115] op_sel_hi:[1,0]
	v_pk_mul_f32 v[64:65], v[64:65], v[114:115] op_sel_hi:[1,0]
	v_pk_mul_f32 v[66:67], v[66:67], v[114:115] op_sel_hi:[1,0]
	v_pk_fma_f32 v[78:79], v[106:107], v[78:79], v[80:81]
	v_pk_fma_f32 v[76:77], v[104:105], v[76:77], v[90:91]
	v_pk_fma_f32 v[74:75], v[102:103], v[74:75], v[82:83]
	v_pk_fma_f32 v[72:73], v[100:101], v[72:73], v[92:93]
	v_pk_fma_f32 v[70:71], v[110:111], v[70:71], v[84:85]
	v_pk_fma_f32 v[68:69], v[108:109], v[68:69], v[94:95]
	v_pk_fma_f32 v[80:81], v[98:99], v[66:67], v[86:87]
	v_pk_fma_f32 v[82:83], v[96:97], v[64:65], v[116:117]
	v_cvt_pk_bf16_f32 v64, v76, v77
	v_cvt_pk_bf16_f32 v65, v78, v79
	v_mul_f32_e32 v66, v77, v77
	v_mul_f32_e32 v67, v79, v79
	v_mul_f32_e32 v77, v73, v73
	v_mul_f32_e32 v79, v75, v75
	v_mul_f32_e32 v84, v69, v69
	v_mul_f32_e32 v85, v71, v71
	v_mul_f32_e32 v86, v83, v83
	v_mul_f32_e32 v87, v81, v81
	v_fmac_f32_e32 v66, v76, v76
	v_fmac_f32_e32 v67, v78, v78
	v_fmac_f32_e32 v77, v72, v72
	v_fmac_f32_e32 v79, v74, v74
	v_fmac_f32_e32 v84, v68, v68
	v_fmac_f32_e32 v85, v70, v70
	v_fmac_f32_e32 v86, v82, v82
	v_fmac_f32_e32 v87, v80, v80
	v_add_f32_e32 v66, v66, v67
	v_add_f32_e32 v67, v77, v79
	v_add_f32_e32 v76, v84, v85
	v_add_f32_e32 v77, v86, v87
	v_add_f32_e32 v66, v66, v67
	v_add_f32_e32 v67, v76, v77
	v_add_f32_e32 v76, v66, v67
	ds_bpermute_b32 v77, v150, v76
	v_cvt_pk_bf16_f32 v66, v72, v73
	v_cvt_pk_bf16_f32 v67, v74, v75
	global_store_dwordx4 v[88:89], v[64:67], off
	s_waitcnt lgkmcnt(0)
	s_nop 0
	v_add_f32_e32 v64, v76, v77
	ds_bpermute_b32 v65, v151, v64
	v_cvt_pk_bf16_f32 v66, v68, v69
	v_cvt_pk_bf16_f32 v67, v70, v71
	v_cvt_pk_bf16_f32 v68, v82, v83
	v_cvt_pk_bf16_f32 v69, v80, v81
	global_store_dwordx4 v[88:89], v[66:69], off offset:256
	s_and_saveexec_b64 s[0:1], s[4:5]
	s_cbranch_execz .LBB0_1456
	v_lshl_add_u32 v66, v112, 4, s24
	s_waitcnt lgkmcnt(0)
	v_add_f32_e32 v64, v64, v65
	ds_write_b32 v66, v64
; DI unsigned pk_bf16(float lo, float hi) { f32x2 v = {lo, hi}; bf16x2_t b = __builtin_convertvector(v, bf16x2_t); return __builtin_bit_cast(unsigned, b); }
; DI float bflo(unsigned w) { return __uint_as_float(w << 16); }
; DI float bfhi(unsigned w) { return __uint_as_float(w & 0xffff0000u); }
;     __device__ __forceinline__ void fused(f32x4 (&acc)[2][2][4][2], const pg8::Unit& u, int wr, int wc, int fr, int fq, PG8_LAS unsigned char* lds, int wid, int lane) const {
;     ...
;         const int colb = u.pn * 256 + wc * 32 + 8 * fq;
;         f32x4 gv[2][2];
; #pragma unroll
;         for (int bj = 0; bj < 2; ++bj)
; #pragma unroll
;             for (int n = 0; n < 2; ++n) gv[bj][n] = *(const f32x4*)(gA + colb + bj * 128 + 4 * n);
; #pragma unroll
;         for (int ai = 0; ai < 2; ++ai)
; #pragma unroll
;             for (int m = 0; m < 4; ++m) {
;                 const int rl = ai * 128 + wr * 64 + m * 16 + fr; const size_t row = (size_t)u.pm * 256 + rl;
;                 const float rm = 1.f / sqrtf(__hip_atomic_load(ssqm + row, __ATOMIC_RELAXED, __HIP_MEMORY_SCOPE_AGENT) * (1.f / DM) + RMS_EPS);
;                 float sh = 0.f;
; #pragma unroll
;                 for (int bj = 0; bj < 2; ++bj) {
;                     const size_t off = row * DM + colb + bj * 128;
;                     f32x4 h0, h1;
;                     if (IN16) { const u32x4 hw = *(const u32x4*)((const bf16_t*)hin + off); h0 = (f32x4){bflo(hw.x), bfhi(hw.x), bflo(hw.y), bfhi(hw.y)}; h1 = (f32x4){bflo(hw.z), bfhi(hw.z), bflo(hw.w), bfhi(hw.w)}; }
;                     else { h0 = *(const f32x4*)((const float*)hin + off); h1 = *(const f32x4*)((const float*)hin + off + 4); }
;                     h0 = h0 + acc[ai][bj][m][0] * rm * gv[bj][0]; h1 = h1 + acc[ai][bj][m][1] * rm * gv[bj][1];
;                     sh += ((h0[0] * h0[0] + h0[1] * h0[1]) + (h0[2] * h0[2] + h0[3] * h0[3])) + ((h1[0] * h1[0] + h1[1] * h1[1]) + (h1[2] * h1[2] + h1[3] * h1[3]));
;                     if (OUT16) { u32x4 w; w.x = pk_bf16(h0[0], h0[1]); w.y = pk_bf16(h0[2], h0[3]); w.z = pk_bf16(h1[0], h1[1]); w.w = pk_bf16(h1[2], h1[3]); *(u32x4*)((bf16_t*)hout + off) = w; }
;                     else { *(f32x4*)((float*)hout + off) = h0; *(f32x4*)((float*)hout + off + 4) = h1; }
;                 }
;                 if (ssqh) { sh += __shfl_xor(sh, 16); sh += __shfl_xor(sh, 32); if (fq == 0) red[rl * 4 + wc] = sh; }
.LBB0_1456:
	s_or_b64 exec, exec, s[0:1]
	v_add_u32_e32 v64, 0x80, v152
	s_waitcnt lgkmcnt(0)
	v_mov_b32_e32 v65, 0
	v_lshl_add_u64 v[66:67], s[14:15], 0, v[64:65]
	v_lshl_add_u64 v[68:69], v[66:67], 2, s[12:13]
	global_load_dword v78, v[68:69], off sc1
	v_lshlrev_b64 v[66:67], 11, v[66:67]
	v_lshl_add_u64 v[66:67], s[10:11], 0, v[66:67]
	v_lshl_add_u64 v[76:77], v[146:147], 1, v[66:67]
	global_load_dwordx4 v[68:71], v[76:77], off
	global_load_dwordx4 v[72:75], v[76:77], off offset:256
	v_mov_b32_e32 v67, 0x358637bd
	v_mov_b32_e32 v66, 0x260
	s_waitcnt vmcnt(2)
	v_fmamk_f32 v78, v78, 0x3a800000, v67
	v_rsq_f32_e32 v252, v78
	s_nop 0
	v_mul_f32_e32 v253, v78, v252
	v_mul_f32_e32 v253, v253, v252
	v_fmaak_f32 v253, -0.5, v253, 0x3fc00000
	v_mul_f32_e32 v252, v252, v253
	s_waitcnt vmcnt(1)
	v_lshlrev_b32_e32 v80, 16, v70
	v_and_b32_e32 v81, 0xffff0000, v70
	v_lshlrev_b32_e32 v78, 16, v68
	v_and_b32_e32 v79, 0xffff0000, v68
	v_lshlrev_b32_e32 v68, 16, v69
	v_and_b32_e32 v69, 0xffff0000, v69
	v_lshlrev_b32_e32 v70, 16, v71
	v_and_b32_e32 v71, 0xffff0000, v71
	s_waitcnt vmcnt(0)
	v_lshlrev_b32_e32 v82, 16, v72
	v_and_b32_e32 v83, 0xffff0000, v72
	v_lshlrev_b32_e32 v72, 16, v73
	v_and_b32_e32 v73, 0xffff0000, v73
	v_mov_b32_e32 v86, v252
	v_lshlrev_b32_e32 v84, 16, v74
	v_and_b32_e32 v85, 0xffff0000, v74
	v_lshlrev_b32_e32 v74, 16, v75
	v_and_b32_e32 v75, 0xffff0000, v75
	v_pk_mul_f32 v[60:61], v[60:61], v[86:87] op_sel_hi:[1,0]
	v_pk_mul_f32 v[62:63], v[62:63], v[86:87] op_sel_hi:[1,0]
	v_pk_mul_f32 v[56:57], v[56:57], v[86:87] op_sel_hi:[1,0]
	v_pk_mul_f32 v[58:59], v[58:59], v[86:87] op_sel_hi:[1,0]
	v_pk_mul_f32 v[52:53], v[52:53], v[86:87] op_sel_hi:[1,0]
	v_pk_mul_f32 v[54:55], v[54:55], v[86:87] op_sel_hi:[1,0]
	v_pk_mul_f32 v[48:49], v[48:49], v[86:87] op_sel_hi:[1,0]
	v_pk_mul_f32 v[50:51], v[50:51], v[86:87] op_sel_hi:[1,0]
	v_pk_fma_f32 v[62:63], v[106:107], v[62:63], v[68:69]
	v_pk_fma_f32 v[60:61], v[104:105], v[60:61], v[78:79]
	v_pk_fma_f32 v[58:59], v[102:103], v[58:59], v[70:71]
	v_pk_fma_f32 v[56:57], v[100:101], v[56:57], v[80:81]
	v_pk_fma_f32 v[54:55], v[110:111], v[54:55], v[72:73]
	v_pk_fma_f32 v[52:53], v[108:109], v[52:53], v[82:83]
	v_pk_fma_f32 v[68:69], v[98:99], v[50:51], v[74:75]
	v_pk_fma_f32 v[70:71], v[96:97], v[48:49], v[84:85]
	v_cvt_pk_bf16_f32 v48, v60, v61
	v_cvt_pk_bf16_f32 v49, v62, v63
	v_mul_f32_e32 v50, v61, v61
	v_mul_f32_e32 v51, v63, v63
	v_mul_f32_e32 v61, v57, v57
	v_mul_f32_e32 v63, v59, v59
	v_mul_f32_e32 v72, v53, v53
	v_mul_f32_e32 v73, v55, v55
	v_mul_f32_e32 v74, v71, v71
	v_mul_f32_e32 v75, v69, v69
	v_fmac_f32_e32 v50, v60, v60
	v_fmac_f32_e32 v51, v62, v62
	v_fmac_f32_e32 v61, v56, v56
	v_fmac_f32_e32 v63, v58, v58
	v_fmac_f32_e32 v72, v52, v52
	v_fmac_f32_e32 v73, v54, v54
	v_fmac_f32_e32 v74, v70, v70
	v_fmac_f32_e32 v75, v68, v68
	v_add_f32_e32 v50, v50, v51
	v_add_f32_e32 v51, v61, v63
	v_add_f32_e32 v60, v72, v73
	v_add_f32_e32 v61, v74, v75
	v_add_f32_e32 v50, v50, v51
	v_add_f32_e32 v51, v60, v61
	v_add_f32_e32 v60, v50, v51
	ds_bpermute_b32 v61, v150, v60
	v_cvt_pk_bf16_f32 v50, v56, v57
	v_cvt_pk_bf16_f32 v51, v58, v59
	global_store_dwordx4 v[76:77], v[48:51], off
	s_waitcnt lgkmcnt(0)
	s_nop 0
	v_add_f32_e32 v48, v60, v61
	ds_bpermute_b32 v49, v151, v48
	v_cvt_pk_bf16_f32 v50, v52, v53
	v_cvt_pk_bf16_f32 v51, v54, v55
	v_cvt_pk_bf16_f32 v52, v70, v71
	v_cvt_pk_bf16_f32 v53, v68, v69
	global_store_dwordx4 v[76:77], v[50:53], off offset:256
	s_and_saveexec_b64 s[0:1], s[4:5]
	s_cbranch_execz .LBB0_1458
	v_lshl_add_u32 v50, v64, 4, s24
	s_waitcnt lgkmcnt(0)
	v_add_f32_e32 v48, v48, v49
	ds_write_b32 v50, v48
.LBB0_1458:
	s_or_b64 exec, exec, s[0:1]
	v_add_u32_e32 v64, 0x90, v152
	s_waitcnt lgkmcnt(0)
	v_lshl_add_u64 v[48:49], s[14:15], 0, v[64:65]
	v_lshl_add_u64 v[50:51], v[48:49], 2, s[12:13]
	global_load_dword v58, v[50:51], off sc1
	v_lshlrev_b64 v[48:49], 11, v[48:49]
	v_lshl_add_u64 v[48:49], s[10:11], 0, v[48:49]
	v_lshl_add_u64 v[56:57], v[146:147], 1, v[48:49]
	global_load_dwordx4 v[48:51], v[56:57], off
	global_load_dwordx4 v[52:55], v[56:57], off offset:256
	s_waitcnt vmcnt(2)
	v_fmac_f32_e32 v67, 0x3a800000, v58
	v_rsq_f32_e32 v252, v67
	s_nop 0
	v_mul_f32_e32 v253, v67, v252
	v_mul_f32_e32 v253, v253, v252
	v_fmaak_f32 v253, -0.5, v253, 0x3fc00000
	v_mul_f32_e32 v252, v252, v253
	s_waitcnt vmcnt(1)
	v_and_b32_e32 v59, 0xffff0000, v48
	v_lshlrev_b32_e32 v60, 16, v50
	v_lshlrev_b32_e32 v58, 16, v48
	v_lshlrev_b32_e32 v48, 16, v49
	v_and_b32_e32 v49, 0xffff0000, v49
	v_and_b32_e32 v61, 0xffff0000, v50
	v_lshlrev_b32_e32 v50, 16, v51
	v_and_b32_e32 v51, 0xffff0000, v51
	s_waitcnt vmcnt(0)
; DI unsigned pk_bf16(float lo, float hi) { f32x2 v = {lo, hi}; bf16x2_t b = __builtin_convertvector(v, bf16x2_t); return __builtin_bit_cast(unsigned, b); }
; DI float bflo(unsigned w) { return __uint_as_float(w << 16); }
; DI float bfhi(unsigned w) { return __uint_as_float(w & 0xffff0000u); }
;     __device__ __forceinline__ void fused(f32x4 (&acc)[2][2][4][2], const pg8::Unit& u, int wr, int wc, int fr, int fq, PG8_LAS unsigned char* lds, int wid, int lane) const {
;     ...
;         const int colb = u.pn * 256 + wc * 32 + 8 * fq;
;         f32x4 gv[2][2];
; #pragma unroll
;         for (int bj = 0; bj < 2; ++bj)
; #pragma unroll
;             for (int n = 0; n < 2; ++n) gv[bj][n] = *(const f32x4*)(gA + colb + bj * 128 + 4 * n);
; #pragma unroll
;         for (int ai = 0; ai < 2; ++ai)
; #pragma unroll
;             for (int m = 0; m < 4; ++m) {
;                 const int rl = ai * 128 + wr * 64 + m * 16 + fr; const size_t row = (size_t)u.pm * 256 + rl;
;                 const float rm = 1.f / sqrtf(__hip_atomic_load(ssqm + row, __ATOMIC_RELAXED, __HIP_MEMORY_SCOPE_AGENT) * (1.f / DM) + RMS_EPS);
;                 float sh = 0.f;
; #pragma unroll
;                 for (int bj = 0; bj < 2; ++bj) {
;                     const size_t off = row * DM + colb + bj * 128;
;                     f32x4 h0, h1;
;                     if (IN16) { const u32x4 hw = *(const u32x4*)((const bf16_t*)hin + off); h0 = (f32x4){bflo(hw.x), bfhi(hw.x), bflo(hw.y), bfhi(hw.y)}; h1 = (f32x4){bflo(hw.z), bfhi(hw.z), bflo(hw.w), bfhi(hw.w)}; }
;                     else { h0 = *(const f32x4*)((const float*)hin + off); h1 = *(const f32x4*)((const float*)hin + off + 4); }
;                     h0 = h0 + acc[ai][bj][m][0] * rm * gv[bj][0]; h1 = h1 + acc[ai][bj][m][1] * rm * gv[bj][1];
;                     sh += ((h0[0] * h0[0] + h0[1] * h0[1]) + (h0[2] * h0[2] + h0[3] * h0[3])) + ((h1[0] * h1[0] + h1[1] * h1[1]) + (h1[2] * h1[2] + h1[3] * h1[3]));
;                     if (OUT16) { u32x4 w; w.x = pk_bf16(h0[0], h0[1]); w.y = pk_bf16(h0[2], h0[3]); w.z = pk_bf16(h1[0], h1[1]); w.w = pk_bf16(h1[2], h1[3]); *(u32x4*)((bf16_t*)hout + off) = w; }
;                     else { *(f32x4*)((float*)hout + off) = h0; *(f32x4*)((float*)hout + off + 4) = h1; }
;                 }
;                 if (ssqh) { sh += __shfl_xor(sh, 16); sh += __shfl_xor(sh, 32); if (fq == 0) red[rl * 4 + wc] = sh; }
	v_lshlrev_b32_e32 v62, 16, v52
	v_and_b32_e32 v63, 0xffff0000, v52
	v_lshlrev_b32_e32 v52, 16, v53
	v_and_b32_e32 v53, 0xffff0000, v53
	v_mov_b32_e32 v66, v252
	v_lshlrev_b32_e32 v68, 16, v54
	v_and_b32_e32 v69, 0xffff0000, v54
	v_lshlrev_b32_e32 v54, 16, v55
	v_and_b32_e32 v55, 0xffff0000, v55
	v_pk_mul_f32 v[44:45], v[44:45], v[66:67] op_sel_hi:[1,0]
	v_pk_mul_f32 v[46:47], v[46:47], v[66:67] op_sel_hi:[1,0]
	v_pk_mul_f32 v[40:41], v[40:41], v[66:67] op_sel_hi:[1,0]
	v_pk_mul_f32 v[42:43], v[42:43], v[66:67] op_sel_hi:[1,0]
	v_pk_mul_f32 v[36:37], v[36:37], v[66:67] op_sel_hi:[1,0]
	v_pk_mul_f32 v[38:39], v[38:39], v[66:67] op_sel_hi:[1,0]
	v_pk_mul_f32 v[32:33], v[32:33], v[66:67] op_sel_hi:[1,0]
	v_pk_mul_f32 v[34:35], v[34:35], v[66:67] op_sel_hi:[1,0]
	v_pk_fma_f32 v[46:47], v[106:107], v[46:47], v[48:49]
	v_pk_fma_f32 v[44:45], v[104:105], v[44:45], v[58:59]
	v_pk_fma_f32 v[42:43], v[102:103], v[42:43], v[50:51]
	v_pk_fma_f32 v[40:41], v[100:101], v[40:41], v[60:61]
	v_pk_fma_f32 v[38:39], v[110:111], v[38:39], v[52:53]
	v_pk_fma_f32 v[36:37], v[108:109], v[36:37], v[62:63]
	v_pk_fma_f32 v[48:49], v[98:99], v[34:35], v[54:55]
	v_pk_fma_f32 v[50:51], v[96:97], v[32:33], v[68:69]
	v_cvt_pk_bf16_f32 v32, v44, v45
	v_cvt_pk_bf16_f32 v33, v46, v47
	v_mul_f32_e32 v34, v45, v45
	v_mul_f32_e32 v35, v47, v47
	v_mul_f32_e32 v45, v41, v41
	v_mul_f32_e32 v47, v43, v43
	v_mul_f32_e32 v52, v37, v37
	v_mul_f32_e32 v53, v39, v39
	v_mul_f32_e32 v54, v51, v51
	v_mul_f32_e32 v55, v49, v49
	v_fmac_f32_e32 v34, v44, v44
	v_fmac_f32_e32 v35, v46, v46
	v_fmac_f32_e32 v45, v40, v40
	v_fmac_f32_e32 v47, v42, v42
	v_fmac_f32_e32 v52, v36, v36
	v_fmac_f32_e32 v53, v38, v38
	v_fmac_f32_e32 v54, v50, v50
	v_fmac_f32_e32 v55, v48, v48
	v_add_f32_e32 v34, v34, v35
	v_add_f32_e32 v35, v45, v47
	v_add_f32_e32 v44, v52, v53
	v_add_f32_e32 v45, v54, v55
	v_add_f32_e32 v34, v34, v35
	v_add_f32_e32 v35, v44, v45
	v_add_f32_e32 v44, v34, v35
	ds_bpermute_b32 v45, v150, v44
	v_cvt_pk_bf16_f32 v34, v40, v41
	v_cvt_pk_bf16_f32 v35, v42, v43
	global_store_dwordx4 v[56:57], v[32:35], off
	s_waitcnt lgkmcnt(0)
	s_nop 0
	v_add_f32_e32 v32, v44, v45
	ds_bpermute_b32 v33, v151, v32
	v_cvt_pk_bf16_f32 v34, v36, v37
	v_cvt_pk_bf16_f32 v35, v38, v39
	v_cvt_pk_bf16_f32 v36, v50, v51
	v_cvt_pk_bf16_f32 v37, v48, v49
	global_store_dwordx4 v[56:57], v[34:37], off offset:256
	s_and_saveexec_b64 s[0:1], s[4:5]
	s_cbranch_execz .LBB0_1460
	v_lshl_add_u32 v34, v64, 4, s24
	s_waitcnt lgkmcnt(0)
	v_add_f32_e32 v32, v32, v33
	ds_write_b32 v34, v32
.LBB0_1460:
	s_or_b64 exec, exec, s[0:1]
	v_add_u32_e32 v32, 0xa0, v152
	s_waitcnt lgkmcnt(0)
	v_mov_b32_e32 v33, 0
	v_lshl_add_u64 v[34:35], s[14:15], 0, v[32:33]
	v_lshl_add_u64 v[36:37], v[34:35], 2, s[12:13]
	global_load_dword v46, v[36:37], off sc1
	v_lshlrev_b64 v[34:35], 11, v[34:35]
	v_lshl_add_u64 v[34:35], s[10:11], 0, v[34:35]
	v_lshl_add_u64 v[44:45], v[146:147], 1, v[34:35]
	global_load_dwordx4 v[36:39], v[44:45], off
	global_load_dwordx4 v[40:43], v[44:45], off offset:256
	v_mov_b32_e32 v35, 0x358637bd
	v_mov_b32_e32 v34, 0x260
	s_waitcnt vmcnt(2)
	v_fmamk_f32 v46, v46, 0x3a800000, v35
	v_rsq_f32_e32 v252, v46
	s_nop 0
	v_mul_f32_e32 v253, v46, v252
	v_mul_f32_e32 v253, v253, v252
	v_fmaak_f32 v253, -0.5, v253, 0x3fc00000
	v_mul_f32_e32 v252, v252, v253
	s_waitcnt vmcnt(1)
	v_lshlrev_b32_e32 v48, 16, v38
	v_and_b32_e32 v49, 0xffff0000, v38
	v_lshlrev_b32_e32 v46, 16, v36
	v_and_b32_e32 v47, 0xffff0000, v36
	v_lshlrev_b32_e32 v36, 16, v37
	v_and_b32_e32 v37, 0xffff0000, v37
	v_lshlrev_b32_e32 v38, 16, v39
	v_and_b32_e32 v39, 0xffff0000, v39
	s_waitcnt vmcnt(0)
	v_lshlrev_b32_e32 v50, 16, v40
	v_and_b32_e32 v51, 0xffff0000, v40
	v_lshlrev_b32_e32 v40, 16, v41
	v_and_b32_e32 v41, 0xffff0000, v41
	v_mov_b32_e32 v54, v252
	v_lshlrev_b32_e32 v52, 16, v42
	v_and_b32_e32 v53, 0xffff0000, v42
	v_lshlrev_b32_e32 v42, 16, v43
	v_and_b32_e32 v43, 0xffff0000, v43
	v_pk_mul_f32 v[28:29], v[28:29], v[54:55] op_sel_hi:[1,0]
	v_pk_mul_f32 v[30:31], v[30:31], v[54:55] op_sel_hi:[1,0]
	v_pk_mul_f32 v[24:25], v[24:25], v[54:55] op_sel_hi:[1,0]
	v_pk_mul_f32 v[26:27], v[26:27], v[54:55] op_sel_hi:[1,0]
	v_pk_mul_f32 v[20:21], v[20:21], v[54:55] op_sel_hi:[1,0]
	v_pk_mul_f32 v[22:23], v[22:23], v[54:55] op_sel_hi:[1,0]
	v_pk_mul_f32 v[16:17], v[16:17], v[54:55] op_sel_hi:[1,0]
	v_pk_mul_f32 v[18:19], v[18:19], v[54:55] op_sel_hi:[1,0]
	v_pk_fma_f32 v[30:31], v[106:107], v[30:31], v[36:37]
	v_pk_fma_f32 v[28:29], v[104:105], v[28:29], v[46:47]
	v_pk_fma_f32 v[26:27], v[102:103], v[26:27], v[38:39]
	v_pk_fma_f32 v[24:25], v[100:101], v[24:25], v[48:49]
	v_pk_fma_f32 v[22:23], v[110:111], v[22:23], v[40:41]
	v_pk_fma_f32 v[20:21], v[108:109], v[20:21], v[50:51]
	v_pk_fma_f32 v[36:37], v[98:99], v[18:19], v[42:43]
	v_pk_fma_f32 v[38:39], v[96:97], v[16:17], v[52:53]
	v_cvt_pk_bf16_f32 v16, v28, v29
	v_cvt_pk_bf16_f32 v17, v30, v31
	v_mul_f32_e32 v18, v29, v29
	v_mul_f32_e32 v19, v31, v31
	v_mul_f32_e32 v29, v25, v25
	v_mul_f32_e32 v31, v27, v27
	v_mul_f32_e32 v40, v21, v21
	v_mul_f32_e32 v41, v23, v23
	v_mul_f32_e32 v42, v39, v39
	v_mul_f32_e32 v43, v37, v37
	v_fmac_f32_e32 v18, v28, v28
	v_fmac_f32_e32 v19, v30, v30
	v_fmac_f32_e32 v29, v24, v24
	v_fmac_f32_e32 v31, v26, v26
	v_fmac_f32_e32 v40, v20, v20
	v_fmac_f32_e32 v41, v22, v22
	v_fmac_f32_e32 v42, v38, v38
	v_fmac_f32_e32 v43, v36, v36
	v_add_f32_e32 v18, v18, v19
	v_add_f32_e32 v19, v29, v31
	v_add_f32_e32 v28, v40, v41
	v_add_f32_e32 v29, v42, v43
	v_add_f32_e32 v18, v18, v19
	v_add_f32_e32 v19, v28, v29
	v_add_f32_e32 v28, v18, v19
	ds_bpermute_b32 v29, v150, v28
	v_cvt_pk_bf16_f32 v18, v24, v25
	v_cvt_pk_bf16_f32 v19, v26, v27
	global_store_dwordx4 v[44:45], v[16:19], off
	s_waitcnt lgkmcnt(0)
	s_nop 0
	v_add_f32_e32 v16, v28, v29
	ds_bpermute_b32 v17, v151, v16
	v_cvt_pk_bf16_f32 v18, v20, v21
	v_cvt_pk_bf16_f32 v19, v22, v23
	v_cvt_pk_bf16_f32 v20, v38, v39
	v_cvt_pk_bf16_f32 v21, v36, v37
	global_store_dwordx4 v[44:45], v[18:21], off offset:256
	s_and_saveexec_b64 s[0:1], s[4:5]
	s_cbranch_execz .LBB0_1462
	v_lshl_add_u32 v18, v32, 4, s24
	s_waitcnt lgkmcnt(0)
	v_add_f32_e32 v16, v16, v17
	ds_write_b32 v18, v16
; DI unsigned pk_bf16(float lo, float hi) { f32x2 v = {lo, hi}; bf16x2_t b = __builtin_convertvector(v, bf16x2_t); return __builtin_bit_cast(unsigned, b); }
; DI float bflo(unsigned w) { return __uint_as_float(w << 16); }
; DI float bfhi(unsigned w) { return __uint_as_float(w & 0xffff0000u); }
;     __device__ __forceinline__ void fused(f32x4 (&acc)[2][2][4][2], const pg8::Unit& u, int wr, int wc, int fr, int fq, PG8_LAS unsigned char* lds, int wid, int lane) const {
;     ...
;         const int colb = u.pn * 256 + wc * 32 + 8 * fq;
;         f32x4 gv[2][2];
; #pragma unroll
;         for (int bj = 0; bj < 2; ++bj)
; #pragma unroll
;             for (int n = 0; n < 2; ++n) gv[bj][n] = *(const f32x4*)(gA + colb + bj * 128 + 4 * n);
; #pragma unroll
;         for (int ai = 0; ai < 2; ++ai)
; #pragma unroll
;             for (int m = 0; m < 4; ++m) {
;                 const int rl = ai * 128 + wr * 64 + m * 16 + fr; const size_t row = (size_t)u.pm * 256 + rl;
;                 const float rm = 1.f / sqrtf(__hip_atomic_load(ssqm + row, __ATOMIC_RELAXED, __HIP_MEMORY_SCOPE_AGENT) * (1.f / DM) + RMS_EPS);
;                 float sh = 0.f;
; #pragma unroll
;                 for (int bj = 0; bj < 2; ++bj) {
;                     const size_t off = row * DM + colb + bj * 128;
;                     f32x4 h0, h1;
;                     if (IN16) { const u32x4 hw = *(const u32x4*)((const bf16_t*)hin + off); h0 = (f32x4){bflo(hw.x), bfhi(hw.x), bflo(hw.y), bfhi(hw.y)}; h1 = (f32x4){bflo(hw.z), bfhi(hw.z), bflo(hw.w), bfhi(hw.w)}; }
;                     else { h0 = *(const f32x4*)((const float*)hin + off); h1 = *(const f32x4*)((const float*)hin + off + 4); }
;                     h0 = h0 + acc[ai][bj][m][0] * rm * gv[bj][0]; h1 = h1 + acc[ai][bj][m][1] * rm * gv[bj][1];
;                     sh += ((h0[0] * h0[0] + h0[1] * h0[1]) + (h0[2] * h0[2] + h0[3] * h0[3])) + ((h1[0] * h1[0] + h1[1] * h1[1]) + (h1[2] * h1[2] + h1[3] * h1[3]));
;                     if (OUT16) { u32x4 w; w.x = pk_bf16(h0[0], h0[1]); w.y = pk_bf16(h0[2], h0[3]); w.z = pk_bf16(h1[0], h1[1]); w.w = pk_bf16(h1[2], h1[3]); *(u32x4*)((bf16_t*)hout + off) = w; }
;                     else { *(f32x4*)((float*)hout + off) = h0; *(f32x4*)((float*)hout + off + 4) = h1; }
;                 }
;                 if (ssqh) { sh += __shfl_xor(sh, 16); sh += __shfl_xor(sh, 32); if (fq == 0) red[rl * 4 + wc] = sh; }
.LBB0_1462:
	s_or_b64 exec, exec, s[0:1]
	v_add_u32_e32 v32, 0xb0, v152
	s_waitcnt lgkmcnt(0)
	v_lshl_add_u64 v[16:17], s[14:15], 0, v[32:33]
	v_lshl_add_u64 v[18:19], v[16:17], 2, s[12:13]
	global_load_dword v26, v[18:19], off sc1
	v_lshlrev_b64 v[16:17], 11, v[16:17]
	v_lshl_add_u64 v[16:17], s[10:11], 0, v[16:17]
	v_lshl_add_u64 v[24:25], v[146:147], 1, v[16:17]
	global_load_dwordx4 v[16:19], v[24:25], off
	global_load_dwordx4 v[20:23], v[24:25], off offset:256
	s_waitcnt vmcnt(2)
	v_fmac_f32_e32 v35, 0x3a800000, v26
	v_rsq_f32_e32 v252, v35
	s_nop 0
	v_mul_f32_e32 v253, v35, v252
	v_mul_f32_e32 v253, v253, v252
	v_fmaak_f32 v253, -0.5, v253, 0x3fc00000
	v_mul_f32_e32 v252, v252, v253
	s_waitcnt vmcnt(1)
	v_and_b32_e32 v27, 0xffff0000, v16
	v_lshlrev_b32_e32 v28, 16, v18
	v_lshlrev_b32_e32 v26, 16, v16
	v_lshlrev_b32_e32 v16, 16, v17
	v_and_b32_e32 v17, 0xffff0000, v17
	v_and_b32_e32 v29, 0xffff0000, v18
	v_lshlrev_b32_e32 v18, 16, v19
	v_and_b32_e32 v19, 0xffff0000, v19
	s_waitcnt vmcnt(0)
	v_lshlrev_b32_e32 v30, 16, v20
	v_and_b32_e32 v31, 0xffff0000, v20
	v_lshlrev_b32_e32 v20, 16, v21
	v_and_b32_e32 v21, 0xffff0000, v21
	v_mov_b32_e32 v34, v252
	v_lshlrev_b32_e32 v36, 16, v22
	v_and_b32_e32 v37, 0xffff0000, v22
	v_lshlrev_b32_e32 v22, 16, v23
	v_and_b32_e32 v23, 0xffff0000, v23
	v_pk_mul_f32 v[12:13], v[12:13], v[34:35] op_sel_hi:[1,0]
	v_pk_mul_f32 v[14:15], v[14:15], v[34:35] op_sel_hi:[1,0]
	v_pk_mul_f32 v[8:9], v[8:9], v[34:35] op_sel_hi:[1,0]
	v_pk_mul_f32 v[10:11], v[10:11], v[34:35] op_sel_hi:[1,0]
	v_pk_mul_f32 v[4:5], v[4:5], v[34:35] op_sel_hi:[1,0]
	v_pk_mul_f32 v[6:7], v[6:7], v[34:35] op_sel_hi:[1,0]
	v_pk_mul_f32 v[0:1], v[0:1], v[34:35] op_sel_hi:[1,0]
	v_pk_mul_f32 v[2:3], v[2:3], v[34:35] op_sel_hi:[1,0]
	v_pk_fma_f32 v[14:15], v[106:107], v[14:15], v[16:17]
	v_pk_fma_f32 v[12:13], v[104:105], v[12:13], v[26:27]
	v_pk_fma_f32 v[10:11], v[102:103], v[10:11], v[18:19]
	v_pk_fma_f32 v[8:9], v[100:101], v[8:9], v[28:29]
	v_pk_fma_f32 v[6:7], v[110:111], v[6:7], v[20:21]
	v_pk_fma_f32 v[4:5], v[108:109], v[4:5], v[30:31]
	v_pk_fma_f32 v[16:17], v[98:99], v[2:3], v[22:23]
	v_pk_fma_f32 v[18:19], v[96:97], v[0:1], v[36:37]
	v_cvt_pk_bf16_f32 v0, v12, v13
	v_cvt_pk_bf16_f32 v1, v14, v15
	v_mul_f32_e32 v2, v13, v13
	v_mul_f32_e32 v3, v15, v15
	v_mul_f32_e32 v13, v9, v9
	v_mul_f32_e32 v15, v11, v11
	v_mul_f32_e32 v20, v5, v5
	v_mul_f32_e32 v21, v7, v7
	v_mul_f32_e32 v22, v19, v19
	v_mul_f32_e32 v23, v17, v17
	v_fmac_f32_e32 v2, v12, v12
	v_fmac_f32_e32 v3, v14, v14
	v_fmac_f32_e32 v13, v8, v8
	v_fmac_f32_e32 v15, v10, v10
	v_fmac_f32_e32 v20, v4, v4
	v_fmac_f32_e32 v21, v6, v6
	v_fmac_f32_e32 v22, v18, v18
	v_fmac_f32_e32 v23, v16, v16
	v_add_f32_e32 v2, v2, v3
	v_add_f32_e32 v3, v13, v15
	v_add_f32_e32 v12, v20, v21
	v_add_f32_e32 v13, v22, v23
	v_add_f32_e32 v2, v2, v3
	v_add_f32_e32 v3, v12, v13
	v_add_f32_e32 v12, v2, v3
	ds_bpermute_b32 v13, v150, v12
	v_cvt_pk_bf16_f32 v2, v8, v9
	v_cvt_pk_bf16_f32 v3, v10, v11
	global_store_dwordx4 v[24:25], v[0:3], off
	s_waitcnt lgkmcnt(0)
	s_nop 0
	v_add_f32_e32 v0, v12, v13
	ds_bpermute_b32 v1, v151, v0
	v_cvt_pk_bf16_f32 v2, v4, v5
	v_cvt_pk_bf16_f32 v3, v6, v7
	v_cvt_pk_bf16_f32 v4, v18, v19
	v_cvt_pk_bf16_f32 v5, v16, v17
	global_store_dwordx4 v[24:25], v[2:5], off offset:256
	s_and_saveexec_b64 s[0:1], s[4:5]
	s_cbranch_execz .LBB0_1464
	v_lshl_add_u32 v2, v32, 4, s24
	s_waitcnt lgkmcnt(0)
	v_add_f32_e32 v0, v0, v1
	ds_write_b32 v2, v0

; DI unsigned pk_bf16(float lo, float hi) { f32x2 v = {lo, hi}; bf16x2_t b = __builtin_convertvector(v, bf16x2_t); return __builtin_bit_cast(unsigned, b); }
; DI float bflo(unsigned w) { return __uint_as_float(w << 16); }
; DI float bfhi(unsigned w) { return __uint_as_float(w & 0xffff0000u); }
;     __device__ __forceinline__ void fused(f32x4 (&acc)[2][2][4][2], const pg8::Unit& u, int wr, int wc, int fr, int fq, PG8_LAS unsigned char* lds, int wid, int lane) const {
;     ...
;             for (int m = 0; m < 4; ++m) {
;                 const int rl = ai * 128 + wr * 64 + m * 16 + fr; const size_t row = (size_t)u.pm * 256 + rl;
;                 const float rm = 1.f / sqrtf(__hip_atomic_load(ssqm + row, __ATOMIC_RELAXED, __HIP_MEMORY_SCOPE_AGENT) * (1.f / DM) + RMS_EPS);
;                 float sh = 0.f;
; #pragma unroll
;                 for (int bj = 0; bj < 2; ++bj) {
;                     const size_t off = row * DM + colb + bj * 128;
;                     f32x4 h0, h1;
;                     if (IN16) { const u32x4 hw = *(const u32x4*)((const bf16_t*)hin + off); h0 = (f32x4){bflo(hw.x), bfhi(hw.x), bflo(hw.y), bfhi(hw.y)}; h1 = (f32x4){bflo(hw.z), bfhi(hw.z), bflo(hw.w), bfhi(hw.w)}; }
;                     else { h0 = *(const f32x4*)((const float*)hin + off); h1 = *(const f32x4*)((const float*)hin + off + 4); }
;                     h0 = h0 + acc[ai][bj][m][0] * rm * gv[bj][0]; h1 = h1 + acc[ai][bj][m][1] * rm * gv[bj][1];
;                     sh += ((h0[0] * h0[0] + h0[1] * h0[1]) + (h0[2] * h0[2] + h0[3] * h0[3])) + ((h1[0] * h1[0] + h1[1] * h1[1]) + (h1[2] * h1[2] + h1[3] * h1[3]));
;                     if (OUT16) { u32x4 w; w.x = pk_bf16(h0[0], h0[1]); w.y = pk_bf16(h0[2], h0[3]); w.z = pk_bf16(h1[0], h1[1]); w.w = pk_bf16(h1[2], h1[3]); *(u32x4*)((bf16_t*)hout + off) = w; }
;                     else { *(f32x4*)((float*)hout + off) = h0; *(f32x4*)((float*)hout + off + 4) = h1; }
;                 }
.LBB0_1629:
	s_or_b64 exec, exec, s[2:3]
	s_lshl_b32 s2, s33, 5
	s_lshl_b32 s3, s30, 8
	s_or_b32 s2, s3, s2
	v_or_b32_e32 v154, s2, v156
	s_lshl_b64 s[10:11], s[0:1], 8
	v_mov_b32_e32 v153, 0
	v_ashrrev_i32_e32 v155, 31, v154
	v_lshl_add_u64 v[164:165], s[10:11], 0, v[152:153]
	v_lshl_add_u64 v[116:117], v[154:155], 2, s[8:9]
	v_lshl_add_u64 v[166:167], v[164:165], 2, s[6:7]
	s_barrier
	global_load_dwordx4 v[120:123], v[116:117], off offset:16
	global_load_dwordx4 v[124:127], v[116:117], off
	global_load_dwordx4 v[108:111], v[116:117], off offset:528
	s_nop 0
	global_load_dwordx4 v[116:119], v[116:117], off offset:512
	v_lshlrev_b64 v[164:165], 10, v[164:165]
	global_load_dword v149, v[166:167], off sc1
	v_lshl_add_u64 v[168:169], v[164:165], 0, v[154:155]
	v_lshlrev_b64 v[170:171], 1, v[168:169]
	v_lshl_add_u64 v[164:165], s[4:5], 0, v[170:171]
	global_load_dwordx4 v[164:167], v[164:165], off
	v_mov_b32_e32 v147, 0x358637bd
	s_mov_b32 s2, 0xf800000
	v_mov_b32_e32 v145, 0x260
	v_readlane_b32 s12, v251, 0
	v_readlane_b32 s14, v251, 2
	v_readlane_b32 s15, v251, 3
	v_or_b32_e32 v170, 0x100, v170
	v_lshl_add_u64 v[170:171], s[4:5], 0, v[170:171]
	v_lshl_add_u64 v[168:169], v[168:169], 2, s[14:15]
	v_readlane_b32 s13, v251, 1
	s_waitcnt vmcnt(1)
	v_fmamk_f32 v149, v149, 0x3a800000, v147
	v_rsq_f32_e32 v252, v149
	s_nop 0
	v_mul_f32_e32 v253, v149, v252
	v_mul_f32_e32 v253, v253, v252
	v_fmaak_f32 v253, -0.5, v253, 0x3fc00000
	v_mul_f32_e32 v252, v252, v253
	s_waitcnt vmcnt(0)
	v_lshlrev_b32_e32 v172, 16, v164
	v_and_b32_e32 v173, 0xffff0000, v164
	v_lshlrev_b32_e32 v164, 16, v165
	v_and_b32_e32 v165, 0xffff0000, v165
	v_lshlrev_b32_e32 v174, 16, v166
	v_and_b32_e32 v175, 0xffff0000, v166
	v_lshlrev_b32_e32 v166, 16, v167
	v_and_b32_e32 v167, 0xffff0000, v167
	s_nop 1
	v_mov_b32_e32 v176, v252
	v_pk_mul_f32 v[140:141], v[140:141], v[176:177] op_sel_hi:[1,0]
	v_pk_mul_f32 v[142:143], v[142:143], v[176:177] op_sel_hi:[1,0]
	v_pk_mul_f32 v[178:179], v[136:137], v[176:177] op_sel_hi:[1,0]
	v_pk_mul_f32 v[180:181], v[138:139], v[176:177] op_sel_hi:[1,0]
	v_pk_fma_f32 v[138:139], v[126:127], v[142:143], v[164:165]
	v_pk_fma_f32 v[136:137], v[124:125], v[140:141], v[172:173]
	v_pk_fma_f32 v[142:143], v[122:123], v[180:181], v[166:167]
	v_pk_fma_f32 v[140:141], v[120:121], v[178:179], v[174:175]
	global_store_dwordx4 v[168:169], v[136:139], off
	global_store_dwordx4 v[168:169], v[140:143], off offset:16
	global_load_dwordx4 v[136:139], v[170:171], off
	v_pk_mul_f32 v[132:133], v[132:133], v[176:177] op_sel_hi:[1,0]
	v_or_b32_e32 v140, 16, v152
	v_mov_b32_e32 v141, v153
	v_lshl_add_u64 v[140:141], s[10:11], 0, v[140:141]
	v_lshl_add_u64 v[142:143], v[140:141], 2, s[6:7]
	v_lshlrev_b64 v[140:141], 10, v[140:141]
	v_pk_mul_f32 v[134:135], v[134:135], v[176:177] op_sel_hi:[1,0]
	v_pk_mul_f32 v[170:171], v[128:129], v[176:177] op_sel_hi:[1,0]
	v_pk_mul_f32 v[172:173], v[130:131], v[176:177] op_sel_hi:[1,0]
	v_lshl_add_u64 v[140:141], v[140:141], 0, v[154:155]
	v_lshlrev_b64 v[164:165], 1, v[140:141]
	v_lshl_add_u64 v[166:167], s[4:5], 0, v[164:165]
	v_or_b32_e32 v164, 0x100, v164
	s_waitcnt vmcnt(0)
	v_lshlrev_b32_e32 v128, 16, v136
	v_and_b32_e32 v129, 0xffff0000, v136
	v_lshlrev_b32_e32 v130, 16, v137
	v_and_b32_e32 v131, 0xffff0000, v137
	v_lshlrev_b32_e32 v136, 16, v138
	v_and_b32_e32 v137, 0xffff0000, v138
	v_lshlrev_b32_e32 v138, 16, v139
	v_and_b32_e32 v139, 0xffff0000, v139
	v_pk_fma_f32 v[130:131], v[118:119], v[134:135], v[130:131]
	v_pk_fma_f32 v[128:129], v[116:117], v[132:133], v[128:129]
	v_pk_fma_f32 v[134:135], v[110:111], v[172:173], v[138:139]
	v_pk_fma_f32 v[132:133], v[108:109], v[170:171], v[136:137]
	global_store_dwordx4 v[168:169], v[128:131], off offset:512
	global_store_dwordx4 v[168:169], v[132:135], off offset:528
	global_load_dword v136, v[142:143], off sc1
	s_nop 0
	global_load_dwordx4 v[128:131], v[166:167], off
	v_lshl_add_u64 v[132:133], v[140:141], 2, s[14:15]
	v_lshl_add_u64 v[134:135], s[4:5], 0, v[164:165]
	s_waitcnt vmcnt(1)
	v_fmamk_f32 v138, v136, 0x3a800000, v147
	v_rsq_f32_e32 v252, v138
	s_nop 0
	v_mul_f32_e32 v253, v138, v252
	v_mul_f32_e32 v253, v253, v252
	v_fmaak_f32 v253, -0.5, v253, 0x3fc00000
	v_mul_f32_e32 v252, v252, v253
	s_waitcnt vmcnt(0)
	v_lshlrev_b32_e32 v136, 16, v128
	v_and_b32_e32 v137, 0xffff0000, v128
	v_lshlrev_b32_e32 v128, 16, v129
	v_and_b32_e32 v129, 0xffff0000, v129
	v_lshlrev_b32_e32 v138, 16, v130
	v_and_b32_e32 v139, 0xffff0000, v130
	v_lshlrev_b32_e32 v130, 16, v131
	v_and_b32_e32 v131, 0xffff0000, v131
	s_nop 0
	s_nop 1
	v_mov_b32_e32 v140, v252
	v_pk_mul_f32 v[112:113], v[112:113], v[140:141] op_sel_hi:[1,0]
	v_pk_mul_f32 v[114:115], v[114:115], v[140:141] op_sel_hi:[1,0]
	v_pk_mul_f32 v[142:143], v[104:105], v[140:141] op_sel_hi:[1,0]
	v_pk_mul_f32 v[164:165], v[106:107], v[140:141] op_sel_hi:[1,0]
	v_pk_fma_f32 v[106:107], v[126:127], v[114:115], v[128:129]
	v_pk_fma_f32 v[104:105], v[124:125], v[112:113], v[136:137]
	v_pk_fma_f32 v[114:115], v[122:123], v[164:165], v[130:131]
	v_pk_fma_f32 v[112:113], v[120:121], v[142:143], v[138:139]
	global_store_dwordx4 v[132:133], v[104:107], off
	global_store_dwordx4 v[132:133], v[112:115], off offset:16
	global_load_dwordx4 v[104:107], v[134:135], off
	v_pk_mul_f32 v[100:101], v[100:101], v[140:141] op_sel_hi:[1,0]
	v_or_b32_e32 v112, 32, v152
	v_mov_b32_e32 v113, v153
	v_lshl_add_u64 v[112:113], s[10:11], 0, v[112:113]
	v_lshl_add_u64 v[114:115], v[112:113], 2, s[6:7]
	v_lshlrev_b64 v[112:113], 10, v[112:113]
	v_pk_mul_f32 v[102:103], v[102:103], v[140:141] op_sel_hi:[1,0]
	v_pk_mul_f32 v[134:135], v[96:97], v[140:141] op_sel_hi:[1,0]
	v_pk_mul_f32 v[136:137], v[98:99], v[140:141] op_sel_hi:[1,0]
	v_lshl_add_u64 v[112:113], v[112:113], 0, v[154:155]
	v_lshlrev_b64 v[128:129], 1, v[112:113]
	v_lshl_add_u64 v[130:131], s[4:5], 0, v[128:129]
	v_or_b32_e32 v128, 0x100, v128
	s_waitcnt vmcnt(0)
; DI unsigned pk_bf16(float lo, float hi) { f32x2 v = {lo, hi}; bf16x2_t b = __builtin_convertvector(v, bf16x2_t); return __builtin_bit_cast(unsigned, b); }
; DI float bflo(unsigned w) { return __uint_as_float(w << 16); }
; DI float bfhi(unsigned w) { return __uint_as_float(w & 0xffff0000u); }
;     __device__ __forceinline__ void fused(f32x4 (&acc)[2][2][4][2], const pg8::Unit& u, int wr, int wc, int fr, int fq, PG8_LAS unsigned char* lds, int wid, int lane) const {
;     ...
;             for (int m = 0; m < 4; ++m) {
;                 const int rl = ai * 128 + wr * 64 + m * 16 + fr; const size_t row = (size_t)u.pm * 256 + rl;
;                 const float rm = 1.f / sqrtf(__hip_atomic_load(ssqm + row, __ATOMIC_RELAXED, __HIP_MEMORY_SCOPE_AGENT) * (1.f / DM) + RMS_EPS);
;                 float sh = 0.f;
; #pragma unroll
;                 for (int bj = 0; bj < 2; ++bj) {
;                     const size_t off = row * DM + colb + bj * 128;
;                     f32x4 h0, h1;
;                     if (IN16) { const u32x4 hw = *(const u32x4*)((const bf16_t*)hin + off); h0 = (f32x4){bflo(hw.x), bfhi(hw.x), bflo(hw.y), bfhi(hw.y)}; h1 = (f32x4){bflo(hw.z), bfhi(hw.z), bflo(hw.w), bfhi(hw.w)}; }
;                     else { h0 = *(const f32x4*)((const float*)hin + off); h1 = *(const f32x4*)((const float*)hin + off + 4); }
;                     h0 = h0 + acc[ai][bj][m][0] * rm * gv[bj][0]; h1 = h1 + acc[ai][bj][m][1] * rm * gv[bj][1];
;                     sh += ((h0[0] * h0[0] + h0[1] * h0[1]) + (h0[2] * h0[2] + h0[3] * h0[3])) + ((h1[0] * h1[0] + h1[1] * h1[1]) + (h1[2] * h1[2] + h1[3] * h1[3]));
;                     if (OUT16) { u32x4 w; w.x = pk_bf16(h0[0], h0[1]); w.y = pk_bf16(h0[2], h0[3]); w.z = pk_bf16(h1[0], h1[1]); w.w = pk_bf16(h1[2], h1[3]); *(u32x4*)((bf16_t*)hout + off) = w; }
;                     else { *(f32x4*)((float*)hout + off) = h0; *(f32x4*)((float*)hout + off + 4) = h1; }
;                 }
	v_lshlrev_b32_e32 v96, 16, v104
	v_and_b32_e32 v97, 0xffff0000, v104
	v_lshlrev_b32_e32 v98, 16, v105
	v_and_b32_e32 v99, 0xffff0000, v105
	v_lshlrev_b32_e32 v104, 16, v106
	v_and_b32_e32 v105, 0xffff0000, v106
	v_lshlrev_b32_e32 v106, 16, v107
	v_and_b32_e32 v107, 0xffff0000, v107
	v_pk_fma_f32 v[98:99], v[118:119], v[102:103], v[98:99]
	v_pk_fma_f32 v[96:97], v[116:117], v[100:101], v[96:97]
	v_pk_fma_f32 v[102:103], v[110:111], v[136:137], v[106:107]
	v_pk_fma_f32 v[100:101], v[108:109], v[134:135], v[104:105]
	global_store_dwordx4 v[132:133], v[96:99], off offset:512
	global_store_dwordx4 v[132:133], v[100:103], off offset:528
	global_load_dword v104, v[114:115], off sc1
	s_nop 0
	global_load_dwordx4 v[96:99], v[130:131], off
	v_lshl_add_u64 v[100:101], v[112:113], 2, s[14:15]
	v_lshl_add_u64 v[102:103], s[4:5], 0, v[128:129]
	s_waitcnt vmcnt(1)
	v_fmamk_f32 v106, v104, 0x3a800000, v147
	v_rsq_f32_e32 v252, v106
	s_nop 0
	v_mul_f32_e32 v253, v106, v252
	v_mul_f32_e32 v253, v253, v252
	v_fmaak_f32 v253, -0.5, v253, 0x3fc00000
	v_mul_f32_e32 v252, v252, v253
	s_waitcnt vmcnt(0)
	v_lshlrev_b32_e32 v104, 16, v96
	v_and_b32_e32 v105, 0xffff0000, v96
	v_lshlrev_b32_e32 v96, 16, v97
	v_and_b32_e32 v97, 0xffff0000, v97
	v_lshlrev_b32_e32 v106, 16, v98
	v_and_b32_e32 v107, 0xffff0000, v98
	v_lshlrev_b32_e32 v98, 16, v99
	v_and_b32_e32 v99, 0xffff0000, v99
	s_nop 0
	s_nop 1
	v_mov_b32_e32 v112, v252
	v_pk_mul_f32 v[92:93], v[92:93], v[112:113] op_sel_hi:[1,0]
	v_pk_mul_f32 v[94:95], v[94:95], v[112:113] op_sel_hi:[1,0]
	v_pk_mul_f32 v[114:115], v[88:89], v[112:113] op_sel_hi:[1,0]
	v_pk_mul_f32 v[128:129], v[90:91], v[112:113] op_sel_hi:[1,0]
	v_pk_fma_f32 v[90:91], v[126:127], v[94:95], v[96:97]
	v_pk_fma_f32 v[88:89], v[124:125], v[92:93], v[104:105]
	v_pk_fma_f32 v[94:95], v[122:123], v[128:129], v[98:99]
	v_pk_fma_f32 v[92:93], v[120:121], v[114:115], v[106:107]
	global_store_dwordx4 v[100:101], v[88:91], off
	global_store_dwordx4 v[100:101], v[92:95], off offset:16
	global_load_dwordx4 v[88:91], v[102:103], off
	v_pk_mul_f32 v[84:85], v[84:85], v[112:113] op_sel_hi:[1,0]
	v_or_b32_e32 v92, 48, v152
	v_mov_b32_e32 v93, v153
	v_lshl_add_u64 v[92:93], s[10:11], 0, v[92:93]
	v_lshl_add_u64 v[94:95], v[92:93], 2, s[6:7]
	v_lshlrev_b64 v[92:93], 10, v[92:93]
	v_pk_mul_f32 v[86:87], v[86:87], v[112:113] op_sel_hi:[1,0]
	v_pk_mul_f32 v[102:103], v[80:81], v[112:113] op_sel_hi:[1,0]
	v_pk_mul_f32 v[104:105], v[82:83], v[112:113] op_sel_hi:[1,0]
	v_lshl_add_u64 v[92:93], v[92:93], 0, v[154:155]
	v_lshlrev_b64 v[96:97], 1, v[92:93]
	v_lshl_add_u64 v[98:99], s[4:5], 0, v[96:97]
	v_or_b32_e32 v96, 0x100, v96
	s_waitcnt vmcnt(0)
	v_lshlrev_b32_e32 v80, 16, v88
	v_and_b32_e32 v81, 0xffff0000, v88
	v_lshlrev_b32_e32 v82, 16, v89
	v_and_b32_e32 v83, 0xffff0000, v89
	v_lshlrev_b32_e32 v88, 16, v90
	v_and_b32_e32 v89, 0xffff0000, v90
	v_lshlrev_b32_e32 v90, 16, v91
	v_and_b32_e32 v91, 0xffff0000, v91
	v_pk_fma_f32 v[82:83], v[118:119], v[86:87], v[82:83]
	v_pk_fma_f32 v[80:81], v[116:117], v[84:85], v[80:81]
	v_pk_fma_f32 v[86:87], v[110:111], v[104:105], v[90:91]
	v_pk_fma_f32 v[84:85], v[108:109], v[102:103], v[88:89]
	global_store_dwordx4 v[100:101], v[80:83], off offset:512
	global_store_dwordx4 v[100:101], v[84:87], off offset:528
	global_load_dword v88, v[94:95], off sc1
	s_nop 0
	global_load_dwordx4 v[80:83], v[98:99], off
	v_lshl_add_u64 v[84:85], v[92:93], 2, s[14:15]
	v_lshl_add_u64 v[86:87], s[4:5], 0, v[96:97]
	s_waitcnt vmcnt(1)
	v_fmamk_f32 v90, v88, 0x3a800000, v147
	v_rsq_f32_e32 v252, v90
	s_nop 0
	v_mul_f32_e32 v253, v90, v252
	v_mul_f32_e32 v253, v253, v252
	v_fmaak_f32 v253, -0.5, v253, 0x3fc00000
	v_mul_f32_e32 v252, v252, v253
	s_waitcnt vmcnt(0)
	v_lshlrev_b32_e32 v88, 16, v80
	v_and_b32_e32 v89, 0xffff0000, v80
	v_lshlrev_b32_e32 v80, 16, v81
	v_and_b32_e32 v81, 0xffff0000, v81
	v_lshlrev_b32_e32 v90, 16, v82
	v_and_b32_e32 v91, 0xffff0000, v82
	v_lshlrev_b32_e32 v82, 16, v83
	v_and_b32_e32 v83, 0xffff0000, v83
	s_nop 0
	s_nop 1
	v_mov_b32_e32 v92, v252
	v_pk_mul_f32 v[76:77], v[76:77], v[92:93] op_sel_hi:[1,0]
	v_pk_mul_f32 v[78:79], v[78:79], v[92:93] op_sel_hi:[1,0]
	v_pk_mul_f32 v[94:95], v[72:73], v[92:93] op_sel_hi:[1,0]
	v_pk_mul_f32 v[96:97], v[74:75], v[92:93] op_sel_hi:[1,0]
	v_pk_fma_f32 v[74:75], v[126:127], v[78:79], v[80:81]
	v_pk_fma_f32 v[72:73], v[124:125], v[76:77], v[88:89]
	v_pk_fma_f32 v[78:79], v[122:123], v[96:97], v[82:83]
	v_pk_fma_f32 v[76:77], v[120:121], v[94:95], v[90:91]
	global_store_dwordx4 v[84:85], v[72:75], off
	global_store_dwordx4 v[84:85], v[76:79], off offset:16
	global_load_dwordx4 v[72:75], v[86:87], off
	v_pk_mul_f32 v[68:69], v[68:69], v[92:93] op_sel_hi:[1,0]
	v_add_u32_e32 v76, 0x80, v152
	v_mov_b32_e32 v77, v153
	v_lshl_add_u64 v[76:77], s[10:11], 0, v[76:77]
	v_lshl_add_u64 v[78:79], v[76:77], 2, s[6:7]
	v_lshlrev_b64 v[76:77], 10, v[76:77]
	v_pk_mul_f32 v[70:71], v[70:71], v[92:93] op_sel_hi:[1,0]
	v_pk_mul_f32 v[86:87], v[64:65], v[92:93] op_sel_hi:[1,0]
	v_pk_mul_f32 v[88:89], v[66:67], v[92:93] op_sel_hi:[1,0]
	v_lshl_add_u64 v[76:77], v[76:77], 0, v[154:155]
	v_lshlrev_b64 v[80:81], 1, v[76:77]
	v_lshl_add_u64 v[82:83], s[4:5], 0, v[80:81]
	v_or_b32_e32 v80, 0x100, v80
	s_waitcnt vmcnt(0)
; DI unsigned pk_bf16(float lo, float hi) { f32x2 v = {lo, hi}; bf16x2_t b = __builtin_convertvector(v, bf16x2_t); return __builtin_bit_cast(unsigned, b); }
; DI float bflo(unsigned w) { return __uint_as_float(w << 16); }
; DI float bfhi(unsigned w) { return __uint_as_float(w & 0xffff0000u); }
;     __device__ __forceinline__ void fused(f32x4 (&acc)[2][2][4][2], const pg8::Unit& u, int wr, int wc, int fr, int fq, PG8_LAS unsigned char* lds, int wid, int lane) const {
;     ...
;             for (int m = 0; m < 4; ++m) {
;                 const int rl = ai * 128 + wr * 64 + m * 16 + fr; const size_t row = (size_t)u.pm * 256 + rl;
;                 const float rm = 1.f / sqrtf(__hip_atomic_load(ssqm + row, __ATOMIC_RELAXED, __HIP_MEMORY_SCOPE_AGENT) * (1.f / DM) + RMS_EPS);
;                 float sh = 0.f;
; #pragma unroll
;                 for (int bj = 0; bj < 2; ++bj) {
;                     const size_t off = row * DM + colb + bj * 128;
;                     f32x4 h0, h1;
;                     if (IN16) { const u32x4 hw = *(const u32x4*)((const bf16_t*)hin + off); h0 = (f32x4){bflo(hw.x), bfhi(hw.x), bflo(hw.y), bfhi(hw.y)}; h1 = (f32x4){bflo(hw.z), bfhi(hw.z), bflo(hw.w), bfhi(hw.w)}; }
;                     else { h0 = *(const f32x4*)((const float*)hin + off); h1 = *(const f32x4*)((const float*)hin + off + 4); }
;                     h0 = h0 + acc[ai][bj][m][0] * rm * gv[bj][0]; h1 = h1 + acc[ai][bj][m][1] * rm * gv[bj][1];
;                     sh += ((h0[0] * h0[0] + h0[1] * h0[1]) + (h0[2] * h0[2] + h0[3] * h0[3])) + ((h1[0] * h1[0] + h1[1] * h1[1]) + (h1[2] * h1[2] + h1[3] * h1[3]));
;                     if (OUT16) { u32x4 w; w.x = pk_bf16(h0[0], h0[1]); w.y = pk_bf16(h0[2], h0[3]); w.z = pk_bf16(h1[0], h1[1]); w.w = pk_bf16(h1[2], h1[3]); *(u32x4*)((bf16_t*)hout + off) = w; }
;                     else { *(f32x4*)((float*)hout + off) = h0; *(f32x4*)((float*)hout + off + 4) = h1; }
;                 }
	v_lshlrev_b32_e32 v64, 16, v72
	v_and_b32_e32 v65, 0xffff0000, v72
	v_lshlrev_b32_e32 v66, 16, v73
	v_and_b32_e32 v67, 0xffff0000, v73
	v_lshlrev_b32_e32 v72, 16, v74
	v_and_b32_e32 v73, 0xffff0000, v74
	v_lshlrev_b32_e32 v74, 16, v75
	v_and_b32_e32 v75, 0xffff0000, v75
	v_pk_fma_f32 v[66:67], v[118:119], v[70:71], v[66:67]
	v_pk_fma_f32 v[64:65], v[116:117], v[68:69], v[64:65]
	v_pk_fma_f32 v[70:71], v[110:111], v[88:89], v[74:75]
	v_pk_fma_f32 v[68:69], v[108:109], v[86:87], v[72:73]
	global_store_dwordx4 v[84:85], v[64:67], off offset:512
	global_store_dwordx4 v[84:85], v[68:71], off offset:528
	global_load_dword v72, v[78:79], off sc1
	s_nop 0
	global_load_dwordx4 v[64:67], v[82:83], off
	v_lshl_add_u64 v[68:69], v[76:77], 2, s[14:15]
	v_lshl_add_u64 v[70:71], s[4:5], 0, v[80:81]
	s_waitcnt vmcnt(1)
	v_fmamk_f32 v74, v72, 0x3a800000, v147
	v_rsq_f32_e32 v252, v74
	s_nop 0
	v_mul_f32_e32 v253, v74, v252
	v_mul_f32_e32 v253, v253, v252
	v_fmaak_f32 v253, -0.5, v253, 0x3fc00000
	v_mul_f32_e32 v252, v252, v253
	s_waitcnt vmcnt(0)
	v_lshlrev_b32_e32 v72, 16, v64
	v_and_b32_e32 v73, 0xffff0000, v64
	v_lshlrev_b32_e32 v64, 16, v65
	v_and_b32_e32 v65, 0xffff0000, v65
	v_lshlrev_b32_e32 v74, 16, v66
	v_and_b32_e32 v75, 0xffff0000, v66
	v_lshlrev_b32_e32 v66, 16, v67
	v_and_b32_e32 v67, 0xffff0000, v67
	s_nop 0
	s_nop 1
	v_mov_b32_e32 v76, v252
	v_pk_mul_f32 v[60:61], v[60:61], v[76:77] op_sel_hi:[1,0]
	v_pk_mul_f32 v[62:63], v[62:63], v[76:77] op_sel_hi:[1,0]
	v_pk_mul_f32 v[78:79], v[56:57], v[76:77] op_sel_hi:[1,0]
	v_pk_mul_f32 v[80:81], v[58:59], v[76:77] op_sel_hi:[1,0]
	v_pk_fma_f32 v[58:59], v[126:127], v[62:63], v[64:65]
	v_pk_fma_f32 v[56:57], v[124:125], v[60:61], v[72:73]
	v_pk_fma_f32 v[62:63], v[122:123], v[80:81], v[66:67]
	v_pk_fma_f32 v[60:61], v[120:121], v[78:79], v[74:75]
	global_store_dwordx4 v[68:69], v[56:59], off
	global_store_dwordx4 v[68:69], v[60:63], off offset:16
	global_load_dwordx4 v[56:59], v[70:71], off
	v_pk_mul_f32 v[52:53], v[52:53], v[76:77] op_sel_hi:[1,0]
	v_add_u32_e32 v60, 0x90, v152
	v_mov_b32_e32 v61, v153
	v_lshl_add_u64 v[60:61], s[10:11], 0, v[60:61]
	v_lshl_add_u64 v[62:63], v[60:61], 2, s[6:7]
	v_lshlrev_b64 v[60:61], 10, v[60:61]
	v_pk_mul_f32 v[54:55], v[54:55], v[76:77] op_sel_hi:[1,0]
	v_pk_mul_f32 v[70:71], v[48:49], v[76:77] op_sel_hi:[1,0]
	v_pk_mul_f32 v[72:73], v[50:51], v[76:77] op_sel_hi:[1,0]
	v_lshl_add_u64 v[60:61], v[60:61], 0, v[154:155]
	v_lshlrev_b64 v[64:65], 1, v[60:61]
	v_lshl_add_u64 v[66:67], s[4:5], 0, v[64:65]
	v_or_b32_e32 v64, 0x100, v64
	s_waitcnt vmcnt(0)
	v_lshlrev_b32_e32 v48, 16, v56
	v_and_b32_e32 v49, 0xffff0000, v56
	v_lshlrev_b32_e32 v50, 16, v57
	v_and_b32_e32 v51, 0xffff0000, v57
	v_lshlrev_b32_e32 v56, 16, v58
	v_and_b32_e32 v57, 0xffff0000, v58
	v_lshlrev_b32_e32 v58, 16, v59
	v_and_b32_e32 v59, 0xffff0000, v59
	v_pk_fma_f32 v[50:51], v[118:119], v[54:55], v[50:51]
	v_pk_fma_f32 v[48:49], v[116:117], v[52:53], v[48:49]
	v_pk_fma_f32 v[54:55], v[110:111], v[72:73], v[58:59]
	v_pk_fma_f32 v[52:53], v[108:109], v[70:71], v[56:57]
	global_store_dwordx4 v[68:69], v[48:51], off offset:512
	global_store_dwordx4 v[68:69], v[52:55], off offset:528
	global_load_dword v56, v[62:63], off sc1
	s_nop 0
	global_load_dwordx4 v[48:51], v[66:67], off
	v_lshl_add_u64 v[52:53], v[60:61], 2, s[14:15]
	v_lshl_add_u64 v[54:55], s[4:5], 0, v[64:65]
	s_waitcnt vmcnt(1)
	v_fmamk_f32 v58, v56, 0x3a800000, v147
	v_rsq_f32_e32 v252, v58
	s_nop 0
	v_mul_f32_e32 v253, v58, v252
	v_mul_f32_e32 v253, v253, v252
	v_fmaak_f32 v253, -0.5, v253, 0x3fc00000
	v_mul_f32_e32 v252, v252, v253
	s_waitcnt vmcnt(0)
	v_lshlrev_b32_e32 v56, 16, v48
	v_and_b32_e32 v57, 0xffff0000, v48
	v_lshlrev_b32_e32 v48, 16, v49
	v_and_b32_e32 v49, 0xffff0000, v49
	v_lshlrev_b32_e32 v58, 16, v50
	v_and_b32_e32 v59, 0xffff0000, v50
	v_lshlrev_b32_e32 v50, 16, v51
	v_and_b32_e32 v51, 0xffff0000, v51
	s_nop 0
	s_nop 1
	v_mov_b32_e32 v60, v252
	v_pk_mul_f32 v[44:45], v[44:45], v[60:61] op_sel_hi:[1,0]
	v_pk_mul_f32 v[46:47], v[46:47], v[60:61] op_sel_hi:[1,0]
	v_pk_mul_f32 v[62:63], v[40:41], v[60:61] op_sel_hi:[1,0]
	v_pk_mul_f32 v[64:65], v[42:43], v[60:61] op_sel_hi:[1,0]
	v_pk_fma_f32 v[42:43], v[126:127], v[46:47], v[48:49]
	v_pk_fma_f32 v[40:41], v[124:125], v[44:45], v[56:57]
	v_pk_fma_f32 v[46:47], v[122:123], v[64:65], v[50:51]
	v_pk_fma_f32 v[44:45], v[120:121], v[62:63], v[58:59]
	global_store_dwordx4 v[52:53], v[40:43], off
	global_store_dwordx4 v[52:53], v[44:47], off offset:16
	global_load_dwordx4 v[40:43], v[54:55], off
	v_pk_mul_f32 v[36:37], v[36:37], v[60:61] op_sel_hi:[1,0]
	v_add_u32_e32 v44, 0xa0, v152
	v_mov_b32_e32 v45, v153
	v_lshl_add_u64 v[44:45], s[10:11], 0, v[44:45]
	v_lshl_add_u64 v[46:47], v[44:45], 2, s[6:7]
	v_lshlrev_b64 v[44:45], 10, v[44:45]
	v_pk_mul_f32 v[38:39], v[38:39], v[60:61] op_sel_hi:[1,0]
	v_pk_mul_f32 v[54:55], v[32:33], v[60:61] op_sel_hi:[1,0]
	v_pk_mul_f32 v[56:57], v[34:35], v[60:61] op_sel_hi:[1,0]
	v_lshl_add_u64 v[44:45], v[44:45], 0, v[154:155]
	v_lshlrev_b64 v[48:49], 1, v[44:45]
	v_lshl_add_u64 v[50:51], s[4:5], 0, v[48:49]
	v_or_b32_e32 v48, 0x100, v48
	v_add_u32_e32 v152, 0xb0, v152
	s_waitcnt vmcnt(0)
; DI unsigned pk_bf16(float lo, float hi) { f32x2 v = {lo, hi}; bf16x2_t b = __builtin_convertvector(v, bf16x2_t); return __builtin_bit_cast(unsigned, b); }
; DI float bflo(unsigned w) { return __uint_as_float(w << 16); }
; DI float bfhi(unsigned w) { return __uint_as_float(w & 0xffff0000u); }
;     __device__ __forceinline__ void fused(f32x4 (&acc)[2][2][4][2], const pg8::Unit& u, int wr, int wc, int fr, int fq, PG8_LAS unsigned char* lds, int wid, int lane) const {
;     ...
;             for (int m = 0; m < 4; ++m) {
;                 const int rl = ai * 128 + wr * 64 + m * 16 + fr; const size_t row = (size_t)u.pm * 256 + rl;
;                 const float rm = 1.f / sqrtf(__hip_atomic_load(ssqm + row, __ATOMIC_RELAXED, __HIP_MEMORY_SCOPE_AGENT) * (1.f / DM) + RMS_EPS);
;                 float sh = 0.f;
; #pragma unroll
;                 for (int bj = 0; bj < 2; ++bj) {
;                     const size_t off = row * DM + colb + bj * 128;
;                     f32x4 h0, h1;
;                     if (IN16) { const u32x4 hw = *(const u32x4*)((const bf16_t*)hin + off); h0 = (f32x4){bflo(hw.x), bfhi(hw.x), bflo(hw.y), bfhi(hw.y)}; h1 = (f32x4){bflo(hw.z), bfhi(hw.z), bflo(hw.w), bfhi(hw.w)}; }
;                     else { h0 = *(const f32x4*)((const float*)hin + off); h1 = *(const f32x4*)((const float*)hin + off + 4); }
;                     h0 = h0 + acc[ai][bj][m][0] * rm * gv[bj][0]; h1 = h1 + acc[ai][bj][m][1] * rm * gv[bj][1];
;                     sh += ((h0[0] * h0[0] + h0[1] * h0[1]) + (h0[2] * h0[2] + h0[3] * h0[3])) + ((h1[0] * h1[0] + h1[1] * h1[1]) + (h1[2] * h1[2] + h1[3] * h1[3]));
;                     if (OUT16) { u32x4 w; w.x = pk_bf16(h0[0], h0[1]); w.y = pk_bf16(h0[2], h0[3]); w.z = pk_bf16(h1[0], h1[1]); w.w = pk_bf16(h1[2], h1[3]); *(u32x4*)((bf16_t*)hout + off) = w; }
;                     else { *(f32x4*)((float*)hout + off) = h0; *(f32x4*)((float*)hout + off + 4) = h1; }
;                 }
	v_lshlrev_b32_e32 v32, 16, v40
	v_and_b32_e32 v33, 0xffff0000, v40
	v_lshlrev_b32_e32 v34, 16, v41
	v_and_b32_e32 v35, 0xffff0000, v41
	v_lshlrev_b32_e32 v40, 16, v42
	v_and_b32_e32 v41, 0xffff0000, v42
	v_lshlrev_b32_e32 v42, 16, v43
	v_and_b32_e32 v43, 0xffff0000, v43
	v_pk_fma_f32 v[34:35], v[118:119], v[38:39], v[34:35]
	v_pk_fma_f32 v[32:33], v[116:117], v[36:37], v[32:33]
	v_pk_fma_f32 v[38:39], v[110:111], v[56:57], v[42:43]
	v_pk_fma_f32 v[36:37], v[108:109], v[54:55], v[40:41]
	global_store_dwordx4 v[52:53], v[32:35], off offset:512
	global_store_dwordx4 v[52:53], v[36:39], off offset:528
	global_load_dword v40, v[46:47], off sc1
	s_nop 0
	global_load_dwordx4 v[32:35], v[50:51], off
	v_lshl_add_u64 v[36:37], v[44:45], 2, s[14:15]
	v_lshl_add_u64 v[38:39], s[4:5], 0, v[48:49]
	s_waitcnt vmcnt(1)
	v_fmamk_f32 v42, v40, 0x3a800000, v147
	v_rsq_f32_e32 v252, v42
	s_nop 0
	v_mul_f32_e32 v253, v42, v252
	v_mul_f32_e32 v253, v253, v252
	v_fmaak_f32 v253, -0.5, v253, 0x3fc00000
	v_mul_f32_e32 v252, v252, v253
	s_waitcnt vmcnt(0)
	v_lshlrev_b32_e32 v40, 16, v32
	v_and_b32_e32 v41, 0xffff0000, v32
	v_lshlrev_b32_e32 v32, 16, v33
	v_and_b32_e32 v33, 0xffff0000, v33
	v_lshlrev_b32_e32 v42, 16, v34
	v_and_b32_e32 v43, 0xffff0000, v34
	v_lshlrev_b32_e32 v34, 16, v35
	v_and_b32_e32 v35, 0xffff0000, v35
	s_nop 0
	s_nop 1
	v_mov_b32_e32 v44, v252
	v_pk_mul_f32 v[28:29], v[28:29], v[44:45] op_sel_hi:[1,0]
	v_pk_mul_f32 v[30:31], v[30:31], v[44:45] op_sel_hi:[1,0]
	v_pk_mul_f32 v[46:47], v[24:25], v[44:45] op_sel_hi:[1,0]
	v_pk_mul_f32 v[48:49], v[26:27], v[44:45] op_sel_hi:[1,0]
	v_pk_fma_f32 v[26:27], v[126:127], v[30:31], v[32:33]
	v_pk_fma_f32 v[24:25], v[124:125], v[28:29], v[40:41]
	v_pk_fma_f32 v[30:31], v[122:123], v[48:49], v[34:35]
	v_pk_fma_f32 v[28:29], v[120:121], v[46:47], v[42:43]
	global_store_dwordx4 v[36:37], v[24:27], off
	global_store_dwordx4 v[36:37], v[28:31], off offset:16
	global_load_dwordx4 v[24:27], v[38:39], off
	v_pk_mul_f32 v[20:21], v[20:21], v[44:45] op_sel_hi:[1,0]
	v_lshl_add_u64 v[28:29], s[10:11], 0, v[152:153]
	v_lshl_add_u64 v[30:31], v[28:29], 2, s[6:7]
	v_lshlrev_b64 v[28:29], 10, v[28:29]
	v_pk_mul_f32 v[22:23], v[22:23], v[44:45] op_sel_hi:[1,0]
	v_pk_mul_f32 v[38:39], v[16:17], v[44:45] op_sel_hi:[1,0]
	v_pk_mul_f32 v[40:41], v[18:19], v[44:45] op_sel_hi:[1,0]
	v_lshl_add_u64 v[28:29], v[28:29], 0, v[154:155]
	v_lshlrev_b64 v[32:33], 1, v[28:29]
	v_lshl_add_u64 v[34:35], s[4:5], 0, v[32:33]
	v_or_b32_e32 v32, 0x100, v32
	s_waitcnt vmcnt(0)
	v_lshlrev_b32_e32 v16, 16, v24
	v_and_b32_e32 v17, 0xffff0000, v24
	v_lshlrev_b32_e32 v18, 16, v25
	v_and_b32_e32 v19, 0xffff0000, v25
	v_lshlrev_b32_e32 v24, 16, v26
	v_and_b32_e32 v25, 0xffff0000, v26
	v_lshlrev_b32_e32 v26, 16, v27
	v_and_b32_e32 v27, 0xffff0000, v27
	v_pk_fma_f32 v[18:19], v[118:119], v[22:23], v[18:19]
	v_pk_fma_f32 v[16:17], v[116:117], v[20:21], v[16:17]
	v_pk_fma_f32 v[22:23], v[110:111], v[40:41], v[26:27]
	v_pk_fma_f32 v[20:21], v[108:109], v[38:39], v[24:25]
	global_store_dwordx4 v[36:37], v[16:19], off offset:512
	global_store_dwordx4 v[36:37], v[20:23], off offset:528
	global_load_dword v24, v[30:31], off sc1
	s_nop 0
	global_load_dwordx4 v[16:19], v[34:35], off
	v_lshl_add_u64 v[20:21], v[28:29], 2, s[14:15]
	v_lshl_add_u64 v[22:23], s[4:5], 0, v[32:33]
	s_waitcnt vmcnt(1)
	v_fmac_f32_e32 v147, 0x3a800000, v24
	v_rsq_f32_e32 v252, v147
	s_nop 0
	v_mul_f32_e32 v253, v147, v252
	v_mul_f32_e32 v253, v253, v252
	v_fmaak_f32 v253, -0.5, v253, 0x3fc00000
	v_mul_f32_e32 v252, v252, v253
	s_waitcnt vmcnt(0)
	v_lshlrev_b32_e32 v24, 16, v16
	v_and_b32_e32 v25, 0xffff0000, v16
	v_lshlrev_b32_e32 v16, 16, v17
	v_and_b32_e32 v17, 0xffff0000, v17
	v_lshlrev_b32_e32 v26, 16, v18
	v_and_b32_e32 v27, 0xffff0000, v18
	v_lshlrev_b32_e32 v18, 16, v19
	v_and_b32_e32 v19, 0xffff0000, v19
	s_nop 0
	s_nop 1
	v_mov_b32_e32 v28, v252
	v_pk_mul_f32 v[12:13], v[12:13], v[28:29] op_sel_hi:[1,0]
	v_pk_mul_f32 v[14:15], v[14:15], v[28:29] op_sel_hi:[1,0]
	v_pk_mul_f32 v[30:31], v[8:9], v[28:29] op_sel_hi:[1,0]
	v_pk_mul_f32 v[32:33], v[10:11], v[28:29] op_sel_hi:[1,0]
	v_pk_fma_f32 v[10:11], v[126:127], v[14:15], v[16:17]
	v_pk_fma_f32 v[8:9], v[124:125], v[12:13], v[24:25]
	v_pk_fma_f32 v[14:15], v[122:123], v[32:33], v[18:19]
	v_pk_fma_f32 v[12:13], v[120:121], v[30:31], v[26:27]
	global_store_dwordx4 v[20:21], v[8:11], off
	global_store_dwordx4 v[20:21], v[12:15], off offset:16
	global_load_dwordx4 v[8:11], v[22:23], off
	v_pk_mul_f32 v[4:5], v[4:5], v[28:29] op_sel_hi:[1,0]
	v_pk_mul_f32 v[6:7], v[6:7], v[28:29] op_sel_hi:[1,0]
	v_pk_mul_f32 v[12:13], v[0:1], v[28:29] op_sel_hi:[1,0]
	v_pk_mul_f32 v[14:15], v[2:3], v[28:29] op_sel_hi:[1,0]
	s_waitcnt vmcnt(0)
	v_lshlrev_b32_e32 v0, 16, v8
	v_and_b32_e32 v1, 0xffff0000, v8
	v_lshlrev_b32_e32 v2, 16, v9
	v_and_b32_e32 v3, 0xffff0000, v9
	v_lshlrev_b32_e32 v8, 16, v10
	v_and_b32_e32 v9, 0xffff0000, v10
	v_lshlrev_b32_e32 v10, 16, v11
	v_and_b32_e32 v11, 0xffff0000, v11
	v_pk_fma_f32 v[2:3], v[118:119], v[6:7], v[2:3]
	v_pk_fma_f32 v[0:1], v[116:117], v[4:5], v[0:1]
	v_pk_fma_f32 v[6:7], v[110:111], v[14:15], v[10:11]
	v_pk_fma_f32 v[4:5], v[108:109], v[12:13], v[8:9]
	global_store_dwordx4 v[20:21], v[0:3], off offset:512
	global_store_dwordx4 v[20:21], v[4:7], off offset:528
	s_barrier

; DI unsigned pk_bf16(float lo, float hi) { f32x2 v = {lo, hi}; bf16x2_t b = __builtin_convertvector(v, bf16x2_t); return __builtin_bit_cast(unsigned, b); }
; DI float bflo(unsigned w) { return __uint_as_float(w << 16); }
; DI float bfhi(unsigned w) { return __uint_as_float(w & 0xffff0000u); }
;     __device__ __forceinline__ void fused(f32x4 (&acc)[2][2][4][2], const pg8::Unit& u, int wr, int wc, int fr, int fq, PG8_LAS unsigned char* lds, int wid, int lane) const {
;     ...
;             for (int m = 0; m < 4; ++m) {
;                 const int rl = ai * 128 + wr * 64 + m * 16 + fr; const size_t row = (size_t)u.pm * 256 + rl;
;                 const float rm = 1.f / sqrtf(__hip_atomic_load(ssqm + row, __ATOMIC_RELAXED, __HIP_MEMORY_SCOPE_AGENT) * (1.f / DM) + RMS_EPS);
;                 float sh = 0.f;
; #pragma unroll
;                 for (int bj = 0; bj < 2; ++bj) {
;                     const size_t off = row * DM + colb + bj * 128;
;                     f32x4 h0, h1;
;                     if (IN16) { const u32x4 hw = *(const u32x4*)((const bf16_t*)hin + off); h0 = (f32x4){bflo(hw.x), bfhi(hw.x), bflo(hw.y), bfhi(hw.y)}; h1 = (f32x4){bflo(hw.z), bfhi(hw.z), bflo(hw.w), bfhi(hw.w)}; }
;                     else { h0 = *(const f32x4*)((const float*)hin + off); h1 = *(const f32x4*)((const float*)hin + off + 4); }
;                     h0 = h0 + acc[ai][bj][m][0] * rm * gv[bj][0]; h1 = h1 + acc[ai][bj][m][1] * rm * gv[bj][1];
;                     sh += ((h0[0] * h0[0] + h0[1] * h0[1]) + (h0[2] * h0[2] + h0[3] * h0[3])) + ((h1[0] * h1[0] + h1[1] * h1[1]) + (h1[2] * h1[2] + h1[3] * h1[3]));
;                     if (OUT16) { u32x4 w; w.x = pk_bf16(h0[0], h0[1]); w.y = pk_bf16(h0[2], h0[3]); w.z = pk_bf16(h1[0], h1[1]); w.w = pk_bf16(h1[2], h1[3]); *(u32x4*)((bf16_t*)hout + off) = w; }
;                     else { *(f32x4*)((float*)hout + off) = h0; *(f32x4*)((float*)hout + off + 4) = h1; }
;                 }
.LBB0_1666:
	s_or_b64 exec, exec, s[0:1]
	s_lshl_b32 s0, s26, 5
	s_lshl_b32 s1, s22, 8
	s_or_b32 s0, s1, s0
	v_or_b32_e32 v144, s0, v156
	s_lshl_b64 s[2:3], s[2:3], 8
	v_mov_b32_e32 v153, 0
	v_ashrrev_i32_e32 v145, 31, v144
	v_lshl_add_u64 v[146:147], s[2:3], 0, v[152:153]
	v_lshl_add_u64 v[116:117], v[144:145], 2, s[8:9]
	v_lshl_add_u64 v[148:149], v[146:147], 2, s[6:7]
	s_barrier
	global_load_dwordx4 v[120:123], v[116:117], off offset:16
	global_load_dwordx4 v[124:127], v[116:117], off
	global_load_dwordx4 v[112:115], v[116:117], off offset:528
	s_nop 0
	global_load_dwordx4 v[116:119], v[116:117], off offset:512
	v_lshlrev_b64 v[146:147], 10, v[146:147]
	global_load_dword v158, v[148:149], off sc1
	v_lshl_add_u64 v[154:155], v[146:147], 0, v[144:145]
	v_lshlrev_b64 v[156:157], 1, v[154:155]
	v_lshl_add_u64 v[146:147], s[4:5], 0, v[156:157]
	global_load_dwordx4 v[148:151], v[146:147], off
	v_mov_b32_e32 v147, 0x358637bd
	s_mov_b32 s8, 0xf800000
	v_mov_b32_e32 v146, 0x260
	v_readlane_b32 s12, v251, 0
	v_readlane_b32 s14, v251, 2
	v_readlane_b32 s15, v251, 3
	s_mov_b64 s[10:11], s[14:15]
	v_lshl_add_u64 v[154:155], v[154:155], 2, s[10:11]
	v_or_b32_e32 v156, 0x100, v156
	v_lshl_add_u64 v[156:157], s[4:5], 0, v[156:157]
	v_readlane_b32 s13, v251, 1
	s_waitcnt vmcnt(1)
	v_fmamk_f32 v158, v158, 0x3a800000, v147
	v_rsq_f32_e32 v252, v158
	s_nop 0
	v_mul_f32_e32 v253, v158, v252
	v_mul_f32_e32 v253, v253, v252
	v_fmaak_f32 v253, -0.5, v253, 0x3fc00000
	v_mul_f32_e32 v252, v252, v253
	s_waitcnt vmcnt(0)
	v_lshlrev_b32_e32 v160, 16, v150
	v_lshlrev_b32_e32 v158, 16, v148
	v_and_b32_e32 v159, 0xffff0000, v148
	v_lshlrev_b32_e32 v148, 16, v149
	v_and_b32_e32 v149, 0xffff0000, v149
	v_and_b32_e32 v161, 0xffff0000, v150
	v_lshlrev_b32_e32 v150, 16, v151
	v_and_b32_e32 v151, 0xffff0000, v151
	s_nop 1
	v_mov_b32_e32 v162, v252
	v_pk_mul_f32 v[140:141], v[140:141], v[162:163] op_sel_hi:[1,0]
	v_pk_mul_f32 v[142:143], v[142:143], v[162:163] op_sel_hi:[1,0]
	v_pk_mul_f32 v[164:165], v[136:137], v[162:163] op_sel_hi:[1,0]
	v_pk_mul_f32 v[166:167], v[138:139], v[162:163] op_sel_hi:[1,0]
	v_pk_fma_f32 v[138:139], v[126:127], v[142:143], v[148:149]
	v_pk_fma_f32 v[136:137], v[124:125], v[140:141], v[158:159]
	v_pk_fma_f32 v[142:143], v[122:123], v[166:167], v[150:151]
	v_pk_fma_f32 v[140:141], v[120:121], v[164:165], v[160:161]
	global_store_dwordx4 v[154:155], v[136:139], off
	global_store_dwordx4 v[154:155], v[140:143], off offset:16
	global_load_dwordx4 v[136:139], v[156:157], off
	v_pk_mul_f32 v[132:133], v[132:133], v[162:163] op_sel_hi:[1,0]
	v_or_b32_e32 v140, 16, v152
	v_mov_b32_e32 v141, v153
	v_lshl_add_u64 v[140:141], s[2:3], 0, v[140:141]
	v_lshl_add_u64 v[142:143], v[140:141], 2, s[6:7]
	v_lshlrev_b64 v[140:141], 10, v[140:141]
	v_pk_mul_f32 v[134:135], v[134:135], v[162:163] op_sel_hi:[1,0]
	v_pk_mul_f32 v[156:157], v[128:129], v[162:163] op_sel_hi:[1,0]
	v_pk_mul_f32 v[158:159], v[130:131], v[162:163] op_sel_hi:[1,0]
	v_lshl_add_u64 v[140:141], v[140:141], 0, v[144:145]
	v_lshlrev_b64 v[148:149], 1, v[140:141]
	v_lshl_add_u64 v[150:151], s[4:5], 0, v[148:149]
	v_or_b32_e32 v148, 0x100, v148
	s_waitcnt vmcnt(0)
	v_lshlrev_b32_e32 v128, 16, v136
	v_and_b32_e32 v129, 0xffff0000, v136
	v_lshlrev_b32_e32 v130, 16, v137
	v_and_b32_e32 v131, 0xffff0000, v137
	v_lshlrev_b32_e32 v136, 16, v138
	v_and_b32_e32 v137, 0xffff0000, v138
	v_lshlrev_b32_e32 v138, 16, v139
	v_and_b32_e32 v139, 0xffff0000, v139
	v_pk_fma_f32 v[130:131], v[118:119], v[134:135], v[130:131]
	v_pk_fma_f32 v[128:129], v[116:117], v[132:133], v[128:129]
	v_pk_fma_f32 v[134:135], v[114:115], v[158:159], v[138:139]
	v_pk_fma_f32 v[132:133], v[112:113], v[156:157], v[136:137]
	global_store_dwordx4 v[154:155], v[128:131], off offset:512
	global_store_dwordx4 v[154:155], v[132:135], off offset:528
	global_load_dword v136, v[142:143], off sc1
	s_nop 0
	global_load_dwordx4 v[128:131], v[150:151], off
	v_lshl_add_u64 v[132:133], v[140:141], 2, s[10:11]
	v_lshl_add_u64 v[134:135], s[4:5], 0, v[148:149]
	s_waitcnt vmcnt(1)
	v_fmamk_f32 v138, v136, 0x3a800000, v147
	v_rsq_f32_e32 v252, v138
	s_nop 0
	v_mul_f32_e32 v253, v138, v252
	v_mul_f32_e32 v253, v253, v252
	v_fmaak_f32 v253, -0.5, v253, 0x3fc00000
	v_mul_f32_e32 v252, v252, v253
	s_waitcnt vmcnt(0)
	v_lshlrev_b32_e32 v136, 16, v128
	v_and_b32_e32 v137, 0xffff0000, v128
	v_lshlrev_b32_e32 v128, 16, v129
	v_and_b32_e32 v129, 0xffff0000, v129
	v_lshlrev_b32_e32 v138, 16, v130
	v_and_b32_e32 v139, 0xffff0000, v130
	v_lshlrev_b32_e32 v130, 16, v131
	v_and_b32_e32 v131, 0xffff0000, v131
	s_nop 0
	s_nop 1
	v_mov_b32_e32 v140, v252
	v_pk_mul_f32 v[108:109], v[108:109], v[140:141] op_sel_hi:[1,0]
	v_pk_mul_f32 v[110:111], v[110:111], v[140:141] op_sel_hi:[1,0]
	v_pk_mul_f32 v[142:143], v[104:105], v[140:141] op_sel_hi:[1,0]
	v_pk_mul_f32 v[148:149], v[106:107], v[140:141] op_sel_hi:[1,0]
	v_pk_fma_f32 v[106:107], v[126:127], v[110:111], v[128:129]
	v_pk_fma_f32 v[104:105], v[124:125], v[108:109], v[136:137]
	v_pk_fma_f32 v[110:111], v[122:123], v[148:149], v[130:131]
	v_pk_fma_f32 v[108:109], v[120:121], v[142:143], v[138:139]
	global_store_dwordx4 v[132:133], v[104:107], off
	global_store_dwordx4 v[132:133], v[108:111], off offset:16
	global_load_dwordx4 v[104:107], v[134:135], off
	v_pk_mul_f32 v[100:101], v[100:101], v[140:141] op_sel_hi:[1,0]
	v_or_b32_e32 v108, 32, v152
	v_mov_b32_e32 v109, v153
	v_lshl_add_u64 v[108:109], s[2:3], 0, v[108:109]
	v_lshl_add_u64 v[110:111], v[108:109], 2, s[6:7]
	v_lshlrev_b64 v[108:109], 10, v[108:109]
	v_pk_mul_f32 v[102:103], v[102:103], v[140:141] op_sel_hi:[1,0]
	v_pk_mul_f32 v[134:135], v[96:97], v[140:141] op_sel_hi:[1,0]
	v_pk_mul_f32 v[136:137], v[98:99], v[140:141] op_sel_hi:[1,0]
	v_lshl_add_u64 v[108:109], v[108:109], 0, v[144:145]
	v_lshlrev_b64 v[128:129], 1, v[108:109]
	v_lshl_add_u64 v[130:131], s[4:5], 0, v[128:129]
	v_or_b32_e32 v128, 0x100, v128
	s_waitcnt vmcnt(0)
; DI unsigned pk_bf16(float lo, float hi) { f32x2 v = {lo, hi}; bf16x2_t b = __builtin_convertvector(v, bf16x2_t); return __builtin_bit_cast(unsigned, b); }
; DI float bflo(unsigned w) { return __uint_as_float(w << 16); }
; DI float bfhi(unsigned w) { return __uint_as_float(w & 0xffff0000u); }
;     __device__ __forceinline__ void fused(f32x4 (&acc)[2][2][4][2], const pg8::Unit& u, int wr, int wc, int fr, int fq, PG8_LAS unsigned char* lds, int wid, int lane) const {
;     ...
;             for (int m = 0; m < 4; ++m) {
;                 const int rl = ai * 128 + wr * 64 + m * 16 + fr; const size_t row = (size_t)u.pm * 256 + rl;
;                 const float rm = 1.f / sqrtf(__hip_atomic_load(ssqm + row, __ATOMIC_RELAXED, __HIP_MEMORY_SCOPE_AGENT) * (1.f / DM) + RMS_EPS);
;                 float sh = 0.f;
; #pragma unroll
;                 for (int bj = 0; bj < 2; ++bj) {
;                     const size_t off = row * DM + colb + bj * 128;
;                     f32x4 h0, h1;
;                     if (IN16) { const u32x4 hw = *(const u32x4*)((const bf16_t*)hin + off); h0 = (f32x4){bflo(hw.x), bfhi(hw.x), bflo(hw.y), bfhi(hw.y)}; h1 = (f32x4){bflo(hw.z), bfhi(hw.z), bflo(hw.w), bfhi(hw.w)}; }
;                     else { h0 = *(const f32x4*)((const float*)hin + off); h1 = *(const f32x4*)((const float*)hin + off + 4); }
;                     h0 = h0 + acc[ai][bj][m][0] * rm * gv[bj][0]; h1 = h1 + acc[ai][bj][m][1] * rm * gv[bj][1];
;                     sh += ((h0[0] * h0[0] + h0[1] * h0[1]) + (h0[2] * h0[2] + h0[3] * h0[3])) + ((h1[0] * h1[0] + h1[1] * h1[1]) + (h1[2] * h1[2] + h1[3] * h1[3]));
;                     if (OUT16) { u32x4 w; w.x = pk_bf16(h0[0], h0[1]); w.y = pk_bf16(h0[2], h0[3]); w.z = pk_bf16(h1[0], h1[1]); w.w = pk_bf16(h1[2], h1[3]); *(u32x4*)((bf16_t*)hout + off) = w; }
;                     else { *(f32x4*)((float*)hout + off) = h0; *(f32x4*)((float*)hout + off + 4) = h1; }
;                 }
	v_lshlrev_b32_e32 v96, 16, v104
	v_and_b32_e32 v97, 0xffff0000, v104
	v_lshlrev_b32_e32 v98, 16, v105
	v_and_b32_e32 v99, 0xffff0000, v105
	v_lshlrev_b32_e32 v104, 16, v106
	v_and_b32_e32 v105, 0xffff0000, v106
	v_lshlrev_b32_e32 v106, 16, v107
	v_and_b32_e32 v107, 0xffff0000, v107
	v_pk_fma_f32 v[98:99], v[118:119], v[102:103], v[98:99]
	v_pk_fma_f32 v[96:97], v[116:117], v[100:101], v[96:97]
	v_pk_fma_f32 v[102:103], v[114:115], v[136:137], v[106:107]
	v_pk_fma_f32 v[100:101], v[112:113], v[134:135], v[104:105]
	global_store_dwordx4 v[132:133], v[96:99], off offset:512
	global_store_dwordx4 v[132:133], v[100:103], off offset:528
	global_load_dword v104, v[110:111], off sc1
	s_nop 0
	global_load_dwordx4 v[96:99], v[130:131], off
	v_lshl_add_u64 v[100:101], v[108:109], 2, s[10:11]
	v_lshl_add_u64 v[102:103], s[4:5], 0, v[128:129]
	s_waitcnt vmcnt(1)
	v_fmamk_f32 v106, v104, 0x3a800000, v147
	v_rsq_f32_e32 v252, v106
	s_nop 0
	v_mul_f32_e32 v253, v106, v252
	v_mul_f32_e32 v253, v253, v252
	v_fmaak_f32 v253, -0.5, v253, 0x3fc00000
	v_mul_f32_e32 v252, v252, v253
	s_waitcnt vmcnt(0)
	v_lshlrev_b32_e32 v104, 16, v96
	v_and_b32_e32 v105, 0xffff0000, v96
	v_lshlrev_b32_e32 v96, 16, v97
	v_and_b32_e32 v97, 0xffff0000, v97
	v_lshlrev_b32_e32 v106, 16, v98
	v_and_b32_e32 v107, 0xffff0000, v98
	v_lshlrev_b32_e32 v98, 16, v99
	v_and_b32_e32 v99, 0xffff0000, v99
	s_nop 0
	s_nop 1
	v_mov_b32_e32 v108, v252
	v_pk_mul_f32 v[92:93], v[92:93], v[108:109] op_sel_hi:[1,0]
	v_pk_mul_f32 v[94:95], v[94:95], v[108:109] op_sel_hi:[1,0]
	v_pk_mul_f32 v[110:111], v[88:89], v[108:109] op_sel_hi:[1,0]
	v_pk_mul_f32 v[128:129], v[90:91], v[108:109] op_sel_hi:[1,0]
	v_pk_fma_f32 v[90:91], v[126:127], v[94:95], v[96:97]
	v_pk_fma_f32 v[88:89], v[124:125], v[92:93], v[104:105]
	v_pk_fma_f32 v[94:95], v[122:123], v[128:129], v[98:99]
	v_pk_fma_f32 v[92:93], v[120:121], v[110:111], v[106:107]
	global_store_dwordx4 v[100:101], v[88:91], off
	global_store_dwordx4 v[100:101], v[92:95], off offset:16
	global_load_dwordx4 v[88:91], v[102:103], off
	v_pk_mul_f32 v[84:85], v[84:85], v[108:109] op_sel_hi:[1,0]
	v_or_b32_e32 v92, 48, v152
	v_mov_b32_e32 v93, v153
	v_lshl_add_u64 v[92:93], s[2:3], 0, v[92:93]
	v_lshl_add_u64 v[94:95], v[92:93], 2, s[6:7]
	v_lshlrev_b64 v[92:93], 10, v[92:93]
	v_pk_mul_f32 v[86:87], v[86:87], v[108:109] op_sel_hi:[1,0]
	v_pk_mul_f32 v[102:103], v[80:81], v[108:109] op_sel_hi:[1,0]
	v_pk_mul_f32 v[104:105], v[82:83], v[108:109] op_sel_hi:[1,0]
	v_lshl_add_u64 v[92:93], v[92:93], 0, v[144:145]
	v_lshlrev_b64 v[96:97], 1, v[92:93]
	v_lshl_add_u64 v[98:99], s[4:5], 0, v[96:97]
	v_or_b32_e32 v96, 0x100, v96
	s_waitcnt vmcnt(0)
	v_lshlrev_b32_e32 v80, 16, v88
	v_and_b32_e32 v81, 0xffff0000, v88
	v_lshlrev_b32_e32 v82, 16, v89
	v_and_b32_e32 v83, 0xffff0000, v89
	v_lshlrev_b32_e32 v88, 16, v90
	v_and_b32_e32 v89, 0xffff0000, v90
	v_lshlrev_b32_e32 v90, 16, v91
	v_and_b32_e32 v91, 0xffff0000, v91
	v_pk_fma_f32 v[82:83], v[118:119], v[86:87], v[82:83]
	v_pk_fma_f32 v[80:81], v[116:117], v[84:85], v[80:81]
	v_pk_fma_f32 v[86:87], v[114:115], v[104:105], v[90:91]
	v_pk_fma_f32 v[84:85], v[112:113], v[102:103], v[88:89]
	global_store_dwordx4 v[100:101], v[80:83], off offset:512
	global_store_dwordx4 v[100:101], v[84:87], off offset:528
	global_load_dword v88, v[94:95], off sc1
	s_nop 0
	global_load_dwordx4 v[80:83], v[98:99], off
	v_lshl_add_u64 v[84:85], v[92:93], 2, s[10:11]
	v_lshl_add_u64 v[86:87], s[4:5], 0, v[96:97]
	s_waitcnt vmcnt(1)
	v_fmamk_f32 v90, v88, 0x3a800000, v147
	v_rsq_f32_e32 v252, v90
	s_nop 0
	v_mul_f32_e32 v253, v90, v252
	v_mul_f32_e32 v253, v253, v252
	v_fmaak_f32 v253, -0.5, v253, 0x3fc00000
	v_mul_f32_e32 v252, v252, v253
	s_waitcnt vmcnt(0)
	v_lshlrev_b32_e32 v88, 16, v80
	v_and_b32_e32 v89, 0xffff0000, v80
	v_lshlrev_b32_e32 v80, 16, v81
	v_and_b32_e32 v81, 0xffff0000, v81
	v_lshlrev_b32_e32 v90, 16, v82
	v_and_b32_e32 v91, 0xffff0000, v82
	v_lshlrev_b32_e32 v82, 16, v83
	v_and_b32_e32 v83, 0xffff0000, v83
	s_nop 0
	s_nop 1
	v_mov_b32_e32 v92, v252
	v_pk_mul_f32 v[76:77], v[76:77], v[92:93] op_sel_hi:[1,0]
	v_pk_mul_f32 v[78:79], v[78:79], v[92:93] op_sel_hi:[1,0]
	v_pk_mul_f32 v[94:95], v[72:73], v[92:93] op_sel_hi:[1,0]
	v_pk_mul_f32 v[96:97], v[74:75], v[92:93] op_sel_hi:[1,0]
	v_pk_fma_f32 v[74:75], v[126:127], v[78:79], v[80:81]
	v_pk_fma_f32 v[72:73], v[124:125], v[76:77], v[88:89]
	v_pk_fma_f32 v[78:79], v[122:123], v[96:97], v[82:83]
	v_pk_fma_f32 v[76:77], v[120:121], v[94:95], v[90:91]
	global_store_dwordx4 v[84:85], v[72:75], off
	global_store_dwordx4 v[84:85], v[76:79], off offset:16
	global_load_dwordx4 v[72:75], v[86:87], off
	v_pk_mul_f32 v[68:69], v[68:69], v[92:93] op_sel_hi:[1,0]
	v_add_u32_e32 v76, 0x80, v152
	v_mov_b32_e32 v77, v153
	v_lshl_add_u64 v[76:77], s[2:3], 0, v[76:77]
	v_lshl_add_u64 v[78:79], v[76:77], 2, s[6:7]
	v_lshlrev_b64 v[76:77], 10, v[76:77]
	v_pk_mul_f32 v[70:71], v[70:71], v[92:93] op_sel_hi:[1,0]
	v_pk_mul_f32 v[86:87], v[64:65], v[92:93] op_sel_hi:[1,0]
	v_pk_mul_f32 v[88:89], v[66:67], v[92:93] op_sel_hi:[1,0]
	v_lshl_add_u64 v[76:77], v[76:77], 0, v[144:145]
	v_lshlrev_b64 v[80:81], 1, v[76:77]
	v_lshl_add_u64 v[82:83], s[4:5], 0, v[80:81]
	v_or_b32_e32 v80, 0x100, v80
	s_waitcnt vmcnt(0)
; DI unsigned pk_bf16(float lo, float hi) { f32x2 v = {lo, hi}; bf16x2_t b = __builtin_convertvector(v, bf16x2_t); return __builtin_bit_cast(unsigned, b); }
; DI float bflo(unsigned w) { return __uint_as_float(w << 16); }
; DI float bfhi(unsigned w) { return __uint_as_float(w & 0xffff0000u); }
;     __device__ __forceinline__ void fused(f32x4 (&acc)[2][2][4][2], const pg8::Unit& u, int wr, int wc, int fr, int fq, PG8_LAS unsigned char* lds, int wid, int lane) const {
;     ...
;         for (int ai = 0; ai < 2; ++ai)
; #pragma unroll
;             for (int m = 0; m < 4; ++m) {
;                 const int rl = ai * 128 + wr * 64 + m * 16 + fr; const size_t row = (size_t)u.pm * 256 + rl;
;                 const float rm = 1.f / sqrtf(__hip_atomic_load(ssqm + row, __ATOMIC_RELAXED, __HIP_MEMORY_SCOPE_AGENT) * (1.f / DM) + RMS_EPS);
;                 float sh = 0.f;
; #pragma unroll
;                 for (int bj = 0; bj < 2; ++bj) {
;                     const size_t off = row * DM + colb + bj * 128;
;                     f32x4 h0, h1;
;                     if (IN16) { const u32x4 hw = *(const u32x4*)((const bf16_t*)hin + off); h0 = (f32x4){bflo(hw.x), bfhi(hw.x), bflo(hw.y), bfhi(hw.y)}; h1 = (f32x4){bflo(hw.z), bfhi(hw.z), bflo(hw.w), bfhi(hw.w)}; }
;                     else { h0 = *(const f32x4*)((const float*)hin + off); h1 = *(const f32x4*)((const float*)hin + off + 4); }
;                     h0 = h0 + acc[ai][bj][m][0] * rm * gv[bj][0]; h1 = h1 + acc[ai][bj][m][1] * rm * gv[bj][1];
;                     sh += ((h0[0] * h0[0] + h0[1] * h0[1]) + (h0[2] * h0[2] + h0[3] * h0[3])) + ((h1[0] * h1[0] + h1[1] * h1[1]) + (h1[2] * h1[2] + h1[3] * h1[3]));
;                     if (OUT16) { u32x4 w; w.x = pk_bf16(h0[0], h0[1]); w.y = pk_bf16(h0[2], h0[3]); w.z = pk_bf16(h1[0], h1[1]); w.w = pk_bf16(h1[2], h1[3]); *(u32x4*)((bf16_t*)hout + off) = w; }
;                     else { *(f32x4*)((float*)hout + off) = h0; *(f32x4*)((float*)hout + off + 4) = h1; }
;                 }
	v_lshlrev_b32_e32 v64, 16, v72
	v_and_b32_e32 v65, 0xffff0000, v72
	v_lshlrev_b32_e32 v66, 16, v73
	v_and_b32_e32 v67, 0xffff0000, v73
	v_lshlrev_b32_e32 v72, 16, v74
	v_and_b32_e32 v73, 0xffff0000, v74
	v_lshlrev_b32_e32 v74, 16, v75
	v_and_b32_e32 v75, 0xffff0000, v75
	v_pk_fma_f32 v[66:67], v[118:119], v[70:71], v[66:67]
	v_pk_fma_f32 v[64:65], v[116:117], v[68:69], v[64:65]
	v_pk_fma_f32 v[70:71], v[114:115], v[88:89], v[74:75]
	v_pk_fma_f32 v[68:69], v[112:113], v[86:87], v[72:73]
	global_store_dwordx4 v[84:85], v[64:67], off offset:512
	global_store_dwordx4 v[84:85], v[68:71], off offset:528
	global_load_dword v72, v[78:79], off sc1
	s_nop 0
	global_load_dwordx4 v[64:67], v[82:83], off
	v_lshl_add_u64 v[68:69], v[76:77], 2, s[10:11]
	v_lshl_add_u64 v[70:71], s[4:5], 0, v[80:81]
	s_waitcnt vmcnt(1)
	v_fmamk_f32 v74, v72, 0x3a800000, v147
	v_rsq_f32_e32 v252, v74
	s_nop 0
	v_mul_f32_e32 v253, v74, v252
	v_mul_f32_e32 v253, v253, v252
	v_fmaak_f32 v253, -0.5, v253, 0x3fc00000
	v_mul_f32_e32 v252, v252, v253
	s_waitcnt vmcnt(0)
	v_lshlrev_b32_e32 v72, 16, v64
	v_and_b32_e32 v73, 0xffff0000, v64
	v_lshlrev_b32_e32 v64, 16, v65
	v_and_b32_e32 v65, 0xffff0000, v65
	v_lshlrev_b32_e32 v74, 16, v66
	v_and_b32_e32 v75, 0xffff0000, v66
	v_lshlrev_b32_e32 v66, 16, v67
	v_and_b32_e32 v67, 0xffff0000, v67
	s_nop 0
	s_nop 1
	v_mov_b32_e32 v76, v252
	v_pk_mul_f32 v[60:61], v[60:61], v[76:77] op_sel_hi:[1,0]
	v_pk_mul_f32 v[62:63], v[62:63], v[76:77] op_sel_hi:[1,0]
	v_pk_mul_f32 v[78:79], v[56:57], v[76:77] op_sel_hi:[1,0]
	v_pk_mul_f32 v[80:81], v[58:59], v[76:77] op_sel_hi:[1,0]
	v_pk_fma_f32 v[58:59], v[126:127], v[62:63], v[64:65]
	v_pk_fma_f32 v[56:57], v[124:125], v[60:61], v[72:73]
	v_pk_fma_f32 v[62:63], v[122:123], v[80:81], v[66:67]
	v_pk_fma_f32 v[60:61], v[120:121], v[78:79], v[74:75]
	global_store_dwordx4 v[68:69], v[56:59], off
	global_store_dwordx4 v[68:69], v[60:63], off offset:16
	global_load_dwordx4 v[56:59], v[70:71], off
	v_pk_mul_f32 v[52:53], v[52:53], v[76:77] op_sel_hi:[1,0]
	v_add_u32_e32 v60, 0x90, v152
	v_mov_b32_e32 v61, v153
	v_lshl_add_u64 v[60:61], s[2:3], 0, v[60:61]
	v_lshl_add_u64 v[62:63], v[60:61], 2, s[6:7]
	v_lshlrev_b64 v[60:61], 10, v[60:61]
	v_pk_mul_f32 v[54:55], v[54:55], v[76:77] op_sel_hi:[1,0]
	v_pk_mul_f32 v[70:71], v[48:49], v[76:77] op_sel_hi:[1,0]
	v_pk_mul_f32 v[72:73], v[50:51], v[76:77] op_sel_hi:[1,0]
	v_lshl_add_u64 v[60:61], v[60:61], 0, v[144:145]
	v_lshlrev_b64 v[64:65], 1, v[60:61]
	v_lshl_add_u64 v[66:67], s[4:5], 0, v[64:65]
	v_or_b32_e32 v64, 0x100, v64
	s_waitcnt vmcnt(0)
	v_lshlrev_b32_e32 v48, 16, v56
	v_and_b32_e32 v49, 0xffff0000, v56
	v_lshlrev_b32_e32 v50, 16, v57
	v_and_b32_e32 v51, 0xffff0000, v57
	v_lshlrev_b32_e32 v56, 16, v58
	v_and_b32_e32 v57, 0xffff0000, v58
	v_lshlrev_b32_e32 v58, 16, v59
	v_and_b32_e32 v59, 0xffff0000, v59
	v_pk_fma_f32 v[50:51], v[118:119], v[54:55], v[50:51]
	v_pk_fma_f32 v[48:49], v[116:117], v[52:53], v[48:49]
	v_pk_fma_f32 v[54:55], v[114:115], v[72:73], v[58:59]
	v_pk_fma_f32 v[52:53], v[112:113], v[70:71], v[56:57]
	global_store_dwordx4 v[68:69], v[48:51], off offset:512
	global_store_dwordx4 v[68:69], v[52:55], off offset:528
	global_load_dword v56, v[62:63], off sc1
	s_nop 0
	global_load_dwordx4 v[48:51], v[66:67], off
	v_lshl_add_u64 v[52:53], v[60:61], 2, s[10:11]
	v_lshl_add_u64 v[54:55], s[4:5], 0, v[64:65]
	s_waitcnt vmcnt(1)
	v_fmamk_f32 v58, v56, 0x3a800000, v147
	v_rsq_f32_e32 v252, v58
	s_nop 0
	v_mul_f32_e32 v253, v58, v252
	v_mul_f32_e32 v253, v253, v252
	v_fmaak_f32 v253, -0.5, v253, 0x3fc00000
	v_mul_f32_e32 v252, v252, v253
	s_waitcnt vmcnt(0)
	v_lshlrev_b32_e32 v56, 16, v48
	v_and_b32_e32 v57, 0xffff0000, v48
	v_lshlrev_b32_e32 v48, 16, v49
	v_and_b32_e32 v49, 0xffff0000, v49
	v_lshlrev_b32_e32 v58, 16, v50
	v_and_b32_e32 v59, 0xffff0000, v50
	v_lshlrev_b32_e32 v50, 16, v51
	v_and_b32_e32 v51, 0xffff0000, v51
	s_nop 0
	s_nop 1
	v_mov_b32_e32 v60, v252
	v_pk_mul_f32 v[44:45], v[44:45], v[60:61] op_sel_hi:[1,0]
	v_pk_mul_f32 v[46:47], v[46:47], v[60:61] op_sel_hi:[1,0]
	v_pk_mul_f32 v[62:63], v[40:41], v[60:61] op_sel_hi:[1,0]
	v_pk_mul_f32 v[64:65], v[42:43], v[60:61] op_sel_hi:[1,0]
	v_pk_fma_f32 v[42:43], v[126:127], v[46:47], v[48:49]
	v_pk_fma_f32 v[40:41], v[124:125], v[44:45], v[56:57]
	v_pk_fma_f32 v[46:47], v[122:123], v[64:65], v[50:51]
	v_pk_fma_f32 v[44:45], v[120:121], v[62:63], v[58:59]
	global_store_dwordx4 v[52:53], v[40:43], off
	global_store_dwordx4 v[52:53], v[44:47], off offset:16
	global_load_dwordx4 v[40:43], v[54:55], off
	v_pk_mul_f32 v[36:37], v[36:37], v[60:61] op_sel_hi:[1,0]
	v_add_u32_e32 v44, 0xa0, v152
	v_mov_b32_e32 v45, v153
	v_lshl_add_u64 v[44:45], s[2:3], 0, v[44:45]
	v_lshl_add_u64 v[46:47], v[44:45], 2, s[6:7]
	v_lshlrev_b64 v[44:45], 10, v[44:45]
	v_pk_mul_f32 v[38:39], v[38:39], v[60:61] op_sel_hi:[1,0]
	v_pk_mul_f32 v[54:55], v[32:33], v[60:61] op_sel_hi:[1,0]
	v_pk_mul_f32 v[56:57], v[34:35], v[60:61] op_sel_hi:[1,0]
	v_lshl_add_u64 v[44:45], v[44:45], 0, v[144:145]
	v_lshlrev_b64 v[48:49], 1, v[44:45]
	v_lshl_add_u64 v[50:51], s[4:5], 0, v[48:49]
	v_or_b32_e32 v48, 0x100, v48
	v_add_u32_e32 v152, 0xb0, v152
	s_waitcnt vmcnt(0)
; DI unsigned pk_bf16(float lo, float hi) { f32x2 v = {lo, hi}; bf16x2_t b = __builtin_convertvector(v, bf16x2_t); return __builtin_bit_cast(unsigned, b); }
; DI float bflo(unsigned w) { return __uint_as_float(w << 16); }
; DI float bfhi(unsigned w) { return __uint_as_float(w & 0xffff0000u); }
;     __device__ __forceinline__ void fused(f32x4 (&acc)[2][2][4][2], const pg8::Unit& u, int wr, int wc, int fr, int fq, PG8_LAS unsigned char* lds, int wid, int lane) const {
;     ...
;         for (int ai = 0; ai < 2; ++ai)
; #pragma unroll
;             for (int m = 0; m < 4; ++m) {
;                 const int rl = ai * 128 + wr * 64 + m * 16 + fr; const size_t row = (size_t)u.pm * 256 + rl;
;                 const float rm = 1.f / sqrtf(__hip_atomic_load(ssqm + row, __ATOMIC_RELAXED, __HIP_MEMORY_SCOPE_AGENT) * (1.f / DM) + RMS_EPS);
;                 float sh = 0.f;
; #pragma unroll
;                 for (int bj = 0; bj < 2; ++bj) {
;                     const size_t off = row * DM + colb + bj * 128;
;                     f32x4 h0, h1;
;                     if (IN16) { const u32x4 hw = *(const u32x4*)((const bf16_t*)hin + off); h0 = (f32x4){bflo(hw.x), bfhi(hw.x), bflo(hw.y), bfhi(hw.y)}; h1 = (f32x4){bflo(hw.z), bfhi(hw.z), bflo(hw.w), bfhi(hw.w)}; }
;                     else { h0 = *(const f32x4*)((const float*)hin + off); h1 = *(const f32x4*)((const float*)hin + off + 4); }
;                     h0 = h0 + acc[ai][bj][m][0] * rm * gv[bj][0]; h1 = h1 + acc[ai][bj][m][1] * rm * gv[bj][1];
;                     sh += ((h0[0] * h0[0] + h0[1] * h0[1]) + (h0[2] * h0[2] + h0[3] * h0[3])) + ((h1[0] * h1[0] + h1[1] * h1[1]) + (h1[2] * h1[2] + h1[3] * h1[3]));
;                     if (OUT16) { u32x4 w; w.x = pk_bf16(h0[0], h0[1]); w.y = pk_bf16(h0[2], h0[3]); w.z = pk_bf16(h1[0], h1[1]); w.w = pk_bf16(h1[2], h1[3]); *(u32x4*)((bf16_t*)hout + off) = w; }
;                     else { *(f32x4*)((float*)hout + off) = h0; *(f32x4*)((float*)hout + off + 4) = h1; }
;                 }
;                 if (ssqh) { sh += __shfl_xor(sh, 16); sh += __shfl_xor(sh, 32); if (fq == 0) red[rl * 4 + wc] = sh; }
;             }
;         if (ssqh) { __syncthreads(); if (tid < 256) atomicAdd(ssqh + u.pm * 256 + tid, (red[tid * 4] + red[tid * 4 + 1]) + (red[tid * 4 + 2] + red[tid * 4 + 3])); }
;         __syncthreads();
	v_lshlrev_b32_e32 v32, 16, v40
	v_and_b32_e32 v33, 0xffff0000, v40
	v_lshlrev_b32_e32 v34, 16, v41
	v_and_b32_e32 v35, 0xffff0000, v41
	v_lshlrev_b32_e32 v40, 16, v42
	v_and_b32_e32 v41, 0xffff0000, v42
	v_lshlrev_b32_e32 v42, 16, v43
	v_and_b32_e32 v43, 0xffff0000, v43
	v_pk_fma_f32 v[34:35], v[118:119], v[38:39], v[34:35]
	v_pk_fma_f32 v[32:33], v[116:117], v[36:37], v[32:33]
	v_pk_fma_f32 v[38:39], v[114:115], v[56:57], v[42:43]
	v_pk_fma_f32 v[36:37], v[112:113], v[54:55], v[40:41]
	global_store_dwordx4 v[52:53], v[32:35], off offset:512
	global_store_dwordx4 v[52:53], v[36:39], off offset:528
	global_load_dword v40, v[46:47], off sc1
	s_nop 0
	global_load_dwordx4 v[32:35], v[50:51], off
	v_lshl_add_u64 v[36:37], v[44:45], 2, s[10:11]
	v_lshl_add_u64 v[38:39], s[4:5], 0, v[48:49]
	s_waitcnt vmcnt(1)
	v_fmamk_f32 v42, v40, 0x3a800000, v147
	v_rsq_f32_e32 v252, v42
	s_nop 0
	v_mul_f32_e32 v253, v42, v252
	v_mul_f32_e32 v253, v253, v252
	v_fmaak_f32 v253, -0.5, v253, 0x3fc00000
	v_mul_f32_e32 v252, v252, v253
	s_waitcnt vmcnt(0)
	v_lshlrev_b32_e32 v40, 16, v32
	v_and_b32_e32 v41, 0xffff0000, v32
	v_lshlrev_b32_e32 v32, 16, v33
	v_and_b32_e32 v33, 0xffff0000, v33
	v_lshlrev_b32_e32 v42, 16, v34
	v_and_b32_e32 v43, 0xffff0000, v34
	v_lshlrev_b32_e32 v34, 16, v35
	v_and_b32_e32 v35, 0xffff0000, v35
	s_nop 0
	s_nop 1
	v_mov_b32_e32 v44, v252
	v_pk_mul_f32 v[28:29], v[28:29], v[44:45] op_sel_hi:[1,0]
	v_pk_mul_f32 v[30:31], v[30:31], v[44:45] op_sel_hi:[1,0]
	v_pk_mul_f32 v[46:47], v[24:25], v[44:45] op_sel_hi:[1,0]
	v_pk_mul_f32 v[48:49], v[26:27], v[44:45] op_sel_hi:[1,0]
	v_pk_fma_f32 v[26:27], v[126:127], v[30:31], v[32:33]
	v_pk_fma_f32 v[24:25], v[124:125], v[28:29], v[40:41]
	v_pk_fma_f32 v[30:31], v[122:123], v[48:49], v[34:35]
	v_pk_fma_f32 v[28:29], v[120:121], v[46:47], v[42:43]
	global_store_dwordx4 v[36:37], v[24:27], off
	global_store_dwordx4 v[36:37], v[28:31], off offset:16
	global_load_dwordx4 v[24:27], v[38:39], off
	v_pk_mul_f32 v[20:21], v[20:21], v[44:45] op_sel_hi:[1,0]
	v_lshl_add_u64 v[28:29], s[2:3], 0, v[152:153]
	v_lshl_add_u64 v[30:31], v[28:29], 2, s[6:7]
	v_lshlrev_b64 v[28:29], 10, v[28:29]
	v_pk_mul_f32 v[22:23], v[22:23], v[44:45] op_sel_hi:[1,0]
	v_pk_mul_f32 v[38:39], v[16:17], v[44:45] op_sel_hi:[1,0]
	v_pk_mul_f32 v[40:41], v[18:19], v[44:45] op_sel_hi:[1,0]
	v_lshl_add_u64 v[28:29], v[28:29], 0, v[144:145]
	v_lshlrev_b64 v[32:33], 1, v[28:29]
	v_lshl_add_u64 v[34:35], s[4:5], 0, v[32:33]
	v_or_b32_e32 v32, 0x100, v32
	s_waitcnt vmcnt(0)
	v_lshlrev_b32_e32 v16, 16, v24
	v_and_b32_e32 v17, 0xffff0000, v24
	v_lshlrev_b32_e32 v18, 16, v25
	v_and_b32_e32 v19, 0xffff0000, v25
	v_lshlrev_b32_e32 v24, 16, v26
	v_and_b32_e32 v25, 0xffff0000, v26
	v_lshlrev_b32_e32 v26, 16, v27
	v_and_b32_e32 v27, 0xffff0000, v27
	v_pk_fma_f32 v[18:19], v[118:119], v[22:23], v[18:19]
	v_pk_fma_f32 v[16:17], v[116:117], v[20:21], v[16:17]
	v_pk_fma_f32 v[22:23], v[114:115], v[40:41], v[26:27]
	v_pk_fma_f32 v[20:21], v[112:113], v[38:39], v[24:25]
	global_store_dwordx4 v[36:37], v[16:19], off offset:512
	global_store_dwordx4 v[36:37], v[20:23], off offset:528
	global_load_dword v24, v[30:31], off sc1
	s_nop 0
	global_load_dwordx4 v[16:19], v[34:35], off
	v_lshl_add_u64 v[20:21], v[28:29], 2, s[10:11]
	v_lshl_add_u64 v[22:23], s[4:5], 0, v[32:33]
	s_waitcnt vmcnt(1)
	v_fmac_f32_e32 v147, 0x3a800000, v24
	v_rsq_f32_e32 v252, v147
	s_nop 0
	v_mul_f32_e32 v253, v147, v252
	v_mul_f32_e32 v253, v253, v252
	v_fmaak_f32 v253, -0.5, v253, 0x3fc00000
	v_mul_f32_e32 v252, v252, v253
	s_waitcnt vmcnt(0)
	v_lshlrev_b32_e32 v24, 16, v16
	v_and_b32_e32 v25, 0xffff0000, v16
	v_lshlrev_b32_e32 v16, 16, v17
	v_and_b32_e32 v17, 0xffff0000, v17
	v_lshlrev_b32_e32 v26, 16, v18
	v_and_b32_e32 v27, 0xffff0000, v18
	v_lshlrev_b32_e32 v18, 16, v19
	v_and_b32_e32 v19, 0xffff0000, v19
	s_nop 0
	s_nop 1
	v_mov_b32_e32 v28, v252
	v_pk_mul_f32 v[12:13], v[12:13], v[28:29] op_sel_hi:[1,0]
	v_pk_mul_f32 v[14:15], v[14:15], v[28:29] op_sel_hi:[1,0]
	v_pk_mul_f32 v[30:31], v[8:9], v[28:29] op_sel_hi:[1,0]
	v_pk_mul_f32 v[32:33], v[10:11], v[28:29] op_sel_hi:[1,0]
	v_pk_fma_f32 v[10:11], v[126:127], v[14:15], v[16:17]
	v_pk_fma_f32 v[8:9], v[124:125], v[12:13], v[24:25]
	v_pk_fma_f32 v[14:15], v[122:123], v[32:33], v[18:19]
	v_pk_fma_f32 v[12:13], v[120:121], v[30:31], v[26:27]
	global_store_dwordx4 v[20:21], v[8:11], off
	global_store_dwordx4 v[20:21], v[12:15], off offset:16
	global_load_dwordx4 v[8:11], v[22:23], off
	v_pk_mul_f32 v[4:5], v[4:5], v[28:29] op_sel_hi:[1,0]
	v_pk_mul_f32 v[6:7], v[6:7], v[28:29] op_sel_hi:[1,0]
	v_pk_mul_f32 v[12:13], v[0:1], v[28:29] op_sel_hi:[1,0]
	v_pk_mul_f32 v[14:15], v[2:3], v[28:29] op_sel_hi:[1,0]
	s_waitcnt vmcnt(0)
	v_lshlrev_b32_e32 v0, 16, v8
	v_and_b32_e32 v1, 0xffff0000, v8
	v_lshlrev_b32_e32 v2, 16, v9
	v_and_b32_e32 v3, 0xffff0000, v9
	v_lshlrev_b32_e32 v8, 16, v10
	v_and_b32_e32 v9, 0xffff0000, v10
	v_lshlrev_b32_e32 v10, 16, v11
	v_and_b32_e32 v11, 0xffff0000, v11
	v_pk_fma_f32 v[2:3], v[118:119], v[6:7], v[2:3]
	v_pk_fma_f32 v[0:1], v[116:117], v[4:5], v[0:1]
	v_pk_fma_f32 v[6:7], v[114:115], v[14:15], v[10:11]
	v_pk_fma_f32 v[4:5], v[112:113], v[12:13], v[8:9]
	global_store_dwordx4 v[20:21], v[0:3], off offset:512
	global_store_dwordx4 v[20:21], v[4:7], off offset:528
	s_barrier
